# baseline (speedup 1.0000x reference)
; #define STAGE(P, BASE, br, kt) do { const char* _gb = (const char*)(BASE) + ((size_t)(br) * K + (size_t)(kt) * BK) * 2; \
;     __builtin_amdgcn_global_load_lds((const unsigned*)(_gb + loff0), (unsigned*)((char*)(P) + tid * 16), 16, 0, 0); \
;     __builtin_amdgcn_global_load_lds((const unsigned*)(_gb + (size_t)K * 128 + loff0), (unsigned*)((char*)(P) + tid * 16 + 8192), 16, 0, 0); } while (0)
; #define LDA(dst, b, h) for (int m = 0; m < 4; ++m) { \
;     dst[m][0] = *reinterpret_cast<const bf16x8*>((char*)SA(b, h) + aoff0 + m * 2048); \
;     dst[m][1] = *reinterpret_cast<const bf16x8*>((char*)SA(b, h) + aoff1 + m * 2048); }
; #define LDB(dst, b, h) for (int n = 0; n < 2; ++n) { \
;     dst[n][0] = *reinterpret_cast<const bf16x8*>((char*)SB(b, h) + boff0 + n * 256); \
;     dst[n][1] = *reinterpret_cast<const bf16x8*>((char*)SB(b, h) + boff1 + n * 256); }
; #define MMA(ai, bj, At, Btf) do { __builtin_amdgcn_s_setprio(1); \
;     for (int m = 0; m < 4; ++m) for (int n = 0; n < 2; ++n) for (int k = 0; k < 2; ++k) \
;       acc[ai][bj][m][n] = __builtin_amdgcn_mfma_f32_16x16x32_bf16(Btf[n][k], At[m][k], acc[ai][bj][m][n], 0, 0, 0); \
;     __builtin_amdgcn_s_setprio(0); } while (0)
; #define WAIT_V(n) asm volatile("s_waitcnt vmcnt(" #n ")" ::: "memory")
; #define WAIT_L(n) asm volatile("s_waitcnt lgkmcnt(" #n ")" ::: "memory")
; #define BAR __builtin_amdgcn_s_barrier()
; template <int EPI> ...
;     ...
;   for (int t = 0; t < nt - 2; t += 2) {
;     LDB(B0, 0, 0); SCHED; LDA(At, 0, 0); STAGE(SA(1, 1), A, brow + HALF, t + 1);
;     WAIT_L(8); BAR; WAIT_L(0); MMA(0, 0, At, B0); BAR; SCHED;
;     LDB(B1, 0, 1); STAGE(SB(0, 0), Bt, bcol, t + 2);
;     BAR; WAIT_L(0); MMA(0, 1, At, B1); BAR;
;     LDA(At, 0, 1); STAGE(SA(0, 0), A, brow, t + 2);
;     BAR; WAIT_L(0); MMA(1, 0, At, B0); BAR; SCHED;
;     STAGE(SB(0, 1), Bt, bcol + HALF, t + 2);
;     WAIT_V(6); BAR; MMA(1, 1, At, B1); BAR;
;     LDB(B0, 1, 0); SCHED; LDA(At, 1, 0); STAGE(SA(0, 1), A, brow + HALF, t + 2);
;     WAIT_L(8); BAR; WAIT_L(0); MMA(0, 0, At, B0); BAR; SCHED;
;     LDB(B1, 1, 1); STAGE(SB(1, 0), Bt, bcol, t + 3);
;     BAR; WAIT_L(0); MMA(0, 1, At, B1); BAR;
;     LDA(At, 1, 1); STAGE(SA(1, 0), A, brow, t + 3);
;     BAR; WAIT_L(0); MMA(1, 0, At, B0); BAR; SCHED;
;     STAGE(SB(1, 1), Bt, bcol + HALF, t + 3);
;     WAIT_V(6); BAR; MMA(1, 1, At, B1); BAR;
;   }
.LBB0_277:
	ds_read_b128 v[162:165], v153
	ds_read_b128 v[166:169], v153 offset:256
	ds_read_b128 v[170:173], v154
	ds_read_b128 v[174:177], v154 offset:256
	v_lshl_add_u64 v[226:227], s[70:71], 0, v[130:131]
	v_readfirstlane_b32 s72, v151
	v_lshl_add_u64 v[210:211], v[226:227], 0, s[18:19]
	s_mov_b32 m0, s72
	v_readfirstlane_b32 s72, v152
	ds_read_b128 v[178:181], v150
	ds_read_b128 v[182:185], v150 offset:1024
	ds_read_b128 v[186:189], v150 offset:2048
	ds_read_b128 v[190:193], v150 offset:3072
	ds_read_b128 v[194:197], v150 offset:4096
	ds_read_b128 v[198:201], v150 offset:5120
	ds_read_b128 v[202:205], v150 offset:6144
	ds_read_b128 v[206:209], v150 offset:7168
	global_load_lds_dwordx4 v[210:211], off
	v_lshl_add_u64 v[210:211], v[226:227], 0, s[20:21]
	s_mov_b32 m0, s72
	s_nop 0
	global_load_lds_dwordx4 v[210:211], off
	s_waitcnt lgkmcnt(8)
	v_readfirstlane_b32 s72, v149
	v_lshl_add_u64 v[246:247], v[228:229], 0, s[60:61]
	s_mov_b32 m0, s72
	s_nop 0
	global_load_lds_dwordx4 v[246:247], off
	ds_read_b128 v[210:213], v155
	ds_read_b128 v[214:217], v155 offset:256
	ds_read_b128 v[218:221], v156
	ds_read_b128 v[222:225], v156 offset:256
	s_barrier
	s_waitcnt lgkmcnt(0)
	s_setprio 1
	v_mfma_f32_16x16x32_bf16 v[124:127], v[162:165], v[178:181], v[124:127]
	v_mfma_f32_16x16x32_bf16 v[120:123], v[166:169], v[178:181], v[120:123]
	v_mfma_f32_16x16x32_bf16 v[116:119], v[162:165], v[186:189], v[116:119]
	v_mfma_f32_16x16x32_bf16 v[112:115], v[166:169], v[186:189], v[112:115]
	v_mfma_f32_16x16x32_bf16 v[108:111], v[162:165], v[194:197], v[108:111]
	v_mfma_f32_16x16x32_bf16 v[104:107], v[166:169], v[194:197], v[104:107]
	v_mfma_f32_16x16x32_bf16 v[100:103], v[162:165], v[202:205], v[100:103]
	v_mfma_f32_16x16x32_bf16 v[96:99], v[166:169], v[202:205], v[96:99]
	v_mfma_f32_16x16x32_bf16 v[124:127], v[170:173], v[182:185], v[124:127]
	v_mfma_f32_16x16x32_bf16 v[120:123], v[174:177], v[182:185], v[120:123]
	v_mfma_f32_16x16x32_bf16 v[116:119], v[170:173], v[190:193], v[116:119]
	v_mfma_f32_16x16x32_bf16 v[112:115], v[174:177], v[190:193], v[112:115]
	v_mfma_f32_16x16x32_bf16 v[108:111], v[170:173], v[198:201], v[108:111]
	v_mfma_f32_16x16x32_bf16 v[104:107], v[174:177], v[198:201], v[104:107]
	v_mfma_f32_16x16x32_bf16 v[100:103], v[170:173], v[206:209], v[100:103]
	v_mfma_f32_16x16x32_bf16 v[96:99], v[174:177], v[206:209], v[96:99]
	v_mfma_f32_16x16x32_bf16 v[92:95], v[210:213], v[178:181], v[92:95]
	v_mfma_f32_16x16x32_bf16 v[88:91], v[214:217], v[178:181], v[88:91]
	v_mfma_f32_16x16x32_bf16 v[84:87], v[210:213], v[186:189], v[84:87]
	v_mfma_f32_16x16x32_bf16 v[80:83], v[214:217], v[186:189], v[80:83]
	v_mfma_f32_16x16x32_bf16 v[76:79], v[210:213], v[194:197], v[76:79]
	v_mfma_f32_16x16x32_bf16 v[72:75], v[214:217], v[194:197], v[72:75]
	v_mfma_f32_16x16x32_bf16 v[68:71], v[210:213], v[202:205], v[68:71]
	v_mfma_f32_16x16x32_bf16 v[64:67], v[214:217], v[202:205], v[64:67]
	v_mfma_f32_16x16x32_bf16 v[92:95], v[218:221], v[182:185], v[92:95]
	v_mfma_f32_16x16x32_bf16 v[88:91], v[222:225], v[182:185], v[88:91]
	v_mfma_f32_16x16x32_bf16 v[84:87], v[218:221], v[190:193], v[84:87]
	v_mfma_f32_16x16x32_bf16 v[80:83], v[222:225], v[190:193], v[80:83]
	v_mfma_f32_16x16x32_bf16 v[76:79], v[218:221], v[198:201], v[76:79]
	v_mfma_f32_16x16x32_bf16 v[72:75], v[222:225], v[198:201], v[72:75]
	v_mfma_f32_16x16x32_bf16 v[68:71], v[218:221], v[206:209], v[68:71]
	v_mfma_f32_16x16x32_bf16 v[64:67], v[222:225], v[206:209], v[64:67]
	s_setprio 0
	s_barrier
	v_lshl_add_u64 v[228:229], s[68:69], 0, v[130:131]
	v_readfirstlane_b32 s72, v136
	v_lshl_add_u64 v[230:231], v[228:229], 0, s[22:23]
	s_mov_b32 m0, s72
	v_readfirstlane_b32 s72, v137
	global_load_lds_dwordx4 v[230:231], off
	v_lshl_add_u64 v[230:231], v[228:229], 0, s[26:27]
	s_mov_b32 m0, s72
	s_nop 0
	global_load_lds_dwordx4 v[230:231], off
	v_readfirstlane_b32 s72, v138
	v_lshl_add_u64 v[230:231], v[226:227], 0, s[28:29]
	s_mov_b32 m0, s72
	v_readfirstlane_b32 s72, v139
	ds_read_b128 v[178:181], v150 offset:16384
	ds_read_b128 v[182:185], v150 offset:17408
	ds_read_b128 v[186:189], v150 offset:18432
	ds_read_b128 v[190:193], v150 offset:19456
	ds_read_b128 v[194:197], v150 offset:20480
	ds_read_b128 v[198:201], v150 offset:21504
	ds_read_b128 v[202:205], v150 offset:22528
	ds_read_b128 v[206:209], v150 offset:23552
	global_load_lds_dwordx4 v[230:231], off
	v_lshl_add_u64 v[230:231], v[226:227], 0, s[30:31]
	s_mov_b32 m0, s72
	s_nop 0
	global_load_lds_dwordx4 v[230:231], off
	v_readfirstlane_b32 s72, v140
	v_lshl_add_u64 v[246:247], v[228:229], 0, s[36:37]
	s_mov_b32 m0, s72
	v_readfirstlane_b32 s72, v141
	global_load_lds_dwordx4 v[246:247], off
	s_waitcnt vmcnt(5)
	s_barrier
; #define STAGE(P, BASE, br, kt) do { const char* _gb = (const char*)(BASE) + ((size_t)(br) * K + (size_t)(kt) * BK) * 2; \
;     __builtin_amdgcn_global_load_lds((const unsigned*)(_gb + loff0), (unsigned*)((char*)(P) + tid * 16), 16, 0, 0); \
;     __builtin_amdgcn_global_load_lds((const unsigned*)(_gb + (size_t)K * 128 + loff0), (unsigned*)((char*)(P) + tid * 16 + 8192), 16, 0, 0); } while (0)
; #define LDA(dst, b, h) for (int m = 0; m < 4; ++m) { \
;     dst[m][0] = *reinterpret_cast<const bf16x8*>((char*)SA(b, h) + aoff0 + m * 2048); \
;     dst[m][1] = *reinterpret_cast<const bf16x8*>((char*)SA(b, h) + aoff1 + m * 2048); }
; #define LDB(dst, b, h) for (int n = 0; n < 2; ++n) { \
;     dst[n][0] = *reinterpret_cast<const bf16x8*>((char*)SB(b, h) + boff0 + n * 256); \
;     dst[n][1] = *reinterpret_cast<const bf16x8*>((char*)SB(b, h) + boff1 + n * 256); }
; #define MMA(ai, bj, At, Btf) do { __builtin_amdgcn_s_setprio(1); \
;     for (int m = 0; m < 4; ++m) for (int n = 0; n < 2; ++n) for (int k = 0; k < 2; ++k) \
;       acc[ai][bj][m][n] = __builtin_amdgcn_mfma_f32_16x16x32_bf16(Btf[n][k], At[m][k], acc[ai][bj][m][n], 0, 0, 0); \
;     __builtin_amdgcn_s_setprio(0); } while (0)
; #define WAIT_V(n) asm volatile("s_waitcnt vmcnt(" #n ")" ::: "memory")
; #define WAIT_L(n) asm volatile("s_waitcnt lgkmcnt(" #n ")" ::: "memory")
; #define BAR __builtin_amdgcn_s_barrier()
; template <int EPI> ...
;     ...
;   for (int t = 0; t < nt - 2; t += 2) {
;     LDB(B0, 0, 0); SCHED; LDA(At, 0, 0); STAGE(SA(1, 1), A, brow + HALF, t + 1);
;     WAIT_L(8); BAR; WAIT_L(0); MMA(0, 0, At, B0); BAR; SCHED;
;     LDB(B1, 0, 1); STAGE(SB(0, 0), Bt, bcol, t + 2);
;     BAR; WAIT_L(0); MMA(0, 1, At, B1); BAR;
;     LDA(At, 0, 1); STAGE(SA(0, 0), A, brow, t + 2);
;     BAR; WAIT_L(0); MMA(1, 0, At, B0); BAR; SCHED;
;     STAGE(SB(0, 1), Bt, bcol + HALF, t + 2);
;     WAIT_V(6); BAR; MMA(1, 1, At, B1); BAR;
;     LDB(B0, 1, 0); SCHED; LDA(At, 1, 0); STAGE(SA(0, 1), A, brow + HALF, t + 2);
;     WAIT_L(8); BAR; WAIT_L(0); MMA(0, 0, At, B0); BAR; SCHED;
;     LDB(B1, 1, 1); STAGE(SB(1, 0), Bt, bcol, t + 3);
;     BAR; WAIT_L(0); MMA(0, 1, At, B1); BAR;
;     LDA(At, 1, 1); STAGE(SA(1, 0), A, brow, t + 3);
;     BAR; WAIT_L(0); MMA(1, 0, At, B0); BAR; SCHED;
;     STAGE(SB(1, 1), Bt, bcol + HALF, t + 3);
;     WAIT_V(6); BAR; MMA(1, 1, At, B1); BAR;
;   }
	s_waitcnt lgkmcnt(0)
	s_setprio 1
	v_mfma_f32_16x16x32_bf16 v[60:63], v[162:165], v[178:181], v[60:63]
	v_mfma_f32_16x16x32_bf16 v[56:59], v[166:169], v[178:181], v[56:59]
	v_mfma_f32_16x16x32_bf16 v[52:55], v[162:165], v[186:189], v[52:55]
	v_mfma_f32_16x16x32_bf16 v[48:51], v[166:169], v[186:189], v[48:51]
	v_mfma_f32_16x16x32_bf16 v[44:47], v[162:165], v[194:197], v[44:47]
	v_mfma_f32_16x16x32_bf16 v[40:43], v[166:169], v[194:197], v[40:43]
	v_mfma_f32_16x16x32_bf16 v[36:39], v[162:165], v[202:205], v[36:39]
	v_mfma_f32_16x16x32_bf16 v[32:35], v[166:169], v[202:205], v[32:35]
	v_mfma_f32_16x16x32_bf16 v[60:63], v[170:173], v[182:185], v[60:63]
	v_mfma_f32_16x16x32_bf16 v[56:59], v[174:177], v[182:185], v[56:59]
	v_mfma_f32_16x16x32_bf16 v[52:55], v[170:173], v[190:193], v[52:55]
	v_mfma_f32_16x16x32_bf16 v[48:51], v[174:177], v[190:193], v[48:51]
	v_mfma_f32_16x16x32_bf16 v[44:47], v[170:173], v[198:201], v[44:47]
	v_mfma_f32_16x16x32_bf16 v[40:43], v[174:177], v[198:201], v[40:43]
	v_mfma_f32_16x16x32_bf16 v[36:39], v[170:173], v[206:209], v[36:39]
	v_mfma_f32_16x16x32_bf16 v[32:35], v[174:177], v[206:209], v[32:35]
	v_mfma_f32_16x16x32_bf16 v[28:31], v[210:213], v[178:181], v[28:31]
	v_mfma_f32_16x16x32_bf16 v[24:27], v[214:217], v[178:181], v[24:27]
	v_mfma_f32_16x16x32_bf16 v[20:23], v[210:213], v[186:189], v[20:23]
	v_mfma_f32_16x16x32_bf16 v[16:19], v[214:217], v[186:189], v[16:19]
	v_mfma_f32_16x16x32_bf16 v[12:15], v[210:213], v[194:197], v[12:15]
	v_mfma_f32_16x16x32_bf16 v[8:11], v[214:217], v[194:197], v[8:11]
	v_mfma_f32_16x16x32_bf16 v[4:7], v[210:213], v[202:205], v[4:7]
	v_mfma_f32_16x16x32_bf16 v[0:3], v[214:217], v[202:205], v[0:3]
	v_mfma_f32_16x16x32_bf16 v[28:31], v[218:221], v[182:185], v[28:31]
	v_mfma_f32_16x16x32_bf16 v[24:27], v[222:225], v[182:185], v[24:27]
	v_mfma_f32_16x16x32_bf16 v[20:23], v[218:221], v[190:193], v[20:23]
	v_mfma_f32_16x16x32_bf16 v[16:19], v[222:225], v[190:193], v[16:19]
	v_mfma_f32_16x16x32_bf16 v[12:15], v[218:221], v[198:201], v[12:15]
	v_mfma_f32_16x16x32_bf16 v[8:11], v[222:225], v[198:201], v[8:11]
	v_mfma_f32_16x16x32_bf16 v[4:7], v[218:221], v[206:209], v[4:7]
	v_mfma_f32_16x16x32_bf16 v[0:3], v[222:225], v[206:209], v[0:3]
	s_setprio 0
	s_barrier
	ds_read_b128 v[162:165], v157
	ds_read_b128 v[166:169], v157 offset:256
	ds_read_b128 v[170:173], v158
	ds_read_b128 v[174:177], v158 offset:256
	v_readfirstlane_b32 s72, v142
	v_lshl_add_u64 v[210:211], v[226:227], 0, s[46:47]
	s_mov_b32 m0, s72
	v_readfirstlane_b32 s72, v143
	ds_read_b128 v[178:181], v150 offset:32768
	ds_read_b128 v[182:185], v150 offset:33792
	ds_read_b128 v[186:189], v150 offset:34816
	ds_read_b128 v[190:193], v150 offset:35840
	ds_read_b128 v[194:197], v150 offset:36864
	ds_read_b128 v[198:201], v150 offset:37888
	ds_read_b128 v[202:205], v150 offset:38912
	ds_read_b128 v[206:209], v150 offset:39936
	global_load_lds_dwordx4 v[210:211], off
	v_lshl_add_u64 v[210:211], v[226:227], 0, s[48:49]
	s_mov_b32 m0, s72
	s_nop 0
	global_load_lds_dwordx4 v[210:211], off
	s_waitcnt lgkmcnt(8)
	v_readfirstlane_b32 s72, v141
	v_lshl_add_u64 v[246:247], v[228:229], 0, s[38:39]
	s_mov_b32 m0, s72
	s_nop 0
	global_load_lds_dwordx4 v[246:247], off
	ds_read_b128 v[210:213], v159
	ds_read_b128 v[214:217], v159 offset:256
	ds_read_b128 v[218:221], v160
	ds_read_b128 v[222:225], v160 offset:256
	s_barrier
	s_waitcnt lgkmcnt(0)
	s_setprio 1
	v_mfma_f32_16x16x32_bf16 v[124:127], v[162:165], v[178:181], v[124:127]
	v_mfma_f32_16x16x32_bf16 v[120:123], v[166:169], v[178:181], v[120:123]
	v_mfma_f32_16x16x32_bf16 v[116:119], v[162:165], v[186:189], v[116:119]
	v_mfma_f32_16x16x32_bf16 v[112:115], v[166:169], v[186:189], v[112:115]
	v_mfma_f32_16x16x32_bf16 v[108:111], v[162:165], v[194:197], v[108:111]
	v_mfma_f32_16x16x32_bf16 v[104:107], v[166:169], v[194:197], v[104:107]
	v_mfma_f32_16x16x32_bf16 v[100:103], v[162:165], v[202:205], v[100:103]
	v_mfma_f32_16x16x32_bf16 v[96:99], v[166:169], v[202:205], v[96:99]
	v_mfma_f32_16x16x32_bf16 v[124:127], v[170:173], v[182:185], v[124:127]
	v_mfma_f32_16x16x32_bf16 v[120:123], v[174:177], v[182:185], v[120:123]
	v_mfma_f32_16x16x32_bf16 v[116:119], v[170:173], v[190:193], v[116:119]
	v_mfma_f32_16x16x32_bf16 v[112:115], v[174:177], v[190:193], v[112:115]
	v_mfma_f32_16x16x32_bf16 v[108:111], v[170:173], v[198:201], v[108:111]
	v_mfma_f32_16x16x32_bf16 v[104:107], v[174:177], v[198:201], v[104:107]
	v_mfma_f32_16x16x32_bf16 v[100:103], v[170:173], v[206:209], v[100:103]
	v_mfma_f32_16x16x32_bf16 v[96:99], v[174:177], v[206:209], v[96:99]
	v_mfma_f32_16x16x32_bf16 v[92:95], v[210:213], v[178:181], v[92:95]
	v_mfma_f32_16x16x32_bf16 v[88:91], v[214:217], v[178:181], v[88:91]
	v_mfma_f32_16x16x32_bf16 v[84:87], v[210:213], v[186:189], v[84:87]
	v_mfma_f32_16x16x32_bf16 v[80:83], v[214:217], v[186:189], v[80:83]
	v_mfma_f32_16x16x32_bf16 v[76:79], v[210:213], v[194:197], v[76:79]
	v_mfma_f32_16x16x32_bf16 v[72:75], v[214:217], v[194:197], v[72:75]
	v_mfma_f32_16x16x32_bf16 v[68:71], v[210:213], v[202:205], v[68:71]
	v_mfma_f32_16x16x32_bf16 v[64:67], v[214:217], v[202:205], v[64:67]
	v_mfma_f32_16x16x32_bf16 v[92:95], v[218:221], v[182:185], v[92:95]
	v_mfma_f32_16x16x32_bf16 v[88:91], v[222:225], v[182:185], v[88:91]
	v_mfma_f32_16x16x32_bf16 v[84:87], v[218:221], v[190:193], v[84:87]
	v_mfma_f32_16x16x32_bf16 v[80:83], v[222:225], v[190:193], v[80:83]
	v_mfma_f32_16x16x32_bf16 v[76:79], v[218:221], v[198:201], v[76:79]
	v_mfma_f32_16x16x32_bf16 v[72:75], v[222:225], v[198:201], v[72:75]
	v_mfma_f32_16x16x32_bf16 v[68:71], v[218:221], v[206:209], v[68:71]
	v_mfma_f32_16x16x32_bf16 v[64:67], v[222:225], v[206:209], v[64:67]
	s_setprio 0
	s_barrier
; #define STAGE(P, BASE, br, kt) do { const char* _gb = (const char*)(BASE) + ((size_t)(br) * K + (size_t)(kt) * BK) * 2; \
;     __builtin_amdgcn_global_load_lds((const unsigned*)(_gb + loff0), (unsigned*)((char*)(P) + tid * 16), 16, 0, 0); \
;     __builtin_amdgcn_global_load_lds((const unsigned*)(_gb + (size_t)K * 128 + loff0), (unsigned*)((char*)(P) + tid * 16 + 8192), 16, 0, 0); } while (0)
; #define LDA(dst, b, h) for (int m = 0; m < 4; ++m) { \
;     dst[m][0] = *reinterpret_cast<const bf16x8*>((char*)SA(b, h) + aoff0 + m * 2048); \
;     dst[m][1] = *reinterpret_cast<const bf16x8*>((char*)SA(b, h) + aoff1 + m * 2048); }
; #define LDB(dst, b, h) for (int n = 0; n < 2; ++n) { \
;     dst[n][0] = *reinterpret_cast<const bf16x8*>((char*)SB(b, h) + boff0 + n * 256); \
;     dst[n][1] = *reinterpret_cast<const bf16x8*>((char*)SB(b, h) + boff1 + n * 256); }
; #define MMA(ai, bj, At, Btf) do { __builtin_amdgcn_s_setprio(1); \
;     for (int m = 0; m < 4; ++m) for (int n = 0; n < 2; ++n) for (int k = 0; k < 2; ++k) \
;       acc[ai][bj][m][n] = __builtin_amdgcn_mfma_f32_16x16x32_bf16(Btf[n][k], At[m][k], acc[ai][bj][m][n], 0, 0, 0); \
;     __builtin_amdgcn_s_setprio(0); } while (0)
; #define WAIT_V(n) asm volatile("s_waitcnt vmcnt(" #n ")" ::: "memory")
; #define WAIT_L(n) asm volatile("s_waitcnt lgkmcnt(" #n ")" ::: "memory")
; #define BAR __builtin_amdgcn_s_barrier()
; #define SCHED __builtin_amdgcn_sched_barrier(0)
; template <int EPI> ...
;     ...
;     LDB(B1, 1, 1); STAGE(SB(1, 0), Bt, bcol, t + 3);
;     BAR; WAIT_L(0); MMA(0, 1, At, B1); BAR;
;     LDA(At, 1, 1); STAGE(SA(1, 0), A, brow, t + 3);
;     BAR; WAIT_L(0); MMA(1, 0, At, B0); BAR; SCHED;
;     STAGE(SB(1, 1), Bt, bcol + HALF, t + 3);
;     WAIT_V(6); BAR; MMA(1, 1, At, B1); BAR;
;   }
;   { LDB(B0, 0, 0); LDA(At, 0, 0); STAGE(SA(1, 1), A, brow + HALF, nt - 1);
;     BAR; WAIT_L(0); MMA(0, 0, At, B0); BAR;
	v_readfirstlane_b32 s72, v144
	v_lshl_add_u64 v[230:231], v[228:229], 0, s[50:51]
	s_mov_b32 m0, s72
	v_readfirstlane_b32 s72, v145
	global_load_lds_dwordx4 v[230:231], off
	v_lshl_add_u64 v[230:231], v[228:229], 0, s[52:53]
	s_mov_b32 m0, s72
	s_nop 0
	global_load_lds_dwordx4 v[230:231], off
	v_readfirstlane_b32 s72, v146
	v_lshl_add_u64 v[230:231], v[226:227], 0, s[54:55]
	s_mov_b32 m0, s72
	v_readfirstlane_b32 s72, v147
	ds_read_b128 v[178:181], v150 offset:49152
	ds_read_b128 v[182:185], v150 offset:50176
	ds_read_b128 v[186:189], v150 offset:51200
	ds_read_b128 v[190:193], v150 offset:52224
	ds_read_b128 v[194:197], v150 offset:53248
	ds_read_b128 v[198:201], v150 offset:54272
	ds_read_b128 v[202:205], v150 offset:55296
	ds_read_b128 v[206:209], v150 offset:56320
	global_load_lds_dwordx4 v[230:231], off
	v_lshl_add_u64 v[226:227], v[226:227], 0, s[56:57]
	s_mov_b32 m0, s72
	s_nop 0
	global_load_lds_dwordx4 v[226:227], off
	v_readfirstlane_b32 s72, v148
	v_lshl_add_u64 v[246:247], v[228:229], 0, s[58:59]
	s_mov_b32 m0, s72
	v_readfirstlane_b32 s72, v149
	global_load_lds_dwordx4 v[246:247], off
	s_waitcnt vmcnt(5)
	s_barrier
	s_waitcnt lgkmcnt(0)
	s_setprio 1
	s_waitcnt lgkmcnt(0)
	v_mfma_f32_16x16x32_bf16 v[60:63], v[162:165], v[178:181], v[60:63]
	v_mfma_f32_16x16x32_bf16 v[56:59], v[166:169], v[178:181], v[56:59]
	v_mfma_f32_16x16x32_bf16 v[52:55], v[162:165], v[186:189], v[52:55]
	v_mfma_f32_16x16x32_bf16 v[48:51], v[166:169], v[186:189], v[48:51]
	v_mfma_f32_16x16x32_bf16 v[44:47], v[162:165], v[194:197], v[44:47]
	v_mfma_f32_16x16x32_bf16 v[40:43], v[166:169], v[194:197], v[40:43]
	v_mfma_f32_16x16x32_bf16 v[36:39], v[162:165], v[202:205], v[36:39]
	v_mfma_f32_16x16x32_bf16 v[32:35], v[166:169], v[202:205], v[32:35]
	v_mfma_f32_16x16x32_bf16 v[60:63], v[170:173], v[182:185], v[60:63]
	v_mfma_f32_16x16x32_bf16 v[56:59], v[174:177], v[182:185], v[56:59]
	v_mfma_f32_16x16x32_bf16 v[52:55], v[170:173], v[190:193], v[52:55]
	v_mfma_f32_16x16x32_bf16 v[48:51], v[174:177], v[190:193], v[48:51]
	v_mfma_f32_16x16x32_bf16 v[44:47], v[170:173], v[198:201], v[44:47]
	v_mfma_f32_16x16x32_bf16 v[40:43], v[174:177], v[198:201], v[40:43]
	v_mfma_f32_16x16x32_bf16 v[36:39], v[170:173], v[206:209], v[36:39]
	v_mfma_f32_16x16x32_bf16 v[32:35], v[174:177], v[206:209], v[32:35]
	s_setprio 0
	s_setprio 1
	v_mfma_f32_16x16x32_bf16 v[28:31], v[210:213], v[178:181], v[28:31]
	v_mfma_f32_16x16x32_bf16 v[24:27], v[214:217], v[178:181], v[24:27]
	v_mfma_f32_16x16x32_bf16 v[20:23], v[210:213], v[186:189], v[20:23]
	v_mfma_f32_16x16x32_bf16 v[16:19], v[214:217], v[186:189], v[16:19]
	v_mfma_f32_16x16x32_bf16 v[12:15], v[210:213], v[194:197], v[12:15]
	v_mfma_f32_16x16x32_bf16 v[8:11], v[214:217], v[194:197], v[8:11]
	v_mfma_f32_16x16x32_bf16 v[4:7], v[210:213], v[202:205], v[4:7]
	v_mfma_f32_16x16x32_bf16 v[0:3], v[214:217], v[202:205], v[0:3]
	v_mfma_f32_16x16x32_bf16 v[28:31], v[218:221], v[182:185], v[28:31]
	v_mfma_f32_16x16x32_bf16 v[24:27], v[222:225], v[182:185], v[24:27]
	v_mfma_f32_16x16x32_bf16 v[20:23], v[218:221], v[190:193], v[20:23]
	v_mfma_f32_16x16x32_bf16 v[16:19], v[222:225], v[190:193], v[16:19]
	v_mfma_f32_16x16x32_bf16 v[12:15], v[218:221], v[198:201], v[12:15]
	v_mfma_f32_16x16x32_bf16 v[8:11], v[222:225], v[198:201], v[8:11]
	v_mfma_f32_16x16x32_bf16 v[4:7], v[218:221], v[206:209], v[4:7]
	v_mfma_f32_16x16x32_bf16 v[0:3], v[222:225], v[206:209], v[0:3]
	s_setprio 0
	s_add_i32 s67, s67, 2
	s_add_u32 s70, s70, 0x100
	s_addc_u32 s71, s71, 0
	s_add_u32 s68, s68, 0x100
	s_addc_u32 s69, s69, 0
	s_cmp_lt_u32 s67, 28
	s_barrier
	s_cbranch_scc1 .LBB0_277
	v_readfirstlane_b32 s72, v149
	v_lshl_add_u64 v[246:247], v[228:229], 0, s[60:61]
	s_mov_b32 m0, s72
	s_nop 0
	global_load_lds_dwordx4 v[246:247], off
	v_readfirstlane_b32 s67, v151
	v_lshl_add_u64 v[210:211], v[132:133], 0, s[62:63]
	s_mov_b32 m0, s67
	v_readfirstlane_b32 s67, v152
	ds_read_b128 v[162:165], v153
	ds_read_b128 v[166:169], v153 offset:256
	ds_read_b128 v[170:173], v154
	ds_read_b128 v[174:177], v154 offset:256
	ds_read_b128 v[178:181], v150
	ds_read_b128 v[182:185], v150 offset:1024
	ds_read_b128 v[186:189], v150 offset:2048
	ds_read_b128 v[190:193], v150 offset:3072
	ds_read_b128 v[194:197], v150 offset:4096
	ds_read_b128 v[198:201], v150 offset:5120
	ds_read_b128 v[202:205], v150 offset:6144
	ds_read_b128 v[206:209], v150 offset:7168
	global_load_lds_dwordx4 v[210:211], off
	v_lshl_add_u64 v[132:133], v[132:133], 0, s[64:65]
	s_mov_b32 m0, s67
	s_nop 0
	global_load_lds_dwordx4 v[132:133], off
	s_barrier
	s_waitcnt lgkmcnt(0)
	s_setprio 1
	v_mfma_f32_16x16x32_bf16 v[124:127], v[162:165], v[178:181], v[124:127]
	v_mfma_f32_16x16x32_bf16 v[116:119], v[162:165], v[186:189], v[116:119]
	v_mfma_f32_16x16x32_bf16 v[108:111], v[162:165], v[194:197], v[108:111]
	v_mfma_f32_16x16x32_bf16 v[100:103], v[162:165], v[202:205], v[100:103]
	v_mfma_f32_16x16x32_bf16 v[124:127], v[170:173], v[182:185], v[124:127]
	v_mfma_f32_16x16x32_bf16 v[120:123], v[166:169], v[178:181], v[120:123]
	v_mfma_f32_16x16x32_bf16 v[116:119], v[170:173], v[190:193], v[116:119]
	v_mfma_f32_16x16x32_bf16 v[112:115], v[166:169], v[186:189], v[112:115]
	v_mfma_f32_16x16x32_bf16 v[108:111], v[170:173], v[198:201], v[108:111]
	v_mfma_f32_16x16x32_bf16 v[104:107], v[166:169], v[194:197], v[104:107]
	v_mfma_f32_16x16x32_bf16 v[100:103], v[170:173], v[206:209], v[100:103]
	v_mfma_f32_16x16x32_bf16 v[96:99], v[166:169], v[202:205], v[96:99]
	v_mfma_f32_16x16x32_bf16 v[210:213], v[174:177], v[182:185], v[120:123]
	v_mfma_f32_16x16x32_bf16 v[214:217], v[174:177], v[190:193], v[112:115]
	v_mfma_f32_16x16x32_bf16 v[218:221], v[174:177], v[198:201], v[104:107]
	v_mfma_f32_16x16x32_bf16 v[222:225], v[174:177], v[206:209], v[96:99]
	s_setprio 0
	s_barrier
; #define LDA(dst, b, h) for (int m = 0; m < 4; ++m) { \
;     dst[m][0] = *reinterpret_cast<const bf16x8*>((char*)SA(b, h) + aoff0 + m * 2048); \
;     dst[m][1] = *reinterpret_cast<const bf16x8*>((char*)SA(b, h) + aoff1 + m * 2048); }
; #define LDB(dst, b, h) for (int n = 0; n < 2; ++n) { \
;     dst[n][0] = *reinterpret_cast<const bf16x8*>((char*)SB(b, h) + boff0 + n * 256); \
;     dst[n][1] = *reinterpret_cast<const bf16x8*>((char*)SB(b, h) + boff1 + n * 256); }
; #define MMA(ai, bj, At, Btf) do { __builtin_amdgcn_s_setprio(1); \
;     for (int m = 0; m < 4; ++m) for (int n = 0; n < 2; ++n) for (int k = 0; k < 2; ++k) \
;       acc[ai][bj][m][n] = __builtin_amdgcn_mfma_f32_16x16x32_bf16(Btf[n][k], At[m][k], acc[ai][bj][m][n], 0, 0, 0); \
;     __builtin_amdgcn_s_setprio(0); } while (0)
; #define WAIT_V(n) asm volatile("s_waitcnt vmcnt(" #n ")" ::: "memory")
; #define WAIT_L(n) asm volatile("s_waitcnt lgkmcnt(" #n ")" ::: "memory")
; #define BAR __builtin_amdgcn_s_barrier()
; template <int EPI> ...
;     ...
;     LDB(B1, 0, 1); BAR; WAIT_L(0); MMA(0, 1, At, B1); BAR;
;     LDA(At, 0, 1); WAIT_V(4); BAR; WAIT_L(0); MMA(1, 0, At, B0); MMA(1, 1, At, B1); BAR; }
;   { LDB(B0, 1, 0); LDA(At, 1, 0); WAIT_V(2); BAR; WAIT_L(0); MMA(0, 0, At, B0); BAR;
	s_nop 1
	ds_read_b128 v[96:99], v155
	ds_read_b128 v[104:107], v155 offset:256
	ds_read_b128 v[112:115], v156
	ds_read_b128 v[120:123], v156 offset:256
	s_barrier
	s_waitcnt lgkmcnt(0)
	s_setprio 1
	v_mfma_f32_16x16x32_bf16 v[92:95], v[96:99], v[178:181], v[92:95]
	v_mfma_f32_16x16x32_bf16 v[84:87], v[96:99], v[186:189], v[84:87]
	v_mfma_f32_16x16x32_bf16 v[76:79], v[96:99], v[194:197], v[76:79]
	v_mfma_f32_16x16x32_bf16 v[68:71], v[96:99], v[202:205], v[68:71]
	v_mfma_f32_16x16x32_bf16 v[92:95], v[112:115], v[182:185], v[92:95]
	v_mfma_f32_16x16x32_bf16 v[88:91], v[104:107], v[178:181], v[88:91]
	v_mfma_f32_16x16x32_bf16 v[84:87], v[112:115], v[190:193], v[84:87]
	v_mfma_f32_16x16x32_bf16 v[80:83], v[104:107], v[186:189], v[80:83]
	v_mfma_f32_16x16x32_bf16 v[76:79], v[112:115], v[198:201], v[76:79]
	v_mfma_f32_16x16x32_bf16 v[72:75], v[104:107], v[194:197], v[72:75]
	v_mfma_f32_16x16x32_bf16 v[68:71], v[112:115], v[206:209], v[68:71]
	v_mfma_f32_16x16x32_bf16 v[64:67], v[104:107], v[202:205], v[64:67]
	v_mfma_f32_16x16x32_bf16 v[178:181], v[120:123], v[182:185], v[88:91]
	v_mfma_f32_16x16x32_bf16 v[182:185], v[120:123], v[190:193], v[80:83]
	v_mfma_f32_16x16x32_bf16 v[186:189], v[120:123], v[198:201], v[72:75]
	v_mfma_f32_16x16x32_bf16 v[190:193], v[120:123], v[206:209], v[64:67]
	s_setprio 0
	s_barrier
	s_nop 1
	ds_read_b128 v[64:67], v150 offset:16384
	ds_read_b128 v[72:75], v150 offset:17408
	ds_read_b128 v[80:83], v150 offset:18432
	ds_read_b128 v[88:91], v150 offset:19456
	ds_read_b128 v[194:197], v150 offset:20480
	ds_read_b128 v[198:201], v150 offset:21504
	ds_read_b128 v[202:205], v150 offset:22528
	ds_read_b128 v[206:209], v150 offset:23552
	s_waitcnt vmcnt(4)
	s_barrier
	s_waitcnt lgkmcnt(0)
	s_setprio 1
	v_mfma_f32_16x16x32_bf16 v[60:63], v[162:165], v[64:67], v[60:63]
	v_mfma_f32_16x16x32_bf16 v[56:59], v[166:169], v[64:67], v[56:59]
	v_mfma_f32_16x16x32_bf16 v[52:55], v[162:165], v[80:83], v[52:55]
	v_mfma_f32_16x16x32_bf16 v[40:43], v[166:169], v[194:197], v[40:43]
	v_mfma_f32_16x16x32_bf16 v[36:39], v[162:165], v[202:205], v[36:39]
	v_mfma_f32_16x16x32_bf16 v[60:63], v[170:173], v[72:75], v[60:63]
	v_mfma_f32_16x16x32_bf16 v[56:59], v[174:177], v[72:75], v[56:59]
	v_mfma_f32_16x16x32_bf16 v[52:55], v[170:173], v[88:91], v[52:55]
	v_mfma_f32_16x16x32_bf16 v[48:51], v[166:169], v[80:83], v[48:51]
	v_mfma_f32_16x16x32_bf16 v[44:47], v[162:165], v[194:197], v[44:47]
	v_mfma_f32_16x16x32_bf16 v[40:43], v[174:177], v[198:201], v[40:43]
	v_mfma_f32_16x16x32_bf16 v[36:39], v[170:173], v[206:209], v[36:39]
	v_mfma_f32_16x16x32_bf16 v[32:35], v[166:169], v[202:205], v[32:35]
	v_mfma_f32_16x16x32_bf16 v[226:229], v[174:177], v[88:91], v[48:51]
	v_mfma_f32_16x16x32_bf16 v[230:233], v[170:173], v[198:201], v[44:47]
	v_mfma_f32_16x16x32_bf16 v[162:165], v[174:177], v[206:209], v[32:35]
	v_mfma_f32_16x16x32_bf16 v[24:27], v[104:107], v[64:67], v[24:27]
	v_mfma_f32_16x16x32_bf16 v[20:23], v[96:99], v[80:83], v[20:23]
	v_mfma_f32_16x16x32_bf16 v[8:11], v[104:107], v[194:197], v[8:11]
	v_mfma_f32_16x16x32_bf16 v[4:7], v[96:99], v[202:205], v[4:7]
	v_mfma_f32_16x16x32_bf16 v[28:31], v[96:99], v[64:67], v[28:31]
	v_mfma_f32_16x16x32_bf16 v[24:27], v[120:123], v[72:75], v[24:27]
	v_mfma_f32_16x16x32_bf16 v[20:23], v[112:115], v[88:91], v[20:23]
	v_mfma_f32_16x16x32_bf16 v[16:19], v[104:107], v[80:83], v[16:19]
	v_mfma_f32_16x16x32_bf16 v[12:15], v[96:99], v[194:197], v[12:15]
	v_mfma_f32_16x16x32_bf16 v[8:11], v[120:123], v[198:201], v[8:11]
	v_mfma_f32_16x16x32_bf16 v[4:7], v[112:115], v[206:209], v[4:7]
	v_mfma_f32_16x16x32_bf16 v[0:3], v[104:107], v[202:205], v[0:3]
	v_mfma_f32_16x16x32_bf16 v[166:169], v[112:115], v[72:75], v[28:31]
	v_mfma_f32_16x16x32_bf16 v[170:173], v[120:123], v[88:91], v[16:19]
	v_mfma_f32_16x16x32_bf16 v[174:177], v[112:115], v[198:201], v[12:15]
	v_mfma_f32_16x16x32_bf16 v[194:197], v[120:123], v[206:209], v[0:3]
	s_setprio 0
	s_barrier
	s_nop 1
	ds_read_b128 v[0:3], v157
	ds_read_b128 v[198:201], v157 offset:256
	ds_read_b128 v[12:15], v158
	ds_read_b128 v[202:205], v158 offset:256
	ds_read_b128 v[16:19], v150 offset:32768
	ds_read_b128 v[28:31], v150 offset:33792
	ds_read_b128 v[32:35], v150 offset:34816
	ds_read_b128 v[44:47], v150 offset:35840
	ds_read_b128 v[48:51], v150 offset:36864
	ds_read_b128 v[206:209], v150 offset:37888
	ds_read_b128 v[234:237], v150 offset:38912
	ds_read_b128 v[238:241], v150 offset:39936
	s_waitcnt vmcnt(2)
	s_barrier
; #define LDA(dst, b, h) for (int m = 0; m < 4; ++m) { \
;     dst[m][0] = *reinterpret_cast<const bf16x8*>((char*)SA(b, h) + aoff0 + m * 2048); \
;     dst[m][1] = *reinterpret_cast<const bf16x8*>((char*)SA(b, h) + aoff1 + m * 2048); }
; #define LDB(dst, b, h) for (int n = 0; n < 2; ++n) { \
;     dst[n][0] = *reinterpret_cast<const bf16x8*>((char*)SB(b, h) + boff0 + n * 256); \
;     dst[n][1] = *reinterpret_cast<const bf16x8*>((char*)SB(b, h) + boff1 + n * 256); }
; #define MMA(ai, bj, At, Btf) do { __builtin_amdgcn_s_setprio(1); \
;     for (int m = 0; m < 4; ++m) for (int n = 0; n < 2; ++n) for (int k = 0; k < 2; ++k) \
;       acc[ai][bj][m][n] = __builtin_amdgcn_mfma_f32_16x16x32_bf16(Btf[n][k], At[m][k], acc[ai][bj][m][n], 0, 0, 0); \
;     __builtin_amdgcn_s_setprio(0); } while (0)
; #define WAIT_V(n) asm volatile("s_waitcnt vmcnt(" #n ")" ::: "memory")
; #define WAIT_L(n) asm volatile("s_waitcnt lgkmcnt(" #n ")" ::: "memory")
; #define BAR __builtin_amdgcn_s_barrier()
; template <int EPI> ...
;     ...
;   { LDB(B0, 1, 0); LDA(At, 1, 0); WAIT_V(2); BAR; WAIT_L(0); MMA(0, 0, At, B0); BAR;
;     LDB(B1, 1, 1); WAIT_V(0); BAR; WAIT_L(0); MMA(0, 1, At, B1); BAR;
;     LDA(At, 1, 1); BAR; WAIT_L(0); MMA(1, 0, At, B0); MMA(1, 1, At, B1); BAR; }
;   if (wr == 0) BAR;
	s_waitcnt lgkmcnt(0)
	s_setprio 1
	v_mfma_f32_16x16x32_bf16 v[64:67], v[0:3], v[16:19], v[124:127]
	v_mfma_f32_16x16x32_bf16 v[120:123], v[12:15], v[28:31], v[64:67]
	v_mfma_f32_16x16x32_bf16 v[64:67], v[198:201], v[16:19], v[210:213]
	v_mfma_f32_16x16x32_bf16 v[112:115], v[202:205], v[28:31], v[64:67]
	v_mfma_f32_16x16x32_bf16 v[64:67], v[0:3], v[32:35], v[116:119]
	v_mfma_f32_16x16x32_bf16 v[104:107], v[12:15], v[44:47], v[64:67]
	v_mfma_f32_16x16x32_bf16 v[64:67], v[198:201], v[32:35], v[214:217]
	v_mfma_f32_16x16x32_bf16 v[96:99], v[202:205], v[44:47], v[64:67]
	v_mfma_f32_16x16x32_bf16 v[64:67], v[0:3], v[48:51], v[108:111]
	v_mfma_f32_16x16x32_bf16 v[88:91], v[12:15], v[206:209], v[64:67]
	v_mfma_f32_16x16x32_bf16 v[64:67], v[198:201], v[48:51], v[218:221]
	v_mfma_f32_16x16x32_bf16 v[80:83], v[202:205], v[206:209], v[64:67]
	v_mfma_f32_16x16x32_bf16 v[64:67], v[0:3], v[234:237], v[100:103]
	v_mfma_f32_16x16x32_bf16 v[72:75], v[12:15], v[238:241], v[64:67]
	v_mfma_f32_16x16x32_bf16 v[64:67], v[198:201], v[234:237], v[222:225]
	v_mfma_f32_16x16x32_bf16 v[64:67], v[202:205], v[238:241], v[64:67]
	s_setprio 0
	s_barrier
	ds_read_b128 v[210:213], v159
	ds_read_b128 v[214:217], v159 offset:256
	ds_read_b128 v[218:221], v160
	ds_read_b128 v[222:225], v160 offset:256
	s_waitcnt vmcnt(0)
	s_barrier
	s_waitcnt lgkmcnt(0)
	s_setprio 1
	v_mfma_f32_16x16x32_bf16 v[92:95], v[210:213], v[16:19], v[92:95]
	v_mfma_f32_16x16x32_bf16 v[16:19], v[214:217], v[16:19], v[178:181]
	v_mfma_f32_16x16x32_bf16 v[116:119], v[222:225], v[28:31], v[16:19]
	v_mfma_f32_16x16x32_bf16 v[16:19], v[210:213], v[32:35], v[84:87]
	v_mfma_f32_16x16x32_bf16 v[108:111], v[218:221], v[44:47], v[16:19]
	v_mfma_f32_16x16x32_bf16 v[16:19], v[214:217], v[32:35], v[182:185]
	v_mfma_f32_16x16x32_bf16 v[100:103], v[222:225], v[44:47], v[16:19]
	v_mfma_f32_16x16x32_bf16 v[16:19], v[210:213], v[48:51], v[76:79]
	v_mfma_f32_16x16x32_bf16 v[124:127], v[218:221], v[28:31], v[92:95]
	v_mfma_f32_16x16x32_bf16 v[92:95], v[218:221], v[206:209], v[16:19]
	v_mfma_f32_16x16x32_bf16 v[16:19], v[214:217], v[48:51], v[186:189]
	v_mfma_f32_16x16x32_bf16 v[84:87], v[222:225], v[206:209], v[16:19]
	v_mfma_f32_16x16x32_bf16 v[16:19], v[210:213], v[234:237], v[68:71]
	v_mfma_f32_16x16x32_bf16 v[76:79], v[218:221], v[238:241], v[16:19]
	v_mfma_f32_16x16x32_bf16 v[16:19], v[214:217], v[234:237], v[190:193]
	v_mfma_f32_16x16x32_bf16 v[68:71], v[222:225], v[238:241], v[16:19]
	s_setprio 0
	s_barrier
	ds_read_b128 v[178:181], v150 offset:49152
	ds_read_b128 v[182:185], v150 offset:50176
	ds_read_b128 v[186:189], v150 offset:51200
	ds_read_b128 v[190:193], v150 offset:52224
	ds_read_b128 v[206:209], v150 offset:53248
	ds_read_b128 v[234:237], v150 offset:54272
	ds_read_b128 v[238:241], v150 offset:55296
	ds_read_b128 v[242:245], v150 offset:56320
	s_barrier
	s_waitcnt lgkmcnt(0)
	s_setprio 1
	v_mfma_f32_16x16x32_bf16 v[16:19], v[0:3], v[178:181], v[60:63]
	v_mfma_f32_16x16x32_bf16 v[60:63], v[12:15], v[182:185], v[16:19]
	v_mfma_f32_16x16x32_bf16 v[16:19], v[198:201], v[178:181], v[56:59]
	v_mfma_f32_16x16x32_bf16 v[48:51], v[202:205], v[182:185], v[16:19]
	v_mfma_f32_16x16x32_bf16 v[16:19], v[0:3], v[186:189], v[52:55]
	v_mfma_f32_16x16x32_bf16 v[44:47], v[12:15], v[190:193], v[16:19]
	v_mfma_f32_16x16x32_bf16 v[16:19], v[198:201], v[186:189], v[226:229]
	v_mfma_f32_16x16x32_bf16 v[32:35], v[202:205], v[190:193], v[16:19]
	v_mfma_f32_16x16x32_bf16 v[16:19], v[0:3], v[206:209], v[230:233]
	v_mfma_f32_16x16x32_bf16 v[0:3], v[0:3], v[238:241], v[36:39]
	v_mfma_f32_16x16x32_bf16 v[28:31], v[12:15], v[234:237], v[16:19]
	v_mfma_f32_16x16x32_bf16 v[16:19], v[198:201], v[206:209], v[40:43]
	v_mfma_f32_16x16x32_bf16 v[12:15], v[12:15], v[242:245], v[0:3]
	v_mfma_f32_16x16x32_bf16 v[0:3], v[198:201], v[238:241], v[162:165]
	v_mfma_f32_16x16x32_bf16 v[16:19], v[202:205], v[234:237], v[16:19]
	v_mfma_f32_16x16x32_bf16 v[0:3], v[202:205], v[242:245], v[0:3]
	v_mfma_f32_16x16x32_bf16 v[20:23], v[210:213], v[186:189], v[20:23]
	v_mfma_f32_16x16x32_bf16 v[36:39], v[210:213], v[178:181], v[166:169]
	v_mfma_f32_16x16x32_bf16 v[40:43], v[218:221], v[190:193], v[20:23]
	v_mfma_f32_16x16x32_bf16 v[20:23], v[214:217], v[186:189], v[170:173]
	v_mfma_f32_16x16x32_bf16 v[56:59], v[218:221], v[182:185], v[36:39]
	v_mfma_f32_16x16x32_bf16 v[24:27], v[214:217], v[178:181], v[24:27]
	v_mfma_f32_16x16x32_bf16 v[36:39], v[222:225], v[190:193], v[20:23]
	v_mfma_f32_16x16x32_bf16 v[20:23], v[210:213], v[206:209], v[174:177]
	v_mfma_f32_16x16x32_bf16 v[8:11], v[214:217], v[206:209], v[8:11]
	v_mfma_f32_16x16x32_bf16 v[4:7], v[210:213], v[238:241], v[4:7]
	v_mfma_f32_16x16x32_bf16 v[52:55], v[222:225], v[182:185], v[24:27]
	v_mfma_f32_16x16x32_bf16 v[24:27], v[218:221], v[234:237], v[20:23]
	v_mfma_f32_16x16x32_bf16 v[20:23], v[222:225], v[234:237], v[8:11]
	v_mfma_f32_16x16x32_bf16 v[8:11], v[218:221], v[242:245], v[4:7]
	v_mfma_f32_16x16x32_bf16 v[4:7], v[214:217], v[238:241], v[194:197]
	v_mfma_f32_16x16x32_bf16 v[4:7], v[222:225], v[242:245], v[4:7]
	s_setprio 0
	s_barrier
	s_and_saveexec_b64 s[68:69], s[2:3]
	s_cbranch_execz .LBB0_271
	s_barrier
	s_branch .LBB0_271

; #define STAGE(P, BASE, br, kt) do { const char* _gb = (const char*)(BASE) + ((size_t)(br) * K + (size_t)(kt) * BK) * 2; \
;     __builtin_amdgcn_global_load_lds((const unsigned*)(_gb + loff0), (unsigned*)((char*)(P) + tid * 16), 16, 0, 0); \
;     __builtin_amdgcn_global_load_lds((const unsigned*)(_gb + (size_t)K * 128 + loff0), (unsigned*)((char*)(P) + tid * 16 + 8192), 16, 0, 0); } while (0)
; #define LDA(dst, b, h) for (int m = 0; m < 4; ++m) { \
;     dst[m][0] = *reinterpret_cast<const bf16x8*>((char*)SA(b, h) + aoff0 + m * 2048); \
;     dst[m][1] = *reinterpret_cast<const bf16x8*>((char*)SA(b, h) + aoff1 + m * 2048); }
; #define LDB(dst, b, h) for (int n = 0; n < 2; ++n) { \
;     dst[n][0] = *reinterpret_cast<const bf16x8*>((char*)SB(b, h) + boff0 + n * 256); \
;     dst[n][1] = *reinterpret_cast<const bf16x8*>((char*)SB(b, h) + boff1 + n * 256); }
; #define MMA(ai, bj, At, Btf) do { __builtin_amdgcn_s_setprio(1); \
;     for (int m = 0; m < 4; ++m) for (int n = 0; n < 2; ++n) for (int k = 0; k < 2; ++k) \
;       acc[ai][bj][m][n] = __builtin_amdgcn_mfma_f32_16x16x32_bf16(Btf[n][k], At[m][k], acc[ai][bj][m][n], 0, 0, 0); \
;     __builtin_amdgcn_s_setprio(0); } while (0)
; #define WAIT_L(n) asm volatile("s_waitcnt lgkmcnt(" #n ")" ::: "memory")
; #define BAR __builtin_amdgcn_s_barrier()
; #define SCHED __builtin_amdgcn_sched_barrier(0)
; template <int EPI> ...
;     ...
;     LDB(B0, 0, 0); SCHED; LDA(At, 0, 0); STAGE(SA(1, 1), A, brow + HALF, t + 1);
;     WAIT_L(8); BAR; WAIT_L(0); MMA(0, 0, At, B0); BAR; SCHED;
;     LDB(B1, 0, 1); STAGE(SB(0, 0), Bt, bcol, t + 2);
;     BAR; WAIT_L(0); MMA(0, 1, At, B1); BAR;
;     LDA(At, 0, 1); STAGE(SA(0, 0), A, brow, t + 2);
;     BAR; WAIT_L(0); MMA(1, 0, At, B0); BAR; SCHED;
.LBB0_324:
	ds_read_b128 v[160:163], v152
	ds_read_b128 v[164:167], v152 offset:256
	ds_read_b128 v[168:171], v153
	ds_read_b128 v[172:175], v153 offset:256
	v_lshl_add_u64 v[224:225], s[64:65], 0, v[132:133]
	v_readfirstlane_b32 s77, v150
	v_lshl_add_u64 v[208:209], v[224:225], 0, s[16:17]
	s_mov_b32 m0, s77
	v_readfirstlane_b32 s77, v151
	ds_read_b128 v[176:179], v149
	ds_read_b128 v[180:183], v149 offset:1024
	ds_read_b128 v[184:187], v149 offset:2048
	ds_read_b128 v[188:191], v149 offset:3072
	ds_read_b128 v[192:195], v149 offset:4096
	ds_read_b128 v[196:199], v149 offset:5120
	ds_read_b128 v[200:203], v149 offset:6144
	ds_read_b128 v[204:207], v149 offset:7168
	global_load_lds_dwordx4 v[208:209], off
	v_lshl_add_u64 v[208:209], v[224:225], 0, s[18:19]
	s_mov_b32 m0, s77
	s_nop 0
	global_load_lds_dwordx4 v[208:209], off
	s_waitcnt lgkmcnt(8)
	v_readfirstlane_b32 s77, v148
	v_lshl_add_u64 v[246:247], v[228:229], 0, s[58:59]
	s_mov_b32 m0, s77
	s_nop 0
	global_load_lds_dwordx4 v[246:247], off
	ds_read_b128 v[208:211], v154
	ds_read_b128 v[212:215], v154 offset:256
	ds_read_b128 v[216:219], v155
	ds_read_b128 v[220:223], v155 offset:256
	s_barrier
	s_waitcnt lgkmcnt(0)
	s_setprio 1
	v_mfma_f32_16x16x32_bf16 v[124:127], v[160:163], v[176:179], v[124:127]
	v_mfma_f32_16x16x32_bf16 v[120:123], v[164:167], v[176:179], v[120:123]
	v_mfma_f32_16x16x32_bf16 v[116:119], v[160:163], v[184:187], v[116:119]
	v_mfma_f32_16x16x32_bf16 v[112:115], v[164:167], v[184:187], v[112:115]
	v_mfma_f32_16x16x32_bf16 v[108:111], v[160:163], v[192:195], v[108:111]
	v_mfma_f32_16x16x32_bf16 v[104:107], v[164:167], v[192:195], v[104:107]
	v_mfma_f32_16x16x32_bf16 v[100:103], v[160:163], v[200:203], v[100:103]
	v_mfma_f32_16x16x32_bf16 v[96:99], v[164:167], v[200:203], v[96:99]
	v_mfma_f32_16x16x32_bf16 v[124:127], v[168:171], v[180:183], v[124:127]
	v_mfma_f32_16x16x32_bf16 v[120:123], v[172:175], v[180:183], v[120:123]
	v_mfma_f32_16x16x32_bf16 v[116:119], v[168:171], v[188:191], v[116:119]
	v_mfma_f32_16x16x32_bf16 v[112:115], v[172:175], v[188:191], v[112:115]
	v_mfma_f32_16x16x32_bf16 v[108:111], v[168:171], v[196:199], v[108:111]
	v_mfma_f32_16x16x32_bf16 v[104:107], v[172:175], v[196:199], v[104:107]
	v_mfma_f32_16x16x32_bf16 v[100:103], v[168:171], v[204:207], v[100:103]
	v_mfma_f32_16x16x32_bf16 v[96:99], v[172:175], v[204:207], v[96:99]
	v_mfma_f32_16x16x32_bf16 v[92:95], v[208:211], v[176:179], v[92:95]
	v_mfma_f32_16x16x32_bf16 v[88:91], v[212:215], v[176:179], v[88:91]
	v_mfma_f32_16x16x32_bf16 v[84:87], v[208:211], v[184:187], v[84:87]
	v_mfma_f32_16x16x32_bf16 v[80:83], v[212:215], v[184:187], v[80:83]
	v_mfma_f32_16x16x32_bf16 v[76:79], v[208:211], v[192:195], v[76:79]
	v_mfma_f32_16x16x32_bf16 v[72:75], v[212:215], v[192:195], v[72:75]
	v_mfma_f32_16x16x32_bf16 v[68:71], v[208:211], v[200:203], v[68:71]
	v_mfma_f32_16x16x32_bf16 v[64:67], v[212:215], v[200:203], v[64:67]
	v_mfma_f32_16x16x32_bf16 v[92:95], v[216:219], v[180:183], v[92:95]
	v_mfma_f32_16x16x32_bf16 v[88:91], v[220:223], v[180:183], v[88:91]
	v_mfma_f32_16x16x32_bf16 v[84:87], v[216:219], v[188:191], v[84:87]
	v_mfma_f32_16x16x32_bf16 v[80:83], v[220:223], v[188:191], v[80:83]
	v_mfma_f32_16x16x32_bf16 v[76:79], v[216:219], v[196:199], v[76:79]
	v_mfma_f32_16x16x32_bf16 v[72:75], v[220:223], v[196:199], v[72:75]
	v_mfma_f32_16x16x32_bf16 v[68:71], v[216:219], v[204:207], v[68:71]
	v_mfma_f32_16x16x32_bf16 v[64:67], v[220:223], v[204:207], v[64:67]
	s_setprio 0
	s_barrier
	v_lshl_add_u64 v[226:227], s[66:67], 0, v[132:133]
	v_readfirstlane_b32 s77, v135
	v_lshl_add_u64 v[228:229], v[226:227], 0, s[20:21]
	s_mov_b32 m0, s77
	v_readfirstlane_b32 s77, v136
	global_load_lds_dwordx4 v[228:229], off
	v_lshl_add_u64 v[228:229], v[226:227], 0, s[22:23]
	s_mov_b32 m0, s77
	s_nop 0
	global_load_lds_dwordx4 v[228:229], off
	v_readfirstlane_b32 s77, v137
	v_lshl_add_u64 v[228:229], v[224:225], 0, s[26:27]
	s_mov_b32 m0, s77
	v_readfirstlane_b32 s77, v138
	ds_read_b128 v[176:179], v149 offset:16384
	ds_read_b128 v[180:183], v149 offset:17408
	ds_read_b128 v[184:187], v149 offset:18432
	ds_read_b128 v[188:191], v149 offset:19456
	ds_read_b128 v[192:195], v149 offset:20480
	ds_read_b128 v[196:199], v149 offset:21504
	ds_read_b128 v[200:203], v149 offset:22528
	ds_read_b128 v[204:207], v149 offset:23552
	global_load_lds_dwordx4 v[228:229], off
	v_lshl_add_u64 v[228:229], v[224:225], 0, s[28:29]
	s_mov_b32 m0, s77
	s_nop 0
	global_load_lds_dwordx4 v[228:229], off
	v_lshl_add_u64 v[228:229], s[62:63], 0, v[132:133]
	v_readfirstlane_b32 s77, v139
	v_lshl_add_u64 v[246:247], v[228:229], 0, s[30:31]
	s_mov_b32 m0, s77
	v_readfirstlane_b32 s77, v140
	global_load_lds_dwordx4 v[246:247], off
	s_waitcnt vmcnt(5)
	s_barrier
; #define STAGE(P, BASE, br, kt) do { const char* _gb = (const char*)(BASE) + ((size_t)(br) * K + (size_t)(kt) * BK) * 2; \
;     __builtin_amdgcn_global_load_lds((const unsigned*)(_gb + loff0), (unsigned*)((char*)(P) + tid * 16), 16, 0, 0); \
;     __builtin_amdgcn_global_load_lds((const unsigned*)(_gb + (size_t)K * 128 + loff0), (unsigned*)((char*)(P) + tid * 16 + 8192), 16, 0, 0); } while (0)
; #define LDA(dst, b, h) for (int m = 0; m < 4; ++m) { \
;     dst[m][0] = *reinterpret_cast<const bf16x8*>((char*)SA(b, h) + aoff0 + m * 2048); \
;     dst[m][1] = *reinterpret_cast<const bf16x8*>((char*)SA(b, h) + aoff1 + m * 2048); }
; #define LDB(dst, b, h) for (int n = 0; n < 2; ++n) { \
;     dst[n][0] = *reinterpret_cast<const bf16x8*>((char*)SB(b, h) + boff0 + n * 256); \
;     dst[n][1] = *reinterpret_cast<const bf16x8*>((char*)SB(b, h) + boff1 + n * 256); }
; #define MMA(ai, bj, At, Btf) do { __builtin_amdgcn_s_setprio(1); \
;     for (int m = 0; m < 4; ++m) for (int n = 0; n < 2; ++n) for (int k = 0; k < 2; ++k) \
;       acc[ai][bj][m][n] = __builtin_amdgcn_mfma_f32_16x16x32_bf16(Btf[n][k], At[m][k], acc[ai][bj][m][n], 0, 0, 0); \
;     __builtin_amdgcn_s_setprio(0); } while (0)
; #define WAIT_V(n) asm volatile("s_waitcnt vmcnt(" #n ")" ::: "memory")
; #define WAIT_L(n) asm volatile("s_waitcnt lgkmcnt(" #n ")" ::: "memory")
; #define BAR __builtin_amdgcn_s_barrier()
; #define SCHED __builtin_amdgcn_sched_barrier(0)
; template <int EPI> ...
;     ...
;     BAR; WAIT_L(0); MMA(1, 0, At, B0); BAR; SCHED;
;     STAGE(SB(0, 1), Bt, bcol + HALF, t + 2);
;     WAIT_V(6); BAR; MMA(1, 1, At, B1); BAR;
;     LDB(B0, 1, 0); SCHED; LDA(At, 1, 0); STAGE(SA(0, 1), A, brow + HALF, t + 2);
;     WAIT_L(8); BAR; WAIT_L(0); MMA(0, 0, At, B0); BAR; SCHED;
;     LDB(B1, 1, 1); STAGE(SB(1, 0), Bt, bcol, t + 3);
;     BAR; WAIT_L(0); MMA(0, 1, At, B1); BAR;
	s_waitcnt lgkmcnt(0)
	s_setprio 1
	v_mfma_f32_16x16x32_bf16 v[60:63], v[160:163], v[176:179], v[60:63]
	v_mfma_f32_16x16x32_bf16 v[56:59], v[164:167], v[176:179], v[56:59]
	v_mfma_f32_16x16x32_bf16 v[52:55], v[160:163], v[184:187], v[52:55]
	v_mfma_f32_16x16x32_bf16 v[48:51], v[164:167], v[184:187], v[48:51]
	v_mfma_f32_16x16x32_bf16 v[44:47], v[160:163], v[192:195], v[44:47]
	v_mfma_f32_16x16x32_bf16 v[40:43], v[164:167], v[192:195], v[40:43]
	v_mfma_f32_16x16x32_bf16 v[36:39], v[160:163], v[200:203], v[36:39]
	v_mfma_f32_16x16x32_bf16 v[32:35], v[164:167], v[200:203], v[32:35]
	v_mfma_f32_16x16x32_bf16 v[60:63], v[168:171], v[180:183], v[60:63]
	v_mfma_f32_16x16x32_bf16 v[56:59], v[172:175], v[180:183], v[56:59]
	v_mfma_f32_16x16x32_bf16 v[52:55], v[168:171], v[188:191], v[52:55]
	v_mfma_f32_16x16x32_bf16 v[48:51], v[172:175], v[188:191], v[48:51]
	v_mfma_f32_16x16x32_bf16 v[44:47], v[168:171], v[196:199], v[44:47]
	v_mfma_f32_16x16x32_bf16 v[40:43], v[172:175], v[196:199], v[40:43]
	v_mfma_f32_16x16x32_bf16 v[36:39], v[168:171], v[204:207], v[36:39]
	v_mfma_f32_16x16x32_bf16 v[32:35], v[172:175], v[204:207], v[32:35]
	v_mfma_f32_16x16x32_bf16 v[28:31], v[208:211], v[176:179], v[28:31]
	v_mfma_f32_16x16x32_bf16 v[24:27], v[212:215], v[176:179], v[24:27]
	v_mfma_f32_16x16x32_bf16 v[20:23], v[208:211], v[184:187], v[20:23]
	v_mfma_f32_16x16x32_bf16 v[16:19], v[212:215], v[184:187], v[16:19]
	v_mfma_f32_16x16x32_bf16 v[12:15], v[208:211], v[192:195], v[12:15]
	v_mfma_f32_16x16x32_bf16 v[8:11], v[212:215], v[192:195], v[8:11]
	v_mfma_f32_16x16x32_bf16 v[4:7], v[208:211], v[200:203], v[4:7]
	v_mfma_f32_16x16x32_bf16 v[0:3], v[212:215], v[200:203], v[0:3]
	v_mfma_f32_16x16x32_bf16 v[28:31], v[216:219], v[180:183], v[28:31]
	v_mfma_f32_16x16x32_bf16 v[24:27], v[220:223], v[180:183], v[24:27]
	v_mfma_f32_16x16x32_bf16 v[20:23], v[216:219], v[188:191], v[20:23]
	v_mfma_f32_16x16x32_bf16 v[16:19], v[220:223], v[188:191], v[16:19]
	v_mfma_f32_16x16x32_bf16 v[12:15], v[216:219], v[196:199], v[12:15]
	v_mfma_f32_16x16x32_bf16 v[8:11], v[220:223], v[196:199], v[8:11]
	v_mfma_f32_16x16x32_bf16 v[4:7], v[216:219], v[204:207], v[4:7]
	v_mfma_f32_16x16x32_bf16 v[0:3], v[220:223], v[204:207], v[0:3]
	s_setprio 0
	s_barrier
	ds_read_b128 v[160:163], v156
	ds_read_b128 v[164:167], v156 offset:256
	ds_read_b128 v[168:171], v157
	ds_read_b128 v[172:175], v157 offset:256
	v_readfirstlane_b32 s77, v141
	v_lshl_add_u64 v[208:209], v[224:225], 0, s[38:39]
	s_mov_b32 m0, s77
	v_readfirstlane_b32 s77, v142
	ds_read_b128 v[176:179], v149 offset:32768
	ds_read_b128 v[180:183], v149 offset:33792
	ds_read_b128 v[184:187], v149 offset:34816
	ds_read_b128 v[188:191], v149 offset:35840
	ds_read_b128 v[192:195], v149 offset:36864
	ds_read_b128 v[196:199], v149 offset:37888
	ds_read_b128 v[200:203], v149 offset:38912
	ds_read_b128 v[204:207], v149 offset:39936
	global_load_lds_dwordx4 v[208:209], off
	v_lshl_add_u64 v[208:209], v[224:225], 0, s[46:47]
	s_mov_b32 m0, s77
	s_nop 0
	global_load_lds_dwordx4 v[208:209], off
	s_waitcnt lgkmcnt(8)
	v_readfirstlane_b32 s77, v140
	v_lshl_add_u64 v[246:247], v[228:229], 0, s[36:37]
	s_mov_b32 m0, s77
	s_nop 0
	global_load_lds_dwordx4 v[246:247], off
	ds_read_b128 v[208:211], v158
	ds_read_b128 v[212:215], v158 offset:256
	ds_read_b128 v[216:219], v159
	ds_read_b128 v[220:223], v159 offset:256
	s_barrier
	s_waitcnt lgkmcnt(0)
	s_setprio 1
	v_mfma_f32_16x16x32_bf16 v[124:127], v[160:163], v[176:179], v[124:127]
	v_mfma_f32_16x16x32_bf16 v[120:123], v[164:167], v[176:179], v[120:123]
	v_mfma_f32_16x16x32_bf16 v[116:119], v[160:163], v[184:187], v[116:119]
	v_mfma_f32_16x16x32_bf16 v[112:115], v[164:167], v[184:187], v[112:115]
	v_mfma_f32_16x16x32_bf16 v[108:111], v[160:163], v[192:195], v[108:111]
	v_mfma_f32_16x16x32_bf16 v[104:107], v[164:167], v[192:195], v[104:107]
	v_mfma_f32_16x16x32_bf16 v[100:103], v[160:163], v[200:203], v[100:103]
	v_mfma_f32_16x16x32_bf16 v[96:99], v[164:167], v[200:203], v[96:99]
	v_mfma_f32_16x16x32_bf16 v[124:127], v[168:171], v[180:183], v[124:127]
	v_mfma_f32_16x16x32_bf16 v[120:123], v[172:175], v[180:183], v[120:123]
	v_mfma_f32_16x16x32_bf16 v[116:119], v[168:171], v[188:191], v[116:119]
	v_mfma_f32_16x16x32_bf16 v[112:115], v[172:175], v[188:191], v[112:115]
	v_mfma_f32_16x16x32_bf16 v[108:111], v[168:171], v[196:199], v[108:111]
	v_mfma_f32_16x16x32_bf16 v[104:107], v[172:175], v[196:199], v[104:107]
	v_mfma_f32_16x16x32_bf16 v[100:103], v[168:171], v[204:207], v[100:103]
	v_mfma_f32_16x16x32_bf16 v[96:99], v[172:175], v[204:207], v[96:99]
	v_mfma_f32_16x16x32_bf16 v[92:95], v[208:211], v[176:179], v[92:95]
	v_mfma_f32_16x16x32_bf16 v[88:91], v[212:215], v[176:179], v[88:91]
	v_mfma_f32_16x16x32_bf16 v[84:87], v[208:211], v[184:187], v[84:87]
	v_mfma_f32_16x16x32_bf16 v[80:83], v[212:215], v[184:187], v[80:83]
	v_mfma_f32_16x16x32_bf16 v[76:79], v[208:211], v[192:195], v[76:79]
	v_mfma_f32_16x16x32_bf16 v[72:75], v[212:215], v[192:195], v[72:75]
	v_mfma_f32_16x16x32_bf16 v[68:71], v[208:211], v[200:203], v[68:71]
	v_mfma_f32_16x16x32_bf16 v[64:67], v[212:215], v[200:203], v[64:67]
	v_mfma_f32_16x16x32_bf16 v[92:95], v[216:219], v[180:183], v[92:95]
	v_mfma_f32_16x16x32_bf16 v[88:91], v[220:223], v[180:183], v[88:91]
	v_mfma_f32_16x16x32_bf16 v[84:87], v[216:219], v[188:191], v[84:87]
	v_mfma_f32_16x16x32_bf16 v[80:83], v[220:223], v[188:191], v[80:83]
	v_mfma_f32_16x16x32_bf16 v[76:79], v[216:219], v[196:199], v[76:79]
	v_mfma_f32_16x16x32_bf16 v[72:75], v[220:223], v[196:199], v[72:75]
	v_mfma_f32_16x16x32_bf16 v[68:71], v[216:219], v[204:207], v[68:71]
	v_mfma_f32_16x16x32_bf16 v[64:67], v[220:223], v[204:207], v[64:67]
	s_setprio 0
	s_barrier
; #define STAGE(P, BASE, br, kt) do { const char* _gb = (const char*)(BASE) + ((size_t)(br) * K + (size_t)(kt) * BK) * 2; \
;     __builtin_amdgcn_global_load_lds((const unsigned*)(_gb + loff0), (unsigned*)((char*)(P) + tid * 16), 16, 0, 0); \
;     __builtin_amdgcn_global_load_lds((const unsigned*)(_gb + (size_t)K * 128 + loff0), (unsigned*)((char*)(P) + tid * 16 + 8192), 16, 0, 0); } while (0)
; #define LDA(dst, b, h) for (int m = 0; m < 4; ++m) { \
;     dst[m][0] = *reinterpret_cast<const bf16x8*>((char*)SA(b, h) + aoff0 + m * 2048); \
;     dst[m][1] = *reinterpret_cast<const bf16x8*>((char*)SA(b, h) + aoff1 + m * 2048); }
; #define LDB(dst, b, h) for (int n = 0; n < 2; ++n) { \
;     dst[n][0] = *reinterpret_cast<const bf16x8*>((char*)SB(b, h) + boff0 + n * 256); \
;     dst[n][1] = *reinterpret_cast<const bf16x8*>((char*)SB(b, h) + boff1 + n * 256); }
; #define MMA(ai, bj, At, Btf) do { __builtin_amdgcn_s_setprio(1); \
;     for (int m = 0; m < 4; ++m) for (int n = 0; n < 2; ++n) for (int k = 0; k < 2; ++k) \
;       acc[ai][bj][m][n] = __builtin_amdgcn_mfma_f32_16x16x32_bf16(Btf[n][k], At[m][k], acc[ai][bj][m][n], 0, 0, 0); \
;     __builtin_amdgcn_s_setprio(0); } while (0)
; #define WAIT_V(n) asm volatile("s_waitcnt vmcnt(" #n ")" ::: "memory")
; #define WAIT_L(n) asm volatile("s_waitcnt lgkmcnt(" #n ")" ::: "memory")
; #define BAR __builtin_amdgcn_s_barrier()
; #define SCHED __builtin_amdgcn_sched_barrier(0)
; template <int EPI> ...
;     ...
;     LDA(At, 1, 1); STAGE(SA(1, 0), A, brow, t + 3);
;     BAR; WAIT_L(0); MMA(1, 0, At, B0); BAR; SCHED;
;     STAGE(SB(1, 1), Bt, bcol + HALF, t + 3);
;     WAIT_V(6); BAR; MMA(1, 1, At, B1); BAR;
;   }
;   { LDB(B0, 0, 0); LDA(At, 0, 0); STAGE(SA(1, 1), A, brow + HALF, nt - 1);
;     BAR; WAIT_L(0); MMA(0, 0, At, B0); BAR;
	v_readfirstlane_b32 s77, v143
	v_lshl_add_u64 v[230:231], v[226:227], 0, s[48:49]
	s_mov_b32 m0, s77
	v_readfirstlane_b32 s77, v144
	global_load_lds_dwordx4 v[230:231], off
	v_lshl_add_u64 v[226:227], v[226:227], 0, s[50:51]
	s_mov_b32 m0, s77
	s_nop 0
	global_load_lds_dwordx4 v[226:227], off
	v_readfirstlane_b32 s77, v145
	v_lshl_add_u64 v[226:227], v[224:225], 0, s[52:53]
	s_mov_b32 m0, s77
	v_readfirstlane_b32 s77, v146
	ds_read_b128 v[176:179], v149 offset:49152
	ds_read_b128 v[180:183], v149 offset:50176
	ds_read_b128 v[184:187], v149 offset:51200
	ds_read_b128 v[188:191], v149 offset:52224
	ds_read_b128 v[192:195], v149 offset:53248
	ds_read_b128 v[196:199], v149 offset:54272
	ds_read_b128 v[200:203], v149 offset:55296
	ds_read_b128 v[204:207], v149 offset:56320
	global_load_lds_dwordx4 v[226:227], off
	v_lshl_add_u64 v[224:225], v[224:225], 0, s[54:55]
	s_mov_b32 m0, s77
	s_nop 0
	global_load_lds_dwordx4 v[224:225], off
	v_readfirstlane_b32 s77, v147
	v_lshl_add_u64 v[246:247], v[228:229], 0, s[56:57]
	s_mov_b32 m0, s77
	v_readfirstlane_b32 s77, v148
	global_load_lds_dwordx4 v[246:247], off
	s_waitcnt vmcnt(5)
	s_barrier
	s_waitcnt lgkmcnt(0)
	s_setprio 1
	s_waitcnt lgkmcnt(0)
	v_mfma_f32_16x16x32_bf16 v[60:63], v[160:163], v[176:179], v[60:63]
	v_mfma_f32_16x16x32_bf16 v[56:59], v[164:167], v[176:179], v[56:59]
	v_mfma_f32_16x16x32_bf16 v[52:55], v[160:163], v[184:187], v[52:55]
	v_mfma_f32_16x16x32_bf16 v[48:51], v[164:167], v[184:187], v[48:51]
	v_mfma_f32_16x16x32_bf16 v[44:47], v[160:163], v[192:195], v[44:47]
	v_mfma_f32_16x16x32_bf16 v[40:43], v[164:167], v[192:195], v[40:43]
	v_mfma_f32_16x16x32_bf16 v[36:39], v[160:163], v[200:203], v[36:39]
	v_mfma_f32_16x16x32_bf16 v[32:35], v[164:167], v[200:203], v[32:35]
	v_mfma_f32_16x16x32_bf16 v[60:63], v[168:171], v[180:183], v[60:63]
	v_mfma_f32_16x16x32_bf16 v[56:59], v[172:175], v[180:183], v[56:59]
	v_mfma_f32_16x16x32_bf16 v[52:55], v[168:171], v[188:191], v[52:55]
	v_mfma_f32_16x16x32_bf16 v[48:51], v[172:175], v[188:191], v[48:51]
	v_mfma_f32_16x16x32_bf16 v[44:47], v[168:171], v[196:199], v[44:47]
	v_mfma_f32_16x16x32_bf16 v[40:43], v[172:175], v[196:199], v[40:43]
	v_mfma_f32_16x16x32_bf16 v[36:39], v[168:171], v[204:207], v[36:39]
	v_mfma_f32_16x16x32_bf16 v[32:35], v[172:175], v[204:207], v[32:35]
	s_setprio 0
	s_setprio 1
	v_mfma_f32_16x16x32_bf16 v[28:31], v[208:211], v[176:179], v[28:31]
	v_mfma_f32_16x16x32_bf16 v[24:27], v[212:215], v[176:179], v[24:27]
	v_mfma_f32_16x16x32_bf16 v[20:23], v[208:211], v[184:187], v[20:23]
	v_mfma_f32_16x16x32_bf16 v[16:19], v[212:215], v[184:187], v[16:19]
	v_mfma_f32_16x16x32_bf16 v[12:15], v[208:211], v[192:195], v[12:15]
	v_mfma_f32_16x16x32_bf16 v[8:11], v[212:215], v[192:195], v[8:11]
	v_mfma_f32_16x16x32_bf16 v[4:7], v[208:211], v[200:203], v[4:7]
	v_mfma_f32_16x16x32_bf16 v[0:3], v[212:215], v[200:203], v[0:3]
	v_mfma_f32_16x16x32_bf16 v[28:31], v[216:219], v[180:183], v[28:31]
	v_mfma_f32_16x16x32_bf16 v[24:27], v[220:223], v[180:183], v[24:27]
	v_mfma_f32_16x16x32_bf16 v[20:23], v[216:219], v[188:191], v[20:23]
	v_mfma_f32_16x16x32_bf16 v[16:19], v[220:223], v[188:191], v[16:19]
	v_mfma_f32_16x16x32_bf16 v[12:15], v[216:219], v[196:199], v[12:15]
	v_mfma_f32_16x16x32_bf16 v[8:11], v[220:223], v[196:199], v[8:11]
	v_mfma_f32_16x16x32_bf16 v[4:7], v[216:219], v[204:207], v[4:7]
	v_mfma_f32_16x16x32_bf16 v[0:3], v[220:223], v[204:207], v[0:3]
	s_setprio 0
	s_add_i32 s76, s76, 2
	s_add_u32 s62, s62, 0x100
	s_addc_u32 s63, s63, 0
	s_add_u32 s64, s64, 0x100
	s_addc_u32 s65, s65, 0
	s_add_u32 s66, s66, 0x100
	s_addc_u32 s67, s67, 0
	s_cmpk_lt_u32 s76, 0x54
	s_barrier
	s_cbranch_scc1 .LBB0_324
	v_readfirstlane_b32 s77, v148
	v_lshl_add_u64 v[246:247], v[228:229], 0, s[58:59]
	s_mov_b32 m0, s77
	s_nop 0
	global_load_lds_dwordx4 v[246:247], off
	s_add_u32 s62, s70, s75
	s_addc_u32 s63, s71, s74
	v_lshl_add_u64 v[208:209], s[62:63], 0, v[128:129]
	v_readfirstlane_b32 s62, v150
	s_mov_b32 m0, s62
	v_readfirstlane_b32 s62, v151
	ds_read_b128 v[160:163], v152
	ds_read_b128 v[164:167], v152 offset:256
	ds_read_b128 v[168:171], v153
	ds_read_b128 v[172:175], v153 offset:256
	ds_read_b128 v[176:179], v149
	ds_read_b128 v[180:183], v149 offset:1024
	ds_read_b128 v[184:187], v149 offset:2048
	ds_read_b128 v[188:191], v149 offset:3072
	ds_read_b128 v[192:195], v149 offset:4096
	ds_read_b128 v[196:199], v149 offset:5120
	ds_read_b128 v[200:203], v149 offset:6144
	ds_read_b128 v[204:207], v149 offset:7168
	global_load_lds_dwordx4 v[208:209], off
	v_lshl_add_u64 v[208:209], v[208:209], 0, s[8:9]
	s_mov_b32 m0, s62
	s_nop 0
	global_load_lds_dwordx4 v[208:209], off
	s_barrier
	s_waitcnt lgkmcnt(0)
	s_setprio 1
	v_mfma_f32_16x16x32_bf16 v[124:127], v[160:163], v[176:179], v[124:127]
	v_mfma_f32_16x16x32_bf16 v[116:119], v[160:163], v[184:187], v[116:119]
	v_mfma_f32_16x16x32_bf16 v[108:111], v[160:163], v[192:195], v[108:111]
	v_mfma_f32_16x16x32_bf16 v[100:103], v[160:163], v[200:203], v[100:103]
	v_mfma_f32_16x16x32_bf16 v[96:99], v[164:167], v[200:203], v[96:99]
	v_mfma_f32_16x16x32_bf16 v[124:127], v[168:171], v[180:183], v[124:127]
	v_mfma_f32_16x16x32_bf16 v[120:123], v[164:167], v[176:179], v[120:123]
	v_mfma_f32_16x16x32_bf16 v[116:119], v[168:171], v[188:191], v[116:119]
	v_mfma_f32_16x16x32_bf16 v[112:115], v[164:167], v[184:187], v[112:115]
	v_mfma_f32_16x16x32_bf16 v[108:111], v[168:171], v[196:199], v[108:111]
	v_mfma_f32_16x16x32_bf16 v[104:107], v[164:167], v[192:195], v[104:107]
	v_mfma_f32_16x16x32_bf16 v[100:103], v[168:171], v[204:207], v[100:103]
	v_mfma_f32_16x16x32_bf16 v[96:99], v[172:175], v[204:207], v[96:99]
	v_mfma_f32_16x16x32_bf16 v[208:211], v[172:175], v[180:183], v[120:123]
	v_mfma_f32_16x16x32_bf16 v[212:215], v[172:175], v[188:191], v[112:115]
	v_mfma_f32_16x16x32_bf16 v[216:219], v[172:175], v[196:199], v[104:107]
	s_setprio 0
	s_barrier
; #define LDA(dst, b, h) for (int m = 0; m < 4; ++m) { \
;     dst[m][0] = *reinterpret_cast<const bf16x8*>((char*)SA(b, h) + aoff0 + m * 2048); \
;     dst[m][1] = *reinterpret_cast<const bf16x8*>((char*)SA(b, h) + aoff1 + m * 2048); }
; #define LDB(dst, b, h) for (int n = 0; n < 2; ++n) { \
;     dst[n][0] = *reinterpret_cast<const bf16x8*>((char*)SB(b, h) + boff0 + n * 256); \
;     dst[n][1] = *reinterpret_cast<const bf16x8*>((char*)SB(b, h) + boff1 + n * 256); }
; #define MMA(ai, bj, At, Btf) do { __builtin_amdgcn_s_setprio(1); \
;     for (int m = 0; m < 4; ++m) for (int n = 0; n < 2; ++n) for (int k = 0; k < 2; ++k) \
;       acc[ai][bj][m][n] = __builtin_amdgcn_mfma_f32_16x16x32_bf16(Btf[n][k], At[m][k], acc[ai][bj][m][n], 0, 0, 0); \
;     __builtin_amdgcn_s_setprio(0); } while (0)
; #define WAIT_V(n) asm volatile("s_waitcnt vmcnt(" #n ")" ::: "memory")
; #define WAIT_L(n) asm volatile("s_waitcnt lgkmcnt(" #n ")" ::: "memory")
; #define BAR __builtin_amdgcn_s_barrier()
; template <int EPI> ...
;     ...
;     LDB(B1, 0, 1); BAR; WAIT_L(0); MMA(0, 1, At, B1); BAR;
;     LDA(At, 0, 1); WAIT_V(4); BAR; WAIT_L(0); MMA(1, 0, At, B0); MMA(1, 1, At, B1); BAR; }
;   { LDB(B0, 1, 0); LDA(At, 1, 0); WAIT_V(2); BAR; WAIT_L(0); MMA(0, 0, At, B0); BAR;
	s_nop 0
	ds_read_b128 v[104:107], v154
	ds_read_b128 v[112:115], v154 offset:256
	ds_read_b128 v[120:123], v155
	ds_read_b128 v[220:223], v155 offset:256
	s_barrier
	s_waitcnt lgkmcnt(0)
	s_setprio 1
	v_mfma_f32_16x16x32_bf16 v[84:87], v[104:107], v[184:187], v[84:87]
	v_mfma_f32_16x16x32_bf16 v[76:79], v[104:107], v[192:195], v[76:79]
	v_mfma_f32_16x16x32_bf16 v[72:75], v[112:115], v[192:195], v[72:75]
	v_mfma_f32_16x16x32_bf16 v[92:95], v[104:107], v[176:179], v[92:95]
	v_mfma_f32_16x16x32_bf16 v[88:91], v[112:115], v[176:179], v[88:91]
	v_mfma_f32_16x16x32_bf16 v[84:87], v[120:123], v[188:191], v[84:87]
	v_mfma_f32_16x16x32_bf16 v[80:83], v[112:115], v[184:187], v[80:83]
	v_mfma_f32_16x16x32_bf16 v[76:79], v[120:123], v[196:199], v[76:79]
	v_mfma_f32_16x16x32_bf16 v[72:75], v[220:223], v[196:199], v[72:75]
	v_mfma_f32_16x16x32_bf16 v[68:71], v[104:107], v[200:203], v[68:71]
	v_mfma_f32_16x16x32_bf16 v[64:67], v[112:115], v[200:203], v[64:67]
	v_mfma_f32_16x16x32_bf16 v[224:227], v[120:123], v[180:183], v[92:95]
	v_mfma_f32_16x16x32_bf16 v[176:179], v[220:223], v[180:183], v[88:91]
	v_mfma_f32_16x16x32_bf16 v[180:183], v[220:223], v[188:191], v[80:83]
	v_mfma_f32_16x16x32_bf16 v[184:187], v[120:123], v[204:207], v[68:71]
	v_mfma_f32_16x16x32_bf16 v[188:191], v[220:223], v[204:207], v[64:67]
	s_setprio 0
	s_barrier
	s_nop 0
	ds_read_b128 v[64:67], v149 offset:16384
	ds_read_b128 v[68:71], v149 offset:17408
	ds_read_b128 v[80:83], v149 offset:18432
	ds_read_b128 v[88:91], v149 offset:19456
	ds_read_b128 v[92:95], v149 offset:20480
	ds_read_b128 v[192:195], v149 offset:21504
	ds_read_b128 v[196:199], v149 offset:22528
	ds_read_b128 v[200:203], v149 offset:23552
	s_waitcnt vmcnt(4)
	s_barrier
	s_waitcnt lgkmcnt(0)
	s_setprio 1
	v_mfma_f32_16x16x32_bf16 v[52:55], v[160:163], v[80:83], v[52:55]
	v_mfma_f32_16x16x32_bf16 v[44:47], v[160:163], v[92:95], v[44:47]
	v_mfma_f32_16x16x32_bf16 v[36:39], v[160:163], v[196:199], v[36:39]
	v_mfma_f32_16x16x32_bf16 v[60:63], v[160:163], v[64:67], v[60:63]
	v_mfma_f32_16x16x32_bf16 v[56:59], v[164:167], v[64:67], v[56:59]
	v_mfma_f32_16x16x32_bf16 v[52:55], v[168:171], v[88:91], v[52:55]
	v_mfma_f32_16x16x32_bf16 v[48:51], v[164:167], v[80:83], v[48:51]
	v_mfma_f32_16x16x32_bf16 v[44:47], v[168:171], v[192:195], v[44:47]
	v_mfma_f32_16x16x32_bf16 v[40:43], v[164:167], v[92:95], v[40:43]
	v_mfma_f32_16x16x32_bf16 v[36:39], v[168:171], v[200:203], v[36:39]
	v_mfma_f32_16x16x32_bf16 v[32:35], v[164:167], v[196:199], v[32:35]
	v_mfma_f32_16x16x32_bf16 v[204:207], v[168:171], v[68:71], v[60:63]
	v_mfma_f32_16x16x32_bf16 v[228:231], v[172:175], v[68:71], v[56:59]
	v_mfma_f32_16x16x32_bf16 v[232:235], v[172:175], v[88:91], v[48:51]
	v_mfma_f32_16x16x32_bf16 v[236:239], v[172:175], v[192:195], v[40:43]
	v_mfma_f32_16x16x32_bf16 v[160:163], v[172:175], v[200:203], v[32:35]
	v_mfma_f32_16x16x32_bf16 v[28:31], v[104:107], v[64:67], v[28:31]
	v_mfma_f32_16x16x32_bf16 v[20:23], v[104:107], v[80:83], v[20:23]
	v_mfma_f32_16x16x32_bf16 v[12:15], v[104:107], v[92:95], v[12:15]
	v_mfma_f32_16x16x32_bf16 v[4:7], v[104:107], v[196:199], v[4:7]
	v_mfma_f32_16x16x32_bf16 v[28:31], v[120:123], v[68:71], v[28:31]
	v_mfma_f32_16x16x32_bf16 v[24:27], v[112:115], v[64:67], v[24:27]
	v_mfma_f32_16x16x32_bf16 v[20:23], v[120:123], v[88:91], v[20:23]
	v_mfma_f32_16x16x32_bf16 v[16:19], v[112:115], v[80:83], v[16:19]
	v_mfma_f32_16x16x32_bf16 v[12:15], v[120:123], v[192:195], v[12:15]
	v_mfma_f32_16x16x32_bf16 v[8:11], v[112:115], v[92:95], v[8:11]
	v_mfma_f32_16x16x32_bf16 v[4:7], v[120:123], v[200:203], v[4:7]
	v_mfma_f32_16x16x32_bf16 v[0:3], v[112:115], v[196:199], v[0:3]
	v_mfma_f32_16x16x32_bf16 v[164:167], v[220:223], v[68:71], v[24:27]
	v_mfma_f32_16x16x32_bf16 v[168:171], v[220:223], v[88:91], v[16:19]
	v_mfma_f32_16x16x32_bf16 v[172:175], v[220:223], v[192:195], v[8:11]
	v_mfma_f32_16x16x32_bf16 v[192:195], v[220:223], v[200:203], v[0:3]
	s_setprio 0
	s_barrier
	s_nop 1
	ds_read_b128 v[0:3], v156
	ds_read_b128 v[8:11], v156 offset:256
	ds_read_b128 v[16:19], v157
	ds_read_b128 v[24:27], v157 offset:256
	ds_read_b128 v[32:35], v149 offset:32768
	ds_read_b128 v[40:43], v149 offset:33792
	ds_read_b128 v[48:51], v149 offset:34816
	ds_read_b128 v[56:59], v149 offset:35840
	ds_read_b128 v[60:63], v149 offset:36864
	ds_read_b128 v[68:71], v149 offset:37888
	ds_read_b128 v[196:199], v149 offset:38912
	ds_read_b128 v[200:203], v149 offset:39936
	s_waitcnt vmcnt(2)
	s_barrier
; #define LDA(dst, b, h) for (int m = 0; m < 4; ++m) { \
;     dst[m][0] = *reinterpret_cast<const bf16x8*>((char*)SA(b, h) + aoff0 + m * 2048); \
;     dst[m][1] = *reinterpret_cast<const bf16x8*>((char*)SA(b, h) + aoff1 + m * 2048); }
; #define LDB(dst, b, h) for (int n = 0; n < 2; ++n) { \
;     dst[n][0] = *reinterpret_cast<const bf16x8*>((char*)SB(b, h) + boff0 + n * 256); \
;     dst[n][1] = *reinterpret_cast<const bf16x8*>((char*)SB(b, h) + boff1 + n * 256); }
; #define MMA(ai, bj, At, Btf) do { __builtin_amdgcn_s_setprio(1); \
;     for (int m = 0; m < 4; ++m) for (int n = 0; n < 2; ++n) for (int k = 0; k < 2; ++k) \
;       acc[ai][bj][m][n] = __builtin_amdgcn_mfma_f32_16x16x32_bf16(Btf[n][k], At[m][k], acc[ai][bj][m][n], 0, 0, 0); \
;     __builtin_amdgcn_s_setprio(0); } while (0)
; #define WAIT_V(n) asm volatile("s_waitcnt vmcnt(" #n ")" ::: "memory")
; #define WAIT_L(n) asm volatile("s_waitcnt lgkmcnt(" #n ")" ::: "memory")
; #define BAR __builtin_amdgcn_s_barrier()
; template <int EPI> ...
;     ...
;   { LDB(B0, 1, 0); LDA(At, 1, 0); WAIT_V(2); BAR; WAIT_L(0); MMA(0, 0, At, B0); BAR;
;     LDB(B1, 1, 1); WAIT_V(0); BAR; WAIT_L(0); MMA(0, 1, At, B1); BAR;
;     LDA(At, 1, 1); BAR; WAIT_L(0); MMA(1, 0, At, B0); MMA(1, 1, At, B1); BAR; }
;   if (wr == 0) BAR;
	s_waitcnt lgkmcnt(0)
	s_setprio 1
	v_mfma_f32_16x16x32_bf16 v[64:67], v[0:3], v[32:35], v[124:127]
	v_mfma_f32_16x16x32_bf16 v[120:123], v[16:19], v[40:43], v[64:67]
	v_mfma_f32_16x16x32_bf16 v[64:67], v[8:11], v[32:35], v[208:211]
	v_mfma_f32_16x16x32_bf16 v[124:127], v[24:27], v[40:43], v[64:67]
	v_mfma_f32_16x16x32_bf16 v[64:67], v[0:3], v[48:51], v[116:119]
	v_mfma_f32_16x16x32_bf16 v[112:115], v[16:19], v[56:59], v[64:67]
	v_mfma_f32_16x16x32_bf16 v[64:67], v[8:11], v[48:51], v[212:215]
	v_mfma_f32_16x16x32_bf16 v[116:119], v[24:27], v[56:59], v[64:67]
	v_mfma_f32_16x16x32_bf16 v[64:67], v[0:3], v[60:63], v[108:111]
	v_mfma_f32_16x16x32_bf16 v[104:107], v[16:19], v[68:71], v[64:67]
	v_mfma_f32_16x16x32_bf16 v[64:67], v[8:11], v[60:63], v[216:219]
	v_mfma_f32_16x16x32_bf16 v[108:111], v[24:27], v[68:71], v[64:67]
	v_mfma_f32_16x16x32_bf16 v[64:67], v[0:3], v[196:199], v[100:103]
	v_mfma_f32_16x16x32_bf16 v[88:91], v[16:19], v[200:203], v[64:67]
	v_mfma_f32_16x16x32_bf16 v[64:67], v[8:11], v[196:199], v[96:99]
	v_mfma_f32_16x16x32_bf16 v[92:95], v[24:27], v[200:203], v[64:67]
	s_setprio 0
	s_barrier
	ds_read_b128 v[208:211], v158
	ds_read_b128 v[212:215], v158 offset:256
	ds_read_b128 v[216:219], v159
	ds_read_b128 v[220:223], v159 offset:256
	s_waitcnt vmcnt(0)
	s_barrier
	s_waitcnt lgkmcnt(0)
	s_setprio 1
	v_mfma_f32_16x16x32_bf16 v[64:67], v[208:211], v[32:35], v[224:227]
	v_mfma_f32_16x16x32_bf16 v[32:35], v[212:215], v[32:35], v[176:179]
	v_mfma_f32_16x16x32_bf16 v[100:103], v[220:223], v[40:43], v[32:35]
	v_mfma_f32_16x16x32_bf16 v[32:35], v[208:211], v[48:51], v[84:87]
	v_mfma_f32_16x16x32_bf16 v[80:83], v[216:219], v[56:59], v[32:35]
	v_mfma_f32_16x16x32_bf16 v[32:35], v[212:215], v[48:51], v[180:183]
	v_mfma_f32_16x16x32_bf16 v[84:87], v[220:223], v[56:59], v[32:35]
	v_mfma_f32_16x16x32_bf16 v[32:35], v[208:211], v[60:63], v[76:79]
	v_mfma_f32_16x16x32_bf16 v[96:99], v[216:219], v[40:43], v[64:67]
	v_mfma_f32_16x16x32_bf16 v[64:67], v[216:219], v[68:71], v[32:35]
	v_mfma_f32_16x16x32_bf16 v[32:35], v[212:215], v[60:63], v[72:75]
	v_mfma_f32_16x16x32_bf16 v[68:71], v[220:223], v[68:71], v[32:35]
	v_mfma_f32_16x16x32_bf16 v[32:35], v[208:211], v[196:199], v[184:187]
	v_mfma_f32_16x16x32_bf16 v[56:59], v[216:219], v[200:203], v[32:35]
	v_mfma_f32_16x16x32_bf16 v[32:35], v[212:215], v[196:199], v[188:191]
	v_mfma_f32_16x16x32_bf16 v[60:63], v[220:223], v[200:203], v[32:35]
	s_setprio 0
	s_barrier
	ds_read_b128 v[176:179], v149 offset:49152
	ds_read_b128 v[180:183], v149 offset:50176
	ds_read_b128 v[184:187], v149 offset:51200
	ds_read_b128 v[188:191], v149 offset:52224
	ds_read_b128 v[196:199], v149 offset:53248
	ds_read_b128 v[200:203], v149 offset:54272
	ds_read_b128 v[224:227], v149 offset:55296
	ds_read_b128 v[240:243], v149 offset:56320
	s_barrier
	s_waitcnt lgkmcnt(0)
	s_setprio 1
	v_mfma_f32_16x16x32_bf16 v[32:35], v[0:3], v[176:179], v[204:207]
	v_mfma_f32_16x16x32_bf16 v[72:75], v[16:19], v[180:183], v[32:35]
	v_mfma_f32_16x16x32_bf16 v[32:35], v[8:11], v[176:179], v[228:231]
	v_mfma_f32_16x16x32_bf16 v[76:79], v[24:27], v[180:183], v[32:35]
	v_mfma_f32_16x16x32_bf16 v[32:35], v[0:3], v[184:187], v[52:55]
	v_mfma_f32_16x16x32_bf16 v[48:51], v[16:19], v[188:191], v[32:35]
	v_mfma_f32_16x16x32_bf16 v[32:35], v[8:11], v[184:187], v[232:235]
	v_mfma_f32_16x16x32_bf16 v[52:55], v[24:27], v[188:191], v[32:35]
	v_mfma_f32_16x16x32_bf16 v[32:35], v[0:3], v[196:199], v[44:47]
	v_mfma_f32_16x16x32_bf16 v[40:43], v[16:19], v[200:203], v[32:35]
	v_mfma_f32_16x16x32_bf16 v[32:35], v[8:11], v[196:199], v[236:239]
	v_mfma_f32_16x16x32_bf16 v[0:3], v[0:3], v[224:227], v[36:39]
	v_mfma_f32_16x16x32_bf16 v[44:47], v[24:27], v[200:203], v[32:35]
	v_mfma_f32_16x16x32_bf16 v[32:35], v[16:19], v[240:243], v[0:3]
	v_mfma_f32_16x16x32_bf16 v[0:3], v[8:11], v[224:227], v[160:163]
	v_mfma_f32_16x16x32_bf16 v[36:39], v[24:27], v[240:243], v[0:3]
	v_mfma_f32_16x16x32_bf16 v[0:3], v[208:211], v[176:179], v[28:31]
	v_mfma_f32_16x16x32_bf16 v[24:27], v[216:219], v[180:183], v[0:3]
	v_mfma_f32_16x16x32_bf16 v[0:3], v[212:215], v[176:179], v[164:167]
	v_mfma_f32_16x16x32_bf16 v[28:31], v[220:223], v[180:183], v[0:3]
	v_mfma_f32_16x16x32_bf16 v[0:3], v[208:211], v[184:187], v[20:23]
	v_mfma_f32_16x16x32_bf16 v[16:19], v[216:219], v[188:191], v[0:3]
	v_mfma_f32_16x16x32_bf16 v[0:3], v[212:215], v[184:187], v[168:171]
	v_mfma_f32_16x16x32_bf16 v[20:23], v[220:223], v[188:191], v[0:3]
	v_mfma_f32_16x16x32_bf16 v[0:3], v[208:211], v[196:199], v[12:15]
	v_mfma_f32_16x16x32_bf16 v[8:11], v[216:219], v[200:203], v[0:3]
	v_mfma_f32_16x16x32_bf16 v[0:3], v[212:215], v[196:199], v[172:175]
	v_mfma_f32_16x16x32_bf16 v[12:15], v[220:223], v[200:203], v[0:3]
	v_mfma_f32_16x16x32_bf16 v[0:3], v[208:211], v[224:227], v[4:7]
	v_mfma_f32_16x16x32_bf16 v[4:7], v[212:215], v[224:227], v[192:195]
	v_mfma_f32_16x16x32_bf16 v[0:3], v[216:219], v[240:243], v[0:3]
	v_mfma_f32_16x16x32_bf16 v[4:7], v[220:223], v[240:243], v[4:7]
	s_setprio 0
	s_barrier
	s_and_saveexec_b64 s[62:63], s[2:3]
	s_cbranch_execz .LBB0_318
	s_barrier
	s_branch .LBB0_318

; #define STAGE(P, BASE, br, kt) do { const char* _gb = (const char*)(BASE) + ((size_t)(br) * K + (size_t)(kt) * BK) * 2; \
;     __builtin_amdgcn_global_load_lds((const unsigned*)(_gb + loff0), (unsigned*)((char*)(P) + tid * 16), 16, 0, 0); \
;     __builtin_amdgcn_global_load_lds((const unsigned*)(_gb + (size_t)K * 128 + loff0), (unsigned*)((char*)(P) + tid * 16 + 8192), 16, 0, 0); } while (0)
; #define LDA(dst, b, h) for (int m = 0; m < 4; ++m) { \
;     dst[m][0] = *reinterpret_cast<const bf16x8*>((char*)SA(b, h) + aoff0 + m * 2048); \
;     dst[m][1] = *reinterpret_cast<const bf16x8*>((char*)SA(b, h) + aoff1 + m * 2048); }
; #define LDB(dst, b, h) for (int n = 0; n < 2; ++n) { \
;     dst[n][0] = *reinterpret_cast<const bf16x8*>((char*)SB(b, h) + boff0 + n * 256); \
;     dst[n][1] = *reinterpret_cast<const bf16x8*>((char*)SB(b, h) + boff1 + n * 256); }
; #define MMA(ai, bj, At, Btf) do { __builtin_amdgcn_s_setprio(1); \
;     for (int m = 0; m < 4; ++m) for (int n = 0; n < 2; ++n) for (int k = 0; k < 2; ++k) \
;       acc[ai][bj][m][n] = __builtin_amdgcn_mfma_f32_16x16x32_bf16(Btf[n][k], At[m][k], acc[ai][bj][m][n], 0, 0, 0); \
;     __builtin_amdgcn_s_setprio(0); } while (0)
; #define WAIT_L(n) asm volatile("s_waitcnt lgkmcnt(" #n ")" ::: "memory")
; #define BAR __builtin_amdgcn_s_barrier()
; #define SCHED __builtin_amdgcn_sched_barrier(0)
; template <int EPI> ...
;     ...
;     LDB(B0, 0, 0); SCHED; LDA(At, 0, 0); STAGE(SA(1, 1), A, brow + HALF, t + 1);
;     WAIT_L(8); BAR; WAIT_L(0); MMA(0, 0, At, B0); BAR; SCHED;
;     LDB(B1, 0, 1); STAGE(SB(0, 0), Bt, bcol, t + 2);
;     BAR; WAIT_L(0); MMA(0, 1, At, B1); BAR;
;     LDA(At, 0, 1); STAGE(SA(0, 0), A, brow, t + 2);
;     BAR; WAIT_L(0); MMA(1, 0, At, B0); BAR; SCHED;
.LBB0_411:
	ds_read_b128 v[160:163], v152
	ds_read_b128 v[164:167], v152 offset:256
	ds_read_b128 v[168:171], v153
	ds_read_b128 v[172:175], v153 offset:256
	v_lshl_add_u64 v[224:225], s[68:69], 0, v[132:133]
	v_readfirstlane_b32 s70, v150
	v_lshl_add_u64 v[208:209], v[224:225], 0, s[16:17]
	s_mov_b32 m0, s70
	v_readfirstlane_b32 s70, v151
	ds_read_b128 v[176:179], v149
	ds_read_b128 v[180:183], v149 offset:1024
	ds_read_b128 v[184:187], v149 offset:2048
	ds_read_b128 v[188:191], v149 offset:3072
	ds_read_b128 v[192:195], v149 offset:4096
	ds_read_b128 v[196:199], v149 offset:5120
	ds_read_b128 v[200:203], v149 offset:6144
	ds_read_b128 v[204:207], v149 offset:7168
	global_load_lds_dwordx4 v[208:209], off
	v_lshl_add_u64 v[208:209], v[224:225], 0, s[18:19]
	s_mov_b32 m0, s70
	s_nop 0
	global_load_lds_dwordx4 v[208:209], off
	s_waitcnt lgkmcnt(8)
	v_readfirstlane_b32 s70, v148
	v_lshl_add_u64 v[246:247], v[226:227], 0, s[58:59]
	s_mov_b32 m0, s70
	s_nop 0
	global_load_lds_dwordx4 v[246:247], off
	ds_read_b128 v[208:211], v154
	ds_read_b128 v[212:215], v154 offset:256
	ds_read_b128 v[216:219], v155
	ds_read_b128 v[220:223], v155 offset:256
	s_barrier
	s_waitcnt lgkmcnt(0)
	s_setprio 1
	v_mfma_f32_16x16x32_bf16 v[124:127], v[160:163], v[176:179], v[124:127]
	v_mfma_f32_16x16x32_bf16 v[120:123], v[164:167], v[176:179], v[120:123]
	v_mfma_f32_16x16x32_bf16 v[116:119], v[160:163], v[184:187], v[116:119]
	v_mfma_f32_16x16x32_bf16 v[112:115], v[164:167], v[184:187], v[112:115]
	v_mfma_f32_16x16x32_bf16 v[108:111], v[160:163], v[192:195], v[108:111]
	v_mfma_f32_16x16x32_bf16 v[104:107], v[164:167], v[192:195], v[104:107]
	v_mfma_f32_16x16x32_bf16 v[100:103], v[160:163], v[200:203], v[100:103]
	v_mfma_f32_16x16x32_bf16 v[96:99], v[164:167], v[200:203], v[96:99]
	v_mfma_f32_16x16x32_bf16 v[124:127], v[168:171], v[180:183], v[124:127]
	v_mfma_f32_16x16x32_bf16 v[120:123], v[172:175], v[180:183], v[120:123]
	v_mfma_f32_16x16x32_bf16 v[116:119], v[168:171], v[188:191], v[116:119]
	v_mfma_f32_16x16x32_bf16 v[112:115], v[172:175], v[188:191], v[112:115]
	v_mfma_f32_16x16x32_bf16 v[108:111], v[168:171], v[196:199], v[108:111]
	v_mfma_f32_16x16x32_bf16 v[104:107], v[172:175], v[196:199], v[104:107]
	v_mfma_f32_16x16x32_bf16 v[100:103], v[168:171], v[204:207], v[100:103]
	v_mfma_f32_16x16x32_bf16 v[96:99], v[172:175], v[204:207], v[96:99]
	v_mfma_f32_16x16x32_bf16 v[92:95], v[208:211], v[176:179], v[92:95]
	v_mfma_f32_16x16x32_bf16 v[88:91], v[212:215], v[176:179], v[88:91]
	v_mfma_f32_16x16x32_bf16 v[84:87], v[208:211], v[184:187], v[84:87]
	v_mfma_f32_16x16x32_bf16 v[80:83], v[212:215], v[184:187], v[80:83]
	v_mfma_f32_16x16x32_bf16 v[76:79], v[208:211], v[192:195], v[76:79]
	v_mfma_f32_16x16x32_bf16 v[72:75], v[212:215], v[192:195], v[72:75]
	v_mfma_f32_16x16x32_bf16 v[68:71], v[208:211], v[200:203], v[68:71]
	v_mfma_f32_16x16x32_bf16 v[64:67], v[212:215], v[200:203], v[64:67]
	v_mfma_f32_16x16x32_bf16 v[92:95], v[216:219], v[180:183], v[92:95]
	v_mfma_f32_16x16x32_bf16 v[88:91], v[220:223], v[180:183], v[88:91]
	v_mfma_f32_16x16x32_bf16 v[84:87], v[216:219], v[188:191], v[84:87]
	v_mfma_f32_16x16x32_bf16 v[80:83], v[220:223], v[188:191], v[80:83]
	v_mfma_f32_16x16x32_bf16 v[76:79], v[216:219], v[196:199], v[76:79]
	v_mfma_f32_16x16x32_bf16 v[72:75], v[220:223], v[196:199], v[72:75]
	v_mfma_f32_16x16x32_bf16 v[68:71], v[216:219], v[204:207], v[68:71]
	v_mfma_f32_16x16x32_bf16 v[64:67], v[220:223], v[204:207], v[64:67]
	s_setprio 0
	s_barrier
	v_lshl_add_u64 v[226:227], s[66:67], 0, v[132:133]
	v_readfirstlane_b32 s70, v135
	v_lshl_add_u64 v[228:229], v[226:227], 0, s[20:21]
	s_mov_b32 m0, s70
	v_readfirstlane_b32 s70, v136
	global_load_lds_dwordx4 v[228:229], off
	v_lshl_add_u64 v[228:229], v[226:227], 0, s[22:23]
	s_mov_b32 m0, s70
	s_nop 0
	global_load_lds_dwordx4 v[228:229], off
	v_readfirstlane_b32 s70, v137
	v_lshl_add_u64 v[228:229], v[224:225], 0, s[26:27]
	s_mov_b32 m0, s70
	v_readfirstlane_b32 s70, v138
	ds_read_b128 v[176:179], v149 offset:16384
	ds_read_b128 v[180:183], v149 offset:17408
	ds_read_b128 v[184:187], v149 offset:18432
	ds_read_b128 v[188:191], v149 offset:19456
	ds_read_b128 v[192:195], v149 offset:20480
	ds_read_b128 v[196:199], v149 offset:21504
	ds_read_b128 v[200:203], v149 offset:22528
	ds_read_b128 v[204:207], v149 offset:23552
	global_load_lds_dwordx4 v[228:229], off
	v_lshl_add_u64 v[228:229], v[224:225], 0, s[28:29]
	s_mov_b32 m0, s70
	s_nop 0
	global_load_lds_dwordx4 v[228:229], off
	v_readfirstlane_b32 s70, v139
	v_lshl_add_u64 v[246:247], v[226:227], 0, s[30:31]
	s_mov_b32 m0, s70
	v_readfirstlane_b32 s70, v140
	global_load_lds_dwordx4 v[246:247], off
	s_waitcnt vmcnt(5)
	s_barrier
; #define STAGE(P, BASE, br, kt) do { const char* _gb = (const char*)(BASE) + ((size_t)(br) * K + (size_t)(kt) * BK) * 2; \
;     __builtin_amdgcn_global_load_lds((const unsigned*)(_gb + loff0), (unsigned*)((char*)(P) + tid * 16), 16, 0, 0); \
;     __builtin_amdgcn_global_load_lds((const unsigned*)(_gb + (size_t)K * 128 + loff0), (unsigned*)((char*)(P) + tid * 16 + 8192), 16, 0, 0); } while (0)
; #define LDA(dst, b, h) for (int m = 0; m < 4; ++m) { \
;     dst[m][0] = *reinterpret_cast<const bf16x8*>((char*)SA(b, h) + aoff0 + m * 2048); \
;     dst[m][1] = *reinterpret_cast<const bf16x8*>((char*)SA(b, h) + aoff1 + m * 2048); }
; #define LDB(dst, b, h) for (int n = 0; n < 2; ++n) { \
;     dst[n][0] = *reinterpret_cast<const bf16x8*>((char*)SB(b, h) + boff0 + n * 256); \
;     dst[n][1] = *reinterpret_cast<const bf16x8*>((char*)SB(b, h) + boff1 + n * 256); }
; #define MMA(ai, bj, At, Btf) do { __builtin_amdgcn_s_setprio(1); \
;     for (int m = 0; m < 4; ++m) for (int n = 0; n < 2; ++n) for (int k = 0; k < 2; ++k) \
;       acc[ai][bj][m][n] = __builtin_amdgcn_mfma_f32_16x16x32_bf16(Btf[n][k], At[m][k], acc[ai][bj][m][n], 0, 0, 0); \
;     __builtin_amdgcn_s_setprio(0); } while (0)
; #define WAIT_V(n) asm volatile("s_waitcnt vmcnt(" #n ")" ::: "memory")
; #define WAIT_L(n) asm volatile("s_waitcnt lgkmcnt(" #n ")" ::: "memory")
; #define BAR __builtin_amdgcn_s_barrier()
; #define SCHED __builtin_amdgcn_sched_barrier(0)
; template <int EPI> ...
;     ...
;     BAR; WAIT_L(0); MMA(1, 0, At, B0); BAR; SCHED;
;     STAGE(SB(0, 1), Bt, bcol + HALF, t + 2);
;     WAIT_V(6); BAR; MMA(1, 1, At, B1); BAR;
;     LDB(B0, 1, 0); SCHED; LDA(At, 1, 0); STAGE(SA(0, 1), A, brow + HALF, t + 2);
;     WAIT_L(8); BAR; WAIT_L(0); MMA(0, 0, At, B0); BAR; SCHED;
;     LDB(B1, 1, 1); STAGE(SB(1, 0), Bt, bcol, t + 3);
;     BAR; WAIT_L(0); MMA(0, 1, At, B1); BAR;
	s_waitcnt lgkmcnt(0)
	s_setprio 1
	v_mfma_f32_16x16x32_bf16 v[60:63], v[160:163], v[176:179], v[60:63]
	v_mfma_f32_16x16x32_bf16 v[56:59], v[164:167], v[176:179], v[56:59]
	v_mfma_f32_16x16x32_bf16 v[52:55], v[160:163], v[184:187], v[52:55]
	v_mfma_f32_16x16x32_bf16 v[48:51], v[164:167], v[184:187], v[48:51]
	v_mfma_f32_16x16x32_bf16 v[44:47], v[160:163], v[192:195], v[44:47]
	v_mfma_f32_16x16x32_bf16 v[40:43], v[164:167], v[192:195], v[40:43]
	v_mfma_f32_16x16x32_bf16 v[36:39], v[160:163], v[200:203], v[36:39]
	v_mfma_f32_16x16x32_bf16 v[32:35], v[164:167], v[200:203], v[32:35]
	v_mfma_f32_16x16x32_bf16 v[60:63], v[168:171], v[180:183], v[60:63]
	v_mfma_f32_16x16x32_bf16 v[56:59], v[172:175], v[180:183], v[56:59]
	v_mfma_f32_16x16x32_bf16 v[52:55], v[168:171], v[188:191], v[52:55]
	v_mfma_f32_16x16x32_bf16 v[48:51], v[172:175], v[188:191], v[48:51]
	v_mfma_f32_16x16x32_bf16 v[44:47], v[168:171], v[196:199], v[44:47]
	v_mfma_f32_16x16x32_bf16 v[40:43], v[172:175], v[196:199], v[40:43]
	v_mfma_f32_16x16x32_bf16 v[36:39], v[168:171], v[204:207], v[36:39]
	v_mfma_f32_16x16x32_bf16 v[32:35], v[172:175], v[204:207], v[32:35]
	v_mfma_f32_16x16x32_bf16 v[28:31], v[208:211], v[176:179], v[28:31]
	v_mfma_f32_16x16x32_bf16 v[24:27], v[212:215], v[176:179], v[24:27]
	v_mfma_f32_16x16x32_bf16 v[20:23], v[208:211], v[184:187], v[20:23]
	v_mfma_f32_16x16x32_bf16 v[16:19], v[212:215], v[184:187], v[16:19]
	v_mfma_f32_16x16x32_bf16 v[12:15], v[208:211], v[192:195], v[12:15]
	v_mfma_f32_16x16x32_bf16 v[8:11], v[212:215], v[192:195], v[8:11]
	v_mfma_f32_16x16x32_bf16 v[4:7], v[208:211], v[200:203], v[4:7]
	v_mfma_f32_16x16x32_bf16 v[0:3], v[212:215], v[200:203], v[0:3]
	v_mfma_f32_16x16x32_bf16 v[28:31], v[216:219], v[180:183], v[28:31]
	v_mfma_f32_16x16x32_bf16 v[24:27], v[220:223], v[180:183], v[24:27]
	v_mfma_f32_16x16x32_bf16 v[20:23], v[216:219], v[188:191], v[20:23]
	v_mfma_f32_16x16x32_bf16 v[16:19], v[220:223], v[188:191], v[16:19]
	v_mfma_f32_16x16x32_bf16 v[12:15], v[216:219], v[196:199], v[12:15]
	v_mfma_f32_16x16x32_bf16 v[8:11], v[220:223], v[196:199], v[8:11]
	v_mfma_f32_16x16x32_bf16 v[4:7], v[216:219], v[204:207], v[4:7]
	v_mfma_f32_16x16x32_bf16 v[0:3], v[220:223], v[204:207], v[0:3]
	s_setprio 0
	s_barrier
	ds_read_b128 v[160:163], v156
	ds_read_b128 v[164:167], v156 offset:256
	ds_read_b128 v[168:171], v157
	ds_read_b128 v[172:175], v157 offset:256
	v_readfirstlane_b32 s70, v141
	v_lshl_add_u64 v[208:209], v[224:225], 0, s[38:39]
	s_mov_b32 m0, s70
	v_readfirstlane_b32 s70, v142
	ds_read_b128 v[176:179], v149 offset:32768
	ds_read_b128 v[180:183], v149 offset:33792
	ds_read_b128 v[184:187], v149 offset:34816
	ds_read_b128 v[188:191], v149 offset:35840
	ds_read_b128 v[192:195], v149 offset:36864
	ds_read_b128 v[196:199], v149 offset:37888
	ds_read_b128 v[200:203], v149 offset:38912
	ds_read_b128 v[204:207], v149 offset:39936
	global_load_lds_dwordx4 v[208:209], off
	v_lshl_add_u64 v[208:209], v[224:225], 0, s[46:47]
	s_mov_b32 m0, s70
	s_nop 0
	global_load_lds_dwordx4 v[208:209], off
	s_waitcnt lgkmcnt(8)
	v_readfirstlane_b32 s70, v140
	v_lshl_add_u64 v[246:247], v[226:227], 0, s[36:37]
	s_mov_b32 m0, s70
	s_nop 0
	global_load_lds_dwordx4 v[246:247], off
	ds_read_b128 v[208:211], v158
	ds_read_b128 v[212:215], v158 offset:256
	ds_read_b128 v[216:219], v159
	ds_read_b128 v[220:223], v159 offset:256
	s_barrier
	s_waitcnt lgkmcnt(0)
	s_setprio 1
	v_mfma_f32_16x16x32_bf16 v[124:127], v[160:163], v[176:179], v[124:127]
	v_mfma_f32_16x16x32_bf16 v[120:123], v[164:167], v[176:179], v[120:123]
	v_mfma_f32_16x16x32_bf16 v[116:119], v[160:163], v[184:187], v[116:119]
	v_mfma_f32_16x16x32_bf16 v[112:115], v[164:167], v[184:187], v[112:115]
	v_mfma_f32_16x16x32_bf16 v[108:111], v[160:163], v[192:195], v[108:111]
	v_mfma_f32_16x16x32_bf16 v[104:107], v[164:167], v[192:195], v[104:107]
	v_mfma_f32_16x16x32_bf16 v[100:103], v[160:163], v[200:203], v[100:103]
	v_mfma_f32_16x16x32_bf16 v[96:99], v[164:167], v[200:203], v[96:99]
	v_mfma_f32_16x16x32_bf16 v[124:127], v[168:171], v[180:183], v[124:127]
	v_mfma_f32_16x16x32_bf16 v[120:123], v[172:175], v[180:183], v[120:123]
	v_mfma_f32_16x16x32_bf16 v[116:119], v[168:171], v[188:191], v[116:119]
	v_mfma_f32_16x16x32_bf16 v[112:115], v[172:175], v[188:191], v[112:115]
	v_mfma_f32_16x16x32_bf16 v[108:111], v[168:171], v[196:199], v[108:111]
	v_mfma_f32_16x16x32_bf16 v[104:107], v[172:175], v[196:199], v[104:107]
	v_mfma_f32_16x16x32_bf16 v[100:103], v[168:171], v[204:207], v[100:103]
	v_mfma_f32_16x16x32_bf16 v[96:99], v[172:175], v[204:207], v[96:99]
	v_mfma_f32_16x16x32_bf16 v[92:95], v[208:211], v[176:179], v[92:95]
	v_mfma_f32_16x16x32_bf16 v[88:91], v[212:215], v[176:179], v[88:91]
	v_mfma_f32_16x16x32_bf16 v[84:87], v[208:211], v[184:187], v[84:87]
	v_mfma_f32_16x16x32_bf16 v[80:83], v[212:215], v[184:187], v[80:83]
	v_mfma_f32_16x16x32_bf16 v[76:79], v[208:211], v[192:195], v[76:79]
	v_mfma_f32_16x16x32_bf16 v[72:75], v[212:215], v[192:195], v[72:75]
	v_mfma_f32_16x16x32_bf16 v[68:71], v[208:211], v[200:203], v[68:71]
	v_mfma_f32_16x16x32_bf16 v[64:67], v[212:215], v[200:203], v[64:67]
	v_mfma_f32_16x16x32_bf16 v[92:95], v[216:219], v[180:183], v[92:95]
	v_mfma_f32_16x16x32_bf16 v[88:91], v[220:223], v[180:183], v[88:91]
	v_mfma_f32_16x16x32_bf16 v[84:87], v[216:219], v[188:191], v[84:87]
	v_mfma_f32_16x16x32_bf16 v[80:83], v[220:223], v[188:191], v[80:83]
	v_mfma_f32_16x16x32_bf16 v[76:79], v[216:219], v[196:199], v[76:79]
	v_mfma_f32_16x16x32_bf16 v[72:75], v[220:223], v[196:199], v[72:75]
	v_mfma_f32_16x16x32_bf16 v[68:71], v[216:219], v[204:207], v[68:71]
	v_mfma_f32_16x16x32_bf16 v[64:67], v[220:223], v[204:207], v[64:67]
	s_setprio 0
	s_barrier
; #define STAGE(P, BASE, br, kt) do { const char* _gb = (const char*)(BASE) + ((size_t)(br) * K + (size_t)(kt) * BK) * 2; \
;     __builtin_amdgcn_global_load_lds((const unsigned*)(_gb + loff0), (unsigned*)((char*)(P) + tid * 16), 16, 0, 0); \
;     __builtin_amdgcn_global_load_lds((const unsigned*)(_gb + (size_t)K * 128 + loff0), (unsigned*)((char*)(P) + tid * 16 + 8192), 16, 0, 0); } while (0)
; #define LDA(dst, b, h) for (int m = 0; m < 4; ++m) { \
;     dst[m][0] = *reinterpret_cast<const bf16x8*>((char*)SA(b, h) + aoff0 + m * 2048); \
;     dst[m][1] = *reinterpret_cast<const bf16x8*>((char*)SA(b, h) + aoff1 + m * 2048); }
; #define LDB(dst, b, h) for (int n = 0; n < 2; ++n) { \
;     dst[n][0] = *reinterpret_cast<const bf16x8*>((char*)SB(b, h) + boff0 + n * 256); \
;     dst[n][1] = *reinterpret_cast<const bf16x8*>((char*)SB(b, h) + boff1 + n * 256); }
; #define MMA(ai, bj, At, Btf) do { __builtin_amdgcn_s_setprio(1); \
;     for (int m = 0; m < 4; ++m) for (int n = 0; n < 2; ++n) for (int k = 0; k < 2; ++k) \
;       acc[ai][bj][m][n] = __builtin_amdgcn_mfma_f32_16x16x32_bf16(Btf[n][k], At[m][k], acc[ai][bj][m][n], 0, 0, 0); \
;     __builtin_amdgcn_s_setprio(0); } while (0)
; #define WAIT_V(n) asm volatile("s_waitcnt vmcnt(" #n ")" ::: "memory")
; #define WAIT_L(n) asm volatile("s_waitcnt lgkmcnt(" #n ")" ::: "memory")
; #define BAR __builtin_amdgcn_s_barrier()
; #define SCHED __builtin_amdgcn_sched_barrier(0)
; template <int EPI> ...
;     ...
;     LDA(At, 1, 1); STAGE(SA(1, 0), A, brow, t + 3);
;     BAR; WAIT_L(0); MMA(1, 0, At, B0); BAR; SCHED;
;     STAGE(SB(1, 1), Bt, bcol + HALF, t + 3);
;     WAIT_V(6); BAR; MMA(1, 1, At, B1); BAR;
;   }
;   { LDB(B0, 0, 0); LDA(At, 0, 0); STAGE(SA(1, 1), A, brow + HALF, nt - 1);
;     BAR; WAIT_L(0); MMA(0, 0, At, B0); BAR;
	v_readfirstlane_b32 s70, v143
	v_lshl_add_u64 v[228:229], v[226:227], 0, s[48:49]
	s_mov_b32 m0, s70
	v_readfirstlane_b32 s70, v144
	global_load_lds_dwordx4 v[228:229], off
	v_lshl_add_u64 v[228:229], v[226:227], 0, s[50:51]
	s_mov_b32 m0, s70
	s_nop 0
	global_load_lds_dwordx4 v[228:229], off
	v_readfirstlane_b32 s70, v145
	v_lshl_add_u64 v[228:229], v[224:225], 0, s[52:53]
	s_mov_b32 m0, s70
	v_readfirstlane_b32 s70, v146
	ds_read_b128 v[176:179], v149 offset:49152
	ds_read_b128 v[180:183], v149 offset:50176
	ds_read_b128 v[184:187], v149 offset:51200
	ds_read_b128 v[188:191], v149 offset:52224
	ds_read_b128 v[192:195], v149 offset:53248
	ds_read_b128 v[196:199], v149 offset:54272
	ds_read_b128 v[200:203], v149 offset:55296
	ds_read_b128 v[204:207], v149 offset:56320
	global_load_lds_dwordx4 v[228:229], off
	v_lshl_add_u64 v[224:225], v[224:225], 0, s[54:55]
	s_mov_b32 m0, s70
	s_nop 0
	global_load_lds_dwordx4 v[224:225], off
	v_readfirstlane_b32 s70, v147
	v_lshl_add_u64 v[246:247], v[226:227], 0, s[56:57]
	s_mov_b32 m0, s70
	v_readfirstlane_b32 s70, v148
	global_load_lds_dwordx4 v[246:247], off
	s_waitcnt vmcnt(5)
	s_barrier
	s_waitcnt lgkmcnt(0)
	s_setprio 1
	s_waitcnt lgkmcnt(0)
	v_mfma_f32_16x16x32_bf16 v[60:63], v[160:163], v[176:179], v[60:63]
	v_mfma_f32_16x16x32_bf16 v[56:59], v[164:167], v[176:179], v[56:59]
	v_mfma_f32_16x16x32_bf16 v[52:55], v[160:163], v[184:187], v[52:55]
	v_mfma_f32_16x16x32_bf16 v[48:51], v[164:167], v[184:187], v[48:51]
	v_mfma_f32_16x16x32_bf16 v[44:47], v[160:163], v[192:195], v[44:47]
	v_mfma_f32_16x16x32_bf16 v[40:43], v[164:167], v[192:195], v[40:43]
	v_mfma_f32_16x16x32_bf16 v[36:39], v[160:163], v[200:203], v[36:39]
	v_mfma_f32_16x16x32_bf16 v[32:35], v[164:167], v[200:203], v[32:35]
	v_mfma_f32_16x16x32_bf16 v[60:63], v[168:171], v[180:183], v[60:63]
	v_mfma_f32_16x16x32_bf16 v[56:59], v[172:175], v[180:183], v[56:59]
	v_mfma_f32_16x16x32_bf16 v[52:55], v[168:171], v[188:191], v[52:55]
	v_mfma_f32_16x16x32_bf16 v[48:51], v[172:175], v[188:191], v[48:51]
	v_mfma_f32_16x16x32_bf16 v[44:47], v[168:171], v[196:199], v[44:47]
	v_mfma_f32_16x16x32_bf16 v[40:43], v[172:175], v[196:199], v[40:43]
	v_mfma_f32_16x16x32_bf16 v[36:39], v[168:171], v[204:207], v[36:39]
	v_mfma_f32_16x16x32_bf16 v[32:35], v[172:175], v[204:207], v[32:35]
	s_setprio 0
	s_setprio 1
	v_mfma_f32_16x16x32_bf16 v[28:31], v[208:211], v[176:179], v[28:31]
	v_mfma_f32_16x16x32_bf16 v[24:27], v[212:215], v[176:179], v[24:27]
	v_mfma_f32_16x16x32_bf16 v[20:23], v[208:211], v[184:187], v[20:23]
	v_mfma_f32_16x16x32_bf16 v[16:19], v[212:215], v[184:187], v[16:19]
	v_mfma_f32_16x16x32_bf16 v[12:15], v[208:211], v[192:195], v[12:15]
	v_mfma_f32_16x16x32_bf16 v[8:11], v[212:215], v[192:195], v[8:11]
	v_mfma_f32_16x16x32_bf16 v[4:7], v[208:211], v[200:203], v[4:7]
	v_mfma_f32_16x16x32_bf16 v[0:3], v[212:215], v[200:203], v[0:3]
	v_mfma_f32_16x16x32_bf16 v[28:31], v[216:219], v[180:183], v[28:31]
	v_mfma_f32_16x16x32_bf16 v[24:27], v[220:223], v[180:183], v[24:27]
	v_mfma_f32_16x16x32_bf16 v[20:23], v[216:219], v[188:191], v[20:23]
	v_mfma_f32_16x16x32_bf16 v[16:19], v[220:223], v[188:191], v[16:19]
	v_mfma_f32_16x16x32_bf16 v[12:15], v[216:219], v[196:199], v[12:15]
	v_mfma_f32_16x16x32_bf16 v[8:11], v[220:223], v[196:199], v[8:11]
	v_mfma_f32_16x16x32_bf16 v[4:7], v[216:219], v[204:207], v[4:7]
	v_mfma_f32_16x16x32_bf16 v[0:3], v[220:223], v[204:207], v[0:3]
	s_setprio 0
	s_add_i32 s61, s61, 2
	s_add_u32 s66, s66, 0x100
	s_addc_u32 s67, s67, 0
	s_add_u32 s68, s68, 0x100
	s_addc_u32 s69, s69, 0
	s_cmp_lt_u32 s61, 28
	s_barrier
	s_cbranch_scc1 .LBB0_411
	v_readfirstlane_b32 s70, v148
	v_lshl_add_u64 v[246:247], v[226:227], 0, s[58:59]
	s_mov_b32 m0, s70
	s_nop 0
	global_load_lds_dwordx4 v[246:247], off
	s_add_u32 s64, s74, s64
	s_addc_u32 s65, s75, s65
	v_readfirstlane_b32 s61, v150
	v_lshl_add_u64 v[208:209], s[64:65], 0, v[128:129]
	s_mov_b32 m0, s61
	v_readfirstlane_b32 s61, v151
	ds_read_b128 v[160:163], v152
	ds_read_b128 v[164:167], v152 offset:256
	ds_read_b128 v[168:171], v153
	ds_read_b128 v[172:175], v153 offset:256
	ds_read_b128 v[176:179], v149
	ds_read_b128 v[180:183], v149 offset:1024
	ds_read_b128 v[184:187], v149 offset:2048
	ds_read_b128 v[188:191], v149 offset:3072
	ds_read_b128 v[192:195], v149 offset:4096
	ds_read_b128 v[196:199], v149 offset:5120
	ds_read_b128 v[200:203], v149 offset:6144
	ds_read_b128 v[204:207], v149 offset:7168
	global_load_lds_dwordx4 v[208:209], off
	v_lshl_add_u64 v[208:209], v[208:209], 0, s[8:9]
	s_mov_b32 m0, s61
	s_nop 0
	global_load_lds_dwordx4 v[208:209], off
	s_barrier
	s_waitcnt lgkmcnt(0)
	s_setprio 1
	v_mfma_f32_16x16x32_bf16 v[124:127], v[160:163], v[176:179], v[124:127]
	v_mfma_f32_16x16x32_bf16 v[116:119], v[160:163], v[184:187], v[116:119]
	v_mfma_f32_16x16x32_bf16 v[108:111], v[160:163], v[192:195], v[108:111]
	v_mfma_f32_16x16x32_bf16 v[100:103], v[160:163], v[200:203], v[100:103]
	v_mfma_f32_16x16x32_bf16 v[96:99], v[164:167], v[200:203], v[96:99]
	v_mfma_f32_16x16x32_bf16 v[124:127], v[168:171], v[180:183], v[124:127]
	v_mfma_f32_16x16x32_bf16 v[120:123], v[164:167], v[176:179], v[120:123]
	v_mfma_f32_16x16x32_bf16 v[116:119], v[168:171], v[188:191], v[116:119]
	v_mfma_f32_16x16x32_bf16 v[112:115], v[164:167], v[184:187], v[112:115]
	v_mfma_f32_16x16x32_bf16 v[108:111], v[168:171], v[196:199], v[108:111]
	v_mfma_f32_16x16x32_bf16 v[104:107], v[164:167], v[192:195], v[104:107]
	v_mfma_f32_16x16x32_bf16 v[100:103], v[168:171], v[204:207], v[100:103]
	v_mfma_f32_16x16x32_bf16 v[96:99], v[172:175], v[204:207], v[96:99]
	v_mfma_f32_16x16x32_bf16 v[208:211], v[172:175], v[180:183], v[120:123]
	v_mfma_f32_16x16x32_bf16 v[212:215], v[172:175], v[188:191], v[112:115]
	v_mfma_f32_16x16x32_bf16 v[216:219], v[172:175], v[196:199], v[104:107]
	s_setprio 0
	s_barrier
; #define LDA(dst, b, h) for (int m = 0; m < 4; ++m) { \
;     dst[m][0] = *reinterpret_cast<const bf16x8*>((char*)SA(b, h) + aoff0 + m * 2048); \
;     dst[m][1] = *reinterpret_cast<const bf16x8*>((char*)SA(b, h) + aoff1 + m * 2048); }
; #define LDB(dst, b, h) for (int n = 0; n < 2; ++n) { \
;     dst[n][0] = *reinterpret_cast<const bf16x8*>((char*)SB(b, h) + boff0 + n * 256); \
;     dst[n][1] = *reinterpret_cast<const bf16x8*>((char*)SB(b, h) + boff1 + n * 256); }
; #define MMA(ai, bj, At, Btf) do { __builtin_amdgcn_s_setprio(1); \
;     for (int m = 0; m < 4; ++m) for (int n = 0; n < 2; ++n) for (int k = 0; k < 2; ++k) \
;       acc[ai][bj][m][n] = __builtin_amdgcn_mfma_f32_16x16x32_bf16(Btf[n][k], At[m][k], acc[ai][bj][m][n], 0, 0, 0); \
;     __builtin_amdgcn_s_setprio(0); } while (0)
; #define WAIT_V(n) asm volatile("s_waitcnt vmcnt(" #n ")" ::: "memory")
; #define WAIT_L(n) asm volatile("s_waitcnt lgkmcnt(" #n ")" ::: "memory")
; #define BAR __builtin_amdgcn_s_barrier()
; template <int EPI> ...
;     ...
;     LDB(B1, 0, 1); BAR; WAIT_L(0); MMA(0, 1, At, B1); BAR;
;     LDA(At, 0, 1); WAIT_V(4); BAR; WAIT_L(0); MMA(1, 0, At, B0); MMA(1, 1, At, B1); BAR; }
;   { LDB(B0, 1, 0); LDA(At, 1, 0); WAIT_V(2); BAR; WAIT_L(0); MMA(0, 0, At, B0); BAR;
	s_nop 0
	ds_read_b128 v[104:107], v154
	ds_read_b128 v[112:115], v154 offset:256
	ds_read_b128 v[120:123], v155
	ds_read_b128 v[220:223], v155 offset:256
	s_barrier
	s_waitcnt lgkmcnt(0)
	s_setprio 1
	v_mfma_f32_16x16x32_bf16 v[92:95], v[104:107], v[176:179], v[92:95]
	v_mfma_f32_16x16x32_bf16 v[88:91], v[112:115], v[176:179], v[88:91]
	v_mfma_f32_16x16x32_bf16 v[76:79], v[104:107], v[192:195], v[76:79]
	v_mfma_f32_16x16x32_bf16 v[72:75], v[112:115], v[192:195], v[72:75]
	v_mfma_f32_16x16x32_bf16 v[92:95], v[120:123], v[180:183], v[92:95]
	v_mfma_f32_16x16x32_bf16 v[88:91], v[220:223], v[180:183], v[88:91]
	v_mfma_f32_16x16x32_bf16 v[84:87], v[104:107], v[184:187], v[84:87]
	v_mfma_f32_16x16x32_bf16 v[80:83], v[112:115], v[184:187], v[80:83]
	v_mfma_f32_16x16x32_bf16 v[76:79], v[120:123], v[196:199], v[76:79]
	v_mfma_f32_16x16x32_bf16 v[72:75], v[220:223], v[196:199], v[72:75]
	v_mfma_f32_16x16x32_bf16 v[68:71], v[104:107], v[200:203], v[68:71]
	v_mfma_f32_16x16x32_bf16 v[64:67], v[112:115], v[200:203], v[64:67]
	v_mfma_f32_16x16x32_bf16 v[176:179], v[120:123], v[188:191], v[84:87]
	v_mfma_f32_16x16x32_bf16 v[180:183], v[220:223], v[188:191], v[80:83]
	v_mfma_f32_16x16x32_bf16 v[184:187], v[120:123], v[204:207], v[68:71]
	v_mfma_f32_16x16x32_bf16 v[188:191], v[220:223], v[204:207], v[64:67]
	s_setprio 0
	s_barrier
	s_nop 1
	ds_read_b128 v[64:67], v149 offset:16384
	ds_read_b128 v[68:71], v149 offset:17408
	ds_read_b128 v[80:83], v149 offset:18432
	ds_read_b128 v[84:87], v149 offset:19456
	ds_read_b128 v[192:195], v149 offset:20480
	ds_read_b128 v[196:199], v149 offset:21504
	ds_read_b128 v[200:203], v149 offset:22528
	ds_read_b128 v[204:207], v149 offset:23552
	s_waitcnt vmcnt(4)
	s_barrier
	s_waitcnt lgkmcnt(0)
	s_setprio 1
	v_mfma_f32_16x16x32_bf16 v[60:63], v[160:163], v[64:67], v[60:63]
	v_mfma_f32_16x16x32_bf16 v[56:59], v[164:167], v[64:67], v[56:59]
	v_mfma_f32_16x16x32_bf16 v[44:47], v[160:163], v[192:195], v[44:47]
	v_mfma_f32_16x16x32_bf16 v[36:39], v[160:163], v[200:203], v[36:39]
	v_mfma_f32_16x16x32_bf16 v[60:63], v[168:171], v[68:71], v[60:63]
	v_mfma_f32_16x16x32_bf16 v[56:59], v[172:175], v[68:71], v[56:59]
	v_mfma_f32_16x16x32_bf16 v[52:55], v[160:163], v[80:83], v[52:55]
	v_mfma_f32_16x16x32_bf16 v[48:51], v[164:167], v[80:83], v[48:51]
	v_mfma_f32_16x16x32_bf16 v[44:47], v[168:171], v[196:199], v[44:47]
	v_mfma_f32_16x16x32_bf16 v[40:43], v[164:167], v[192:195], v[40:43]
	v_mfma_f32_16x16x32_bf16 v[36:39], v[168:171], v[204:207], v[36:39]
	v_mfma_f32_16x16x32_bf16 v[32:35], v[164:167], v[200:203], v[32:35]
	v_mfma_f32_16x16x32_bf16 v[224:227], v[168:171], v[84:87], v[52:55]
	v_mfma_f32_16x16x32_bf16 v[228:231], v[172:175], v[84:87], v[48:51]
	v_mfma_f32_16x16x32_bf16 v[232:235], v[172:175], v[196:199], v[40:43]
	v_mfma_f32_16x16x32_bf16 v[160:163], v[172:175], v[204:207], v[32:35]
	v_mfma_f32_16x16x32_bf16 v[28:31], v[104:107], v[64:67], v[28:31]
	v_mfma_f32_16x16x32_bf16 v[20:23], v[104:107], v[80:83], v[20:23]
	v_mfma_f32_16x16x32_bf16 v[12:15], v[104:107], v[192:195], v[12:15]
	v_mfma_f32_16x16x32_bf16 v[4:7], v[104:107], v[200:203], v[4:7]
	v_mfma_f32_16x16x32_bf16 v[28:31], v[120:123], v[68:71], v[28:31]
	v_mfma_f32_16x16x32_bf16 v[24:27], v[112:115], v[64:67], v[24:27]
	v_mfma_f32_16x16x32_bf16 v[20:23], v[120:123], v[84:87], v[20:23]
	v_mfma_f32_16x16x32_bf16 v[16:19], v[112:115], v[80:83], v[16:19]
	v_mfma_f32_16x16x32_bf16 v[12:15], v[120:123], v[196:199], v[12:15]
	v_mfma_f32_16x16x32_bf16 v[8:11], v[112:115], v[192:195], v[8:11]
	v_mfma_f32_16x16x32_bf16 v[4:7], v[120:123], v[204:207], v[4:7]
	v_mfma_f32_16x16x32_bf16 v[0:3], v[112:115], v[200:203], v[0:3]
	v_mfma_f32_16x16x32_bf16 v[164:167], v[220:223], v[68:71], v[24:27]
	v_mfma_f32_16x16x32_bf16 v[168:171], v[220:223], v[84:87], v[16:19]
	v_mfma_f32_16x16x32_bf16 v[172:175], v[220:223], v[196:199], v[8:11]
	v_mfma_f32_16x16x32_bf16 v[192:195], v[220:223], v[204:207], v[0:3]
	s_setprio 0
	s_barrier
	s_nop 1
	ds_read_b128 v[0:3], v156
	ds_read_b128 v[8:11], v156 offset:256
	ds_read_b128 v[16:19], v157
	ds_read_b128 v[24:27], v157 offset:256
	ds_read_b128 v[32:35], v149 offset:32768
	ds_read_b128 v[40:43], v149 offset:33792
	ds_read_b128 v[48:51], v149 offset:34816
	ds_read_b128 v[52:55], v149 offset:35840
	ds_read_b128 v[68:71], v149 offset:36864
	ds_read_b128 v[196:199], v149 offset:37888
	ds_read_b128 v[200:203], v149 offset:38912
	ds_read_b128 v[204:207], v149 offset:39936
	s_waitcnt vmcnt(2)
	s_barrier
; #define LDA(dst, b, h) for (int m = 0; m < 4; ++m) { \
;     dst[m][0] = *reinterpret_cast<const bf16x8*>((char*)SA(b, h) + aoff0 + m * 2048); \
;     dst[m][1] = *reinterpret_cast<const bf16x8*>((char*)SA(b, h) + aoff1 + m * 2048); }
; #define LDB(dst, b, h) for (int n = 0; n < 2; ++n) { \
;     dst[n][0] = *reinterpret_cast<const bf16x8*>((char*)SB(b, h) + boff0 + n * 256); \
;     dst[n][1] = *reinterpret_cast<const bf16x8*>((char*)SB(b, h) + boff1 + n * 256); }
; #define MMA(ai, bj, At, Btf) do { __builtin_amdgcn_s_setprio(1); \
;     for (int m = 0; m < 4; ++m) for (int n = 0; n < 2; ++n) for (int k = 0; k < 2; ++k) \
;       acc[ai][bj][m][n] = __builtin_amdgcn_mfma_f32_16x16x32_bf16(Btf[n][k], At[m][k], acc[ai][bj][m][n], 0, 0, 0); \
;     __builtin_amdgcn_s_setprio(0); } while (0)
; #define WAIT_V(n) asm volatile("s_waitcnt vmcnt(" #n ")" ::: "memory")
; #define WAIT_L(n) asm volatile("s_waitcnt lgkmcnt(" #n ")" ::: "memory")
; #define BAR __builtin_amdgcn_s_barrier()
; template <int EPI> ...
;     ...
;   { LDB(B0, 1, 0); LDA(At, 1, 0); WAIT_V(2); BAR; WAIT_L(0); MMA(0, 0, At, B0); BAR;
;     LDB(B1, 1, 1); WAIT_V(0); BAR; WAIT_L(0); MMA(0, 1, At, B1); BAR;
;     LDA(At, 1, 1); BAR; WAIT_L(0); MMA(1, 0, At, B0); MMA(1, 1, At, B1); BAR; }
;   if (wr == 0) BAR;
	s_waitcnt lgkmcnt(0)
	s_setprio 1
	v_mfma_f32_16x16x32_bf16 v[64:67], v[0:3], v[32:35], v[124:127]
	v_mfma_f32_16x16x32_bf16 v[120:123], v[16:19], v[40:43], v[64:67]
	v_mfma_f32_16x16x32_bf16 v[64:67], v[8:11], v[32:35], v[208:211]
	v_mfma_f32_16x16x32_bf16 v[124:127], v[24:27], v[40:43], v[64:67]
	v_mfma_f32_16x16x32_bf16 v[64:67], v[0:3], v[48:51], v[116:119]
	v_mfma_f32_16x16x32_bf16 v[112:115], v[16:19], v[52:55], v[64:67]
	v_mfma_f32_16x16x32_bf16 v[64:67], v[8:11], v[48:51], v[212:215]
	v_mfma_f32_16x16x32_bf16 v[116:119], v[24:27], v[52:55], v[64:67]
	v_mfma_f32_16x16x32_bf16 v[64:67], v[0:3], v[68:71], v[108:111]
	v_mfma_f32_16x16x32_bf16 v[104:107], v[16:19], v[196:199], v[64:67]
	v_mfma_f32_16x16x32_bf16 v[64:67], v[8:11], v[68:71], v[216:219]
	v_mfma_f32_16x16x32_bf16 v[108:111], v[24:27], v[196:199], v[64:67]
	v_mfma_f32_16x16x32_bf16 v[64:67], v[0:3], v[200:203], v[100:103]
	v_mfma_f32_16x16x32_bf16 v[80:83], v[16:19], v[204:207], v[64:67]
	v_mfma_f32_16x16x32_bf16 v[64:67], v[8:11], v[200:203], v[96:99]
	v_mfma_f32_16x16x32_bf16 v[84:87], v[24:27], v[204:207], v[64:67]
	s_setprio 0
	s_barrier
	ds_read_b128 v[208:211], v158
	ds_read_b128 v[212:215], v158 offset:256
	ds_read_b128 v[216:219], v159
	ds_read_b128 v[220:223], v159 offset:256
	s_waitcnt vmcnt(0)
	s_barrier
	s_waitcnt lgkmcnt(0)
	s_setprio 1
	v_mfma_f32_16x16x32_bf16 v[64:67], v[208:211], v[32:35], v[92:95]
	v_mfma_f32_16x16x32_bf16 v[32:35], v[212:215], v[32:35], v[88:91]
	v_mfma_f32_16x16x32_bf16 v[100:103], v[220:223], v[40:43], v[32:35]
	v_mfma_f32_16x16x32_bf16 v[32:35], v[208:211], v[48:51], v[176:179]
	v_mfma_f32_16x16x32_bf16 v[88:91], v[216:219], v[52:55], v[32:35]
	v_mfma_f32_16x16x32_bf16 v[32:35], v[212:215], v[48:51], v[180:183]
	v_mfma_f32_16x16x32_bf16 v[92:95], v[220:223], v[52:55], v[32:35]
	v_mfma_f32_16x16x32_bf16 v[32:35], v[208:211], v[68:71], v[76:79]
	v_mfma_f32_16x16x32_bf16 v[96:99], v[216:219], v[40:43], v[64:67]
	v_mfma_f32_16x16x32_bf16 v[64:67], v[216:219], v[196:199], v[32:35]
	v_mfma_f32_16x16x32_bf16 v[32:35], v[212:215], v[68:71], v[72:75]
	v_mfma_f32_16x16x32_bf16 v[68:71], v[220:223], v[196:199], v[32:35]
	v_mfma_f32_16x16x32_bf16 v[32:35], v[208:211], v[200:203], v[184:187]
	v_mfma_f32_16x16x32_bf16 v[48:51], v[216:219], v[204:207], v[32:35]
	v_mfma_f32_16x16x32_bf16 v[32:35], v[212:215], v[200:203], v[188:191]
	v_mfma_f32_16x16x32_bf16 v[52:55], v[220:223], v[204:207], v[32:35]
	s_setprio 0
	s_barrier
	ds_read_b128 v[176:179], v149 offset:49152
	ds_read_b128 v[180:183], v149 offset:50176
	ds_read_b128 v[184:187], v149 offset:51200
	ds_read_b128 v[188:191], v149 offset:52224
	ds_read_b128 v[196:199], v149 offset:53248
	ds_read_b128 v[200:203], v149 offset:54272
	ds_read_b128 v[204:207], v149 offset:55296
	ds_read_b128 v[236:239], v149 offset:56320
	s_barrier
	s_waitcnt lgkmcnt(0)
	s_setprio 1
	v_mfma_f32_16x16x32_bf16 v[32:35], v[0:3], v[176:179], v[60:63]
	v_mfma_f32_16x16x32_bf16 v[72:75], v[16:19], v[180:183], v[32:35]
	v_mfma_f32_16x16x32_bf16 v[32:35], v[8:11], v[176:179], v[56:59]
	v_mfma_f32_16x16x32_bf16 v[76:79], v[24:27], v[180:183], v[32:35]
	v_mfma_f32_16x16x32_bf16 v[32:35], v[0:3], v[184:187], v[224:227]
	v_mfma_f32_16x16x32_bf16 v[56:59], v[16:19], v[188:191], v[32:35]
	v_mfma_f32_16x16x32_bf16 v[32:35], v[8:11], v[184:187], v[228:231]
	v_mfma_f32_16x16x32_bf16 v[60:63], v[24:27], v[188:191], v[32:35]
	v_mfma_f32_16x16x32_bf16 v[32:35], v[0:3], v[196:199], v[44:47]
	v_mfma_f32_16x16x32_bf16 v[40:43], v[16:19], v[200:203], v[32:35]
	v_mfma_f32_16x16x32_bf16 v[32:35], v[8:11], v[196:199], v[232:235]
	v_mfma_f32_16x16x32_bf16 v[0:3], v[0:3], v[204:207], v[36:39]
	v_mfma_f32_16x16x32_bf16 v[44:47], v[24:27], v[200:203], v[32:35]
	v_mfma_f32_16x16x32_bf16 v[32:35], v[16:19], v[236:239], v[0:3]
	v_mfma_f32_16x16x32_bf16 v[0:3], v[8:11], v[204:207], v[160:163]
	v_mfma_f32_16x16x32_bf16 v[36:39], v[24:27], v[236:239], v[0:3]
	v_mfma_f32_16x16x32_bf16 v[0:3], v[208:211], v[176:179], v[28:31]
	v_mfma_f32_16x16x32_bf16 v[24:27], v[216:219], v[180:183], v[0:3]
	v_mfma_f32_16x16x32_bf16 v[0:3], v[212:215], v[176:179], v[164:167]
	v_mfma_f32_16x16x32_bf16 v[28:31], v[220:223], v[180:183], v[0:3]
	v_mfma_f32_16x16x32_bf16 v[0:3], v[208:211], v[184:187], v[20:23]
	v_mfma_f32_16x16x32_bf16 v[16:19], v[216:219], v[188:191], v[0:3]
	v_mfma_f32_16x16x32_bf16 v[0:3], v[212:215], v[184:187], v[168:171]
	v_mfma_f32_16x16x32_bf16 v[20:23], v[220:223], v[188:191], v[0:3]
	v_mfma_f32_16x16x32_bf16 v[0:3], v[208:211], v[196:199], v[12:15]
	v_mfma_f32_16x16x32_bf16 v[8:11], v[216:219], v[200:203], v[0:3]
	v_mfma_f32_16x16x32_bf16 v[0:3], v[212:215], v[196:199], v[172:175]
	v_mfma_f32_16x16x32_bf16 v[12:15], v[220:223], v[200:203], v[0:3]
	v_mfma_f32_16x16x32_bf16 v[0:3], v[208:211], v[204:207], v[4:7]
	v_mfma_f32_16x16x32_bf16 v[4:7], v[212:215], v[204:207], v[192:195]
	v_mfma_f32_16x16x32_bf16 v[0:3], v[216:219], v[236:239], v[0:3]
	v_mfma_f32_16x16x32_bf16 v[4:7], v[220:223], v[236:239], v[4:7]
	s_setprio 0
	s_barrier
	s_and_saveexec_b64 s[64:65], s[2:3]
	s_cbranch_execz .LBB0_405
	s_barrier
	s_branch .LBB0_405

; #define STAGE(P, BASE, br, kt) do { const char* _gb = (const char*)(BASE) + ((size_t)(br) * K + (size_t)(kt) * BK) * 2; \
;     __builtin_amdgcn_global_load_lds((const unsigned*)(_gb + loff0), (unsigned*)((char*)(P) + tid * 16), 16, 0, 0); \
;     __builtin_amdgcn_global_load_lds((const unsigned*)(_gb + (size_t)K * 128 + loff0), (unsigned*)((char*)(P) + tid * 16 + 8192), 16, 0, 0); } while (0)
; #define LDA(dst, b, h) for (int m = 0; m < 4; ++m) { \
;     dst[m][0] = *reinterpret_cast<const bf16x8*>((char*)SA(b, h) + aoff0 + m * 2048); \
;     dst[m][1] = *reinterpret_cast<const bf16x8*>((char*)SA(b, h) + aoff1 + m * 2048); }
; #define LDB(dst, b, h) for (int n = 0; n < 2; ++n) { \
;     dst[n][0] = *reinterpret_cast<const bf16x8*>((char*)SB(b, h) + boff0 + n * 256); \
;     dst[n][1] = *reinterpret_cast<const bf16x8*>((char*)SB(b, h) + boff1 + n * 256); }
; #define MMA(ai, bj, At, Btf) do { __builtin_amdgcn_s_setprio(1); \
;     for (int m = 0; m < 4; ++m) for (int n = 0; n < 2; ++n) for (int k = 0; k < 2; ++k) \
;       acc[ai][bj][m][n] = __builtin_amdgcn_mfma_f32_16x16x32_bf16(Btf[n][k], At[m][k], acc[ai][bj][m][n], 0, 0, 0); \
;     __builtin_amdgcn_s_setprio(0); } while (0)
; #define WAIT_V(n) asm volatile("s_waitcnt vmcnt(" #n ")" ::: "memory")
; #define WAIT_L(n) asm volatile("s_waitcnt lgkmcnt(" #n ")" ::: "memory")
; #define BAR __builtin_amdgcn_s_barrier()
; #define SCHED __builtin_amdgcn_sched_barrier(0)
; template <int EPI> ...
;     ...
;   if (wr == 1) BAR;
;   WAIT_V(4); BAR;
;   STAGE(SB(1, 0), Bt, bcol, 1); STAGE(SA(1, 0), A, brow, 1); STAGE(SB(1, 1), Bt, bcol + HALF, 1);
;   WAIT_V(6); BAR;
;   for (int t = 0; t < nt - 2; t += 2) {
;     LDB(B0, 0, 0); SCHED; LDA(At, 0, 0); STAGE(SA(1, 1), A, brow + HALF, t + 1);
;     WAIT_L(8); BAR; WAIT_L(0); MMA(0, 0, At, B0); BAR; SCHED;
;     LDB(B1, 0, 1); STAGE(SB(0, 0), Bt, bcol, t + 2);
;     BAR; WAIT_L(0); MMA(0, 1, At, B1); BAR;
;     LDA(At, 0, 1); STAGE(SA(0, 0), A, brow, t + 2);
;     BAR; WAIT_L(0); MMA(1, 0, At, B0); BAR; SCHED;
.LBB0_826:
	s_or_b64 exec, exec, s[54:55]
	v_readfirstlane_b32 s54, v164
	v_add_u32_e32 v10, 0x2000, v164
	v_lshl_add_u64 v[8:9], v[6:7], 0, s[10:11]
	s_mov_b32 m0, s54
	v_readfirstlane_b32 s51, v10
	s_waitcnt vmcnt(4)
	s_barrier
	global_load_lds_dwordx4 v[8:9], off
	v_lshl_add_u64 v[8:9], v[6:7], 0, s[12:13]
	s_mov_b32 m0, s51
	v_readfirstlane_b32 s71, v254
	global_load_lds_dwordx4 v[8:9], off
	v_lshl_add_u64 v[8:9], v[4:5], 0, s[10:11]
	s_mov_b32 m0, s71
	v_readfirstlane_b32 s70, v165
	global_load_lds_dwordx4 v[8:9], off
	v_lshl_add_u64 v[8:9], v[4:5], 0, s[12:13]
	s_mov_b32 m0, s70
	v_readfirstlane_b32 s69, v168
	global_load_lds_dwordx4 v[8:9], off
	v_lshl_add_u64 v[8:9], v[2:3], 0, s[10:11]
	s_mov_b32 m0, s69
	v_readfirstlane_b32 s68, v169
	global_load_lds_dwordx4 v[8:9], off
	v_lshl_add_u64 v[8:9], v[2:3], 0, s[12:13]
	s_mov_b32 m0, s68
	s_nop 0
	global_load_lds_dwordx4 v[8:9], off
	s_waitcnt vmcnt(6)
	s_barrier
	ds_read_b128 v[8:11], v176
	ds_read_b128 v[12:15], v176 offset:256
	ds_read_b128 v[16:19], v177
	ds_read_b128 v[20:23], v177 offset:256
	v_readfirstlane_b32 s65, v170
	v_lshl_add_u64 v[56:57], v[0:1], 0, s[10:11]
	s_mov_b32 m0, s65
	v_readfirstlane_b32 s55, v171
	ds_read_b128 v[24:27], v154
	ds_read_b128 v[28:31], v154 offset:1024
	ds_read_b128 v[32:35], v154 offset:2048
	ds_read_b128 v[36:39], v154 offset:3072
	ds_read_b128 v[40:43], v154 offset:4096
	ds_read_b128 v[44:47], v154 offset:5120
	ds_read_b128 v[48:51], v154 offset:6144
	ds_read_b128 v[52:55], v154 offset:7168
	global_load_lds_dwordx4 v[56:57], off
	v_lshl_add_u64 v[56:57], v[0:1], 0, s[12:13]
	s_mov_b32 m0, s55
	s_nop 0
	global_load_lds_dwordx4 v[56:57], off
	s_waitcnt lgkmcnt(8)
	s_barrier
	s_waitcnt lgkmcnt(0)
	s_setprio 1
	v_mfma_f32_16x16x32_bf16 v[56:59], v[8:11], v[24:27], 0
	v_mfma_f32_16x16x32_bf16 v[60:63], v[12:15], v[24:27], 0
	v_mfma_f32_16x16x32_bf16 v[64:67], v[8:11], v[32:35], 0
	v_mfma_f32_16x16x32_bf16 v[68:71], v[12:15], v[32:35], 0
	v_mfma_f32_16x16x32_bf16 v[72:75], v[8:11], v[40:43], 0
	v_mfma_f32_16x16x32_bf16 v[76:79], v[12:15], v[40:43], 0
	v_mfma_f32_16x16x32_bf16 v[80:83], v[8:11], v[48:51], 0
	v_mfma_f32_16x16x32_bf16 v[84:87], v[12:15], v[48:51], 0
	v_mfma_f32_16x16x32_bf16 v[56:59], v[16:19], v[28:31], v[56:59]
	v_mfma_f32_16x16x32_bf16 v[60:63], v[20:23], v[28:31], v[60:63]
	v_mfma_f32_16x16x32_bf16 v[64:67], v[16:19], v[36:39], v[64:67]
	v_mfma_f32_16x16x32_bf16 v[68:71], v[20:23], v[36:39], v[68:71]
	v_mfma_f32_16x16x32_bf16 v[72:75], v[16:19], v[44:47], v[72:75]
	v_mfma_f32_16x16x32_bf16 v[76:79], v[20:23], v[44:47], v[76:79]
	v_mfma_f32_16x16x32_bf16 v[80:83], v[16:19], v[52:55], v[80:83]
	v_mfma_f32_16x16x32_bf16 v[84:87], v[20:23], v[52:55], v[84:87]
	s_setprio 0
	s_barrier
	v_readfirstlane_b32 s64, v156
	v_lshl_add_u64 v[104:105], v[6:7], 0, s[16:17]
	s_mov_b32 m0, s64
	v_readfirstlane_b32 s59, v157
	ds_read_b128 v[88:91], v178
	ds_read_b128 v[92:95], v178 offset:256
	ds_read_b128 v[96:99], v179
	ds_read_b128 v[100:103], v179 offset:256
	global_load_lds_dwordx4 v[104:105], off
	v_lshl_add_u64 v[104:105], v[6:7], 0, s[18:19]
	s_mov_b32 m0, s59
	s_nop 0
	global_load_lds_dwordx4 v[104:105], off
	s_barrier
	s_waitcnt lgkmcnt(0)
	s_setprio 1
	s_waitcnt lgkmcnt(0)
	v_mfma_f32_16x16x32_bf16 v[104:107], v[88:91], v[24:27], 0
	v_mfma_f32_16x16x32_bf16 v[24:27], v[92:95], v[24:27], 0
	v_mfma_f32_16x16x32_bf16 v[104:107], v[96:99], v[28:31], v[104:107]
	v_mfma_f32_16x16x32_bf16 v[24:27], v[100:103], v[28:31], v[24:27]
	v_mfma_f32_16x16x32_bf16 v[28:31], v[88:91], v[32:35], 0
	v_mfma_f32_16x16x32_bf16 v[32:35], v[92:95], v[32:35], 0
	v_mfma_f32_16x16x32_bf16 v[28:31], v[96:99], v[36:39], v[28:31]
	v_mfma_f32_16x16x32_bf16 v[32:35], v[100:103], v[36:39], v[32:35]
	v_mfma_f32_16x16x32_bf16 v[36:39], v[88:91], v[40:43], 0
	v_mfma_f32_16x16x32_bf16 v[40:43], v[92:95], v[40:43], 0
	v_mfma_f32_16x16x32_bf16 v[36:39], v[96:99], v[44:47], v[36:39]
	v_mfma_f32_16x16x32_bf16 v[40:43], v[100:103], v[44:47], v[40:43]
	v_mfma_f32_16x16x32_bf16 v[44:47], v[88:91], v[48:51], 0
	v_mfma_f32_16x16x32_bf16 v[48:51], v[92:95], v[48:51], 0
	v_mfma_f32_16x16x32_bf16 v[44:47], v[96:99], v[52:55], v[44:47]
	v_mfma_f32_16x16x32_bf16 v[48:51], v[100:103], v[52:55], v[48:51]
	s_setprio 0
	v_readfirstlane_b32 s66, v158
	v_lshl_add_u64 v[138:139], v[4:5], 0, s[16:17]
	s_mov_b32 m0, s66
	v_readfirstlane_b32 s60, v159
	s_barrier
	ds_read_b128 v[52:55], v154 offset:16384
	ds_read_b128 v[108:111], v154 offset:17408
	ds_read_b128 v[112:115], v154 offset:18432
	ds_read_b128 v[116:119], v154 offset:19456
	ds_read_b128 v[120:123], v154 offset:20480
	ds_read_b128 v[124:127], v154 offset:21504
	ds_read_b128 v[128:131], v154 offset:22528
	ds_read_b128 v[132:135], v154 offset:23552
	global_load_lds_dwordx4 v[138:139], off
	v_lshl_add_u64 v[138:139], v[4:5], 0, s[18:19]
	s_mov_b32 m0, s60
	s_nop 0
	global_load_lds_dwordx4 v[138:139], off
	s_barrier
	s_waitcnt lgkmcnt(0)
	s_setprio 1
	v_mfma_f32_16x16x32_bf16 v[142:145], v[8:11], v[52:55], 0
	v_mfma_f32_16x16x32_bf16 v[146:149], v[12:15], v[52:55], 0
	v_mfma_f32_16x16x32_bf16 v[150:153], v[8:11], v[112:115], 0
	v_mfma_f32_16x16x32_bf16 v[180:183], v[12:15], v[112:115], 0
	v_mfma_f32_16x16x32_bf16 v[184:187], v[8:11], v[120:123], 0
	v_mfma_f32_16x16x32_bf16 v[188:191], v[12:15], v[120:123], 0
	v_mfma_f32_16x16x32_bf16 v[8:11], v[8:11], v[128:131], 0
	v_mfma_f32_16x16x32_bf16 v[12:15], v[12:15], v[128:131], 0
	v_mfma_f32_16x16x32_bf16 v[8:11], v[16:19], v[132:135], v[8:11]
	v_mfma_f32_16x16x32_bf16 v[12:15], v[20:23], v[132:135], v[12:15]
	v_mfma_f32_16x16x32_bf16 v[142:145], v[16:19], v[108:111], v[142:145]
	v_mfma_f32_16x16x32_bf16 v[146:149], v[20:23], v[108:111], v[146:149]
	v_mfma_f32_16x16x32_bf16 v[150:153], v[16:19], v[116:119], v[150:153]
	v_mfma_f32_16x16x32_bf16 v[180:183], v[20:23], v[116:119], v[180:183]
	v_mfma_f32_16x16x32_bf16 v[184:187], v[16:19], v[124:127], v[184:187]
	v_mfma_f32_16x16x32_bf16 v[188:191], v[20:23], v[124:127], v[188:191]
	s_setprio 0
	s_barrier
; #define STAGE(P, BASE, br, kt) do { const char* _gb = (const char*)(BASE) + ((size_t)(br) * K + (size_t)(kt) * BK) * 2; \
;     __builtin_amdgcn_global_load_lds((const unsigned*)(_gb + loff0), (unsigned*)((char*)(P) + tid * 16), 16, 0, 0); \
;     __builtin_amdgcn_global_load_lds((const unsigned*)(_gb + (size_t)K * 128 + loff0), (unsigned*)((char*)(P) + tid * 16 + 8192), 16, 0, 0); } while (0)
; #define LDA(dst, b, h) for (int m = 0; m < 4; ++m) { \
;     dst[m][0] = *reinterpret_cast<const bf16x8*>((char*)SA(b, h) + aoff0 + m * 2048); \
;     dst[m][1] = *reinterpret_cast<const bf16x8*>((char*)SA(b, h) + aoff1 + m * 2048); }
; #define LDB(dst, b, h) for (int n = 0; n < 2; ++n) { \
;     dst[n][0] = *reinterpret_cast<const bf16x8*>((char*)SB(b, h) + boff0 + n * 256); \
;     dst[n][1] = *reinterpret_cast<const bf16x8*>((char*)SB(b, h) + boff1 + n * 256); }
; #define MMA(ai, bj, At, Btf) do { __builtin_amdgcn_s_setprio(1); \
;     for (int m = 0; m < 4; ++m) for (int n = 0; n < 2; ++n) for (int k = 0; k < 2; ++k) \
;       acc[ai][bj][m][n] = __builtin_amdgcn_mfma_f32_16x16x32_bf16(Btf[n][k], At[m][k], acc[ai][bj][m][n], 0, 0, 0); \
;     __builtin_amdgcn_s_setprio(0); } while (0)
; #define WAIT_V(n) asm volatile("s_waitcnt vmcnt(" #n ")" ::: "memory")
; #define WAIT_L(n) asm volatile("s_waitcnt lgkmcnt(" #n ")" ::: "memory")
; #define BAR __builtin_amdgcn_s_barrier()
; #define SCHED __builtin_amdgcn_sched_barrier(0)
; template <int EPI> ...
;     ...
;     WAIT_V(6); BAR; MMA(1, 1, At, B1); BAR;
;     LDB(B0, 1, 0); SCHED; LDA(At, 1, 0); STAGE(SA(0, 1), A, brow + HALF, t + 2);
;     WAIT_L(8); BAR; WAIT_L(0); MMA(0, 0, At, B0); BAR; SCHED;
;     LDB(B1, 1, 1); STAGE(SB(1, 0), Bt, bcol, t + 3);
;     BAR; WAIT_L(0); MMA(0, 1, At, B1); BAR;
;     LDA(At, 1, 1); STAGE(SA(1, 0), A, brow, t + 3);
	v_readfirstlane_b32 s63, v160
	v_lshl_add_u64 v[16:17], v[2:3], 0, s[16:17]
	s_mov_b32 m0, s63
	v_readfirstlane_b32 s61, v161
	global_load_lds_dwordx4 v[16:17], off
	v_lshl_add_u64 v[16:17], v[2:3], 0, s[18:19]
	s_mov_b32 m0, s61
	s_nop 0
	global_load_lds_dwordx4 v[16:17], off
	s_waitcnt vmcnt(6)
	s_barrier
	s_setprio 1
	v_mfma_f32_16x16x32_bf16 v[16:19], v[88:91], v[52:55], 0
	v_mfma_f32_16x16x32_bf16 v[20:23], v[92:95], v[52:55], 0
	v_mfma_f32_16x16x32_bf16 v[16:19], v[96:99], v[108:111], v[16:19]
	v_mfma_f32_16x16x32_bf16 v[20:23], v[100:103], v[108:111], v[20:23]
	v_mfma_f32_16x16x32_bf16 v[52:55], v[88:91], v[112:115], 0
	v_mfma_f32_16x16x32_bf16 v[108:111], v[92:95], v[112:115], 0
	v_mfma_f32_16x16x32_bf16 v[52:55], v[96:99], v[116:119], v[52:55]
	v_mfma_f32_16x16x32_bf16 v[108:111], v[100:103], v[116:119], v[108:111]
	v_mfma_f32_16x16x32_bf16 v[112:115], v[88:91], v[120:123], 0
	v_mfma_f32_16x16x32_bf16 v[116:119], v[92:95], v[120:123], 0
	v_mfma_f32_16x16x32_bf16 v[88:91], v[88:91], v[128:131], 0
	v_mfma_f32_16x16x32_bf16 v[92:95], v[92:95], v[128:131], 0
	v_mfma_f32_16x16x32_bf16 v[112:115], v[96:99], v[124:127], v[112:115]
	v_mfma_f32_16x16x32_bf16 v[116:119], v[100:103], v[124:127], v[116:119]
	v_mfma_f32_16x16x32_bf16 v[88:91], v[96:99], v[132:135], v[88:91]
	v_mfma_f32_16x16x32_bf16 v[92:95], v[100:103], v[132:135], v[92:95]
	s_setprio 0
	s_barrier
	ds_read_b128 v[96:99], v172
	ds_read_b128 v[100:103], v172 offset:256
	ds_read_b128 v[120:123], v173
	ds_read_b128 v[124:127], v173 offset:256
	v_readfirstlane_b32 s67, v162
	v_lshl_add_u64 v[138:139], v[0:1], 0, s[16:17]
	s_mov_b32 m0, s67
	v_readfirstlane_b32 s62, v163
	ds_read_b128 v[128:131], v154 offset:32768
	ds_read_b128 v[132:135], v154 offset:33792
	ds_read_b128 v[192:195], v154 offset:34816
	ds_read_b128 v[196:199], v154 offset:35840
	ds_read_b128 v[200:203], v154 offset:36864
	ds_read_b128 v[204:207], v154 offset:37888
	ds_read_b128 v[208:211], v154 offset:38912
	ds_read_b128 v[212:215], v154 offset:39936
	global_load_lds_dwordx4 v[138:139], off
	v_lshl_add_u64 v[138:139], v[0:1], 0, s[18:19]
	s_mov_b32 m0, s62
	s_nop 0
	global_load_lds_dwordx4 v[138:139], off
	s_waitcnt lgkmcnt(8)
	s_barrier
	s_waitcnt lgkmcnt(0)
	s_setprio 1
	v_mfma_f32_16x16x32_bf16 v[56:59], v[96:99], v[128:131], v[56:59]
	v_mfma_f32_16x16x32_bf16 v[60:63], v[100:103], v[128:131], v[60:63]
	v_mfma_f32_16x16x32_bf16 v[64:67], v[96:99], v[192:195], v[64:67]
	v_mfma_f32_16x16x32_bf16 v[68:71], v[100:103], v[192:195], v[68:71]
	v_mfma_f32_16x16x32_bf16 v[72:75], v[96:99], v[200:203], v[72:75]
	v_mfma_f32_16x16x32_bf16 v[76:79], v[100:103], v[200:203], v[76:79]
	v_mfma_f32_16x16x32_bf16 v[80:83], v[96:99], v[208:211], v[80:83]
	v_mfma_f32_16x16x32_bf16 v[84:87], v[100:103], v[208:211], v[84:87]
	v_mfma_f32_16x16x32_bf16 v[56:59], v[120:123], v[132:135], v[56:59]
	v_mfma_f32_16x16x32_bf16 v[60:63], v[124:127], v[132:135], v[60:63]
	v_mfma_f32_16x16x32_bf16 v[64:67], v[120:123], v[196:199], v[64:67]
	v_mfma_f32_16x16x32_bf16 v[68:71], v[124:127], v[196:199], v[68:71]
	v_mfma_f32_16x16x32_bf16 v[72:75], v[120:123], v[204:207], v[72:75]
	v_mfma_f32_16x16x32_bf16 v[76:79], v[124:127], v[204:207], v[76:79]
	v_mfma_f32_16x16x32_bf16 v[80:83], v[120:123], v[212:215], v[80:83]
	v_mfma_f32_16x16x32_bf16 v[84:87], v[124:127], v[212:215], v[84:87]
	s_setprio 0
	s_barrier
	s_mov_b32 m0, s54
	v_lshl_add_u64 v[138:139], v[6:7], 0, s[20:21]
	ds_read_b128 v[216:219], v174
	ds_read_b128 v[220:223], v174 offset:256
	ds_read_b128 v[224:227], v175
	ds_read_b128 v[228:231], v175 offset:256
	global_load_lds_dwordx4 v[138:139], off
	v_lshl_add_u64 v[138:139], v[6:7], 0, s[22:23]
	s_mov_b32 m0, s51
	s_nop 0
	global_load_lds_dwordx4 v[138:139], off
	s_barrier
	s_waitcnt lgkmcnt(0)
	s_setprio 1
	s_waitcnt lgkmcnt(0)
	v_mfma_f32_16x16x32_bf16 v[104:107], v[216:219], v[128:131], v[104:107]
	v_mfma_f32_16x16x32_bf16 v[24:27], v[220:223], v[128:131], v[24:27]
	v_mfma_f32_16x16x32_bf16 v[28:31], v[216:219], v[192:195], v[28:31]
	v_mfma_f32_16x16x32_bf16 v[32:35], v[220:223], v[192:195], v[32:35]
	v_mfma_f32_16x16x32_bf16 v[36:39], v[216:219], v[200:203], v[36:39]
	v_mfma_f32_16x16x32_bf16 v[40:43], v[220:223], v[200:203], v[40:43]
	v_mfma_f32_16x16x32_bf16 v[44:47], v[216:219], v[208:211], v[44:47]
	v_mfma_f32_16x16x32_bf16 v[48:51], v[220:223], v[208:211], v[48:51]
	v_mfma_f32_16x16x32_bf16 v[104:107], v[224:227], v[132:135], v[104:107]
	v_mfma_f32_16x16x32_bf16 v[24:27], v[228:231], v[132:135], v[24:27]
	v_mfma_f32_16x16x32_bf16 v[28:31], v[224:227], v[196:199], v[28:31]
	v_mfma_f32_16x16x32_bf16 v[32:35], v[228:231], v[196:199], v[32:35]
	v_mfma_f32_16x16x32_bf16 v[36:39], v[224:227], v[204:207], v[36:39]
	v_mfma_f32_16x16x32_bf16 v[40:43], v[228:231], v[204:207], v[40:43]
	v_mfma_f32_16x16x32_bf16 v[44:47], v[224:227], v[212:215], v[44:47]
	v_mfma_f32_16x16x32_bf16 v[48:51], v[228:231], v[212:215], v[48:51]
	s_setprio 0
	s_mov_b32 m0, s71
	v_lshl_add_u64 v[138:139], v[4:5], 0, s[20:21]
	s_barrier
	ds_read_b128 v[128:131], v154 offset:49152
	ds_read_b128 v[132:135], v154 offset:50176
	ds_read_b128 v[192:195], v154 offset:51200
	ds_read_b128 v[196:199], v154 offset:52224
	ds_read_b128 v[200:203], v154 offset:53248
	ds_read_b128 v[204:207], v154 offset:54272
	ds_read_b128 v[208:211], v154 offset:55296
	ds_read_b128 v[212:215], v154 offset:56320
	global_load_lds_dwordx4 v[138:139], off
	v_lshl_add_u64 v[138:139], v[4:5], 0, s[22:23]
	s_mov_b32 m0, s70
	s_nop 0
	global_load_lds_dwordx4 v[138:139], off
	s_barrier
; #define STAGE(P, BASE, br, kt) do { const char* _gb = (const char*)(BASE) + ((size_t)(br) * K + (size_t)(kt) * BK) * 2; \
;     __builtin_amdgcn_global_load_lds((const unsigned*)(_gb + loff0), (unsigned*)((char*)(P) + tid * 16), 16, 0, 0); \
;     __builtin_amdgcn_global_load_lds((const unsigned*)(_gb + (size_t)K * 128 + loff0), (unsigned*)((char*)(P) + tid * 16 + 8192), 16, 0, 0); } while (0)
; #define LDA(dst, b, h) for (int m = 0; m < 4; ++m) { \
;     dst[m][0] = *reinterpret_cast<const bf16x8*>((char*)SA(b, h) + aoff0 + m * 2048); \
;     dst[m][1] = *reinterpret_cast<const bf16x8*>((char*)SA(b, h) + aoff1 + m * 2048); }
; #define LDB(dst, b, h) for (int n = 0; n < 2; ++n) { \
;     dst[n][0] = *reinterpret_cast<const bf16x8*>((char*)SB(b, h) + boff0 + n * 256); \
;     dst[n][1] = *reinterpret_cast<const bf16x8*>((char*)SB(b, h) + boff1 + n * 256); }
; #define MMA(ai, bj, At, Btf) do { __builtin_amdgcn_s_setprio(1); \
;     for (int m = 0; m < 4; ++m) for (int n = 0; n < 2; ++n) for (int k = 0; k < 2; ++k) \
;       acc[ai][bj][m][n] = __builtin_amdgcn_mfma_f32_16x16x32_bf16(Btf[n][k], At[m][k], acc[ai][bj][m][n], 0, 0, 0); \
;     __builtin_amdgcn_s_setprio(0); } while (0)
; #define WAIT_V(n) asm volatile("s_waitcnt vmcnt(" #n ")" ::: "memory")
; #define WAIT_L(n) asm volatile("s_waitcnt lgkmcnt(" #n ")" ::: "memory")
; #define BAR __builtin_amdgcn_s_barrier()
; #define SCHED __builtin_amdgcn_sched_barrier(0)
; template <int EPI> ...
;     ...
;     LDB(B0, 0, 0); SCHED; LDA(At, 0, 0); STAGE(SA(1, 1), A, brow + HALF, t + 1);
;     WAIT_L(8); BAR; WAIT_L(0); MMA(0, 0, At, B0); BAR; SCHED;
;     LDB(B1, 0, 1); STAGE(SB(0, 0), Bt, bcol, t + 2);
;     BAR; WAIT_L(0); MMA(0, 1, At, B1); BAR;
;     ...
;     BAR; WAIT_L(0); MMA(1, 0, At, B0); BAR; SCHED;
;     STAGE(SB(1, 1), Bt, bcol + HALF, t + 3);
;     WAIT_V(6); BAR; MMA(1, 1, At, B1); BAR;
	s_waitcnt lgkmcnt(0)
	s_setprio 1
	v_mfma_f32_16x16x32_bf16 v[8:11], v[96:99], v[208:211], v[8:11]
	v_mfma_f32_16x16x32_bf16 v[12:15], v[100:103], v[208:211], v[12:15]
	v_mfma_f32_16x16x32_bf16 v[142:145], v[96:99], v[128:131], v[142:145]
	v_mfma_f32_16x16x32_bf16 v[146:149], v[100:103], v[128:131], v[146:149]
	v_mfma_f32_16x16x32_bf16 v[150:153], v[96:99], v[192:195], v[150:153]
	v_mfma_f32_16x16x32_bf16 v[180:183], v[100:103], v[192:195], v[180:183]
	v_mfma_f32_16x16x32_bf16 v[184:187], v[96:99], v[200:203], v[184:187]
	v_mfma_f32_16x16x32_bf16 v[188:191], v[100:103], v[200:203], v[188:191]
	v_mfma_f32_16x16x32_bf16 v[8:11], v[120:123], v[212:215], v[8:11]
	v_mfma_f32_16x16x32_bf16 v[12:15], v[124:127], v[212:215], v[12:15]
	v_mfma_f32_16x16x32_bf16 v[142:145], v[120:123], v[132:135], v[142:145]
	v_mfma_f32_16x16x32_bf16 v[146:149], v[124:127], v[132:135], v[146:149]
	v_mfma_f32_16x16x32_bf16 v[150:153], v[120:123], v[196:199], v[150:153]
	v_mfma_f32_16x16x32_bf16 v[180:183], v[124:127], v[196:199], v[180:183]
	v_mfma_f32_16x16x32_bf16 v[184:187], v[120:123], v[204:207], v[184:187]
	v_mfma_f32_16x16x32_bf16 v[188:191], v[124:127], v[204:207], v[188:191]
	s_setprio 0
	s_barrier
	s_mov_b32 m0, s69
	v_lshl_add_u64 v[96:97], v[2:3], 0, s[20:21]
	global_load_lds_dwordx4 v[96:97], off
	v_lshl_add_u64 v[96:97], v[2:3], 0, s[22:23]
	s_mov_b32 m0, s68
	s_nop 0
	global_load_lds_dwordx4 v[96:97], off
	s_waitcnt vmcnt(6)
	s_barrier
	s_setprio 1
	v_mfma_f32_16x16x32_bf16 v[16:19], v[216:219], v[128:131], v[16:19]
	v_mfma_f32_16x16x32_bf16 v[20:23], v[220:223], v[128:131], v[20:23]
	v_mfma_f32_16x16x32_bf16 v[52:55], v[216:219], v[192:195], v[52:55]
	v_mfma_f32_16x16x32_bf16 v[96:99], v[220:223], v[192:195], v[108:111]
	v_mfma_f32_16x16x32_bf16 v[108:111], v[220:223], v[200:203], v[116:119]
	v_mfma_f32_16x16x32_bf16 v[88:91], v[216:219], v[208:211], v[88:91]
	v_mfma_f32_16x16x32_bf16 v[92:95], v[220:223], v[208:211], v[92:95]
	v_mfma_f32_16x16x32_bf16 v[16:19], v[224:227], v[132:135], v[16:19]
	v_mfma_f32_16x16x32_bf16 v[20:23], v[228:231], v[132:135], v[20:23]
	v_mfma_f32_16x16x32_bf16 v[52:55], v[224:227], v[196:199], v[52:55]
	v_mfma_f32_16x16x32_bf16 v[100:103], v[216:219], v[200:203], v[112:115]
	v_mfma_f32_16x16x32_bf16 v[108:111], v[228:231], v[204:207], v[108:111]
	v_mfma_f32_16x16x32_bf16 v[88:91], v[224:227], v[212:215], v[88:91]
	v_mfma_f32_16x16x32_bf16 v[92:95], v[228:231], v[212:215], v[92:95]
	v_mfma_f32_16x16x32_bf16 v[96:99], v[228:231], v[196:199], v[96:99]
	v_mfma_f32_16x16x32_bf16 v[100:103], v[224:227], v[204:207], v[100:103]
	s_setprio 0
	s_barrier
	ds_read_b128 v[112:115], v176
	ds_read_b128 v[116:119], v176 offset:256
	ds_read_b128 v[120:123], v177
	ds_read_b128 v[124:127], v177 offset:256
	s_mov_b32 m0, s65
	v_lshl_add_u64 v[138:139], v[0:1], 0, s[20:21]
	ds_read_b128 v[128:131], v154
	ds_read_b128 v[132:135], v154 offset:1024
	ds_read_b128 v[192:195], v154 offset:2048
	ds_read_b128 v[196:199], v154 offset:3072
	ds_read_b128 v[200:203], v154 offset:4096
	ds_read_b128 v[204:207], v154 offset:5120
	ds_read_b128 v[208:211], v154 offset:6144
	ds_read_b128 v[212:215], v154 offset:7168
	global_load_lds_dwordx4 v[138:139], off
	v_lshl_add_u64 v[138:139], v[0:1], 0, s[22:23]
	s_mov_b32 m0, s55
	s_nop 0
	global_load_lds_dwordx4 v[138:139], off
	s_waitcnt lgkmcnt(8)
	s_barrier
	s_waitcnt lgkmcnt(0)
	s_setprio 1
	v_mfma_f32_16x16x32_bf16 v[56:59], v[112:115], v[128:131], v[56:59]
	v_mfma_f32_16x16x32_bf16 v[60:63], v[116:119], v[128:131], v[60:63]
	v_mfma_f32_16x16x32_bf16 v[64:67], v[112:115], v[192:195], v[64:67]
	v_mfma_f32_16x16x32_bf16 v[68:71], v[116:119], v[192:195], v[68:71]
	v_mfma_f32_16x16x32_bf16 v[72:75], v[112:115], v[200:203], v[72:75]
	v_mfma_f32_16x16x32_bf16 v[76:79], v[116:119], v[200:203], v[76:79]
	v_mfma_f32_16x16x32_bf16 v[80:83], v[112:115], v[208:211], v[80:83]
	v_mfma_f32_16x16x32_bf16 v[84:87], v[116:119], v[208:211], v[84:87]
	v_mfma_f32_16x16x32_bf16 v[56:59], v[120:123], v[132:135], v[56:59]
	v_mfma_f32_16x16x32_bf16 v[60:63], v[124:127], v[132:135], v[60:63]
	v_mfma_f32_16x16x32_bf16 v[64:67], v[120:123], v[196:199], v[64:67]
	v_mfma_f32_16x16x32_bf16 v[68:71], v[124:127], v[196:199], v[68:71]
	v_mfma_f32_16x16x32_bf16 v[72:75], v[120:123], v[204:207], v[72:75]
	v_mfma_f32_16x16x32_bf16 v[76:79], v[124:127], v[204:207], v[76:79]
	v_mfma_f32_16x16x32_bf16 v[80:83], v[120:123], v[212:215], v[80:83]
	v_mfma_f32_16x16x32_bf16 v[84:87], v[124:127], v[212:215], v[84:87]
	s_setprio 0
	s_barrier
	s_mov_b32 m0, s64
	v_lshl_add_u64 v[138:139], v[6:7], 0, s[24:25]
	ds_read_b128 v[216:219], v178
	ds_read_b128 v[220:223], v178 offset:256
	ds_read_b128 v[224:227], v179
	ds_read_b128 v[228:231], v179 offset:256
	global_load_lds_dwordx4 v[138:139], off
	v_lshl_add_u64 v[138:139], v[6:7], 0, s[26:27]
	s_mov_b32 m0, s59
	s_nop 0
	global_load_lds_dwordx4 v[138:139], off
	s_barrier
	s_waitcnt lgkmcnt(0)
	s_setprio 1
	s_waitcnt lgkmcnt(0)
	v_mfma_f32_16x16x32_bf16 v[104:107], v[216:219], v[128:131], v[104:107]
	v_mfma_f32_16x16x32_bf16 v[24:27], v[220:223], v[128:131], v[24:27]
	v_mfma_f32_16x16x32_bf16 v[28:31], v[216:219], v[192:195], v[28:31]
	v_mfma_f32_16x16x32_bf16 v[32:35], v[220:223], v[192:195], v[32:35]
	v_mfma_f32_16x16x32_bf16 v[36:39], v[216:219], v[200:203], v[36:39]
	v_mfma_f32_16x16x32_bf16 v[40:43], v[220:223], v[200:203], v[40:43]
	v_mfma_f32_16x16x32_bf16 v[44:47], v[216:219], v[208:211], v[44:47]
	v_mfma_f32_16x16x32_bf16 v[48:51], v[220:223], v[208:211], v[48:51]
	v_mfma_f32_16x16x32_bf16 v[104:107], v[224:227], v[132:135], v[104:107]
	v_mfma_f32_16x16x32_bf16 v[24:27], v[228:231], v[132:135], v[24:27]
	v_mfma_f32_16x16x32_bf16 v[28:31], v[224:227], v[196:199], v[28:31]
	v_mfma_f32_16x16x32_bf16 v[32:35], v[228:231], v[196:199], v[32:35]
	v_mfma_f32_16x16x32_bf16 v[36:39], v[224:227], v[204:207], v[36:39]
	v_mfma_f32_16x16x32_bf16 v[40:43], v[228:231], v[204:207], v[40:43]
	v_mfma_f32_16x16x32_bf16 v[44:47], v[224:227], v[212:215], v[44:47]
	v_mfma_f32_16x16x32_bf16 v[48:51], v[228:231], v[212:215], v[48:51]
	s_setprio 0
	s_mov_b32 m0, s66
	v_lshl_add_u64 v[138:139], v[4:5], 0, s[24:25]
	s_barrier
; #define STAGE(P, BASE, br, kt) do { const char* _gb = (const char*)(BASE) + ((size_t)(br) * K + (size_t)(kt) * BK) * 2; \
;     __builtin_amdgcn_global_load_lds((const unsigned*)(_gb + loff0), (unsigned*)((char*)(P) + tid * 16), 16, 0, 0); \
;     __builtin_amdgcn_global_load_lds((const unsigned*)(_gb + (size_t)K * 128 + loff0), (unsigned*)((char*)(P) + tid * 16 + 8192), 16, 0, 0); } while (0)
; #define LDA(dst, b, h) for (int m = 0; m < 4; ++m) { \
;     dst[m][0] = *reinterpret_cast<const bf16x8*>((char*)SA(b, h) + aoff0 + m * 2048); \
;     dst[m][1] = *reinterpret_cast<const bf16x8*>((char*)SA(b, h) + aoff1 + m * 2048); }
; #define LDB(dst, b, h) for (int n = 0; n < 2; ++n) { \
;     dst[n][0] = *reinterpret_cast<const bf16x8*>((char*)SB(b, h) + boff0 + n * 256); \
;     dst[n][1] = *reinterpret_cast<const bf16x8*>((char*)SB(b, h) + boff1 + n * 256); }
; #define MMA(ai, bj, At, Btf) do { __builtin_amdgcn_s_setprio(1); \
;     for (int m = 0; m < 4; ++m) for (int n = 0; n < 2; ++n) for (int k = 0; k < 2; ++k) \
;       acc[ai][bj][m][n] = __builtin_amdgcn_mfma_f32_16x16x32_bf16(Btf[n][k], At[m][k], acc[ai][bj][m][n], 0, 0, 0); \
;     __builtin_amdgcn_s_setprio(0); } while (0)
; #define WAIT_V(n) asm volatile("s_waitcnt vmcnt(" #n ")" ::: "memory")
; #define WAIT_L(n) asm volatile("s_waitcnt lgkmcnt(" #n ")" ::: "memory")
; #define BAR __builtin_amdgcn_s_barrier()
; #define SCHED __builtin_amdgcn_sched_barrier(0)
; template <int EPI> ...
;     ...
;     LDA(At, 0, 1); STAGE(SA(0, 0), A, brow, t + 2);
;     BAR; WAIT_L(0); MMA(1, 0, At, B0); BAR; SCHED;
;     STAGE(SB(0, 1), Bt, bcol + HALF, t + 2);
;     WAIT_V(6); BAR; MMA(1, 1, At, B1); BAR;
;     LDB(B0, 1, 0); SCHED; LDA(At, 1, 0); STAGE(SA(0, 1), A, brow + HALF, t + 2);
;     WAIT_L(8); BAR; WAIT_L(0); MMA(0, 0, At, B0); BAR; SCHED;
;     LDB(B1, 1, 1); STAGE(SB(1, 0), Bt, bcol, t + 3);
	ds_read_b128 v[128:131], v154 offset:16384
	ds_read_b128 v[132:135], v154 offset:17408
	ds_read_b128 v[192:195], v154 offset:18432
	ds_read_b128 v[196:199], v154 offset:19456
	ds_read_b128 v[200:203], v154 offset:20480
	ds_read_b128 v[204:207], v154 offset:21504
	ds_read_b128 v[208:211], v154 offset:22528
	ds_read_b128 v[212:215], v154 offset:23552
	global_load_lds_dwordx4 v[138:139], off
	v_lshl_add_u64 v[138:139], v[4:5], 0, s[26:27]
	s_mov_b32 m0, s60
	s_nop 0
	global_load_lds_dwordx4 v[138:139], off
	s_barrier
	s_waitcnt lgkmcnt(0)
	s_setprio 1
	v_mfma_f32_16x16x32_bf16 v[8:11], v[112:115], v[208:211], v[8:11]
	v_mfma_f32_16x16x32_bf16 v[12:15], v[116:119], v[208:211], v[12:15]
	v_mfma_f32_16x16x32_bf16 v[142:145], v[112:115], v[128:131], v[142:145]
	v_mfma_f32_16x16x32_bf16 v[146:149], v[116:119], v[128:131], v[146:149]
	v_mfma_f32_16x16x32_bf16 v[150:153], v[112:115], v[192:195], v[150:153]
	v_mfma_f32_16x16x32_bf16 v[180:183], v[116:119], v[192:195], v[180:183]
	v_mfma_f32_16x16x32_bf16 v[184:187], v[112:115], v[200:203], v[184:187]
	v_mfma_f32_16x16x32_bf16 v[188:191], v[116:119], v[200:203], v[188:191]
	v_mfma_f32_16x16x32_bf16 v[8:11], v[120:123], v[212:215], v[8:11]
	v_mfma_f32_16x16x32_bf16 v[12:15], v[124:127], v[212:215], v[12:15]
	v_mfma_f32_16x16x32_bf16 v[142:145], v[120:123], v[132:135], v[142:145]
	v_mfma_f32_16x16x32_bf16 v[146:149], v[124:127], v[132:135], v[146:149]
	v_mfma_f32_16x16x32_bf16 v[150:153], v[120:123], v[196:199], v[150:153]
	v_mfma_f32_16x16x32_bf16 v[180:183], v[124:127], v[196:199], v[180:183]
	v_mfma_f32_16x16x32_bf16 v[184:187], v[120:123], v[204:207], v[184:187]
	v_mfma_f32_16x16x32_bf16 v[188:191], v[124:127], v[204:207], v[188:191]
	s_setprio 0
	s_barrier
	s_mov_b32 m0, s63
	v_lshl_add_u64 v[112:113], v[2:3], 0, s[24:25]
	global_load_lds_dwordx4 v[112:113], off
	v_lshl_add_u64 v[112:113], v[2:3], 0, s[26:27]
	s_mov_b32 m0, s61
	s_nop 0
	global_load_lds_dwordx4 v[112:113], off
	s_waitcnt vmcnt(6)
	s_barrier
	s_setprio 1
	v_mfma_f32_16x16x32_bf16 v[16:19], v[216:219], v[128:131], v[16:19]
	v_mfma_f32_16x16x32_bf16 v[20:23], v[220:223], v[128:131], v[20:23]
	v_mfma_f32_16x16x32_bf16 v[52:55], v[216:219], v[192:195], v[52:55]
	v_mfma_f32_16x16x32_bf16 v[108:111], v[220:223], v[200:203], v[108:111]
	v_mfma_f32_16x16x32_bf16 v[88:91], v[216:219], v[208:211], v[88:91]
	v_mfma_f32_16x16x32_bf16 v[92:95], v[220:223], v[208:211], v[92:95]
	v_mfma_f32_16x16x32_bf16 v[16:19], v[224:227], v[132:135], v[16:19]
	v_mfma_f32_16x16x32_bf16 v[20:23], v[228:231], v[132:135], v[20:23]
	v_mfma_f32_16x16x32_bf16 v[52:55], v[224:227], v[196:199], v[52:55]
	v_mfma_f32_16x16x32_bf16 v[96:99], v[220:223], v[192:195], v[96:99]
	v_mfma_f32_16x16x32_bf16 v[100:103], v[216:219], v[200:203], v[100:103]
	v_mfma_f32_16x16x32_bf16 v[108:111], v[228:231], v[204:207], v[108:111]
	v_mfma_f32_16x16x32_bf16 v[88:91], v[224:227], v[212:215], v[88:91]
	v_mfma_f32_16x16x32_bf16 v[92:95], v[228:231], v[212:215], v[92:95]
	v_mfma_f32_16x16x32_bf16 v[96:99], v[228:231], v[196:199], v[96:99]
	v_mfma_f32_16x16x32_bf16 v[100:103], v[224:227], v[204:207], v[100:103]
	s_setprio 0
	s_barrier
	ds_read_b128 v[112:115], v172
	ds_read_b128 v[116:119], v172 offset:256
	ds_read_b128 v[120:123], v173
	ds_read_b128 v[124:127], v173 offset:256
	s_mov_b32 m0, s67
	v_lshl_add_u64 v[138:139], v[0:1], 0, s[24:25]
	ds_read_b128 v[128:131], v154 offset:32768
	ds_read_b128 v[132:135], v154 offset:33792
	ds_read_b128 v[192:195], v154 offset:34816
	ds_read_b128 v[196:199], v154 offset:35840
	ds_read_b128 v[200:203], v154 offset:36864
	ds_read_b128 v[204:207], v154 offset:37888
	ds_read_b128 v[208:211], v154 offset:38912
	ds_read_b128 v[212:215], v154 offset:39936
	global_load_lds_dwordx4 v[138:139], off
	v_lshl_add_u64 v[138:139], v[0:1], 0, s[26:27]
	s_mov_b32 m0, s62
	s_nop 0
	global_load_lds_dwordx4 v[138:139], off
	s_waitcnt lgkmcnt(8)
	s_barrier
	s_waitcnt lgkmcnt(0)
	s_setprio 1
	v_mfma_f32_16x16x32_bf16 v[56:59], v[112:115], v[128:131], v[56:59]
	v_mfma_f32_16x16x32_bf16 v[60:63], v[116:119], v[128:131], v[60:63]
	v_mfma_f32_16x16x32_bf16 v[64:67], v[112:115], v[192:195], v[64:67]
	v_mfma_f32_16x16x32_bf16 v[68:71], v[116:119], v[192:195], v[68:71]
	v_mfma_f32_16x16x32_bf16 v[72:75], v[112:115], v[200:203], v[72:75]
	v_mfma_f32_16x16x32_bf16 v[76:79], v[116:119], v[200:203], v[76:79]
	v_mfma_f32_16x16x32_bf16 v[80:83], v[112:115], v[208:211], v[80:83]
	v_mfma_f32_16x16x32_bf16 v[84:87], v[116:119], v[208:211], v[84:87]
	v_mfma_f32_16x16x32_bf16 v[56:59], v[120:123], v[132:135], v[56:59]
	v_mfma_f32_16x16x32_bf16 v[60:63], v[124:127], v[132:135], v[60:63]
	v_mfma_f32_16x16x32_bf16 v[64:67], v[120:123], v[196:199], v[64:67]
	v_mfma_f32_16x16x32_bf16 v[68:71], v[124:127], v[196:199], v[68:71]
	v_mfma_f32_16x16x32_bf16 v[72:75], v[120:123], v[204:207], v[72:75]
	v_mfma_f32_16x16x32_bf16 v[76:79], v[124:127], v[204:207], v[76:79]
	v_mfma_f32_16x16x32_bf16 v[80:83], v[120:123], v[212:215], v[80:83]
	v_mfma_f32_16x16x32_bf16 v[84:87], v[124:127], v[212:215], v[84:87]
	s_setprio 0
	s_barrier
	s_mov_b32 m0, s54
	v_lshl_add_u64 v[138:139], v[6:7], 0, s[28:29]
	ds_read_b128 v[216:219], v174
	ds_read_b128 v[220:223], v174 offset:256
	ds_read_b128 v[224:227], v175
	ds_read_b128 v[228:231], v175 offset:256
	global_load_lds_dwordx4 v[138:139], off
	v_lshl_add_u64 v[138:139], v[6:7], 0, s[30:31]
	s_mov_b32 m0, s51
	s_nop 0
	global_load_lds_dwordx4 v[138:139], off
	s_barrier
; #define STAGE(P, BASE, br, kt) do { const char* _gb = (const char*)(BASE) + ((size_t)(br) * K + (size_t)(kt) * BK) * 2; \
;     __builtin_amdgcn_global_load_lds((const unsigned*)(_gb + loff0), (unsigned*)((char*)(P) + tid * 16), 16, 0, 0); \
;     __builtin_amdgcn_global_load_lds((const unsigned*)(_gb + (size_t)K * 128 + loff0), (unsigned*)((char*)(P) + tid * 16 + 8192), 16, 0, 0); } while (0)
; #define LDA(dst, b, h) for (int m = 0; m < 4; ++m) { \
;     dst[m][0] = *reinterpret_cast<const bf16x8*>((char*)SA(b, h) + aoff0 + m * 2048); \
;     dst[m][1] = *reinterpret_cast<const bf16x8*>((char*)SA(b, h) + aoff1 + m * 2048); }
; #define LDB(dst, b, h) for (int n = 0; n < 2; ++n) { \
;     dst[n][0] = *reinterpret_cast<const bf16x8*>((char*)SB(b, h) + boff0 + n * 256); \
;     dst[n][1] = *reinterpret_cast<const bf16x8*>((char*)SB(b, h) + boff1 + n * 256); }
; #define MMA(ai, bj, At, Btf) do { __builtin_amdgcn_s_setprio(1); \
;     for (int m = 0; m < 4; ++m) for (int n = 0; n < 2; ++n) for (int k = 0; k < 2; ++k) \
;       acc[ai][bj][m][n] = __builtin_amdgcn_mfma_f32_16x16x32_bf16(Btf[n][k], At[m][k], acc[ai][bj][m][n], 0, 0, 0); \
;     __builtin_amdgcn_s_setprio(0); } while (0)
; #define WAIT_V(n) asm volatile("s_waitcnt vmcnt(" #n ")" ::: "memory")
; #define WAIT_L(n) asm volatile("s_waitcnt lgkmcnt(" #n ")" ::: "memory")
; #define BAR __builtin_amdgcn_s_barrier()
; #define SCHED __builtin_amdgcn_sched_barrier(0)
; template <int EPI> ...
;     ...
;     LDB(B0, 0, 0); SCHED; LDA(At, 0, 0); STAGE(SA(1, 1), A, brow + HALF, t + 1);
;     WAIT_L(8); BAR; WAIT_L(0); MMA(0, 0, At, B0); BAR; SCHED;
;     ...
;     BAR; WAIT_L(0); MMA(0, 1, At, B1); BAR;
;     LDA(At, 1, 1); STAGE(SA(1, 0), A, brow, t + 3);
;     BAR; WAIT_L(0); MMA(1, 0, At, B0); BAR; SCHED;
;     STAGE(SB(1, 1), Bt, bcol + HALF, t + 3);
;     WAIT_V(6); BAR; MMA(1, 1, At, B1); BAR;
	s_waitcnt lgkmcnt(0)
	s_setprio 1
	s_waitcnt lgkmcnt(0)
	v_mfma_f32_16x16x32_bf16 v[104:107], v[216:219], v[128:131], v[104:107]
	v_mfma_f32_16x16x32_bf16 v[24:27], v[220:223], v[128:131], v[24:27]
	v_mfma_f32_16x16x32_bf16 v[28:31], v[216:219], v[192:195], v[28:31]
	v_mfma_f32_16x16x32_bf16 v[32:35], v[220:223], v[192:195], v[32:35]
	v_mfma_f32_16x16x32_bf16 v[36:39], v[216:219], v[200:203], v[36:39]
	v_mfma_f32_16x16x32_bf16 v[40:43], v[220:223], v[200:203], v[40:43]
	v_mfma_f32_16x16x32_bf16 v[44:47], v[216:219], v[208:211], v[44:47]
	v_mfma_f32_16x16x32_bf16 v[48:51], v[220:223], v[208:211], v[48:51]
	v_mfma_f32_16x16x32_bf16 v[104:107], v[224:227], v[132:135], v[104:107]
	v_mfma_f32_16x16x32_bf16 v[24:27], v[228:231], v[132:135], v[24:27]
	v_mfma_f32_16x16x32_bf16 v[28:31], v[224:227], v[196:199], v[28:31]
	v_mfma_f32_16x16x32_bf16 v[32:35], v[228:231], v[196:199], v[32:35]
	v_mfma_f32_16x16x32_bf16 v[36:39], v[224:227], v[204:207], v[36:39]
	v_mfma_f32_16x16x32_bf16 v[40:43], v[228:231], v[204:207], v[40:43]
	v_mfma_f32_16x16x32_bf16 v[44:47], v[224:227], v[212:215], v[44:47]
	v_mfma_f32_16x16x32_bf16 v[48:51], v[228:231], v[212:215], v[48:51]
	s_setprio 0
	v_readfirstlane_b32 s62, v254
	v_lshl_add_u64 v[138:139], v[4:5], 0, s[28:29]
	s_mov_b32 m0, s62
	v_readfirstlane_b32 s55, v165
	s_barrier
	ds_read_b128 v[128:131], v154 offset:49152
	ds_read_b128 v[132:135], v154 offset:50176
	ds_read_b128 v[192:195], v154 offset:51200
	ds_read_b128 v[196:199], v154 offset:52224
	ds_read_b128 v[200:203], v154 offset:53248
	ds_read_b128 v[204:207], v154 offset:54272
	ds_read_b128 v[208:211], v154 offset:55296
	ds_read_b128 v[212:215], v154 offset:56320
	global_load_lds_dwordx4 v[138:139], off
	v_lshl_add_u64 v[138:139], v[4:5], 0, s[30:31]
	s_mov_b32 m0, s55
	s_nop 0
	global_load_lds_dwordx4 v[138:139], off
	s_barrier
	s_waitcnt lgkmcnt(0)
	s_setprio 1
	v_mfma_f32_16x16x32_bf16 v[8:11], v[112:115], v[208:211], v[8:11]
	v_mfma_f32_16x16x32_bf16 v[12:15], v[116:119], v[208:211], v[12:15]
	v_mfma_f32_16x16x32_bf16 v[142:145], v[112:115], v[128:131], v[142:145]
	v_mfma_f32_16x16x32_bf16 v[146:149], v[116:119], v[128:131], v[146:149]
	v_mfma_f32_16x16x32_bf16 v[150:153], v[112:115], v[192:195], v[150:153]
	v_mfma_f32_16x16x32_bf16 v[180:183], v[116:119], v[192:195], v[180:183]
	v_mfma_f32_16x16x32_bf16 v[184:187], v[112:115], v[200:203], v[184:187]
	v_mfma_f32_16x16x32_bf16 v[188:191], v[116:119], v[200:203], v[188:191]
	v_mfma_f32_16x16x32_bf16 v[8:11], v[120:123], v[212:215], v[8:11]
	v_mfma_f32_16x16x32_bf16 v[12:15], v[124:127], v[212:215], v[12:15]
	v_mfma_f32_16x16x32_bf16 v[142:145], v[120:123], v[132:135], v[142:145]
	v_mfma_f32_16x16x32_bf16 v[146:149], v[124:127], v[132:135], v[146:149]
	v_mfma_f32_16x16x32_bf16 v[150:153], v[120:123], v[196:199], v[150:153]
	v_mfma_f32_16x16x32_bf16 v[180:183], v[124:127], v[196:199], v[180:183]
	v_mfma_f32_16x16x32_bf16 v[184:187], v[120:123], v[204:207], v[184:187]
	v_mfma_f32_16x16x32_bf16 v[188:191], v[124:127], v[204:207], v[188:191]
	s_setprio 0
	s_barrier
	v_readfirstlane_b32 s60, v168
	v_lshl_add_u64 v[112:113], v[2:3], 0, s[28:29]
	s_mov_b32 m0, s60
	v_readfirstlane_b32 s59, v169
	global_load_lds_dwordx4 v[112:113], off
	v_lshl_add_u64 v[112:113], v[2:3], 0, s[30:31]
	s_mov_b32 m0, s59
	s_nop 0
	global_load_lds_dwordx4 v[112:113], off
	s_waitcnt vmcnt(6)
	s_barrier
	s_setprio 1
	v_mfma_f32_16x16x32_bf16 v[16:19], v[216:219], v[128:131], v[16:19]
	v_mfma_f32_16x16x32_bf16 v[20:23], v[220:223], v[128:131], v[20:23]
	v_mfma_f32_16x16x32_bf16 v[52:55], v[216:219], v[192:195], v[52:55]
	v_mfma_f32_16x16x32_bf16 v[108:111], v[220:223], v[200:203], v[108:111]
	v_mfma_f32_16x16x32_bf16 v[88:91], v[216:219], v[208:211], v[88:91]
	v_mfma_f32_16x16x32_bf16 v[92:95], v[220:223], v[208:211], v[92:95]
	v_mfma_f32_16x16x32_bf16 v[16:19], v[224:227], v[132:135], v[16:19]
	v_mfma_f32_16x16x32_bf16 v[20:23], v[228:231], v[132:135], v[20:23]
	v_mfma_f32_16x16x32_bf16 v[52:55], v[224:227], v[196:199], v[52:55]
	v_mfma_f32_16x16x32_bf16 v[96:99], v[220:223], v[192:195], v[96:99]
	v_mfma_f32_16x16x32_bf16 v[100:103], v[216:219], v[200:203], v[100:103]
	v_mfma_f32_16x16x32_bf16 v[108:111], v[228:231], v[204:207], v[108:111]
	v_mfma_f32_16x16x32_bf16 v[88:91], v[224:227], v[212:215], v[88:91]
	v_mfma_f32_16x16x32_bf16 v[92:95], v[228:231], v[212:215], v[92:95]
	v_mfma_f32_16x16x32_bf16 v[96:99], v[228:231], v[196:199], v[96:99]
	v_mfma_f32_16x16x32_bf16 v[100:103], v[224:227], v[204:207], v[100:103]
	s_setprio 0
	s_barrier
	ds_read_b128 v[112:115], v176
	ds_read_b128 v[116:119], v176 offset:256
	ds_read_b128 v[120:123], v177
	ds_read_b128 v[124:127], v177 offset:256
	v_readfirstlane_b32 s63, v170
	v_lshl_add_u64 v[138:139], v[0:1], 0, s[28:29]
	s_mov_b32 m0, s63
	v_readfirstlane_b32 s61, v171
	ds_read_b128 v[128:131], v154
	ds_read_b128 v[132:135], v154 offset:1024
	ds_read_b128 v[192:195], v154 offset:2048
	ds_read_b128 v[196:199], v154 offset:3072
	ds_read_b128 v[200:203], v154 offset:4096
	ds_read_b128 v[204:207], v154 offset:5120
	ds_read_b128 v[208:211], v154 offset:6144
	ds_read_b128 v[212:215], v154 offset:7168
	global_load_lds_dwordx4 v[138:139], off
	v_lshl_add_u64 v[138:139], v[0:1], 0, s[30:31]
	s_mov_b32 m0, s61
	s_nop 0
	global_load_lds_dwordx4 v[138:139], off
	s_waitcnt lgkmcnt(8)
	s_barrier
; #define STAGE(P, BASE, br, kt) do { const char* _gb = (const char*)(BASE) + ((size_t)(br) * K + (size_t)(kt) * BK) * 2; \
;     __builtin_amdgcn_global_load_lds((const unsigned*)(_gb + loff0), (unsigned*)((char*)(P) + tid * 16), 16, 0, 0); \
;     __builtin_amdgcn_global_load_lds((const unsigned*)(_gb + (size_t)K * 128 + loff0), (unsigned*)((char*)(P) + tid * 16 + 8192), 16, 0, 0); } while (0)
; #define LDA(dst, b, h) for (int m = 0; m < 4; ++m) { \
;     dst[m][0] = *reinterpret_cast<const bf16x8*>((char*)SA(b, h) + aoff0 + m * 2048); \
;     dst[m][1] = *reinterpret_cast<const bf16x8*>((char*)SA(b, h) + aoff1 + m * 2048); }
; #define LDB(dst, b, h) for (int n = 0; n < 2; ++n) { \
;     dst[n][0] = *reinterpret_cast<const bf16x8*>((char*)SB(b, h) + boff0 + n * 256); \
;     dst[n][1] = *reinterpret_cast<const bf16x8*>((char*)SB(b, h) + boff1 + n * 256); }
; #define MMA(ai, bj, At, Btf) do { __builtin_amdgcn_s_setprio(1); \
;     for (int m = 0; m < 4; ++m) for (int n = 0; n < 2; ++n) for (int k = 0; k < 2; ++k) \
;       acc[ai][bj][m][n] = __builtin_amdgcn_mfma_f32_16x16x32_bf16(Btf[n][k], At[m][k], acc[ai][bj][m][n], 0, 0, 0); \
;     __builtin_amdgcn_s_setprio(0); } while (0)
; #define WAIT_V(n) asm volatile("s_waitcnt vmcnt(" #n ")" ::: "memory")
; #define WAIT_L(n) asm volatile("s_waitcnt lgkmcnt(" #n ")" ::: "memory")
; #define BAR __builtin_amdgcn_s_barrier()
; #define SCHED __builtin_amdgcn_sched_barrier(0)
; template <int EPI> ...
;     ...
;     WAIT_L(8); BAR; WAIT_L(0); MMA(0, 0, At, B0); BAR; SCHED;
;     LDB(B1, 0, 1); STAGE(SB(0, 0), Bt, bcol, t + 2);
;     BAR; WAIT_L(0); MMA(0, 1, At, B1); BAR;
;     LDA(At, 0, 1); STAGE(SA(0, 0), A, brow, t + 2);
;     BAR; WAIT_L(0); MMA(1, 0, At, B0); BAR; SCHED;
;     STAGE(SB(0, 1), Bt, bcol + HALF, t + 2);
;     WAIT_V(6); BAR; MMA(1, 1, At, B1); BAR;
	s_waitcnt lgkmcnt(0)
	s_setprio 1
	v_mfma_f32_16x16x32_bf16 v[56:59], v[112:115], v[128:131], v[56:59]
	v_mfma_f32_16x16x32_bf16 v[60:63], v[116:119], v[128:131], v[60:63]
	v_mfma_f32_16x16x32_bf16 v[64:67], v[112:115], v[192:195], v[64:67]
	v_mfma_f32_16x16x32_bf16 v[68:71], v[116:119], v[192:195], v[68:71]
	v_mfma_f32_16x16x32_bf16 v[72:75], v[112:115], v[200:203], v[72:75]
	v_mfma_f32_16x16x32_bf16 v[76:79], v[116:119], v[200:203], v[76:79]
	v_mfma_f32_16x16x32_bf16 v[80:83], v[112:115], v[208:211], v[80:83]
	v_mfma_f32_16x16x32_bf16 v[84:87], v[116:119], v[208:211], v[84:87]
	v_mfma_f32_16x16x32_bf16 v[56:59], v[120:123], v[132:135], v[56:59]
	v_mfma_f32_16x16x32_bf16 v[60:63], v[124:127], v[132:135], v[60:63]
	v_mfma_f32_16x16x32_bf16 v[64:67], v[120:123], v[196:199], v[64:67]
	v_mfma_f32_16x16x32_bf16 v[68:71], v[124:127], v[196:199], v[68:71]
	v_mfma_f32_16x16x32_bf16 v[72:75], v[120:123], v[204:207], v[72:75]
	v_mfma_f32_16x16x32_bf16 v[76:79], v[124:127], v[204:207], v[76:79]
	v_mfma_f32_16x16x32_bf16 v[80:83], v[120:123], v[212:215], v[80:83]
	v_mfma_f32_16x16x32_bf16 v[84:87], v[124:127], v[212:215], v[84:87]
	s_setprio 0
	s_barrier
	v_readfirstlane_b32 s64, v156
	v_lshl_add_u64 v[138:139], v[6:7], 0, s[36:37]
	s_mov_b32 m0, s64
	v_readfirstlane_b32 s64, v157
	ds_read_b128 v[216:219], v178
	ds_read_b128 v[220:223], v178 offset:256
	ds_read_b128 v[224:227], v179
	ds_read_b128 v[228:231], v179 offset:256
	global_load_lds_dwordx4 v[138:139], off
	v_lshl_add_u64 v[138:139], v[6:7], 0, s[38:39]
	s_mov_b32 m0, s64
	s_nop 0
	global_load_lds_dwordx4 v[138:139], off
	s_barrier
	s_waitcnt lgkmcnt(0)
	s_setprio 1
	s_waitcnt lgkmcnt(0)
	v_mfma_f32_16x16x32_bf16 v[104:107], v[216:219], v[128:131], v[104:107]
	v_mfma_f32_16x16x32_bf16 v[24:27], v[220:223], v[128:131], v[24:27]
	v_mfma_f32_16x16x32_bf16 v[28:31], v[216:219], v[192:195], v[28:31]
	v_mfma_f32_16x16x32_bf16 v[32:35], v[220:223], v[192:195], v[32:35]
	v_mfma_f32_16x16x32_bf16 v[36:39], v[216:219], v[200:203], v[36:39]
	v_mfma_f32_16x16x32_bf16 v[40:43], v[220:223], v[200:203], v[40:43]
	v_mfma_f32_16x16x32_bf16 v[44:47], v[216:219], v[208:211], v[44:47]
	v_mfma_f32_16x16x32_bf16 v[48:51], v[220:223], v[208:211], v[48:51]
	v_mfma_f32_16x16x32_bf16 v[104:107], v[224:227], v[132:135], v[104:107]
	v_mfma_f32_16x16x32_bf16 v[24:27], v[228:231], v[132:135], v[24:27]
	v_mfma_f32_16x16x32_bf16 v[28:31], v[224:227], v[196:199], v[28:31]
	v_mfma_f32_16x16x32_bf16 v[32:35], v[228:231], v[196:199], v[32:35]
	v_mfma_f32_16x16x32_bf16 v[36:39], v[224:227], v[204:207], v[36:39]
	v_mfma_f32_16x16x32_bf16 v[40:43], v[228:231], v[204:207], v[40:43]
	v_mfma_f32_16x16x32_bf16 v[44:47], v[224:227], v[212:215], v[44:47]
	v_mfma_f32_16x16x32_bf16 v[48:51], v[228:231], v[212:215], v[48:51]
	s_setprio 0
	v_readfirstlane_b32 s64, v158
	v_lshl_add_u64 v[138:139], v[4:5], 0, s[36:37]
	s_mov_b32 m0, s64
	v_readfirstlane_b32 s64, v159
	s_barrier
	ds_read_b128 v[128:131], v154 offset:16384
	ds_read_b128 v[132:135], v154 offset:17408
	ds_read_b128 v[192:195], v154 offset:18432
	ds_read_b128 v[196:199], v154 offset:19456
	ds_read_b128 v[200:203], v154 offset:20480
	ds_read_b128 v[204:207], v154 offset:21504
	ds_read_b128 v[208:211], v154 offset:22528
	ds_read_b128 v[212:215], v154 offset:23552
	global_load_lds_dwordx4 v[138:139], off
	v_lshl_add_u64 v[138:139], v[4:5], 0, s[38:39]
	s_mov_b32 m0, s64
	s_nop 0
	global_load_lds_dwordx4 v[138:139], off
	s_barrier
	s_waitcnt lgkmcnt(0)
	s_setprio 1
	v_mfma_f32_16x16x32_bf16 v[8:11], v[112:115], v[208:211], v[8:11]
	v_mfma_f32_16x16x32_bf16 v[12:15], v[116:119], v[208:211], v[12:15]
	v_mfma_f32_16x16x32_bf16 v[142:145], v[112:115], v[128:131], v[142:145]
	v_mfma_f32_16x16x32_bf16 v[146:149], v[116:119], v[128:131], v[146:149]
	v_mfma_f32_16x16x32_bf16 v[150:153], v[112:115], v[192:195], v[150:153]
	v_mfma_f32_16x16x32_bf16 v[180:183], v[116:119], v[192:195], v[180:183]
	v_mfma_f32_16x16x32_bf16 v[184:187], v[112:115], v[200:203], v[184:187]
	v_mfma_f32_16x16x32_bf16 v[188:191], v[116:119], v[200:203], v[188:191]
	v_mfma_f32_16x16x32_bf16 v[8:11], v[120:123], v[212:215], v[8:11]
	v_mfma_f32_16x16x32_bf16 v[12:15], v[124:127], v[212:215], v[12:15]
	v_mfma_f32_16x16x32_bf16 v[142:145], v[120:123], v[132:135], v[142:145]
	v_mfma_f32_16x16x32_bf16 v[146:149], v[124:127], v[132:135], v[146:149]
	v_mfma_f32_16x16x32_bf16 v[150:153], v[120:123], v[196:199], v[150:153]
	v_mfma_f32_16x16x32_bf16 v[180:183], v[124:127], v[196:199], v[180:183]
	v_mfma_f32_16x16x32_bf16 v[184:187], v[120:123], v[204:207], v[184:187]
	v_mfma_f32_16x16x32_bf16 v[188:191], v[124:127], v[204:207], v[188:191]
	s_setprio 0
	s_barrier
	v_readfirstlane_b32 s64, v160
	v_lshl_add_u64 v[112:113], v[2:3], 0, s[36:37]
	s_mov_b32 m0, s64
	v_readfirstlane_b32 s64, v161
	global_load_lds_dwordx4 v[112:113], off
	v_lshl_add_u64 v[112:113], v[2:3], 0, s[38:39]
	s_mov_b32 m0, s64
	s_nop 0
	global_load_lds_dwordx4 v[112:113], off
	s_waitcnt vmcnt(6)
	s_barrier
	s_setprio 1
	v_mfma_f32_16x16x32_bf16 v[16:19], v[216:219], v[128:131], v[16:19]
	v_mfma_f32_16x16x32_bf16 v[20:23], v[220:223], v[128:131], v[20:23]
	v_mfma_f32_16x16x32_bf16 v[52:55], v[216:219], v[192:195], v[52:55]
	v_mfma_f32_16x16x32_bf16 v[108:111], v[220:223], v[200:203], v[108:111]
	v_mfma_f32_16x16x32_bf16 v[88:91], v[216:219], v[208:211], v[88:91]
	v_mfma_f32_16x16x32_bf16 v[92:95], v[220:223], v[208:211], v[92:95]
	v_mfma_f32_16x16x32_bf16 v[16:19], v[224:227], v[132:135], v[16:19]
	v_mfma_f32_16x16x32_bf16 v[20:23], v[228:231], v[132:135], v[20:23]
	v_mfma_f32_16x16x32_bf16 v[52:55], v[224:227], v[196:199], v[52:55]
	v_mfma_f32_16x16x32_bf16 v[96:99], v[220:223], v[192:195], v[96:99]
	v_mfma_f32_16x16x32_bf16 v[100:103], v[216:219], v[200:203], v[100:103]
	v_mfma_f32_16x16x32_bf16 v[108:111], v[228:231], v[204:207], v[108:111]
	v_mfma_f32_16x16x32_bf16 v[88:91], v[224:227], v[212:215], v[88:91]
	v_mfma_f32_16x16x32_bf16 v[92:95], v[228:231], v[212:215], v[92:95]
	v_mfma_f32_16x16x32_bf16 v[96:99], v[228:231], v[196:199], v[96:99]
	v_mfma_f32_16x16x32_bf16 v[100:103], v[224:227], v[204:207], v[100:103]
	s_setprio 0
	s_barrier
; #define STAGE(P, BASE, br, kt) do { const char* _gb = (const char*)(BASE) + ((size_t)(br) * K + (size_t)(kt) * BK) * 2; \
;     __builtin_amdgcn_global_load_lds((const unsigned*)(_gb + loff0), (unsigned*)((char*)(P) + tid * 16), 16, 0, 0); \
;     __builtin_amdgcn_global_load_lds((const unsigned*)(_gb + (size_t)K * 128 + loff0), (unsigned*)((char*)(P) + tid * 16 + 8192), 16, 0, 0); } while (0)
; #define LDA(dst, b, h) for (int m = 0; m < 4; ++m) { \
;     dst[m][0] = *reinterpret_cast<const bf16x8*>((char*)SA(b, h) + aoff0 + m * 2048); \
;     dst[m][1] = *reinterpret_cast<const bf16x8*>((char*)SA(b, h) + aoff1 + m * 2048); }
; #define LDB(dst, b, h) for (int n = 0; n < 2; ++n) { \
;     dst[n][0] = *reinterpret_cast<const bf16x8*>((char*)SB(b, h) + boff0 + n * 256); \
;     dst[n][1] = *reinterpret_cast<const bf16x8*>((char*)SB(b, h) + boff1 + n * 256); }
; #define MMA(ai, bj, At, Btf) do { __builtin_amdgcn_s_setprio(1); \
;     for (int m = 0; m < 4; ++m) for (int n = 0; n < 2; ++n) for (int k = 0; k < 2; ++k) \
;       acc[ai][bj][m][n] = __builtin_amdgcn_mfma_f32_16x16x32_bf16(Btf[n][k], At[m][k], acc[ai][bj][m][n], 0, 0, 0); \
;     __builtin_amdgcn_s_setprio(0); } while (0)
; #define WAIT_L(n) asm volatile("s_waitcnt lgkmcnt(" #n ")" ::: "memory")
; #define BAR __builtin_amdgcn_s_barrier()
; #define SCHED __builtin_amdgcn_sched_barrier(0)
; template <int EPI> ...
;     ...
;     LDB(B0, 1, 0); SCHED; LDA(At, 1, 0); STAGE(SA(0, 1), A, brow + HALF, t + 2);
;     WAIT_L(8); BAR; WAIT_L(0); MMA(0, 0, At, B0); BAR; SCHED;
;     LDB(B1, 1, 1); STAGE(SB(1, 0), Bt, bcol, t + 3);
;     BAR; WAIT_L(0); MMA(0, 1, At, B1); BAR;
;     LDA(At, 1, 1); STAGE(SA(1, 0), A, brow, t + 3);
;     BAR; WAIT_L(0); MMA(1, 0, At, B0); BAR; SCHED;
;     STAGE(SB(1, 1), Bt, bcol + HALF, t + 3);
	ds_read_b128 v[112:115], v172
	ds_read_b128 v[116:119], v172 offset:256
	ds_read_b128 v[120:123], v173
	ds_read_b128 v[124:127], v173 offset:256
	v_readfirstlane_b32 s64, v162
	v_lshl_add_u64 v[138:139], v[0:1], 0, s[36:37]
	s_mov_b32 m0, s64
	v_readfirstlane_b32 s64, v163
	ds_read_b128 v[128:131], v154 offset:32768
	ds_read_b128 v[132:135], v154 offset:33792
	ds_read_b128 v[192:195], v154 offset:34816
	ds_read_b128 v[196:199], v154 offset:35840
	ds_read_b128 v[200:203], v154 offset:36864
	ds_read_b128 v[204:207], v154 offset:37888
	ds_read_b128 v[208:211], v154 offset:38912
	ds_read_b128 v[212:215], v154 offset:39936
	global_load_lds_dwordx4 v[138:139], off
	v_lshl_add_u64 v[138:139], v[0:1], 0, s[38:39]
	s_mov_b32 m0, s64
	s_nop 0
	global_load_lds_dwordx4 v[138:139], off
	s_waitcnt lgkmcnt(8)
	s_barrier
	s_waitcnt lgkmcnt(0)
	s_setprio 1
	v_mfma_f32_16x16x32_bf16 v[56:59], v[112:115], v[128:131], v[56:59]
	v_mfma_f32_16x16x32_bf16 v[60:63], v[116:119], v[128:131], v[60:63]
	v_mfma_f32_16x16x32_bf16 v[64:67], v[112:115], v[192:195], v[64:67]
	v_mfma_f32_16x16x32_bf16 v[68:71], v[116:119], v[192:195], v[68:71]
	v_mfma_f32_16x16x32_bf16 v[72:75], v[112:115], v[200:203], v[72:75]
	v_mfma_f32_16x16x32_bf16 v[76:79], v[116:119], v[200:203], v[76:79]
	v_mfma_f32_16x16x32_bf16 v[80:83], v[112:115], v[208:211], v[80:83]
	v_mfma_f32_16x16x32_bf16 v[84:87], v[116:119], v[208:211], v[84:87]
	v_mfma_f32_16x16x32_bf16 v[56:59], v[120:123], v[132:135], v[56:59]
	v_mfma_f32_16x16x32_bf16 v[60:63], v[124:127], v[132:135], v[60:63]
	v_mfma_f32_16x16x32_bf16 v[64:67], v[120:123], v[196:199], v[64:67]
	v_mfma_f32_16x16x32_bf16 v[68:71], v[124:127], v[196:199], v[68:71]
	v_mfma_f32_16x16x32_bf16 v[72:75], v[120:123], v[204:207], v[72:75]
	v_mfma_f32_16x16x32_bf16 v[76:79], v[124:127], v[204:207], v[76:79]
	v_mfma_f32_16x16x32_bf16 v[80:83], v[120:123], v[212:215], v[80:83]
	v_mfma_f32_16x16x32_bf16 v[84:87], v[124:127], v[212:215], v[84:87]
	s_setprio 0
	s_barrier
	s_mov_b32 m0, s54
	v_lshl_add_u64 v[138:139], v[6:7], 0, s[46:47]
	ds_read_b128 v[216:219], v174
	ds_read_b128 v[220:223], v174 offset:256
	ds_read_b128 v[224:227], v175
	ds_read_b128 v[228:231], v175 offset:256
	global_load_lds_dwordx4 v[138:139], off
	v_lshl_add_u64 v[6:7], v[6:7], 0, s[48:49]
	s_mov_b32 m0, s51
	s_nop 0
	global_load_lds_dwordx4 v[6:7], off
	s_barrier
	s_waitcnt lgkmcnt(0)
	s_setprio 1
	s_waitcnt lgkmcnt(0)
	v_mfma_f32_16x16x32_bf16 v[104:107], v[216:219], v[128:131], v[104:107]
	v_mfma_f32_16x16x32_bf16 v[24:27], v[220:223], v[128:131], v[24:27]
	v_mfma_f32_16x16x32_bf16 v[28:31], v[216:219], v[192:195], v[28:31]
	v_mfma_f32_16x16x32_bf16 v[32:35], v[220:223], v[192:195], v[32:35]
	v_mfma_f32_16x16x32_bf16 v[36:39], v[216:219], v[200:203], v[36:39]
	v_mfma_f32_16x16x32_bf16 v[40:43], v[220:223], v[200:203], v[40:43]
	v_mfma_f32_16x16x32_bf16 v[44:47], v[216:219], v[208:211], v[44:47]
	v_mfma_f32_16x16x32_bf16 v[48:51], v[220:223], v[208:211], v[48:51]
	v_mfma_f32_16x16x32_bf16 v[104:107], v[224:227], v[132:135], v[104:107]
	v_mfma_f32_16x16x32_bf16 v[24:27], v[228:231], v[132:135], v[24:27]
	v_mfma_f32_16x16x32_bf16 v[28:31], v[224:227], v[196:199], v[28:31]
	v_mfma_f32_16x16x32_bf16 v[32:35], v[228:231], v[196:199], v[32:35]
	v_mfma_f32_16x16x32_bf16 v[36:39], v[224:227], v[204:207], v[36:39]
	v_mfma_f32_16x16x32_bf16 v[40:43], v[228:231], v[204:207], v[40:43]
	v_mfma_f32_16x16x32_bf16 v[44:47], v[224:227], v[212:215], v[44:47]
	v_mfma_f32_16x16x32_bf16 v[48:51], v[228:231], v[212:215], v[48:51]
	s_setprio 0
	s_mov_b32 m0, s62
	v_lshl_add_u64 v[6:7], v[4:5], 0, s[46:47]
	s_barrier
	ds_read_b128 v[128:131], v154 offset:49152
	ds_read_b128 v[132:135], v154 offset:50176
	ds_read_b128 v[192:195], v154 offset:51200
	ds_read_b128 v[196:199], v154 offset:52224
	ds_read_b128 v[200:203], v154 offset:53248
	ds_read_b128 v[204:207], v154 offset:54272
	ds_read_b128 v[208:211], v154 offset:55296
	ds_read_b128 v[212:215], v154 offset:56320
	global_load_lds_dwordx4 v[6:7], off
	v_lshl_add_u64 v[4:5], v[4:5], 0, s[48:49]
	s_mov_b32 m0, s55
	s_nop 0
	global_load_lds_dwordx4 v[4:5], off
	s_barrier
	s_waitcnt lgkmcnt(0)
	s_setprio 1
	v_mfma_f32_16x16x32_bf16 v[4:7], v[112:115], v[128:131], v[142:145]
	v_mfma_f32_16x16x32_bf16 v[8:11], v[112:115], v[208:211], v[8:11]
	v_mfma_f32_16x16x32_bf16 v[12:15], v[116:119], v[208:211], v[12:15]
	v_mfma_f32_16x16x32_bf16 v[4:7], v[120:123], v[132:135], v[4:7]
	v_mfma_f32_16x16x32_bf16 v[142:145], v[116:119], v[128:131], v[146:149]
	v_mfma_f32_16x16x32_bf16 v[146:149], v[112:115], v[192:195], v[150:153]
	v_mfma_f32_16x16x32_bf16 v[150:153], v[116:119], v[192:195], v[180:183]
	v_mfma_f32_16x16x32_bf16 v[180:183], v[112:115], v[200:203], v[184:187]
	v_mfma_f32_16x16x32_bf16 v[184:187], v[116:119], v[200:203], v[188:191]
	v_mfma_f32_16x16x32_bf16 v[8:11], v[120:123], v[212:215], v[8:11]
	v_mfma_f32_16x16x32_bf16 v[12:15], v[124:127], v[212:215], v[12:15]
	v_mfma_f32_16x16x32_bf16 v[142:145], v[124:127], v[132:135], v[142:145]
	v_mfma_f32_16x16x32_bf16 v[146:149], v[120:123], v[196:199], v[146:149]
	v_mfma_f32_16x16x32_bf16 v[150:153], v[124:127], v[196:199], v[150:153]
	v_mfma_f32_16x16x32_bf16 v[180:183], v[120:123], v[204:207], v[180:183]
	v_mfma_f32_16x16x32_bf16 v[184:187], v[124:127], v[204:207], v[184:187]
	s_setprio 0
	s_barrier
	s_mov_b32 m0, s60
	v_lshl_add_u64 v[112:113], v[2:3], 0, s[46:47]
	global_load_lds_dwordx4 v[112:113], off
	v_lshl_add_u64 v[2:3], v[2:3], 0, s[48:49]
	s_mov_b32 m0, s59
	s_nop 0
	global_load_lds_dwordx4 v[2:3], off
	s_waitcnt vmcnt(6)
	s_barrier
; #define STAGE(P, BASE, br, kt) do { const char* _gb = (const char*)(BASE) + ((size_t)(br) * K + (size_t)(kt) * BK) * 2; \
;     __builtin_amdgcn_global_load_lds((const unsigned*)(_gb + loff0), (unsigned*)((char*)(P) + tid * 16), 16, 0, 0); \
;     __builtin_amdgcn_global_load_lds((const unsigned*)(_gb + (size_t)K * 128 + loff0), (unsigned*)((char*)(P) + tid * 16 + 8192), 16, 0, 0); } while (0)
; #define LDA(dst, b, h) for (int m = 0; m < 4; ++m) { \
;     dst[m][0] = *reinterpret_cast<const bf16x8*>((char*)SA(b, h) + aoff0 + m * 2048); \
;     dst[m][1] = *reinterpret_cast<const bf16x8*>((char*)SA(b, h) + aoff1 + m * 2048); }
; #define LDB(dst, b, h) for (int n = 0; n < 2; ++n) { \
;     dst[n][0] = *reinterpret_cast<const bf16x8*>((char*)SB(b, h) + boff0 + n * 256); \
;     dst[n][1] = *reinterpret_cast<const bf16x8*>((char*)SB(b, h) + boff1 + n * 256); }
; #define MMA(ai, bj, At, Btf) do { __builtin_amdgcn_s_setprio(1); \
;     for (int m = 0; m < 4; ++m) for (int n = 0; n < 2; ++n) for (int k = 0; k < 2; ++k) \
;       acc[ai][bj][m][n] = __builtin_amdgcn_mfma_f32_16x16x32_bf16(Btf[n][k], At[m][k], acc[ai][bj][m][n], 0, 0, 0); \
;     __builtin_amdgcn_s_setprio(0); } while (0)
; #define WAIT_V(n) asm volatile("s_waitcnt vmcnt(" #n ")" ::: "memory")
; #define WAIT_L(n) asm volatile("s_waitcnt lgkmcnt(" #n ")" ::: "memory")
; #define BAR __builtin_amdgcn_s_barrier()
; template <int EPI> ...
;     ...
;     WAIT_V(6); BAR; MMA(1, 1, At, B1); BAR;
;   }
;   { LDB(B0, 0, 0); LDA(At, 0, 0); STAGE(SA(1, 1), A, brow + HALF, nt - 1);
;     BAR; WAIT_L(0); MMA(0, 0, At, B0); BAR;
;     LDB(B1, 0, 1); BAR; WAIT_L(0); MMA(0, 1, At, B1); BAR;
;     LDA(At, 0, 1); WAIT_V(4); BAR; WAIT_L(0); MMA(1, 0, At, B0); MMA(1, 1, At, B1); BAR; }
	s_setprio 1
	v_mfma_f32_16x16x32_bf16 v[16:19], v[216:219], v[128:131], v[16:19]
	v_mfma_f32_16x16x32_bf16 v[20:23], v[220:223], v[128:131], v[20:23]
	v_mfma_f32_16x16x32_bf16 v[52:55], v[216:219], v[192:195], v[52:55]
	v_mfma_f32_16x16x32_bf16 v[108:111], v[220:223], v[200:203], v[108:111]
	v_mfma_f32_16x16x32_bf16 v[88:91], v[216:219], v[208:211], v[88:91]
	v_mfma_f32_16x16x32_bf16 v[92:95], v[220:223], v[208:211], v[92:95]
	v_mfma_f32_16x16x32_bf16 v[16:19], v[224:227], v[132:135], v[16:19]
	v_mfma_f32_16x16x32_bf16 v[20:23], v[228:231], v[132:135], v[20:23]
	v_mfma_f32_16x16x32_bf16 v[52:55], v[224:227], v[196:199], v[52:55]
	v_mfma_f32_16x16x32_bf16 v[96:99], v[220:223], v[192:195], v[96:99]
	v_mfma_f32_16x16x32_bf16 v[100:103], v[216:219], v[200:203], v[100:103]
	v_mfma_f32_16x16x32_bf16 v[108:111], v[228:231], v[204:207], v[108:111]
	v_mfma_f32_16x16x32_bf16 v[88:91], v[224:227], v[212:215], v[88:91]
	v_mfma_f32_16x16x32_bf16 v[92:95], v[228:231], v[212:215], v[92:95]
	v_mfma_f32_16x16x32_bf16 v[96:99], v[228:231], v[196:199], v[96:99]
	v_mfma_f32_16x16x32_bf16 v[100:103], v[224:227], v[204:207], v[100:103]
	s_setprio 0
	s_mov_b32 m0, s63
	v_lshl_add_u64 v[2:3], v[0:1], 0, s[46:47]
	s_barrier
	ds_read_b128 v[112:115], v176
	ds_read_b128 v[116:119], v176 offset:256
	ds_read_b128 v[120:123], v177
	ds_read_b128 v[124:127], v177 offset:256
	ds_read_b128 v[128:131], v154
	ds_read_b128 v[132:135], v154 offset:1024
	ds_read_b128 v[188:191], v154 offset:2048
	ds_read_b128 v[192:195], v154 offset:3072
	ds_read_b128 v[196:199], v154 offset:4096
	ds_read_b128 v[200:203], v154 offset:5120
	ds_read_b128 v[204:207], v154 offset:6144
	ds_read_b128 v[208:211], v154 offset:7168
	global_load_lds_dwordx4 v[2:3], off
	v_lshl_add_u64 v[0:1], v[0:1], 0, s[48:49]
	s_mov_b32 m0, s61
	s_nop 0
	global_load_lds_dwordx4 v[0:1], off
	s_barrier
	s_waitcnt lgkmcnt(0)
	s_setprio 1
	v_mfma_f32_16x16x32_bf16 v[0:3], v[112:115], v[128:131], v[56:59]
	v_mfma_f32_16x16x32_bf16 v[56:59], v[116:119], v[128:131], v[60:63]
	v_mfma_f32_16x16x32_bf16 v[60:63], v[112:115], v[188:191], v[64:67]
	v_mfma_f32_16x16x32_bf16 v[64:67], v[116:119], v[188:191], v[68:71]
	v_mfma_f32_16x16x32_bf16 v[68:71], v[112:115], v[196:199], v[72:75]
	v_mfma_f32_16x16x32_bf16 v[72:75], v[116:119], v[196:199], v[76:79]
	v_mfma_f32_16x16x32_bf16 v[76:79], v[112:115], v[204:207], v[80:83]
	v_mfma_f32_16x16x32_bf16 v[80:83], v[116:119], v[204:207], v[84:87]
	v_mfma_f32_16x16x32_bf16 v[0:3], v[120:123], v[132:135], v[0:3]
	v_mfma_f32_16x16x32_bf16 v[56:59], v[124:127], v[132:135], v[56:59]
	v_mfma_f32_16x16x32_bf16 v[60:63], v[120:123], v[192:195], v[60:63]
	v_mfma_f32_16x16x32_bf16 v[64:67], v[124:127], v[192:195], v[64:67]
	v_mfma_f32_16x16x32_bf16 v[68:71], v[120:123], v[200:203], v[68:71]
	v_mfma_f32_16x16x32_bf16 v[72:75], v[124:127], v[200:203], v[72:75]
	v_mfma_f32_16x16x32_bf16 v[76:79], v[120:123], v[208:211], v[76:79]
	v_mfma_f32_16x16x32_bf16 v[80:83], v[124:127], v[208:211], v[80:83]
	s_setprio 0
	s_barrier
	ds_read_b128 v[84:87], v178
	ds_read_b128 v[212:215], v178 offset:256
	ds_read_b128 v[216:219], v179
	ds_read_b128 v[220:223], v179 offset:256
	s_barrier
	s_waitcnt lgkmcnt(0)
	s_setprio 1
	v_mfma_f32_16x16x32_bf16 v[24:27], v[212:215], v[128:131], v[24:27]
	v_mfma_f32_16x16x32_bf16 v[28:31], v[84:87], v[188:191], v[28:31]
	v_mfma_f32_16x16x32_bf16 v[32:35], v[212:215], v[188:191], v[32:35]
	v_mfma_f32_16x16x32_bf16 v[36:39], v[84:87], v[196:199], v[36:39]
	v_mfma_f32_16x16x32_bf16 v[40:43], v[212:215], v[196:199], v[40:43]
	v_mfma_f32_16x16x32_bf16 v[44:47], v[84:87], v[204:207], v[44:47]
	v_mfma_f32_16x16x32_bf16 v[48:51], v[212:215], v[204:207], v[48:51]
	v_mfma_f32_16x16x32_bf16 v[104:107], v[84:87], v[128:131], v[104:107]
	v_mfma_f32_16x16x32_bf16 v[24:27], v[220:223], v[132:135], v[24:27]
	v_mfma_f32_16x16x32_bf16 v[28:31], v[216:219], v[192:195], v[28:31]
	v_mfma_f32_16x16x32_bf16 v[32:35], v[220:223], v[192:195], v[32:35]
	v_mfma_f32_16x16x32_bf16 v[36:39], v[216:219], v[200:203], v[36:39]
	v_mfma_f32_16x16x32_bf16 v[40:43], v[220:223], v[200:203], v[40:43]
	v_mfma_f32_16x16x32_bf16 v[44:47], v[216:219], v[208:211], v[44:47]
	v_mfma_f32_16x16x32_bf16 v[48:51], v[220:223], v[208:211], v[48:51]
	v_mfma_f32_16x16x32_bf16 v[224:227], v[216:219], v[132:135], v[104:107]
	s_setprio 0
	s_barrier
	s_nop 0
	ds_read_b128 v[104:107], v154 offset:16384
	ds_read_b128 v[128:131], v154 offset:17408
	ds_read_b128 v[132:135], v154 offset:18432
	ds_read_b128 v[188:191], v154 offset:19456
	ds_read_b128 v[192:195], v154 offset:20480
	ds_read_b128 v[196:199], v154 offset:21504
	ds_read_b128 v[200:203], v154 offset:22528
	ds_read_b128 v[204:207], v154 offset:23552
	s_waitcnt vmcnt(4)
	s_barrier
; #define LDA(dst, b, h) for (int m = 0; m < 4; ++m) { \
;     dst[m][0] = *reinterpret_cast<const bf16x8*>((char*)SA(b, h) + aoff0 + m * 2048); \
;     dst[m][1] = *reinterpret_cast<const bf16x8*>((char*)SA(b, h) + aoff1 + m * 2048); }
; #define LDB(dst, b, h) for (int n = 0; n < 2; ++n) { \
;     dst[n][0] = *reinterpret_cast<const bf16x8*>((char*)SB(b, h) + boff0 + n * 256); \
;     dst[n][1] = *reinterpret_cast<const bf16x8*>((char*)SB(b, h) + boff1 + n * 256); }
; #define MMA(ai, bj, At, Btf) do { __builtin_amdgcn_s_setprio(1); \
;     for (int m = 0; m < 4; ++m) for (int n = 0; n < 2; ++n) for (int k = 0; k < 2; ++k) \
;       acc[ai][bj][m][n] = __builtin_amdgcn_mfma_f32_16x16x32_bf16(Btf[n][k], At[m][k], acc[ai][bj][m][n], 0, 0, 0); \
;     __builtin_amdgcn_s_setprio(0); } while (0)
; #define WAIT_V(n) asm volatile("s_waitcnt vmcnt(" #n ")" ::: "memory")
; #define WAIT_L(n) asm volatile("s_waitcnt lgkmcnt(" #n ")" ::: "memory")
; #define BAR __builtin_amdgcn_s_barrier()
; template <int EPI> ...
;     ...
;     LDA(At, 0, 1); WAIT_V(4); BAR; WAIT_L(0); MMA(1, 0, At, B0); MMA(1, 1, At, B1); BAR; }
;   { LDB(B0, 1, 0); LDA(At, 1, 0); WAIT_V(2); BAR; WAIT_L(0); MMA(0, 0, At, B0); BAR;
	s_waitcnt lgkmcnt(0)
	s_setprio 1
	v_mfma_f32_16x16x32_bf16 v[4:7], v[112:115], v[104:107], v[4:7]
	v_mfma_f32_16x16x32_bf16 v[8:11], v[112:115], v[200:203], v[8:11]
	v_mfma_f32_16x16x32_bf16 v[4:7], v[120:123], v[128:131], v[4:7]
	v_mfma_f32_16x16x32_bf16 v[142:145], v[116:119], v[104:107], v[142:145]
	v_mfma_f32_16x16x32_bf16 v[146:149], v[112:115], v[132:135], v[146:149]
	v_mfma_f32_16x16x32_bf16 v[150:153], v[116:119], v[132:135], v[150:153]
	v_mfma_f32_16x16x32_bf16 v[180:183], v[112:115], v[192:195], v[180:183]
	v_mfma_f32_16x16x32_bf16 v[184:187], v[116:119], v[192:195], v[184:187]
	v_mfma_f32_16x16x32_bf16 v[8:11], v[120:123], v[204:207], v[8:11]
	v_mfma_f32_16x16x32_bf16 v[12:15], v[116:119], v[200:203], v[12:15]
	v_mfma_f32_16x16x32_bf16 v[142:145], v[124:127], v[128:131], v[142:145]
	v_mfma_f32_16x16x32_bf16 v[146:149], v[120:123], v[188:191], v[146:149]
	v_mfma_f32_16x16x32_bf16 v[150:153], v[124:127], v[188:191], v[150:153]
	v_mfma_f32_16x16x32_bf16 v[180:183], v[120:123], v[196:199], v[180:183]
	v_mfma_f32_16x16x32_bf16 v[184:187], v[124:127], v[196:199], v[184:187]
	v_mfma_f32_16x16x32_bf16 v[208:211], v[124:127], v[204:207], v[12:15]
	v_mfma_f32_16x16x32_bf16 v[12:15], v[84:87], v[104:107], v[16:19]
	v_mfma_f32_16x16x32_bf16 v[228:231], v[216:219], v[128:131], v[12:15]
	v_mfma_f32_16x16x32_bf16 v[12:15], v[212:215], v[104:107], v[20:23]
	v_mfma_f32_16x16x32_bf16 v[232:235], v[220:223], v[128:131], v[12:15]
	v_mfma_f32_16x16x32_bf16 v[12:15], v[84:87], v[132:135], v[52:55]
	v_mfma_f32_16x16x32_bf16 v[52:55], v[216:219], v[188:191], v[12:15]
	v_mfma_f32_16x16x32_bf16 v[12:15], v[212:215], v[132:135], v[96:99]
	v_mfma_f32_16x16x32_bf16 v[96:99], v[220:223], v[188:191], v[12:15]
	v_mfma_f32_16x16x32_bf16 v[12:15], v[84:87], v[192:195], v[100:103]
	v_mfma_f32_16x16x32_bf16 v[100:103], v[216:219], v[196:199], v[12:15]
	v_mfma_f32_16x16x32_bf16 v[12:15], v[212:215], v[192:195], v[108:111]
	v_mfma_f32_16x16x32_bf16 v[188:191], v[220:223], v[196:199], v[12:15]
	v_mfma_f32_16x16x32_bf16 v[12:15], v[84:87], v[200:203], v[88:91]
	v_mfma_f32_16x16x32_bf16 v[192:195], v[216:219], v[204:207], v[12:15]
	v_mfma_f32_16x16x32_bf16 v[12:15], v[212:215], v[200:203], v[92:95]
	v_mfma_f32_16x16x32_bf16 v[196:199], v[220:223], v[204:207], v[12:15]
	s_setprio 0
	s_barrier
	ds_read_b128 v[88:91], v172
	ds_read_b128 v[92:95], v172 offset:256
	ds_read_b128 v[200:203], v173
	ds_read_b128 v[204:207], v173 offset:256
	ds_read_b128 v[16:19], v154 offset:32768
	ds_read_b128 v[20:23], v154 offset:33792
	ds_read_b128 v[84:87], v154 offset:34816
	ds_read_b128 v[212:215], v154 offset:35840
	ds_read_b128 v[216:219], v154 offset:36864
	ds_read_b128 v[220:223], v154 offset:37888
	ds_read_b128 v[236:239], v154 offset:38912
	ds_read_b128 v[240:243], v154 offset:39936
	s_waitcnt vmcnt(2)
	s_barrier
	s_waitcnt lgkmcnt(0)
	s_setprio 1
	v_mfma_f32_16x16x32_bf16 v[0:3], v[88:91], v[16:19], v[0:3]
	v_mfma_f32_16x16x32_bf16 v[104:107], v[200:203], v[20:23], v[0:3]
	v_mfma_f32_16x16x32_bf16 v[0:3], v[92:95], v[16:19], v[56:59]
	v_mfma_f32_16x16x32_bf16 v[108:111], v[204:207], v[20:23], v[0:3]
	v_mfma_f32_16x16x32_bf16 v[0:3], v[88:91], v[84:87], v[60:63]
	v_mfma_f32_16x16x32_bf16 v[112:115], v[200:203], v[212:215], v[0:3]
	v_mfma_f32_16x16x32_bf16 v[0:3], v[92:95], v[84:87], v[64:67]
	v_mfma_f32_16x16x32_bf16 v[116:119], v[204:207], v[212:215], v[0:3]
	v_mfma_f32_16x16x32_bf16 v[0:3], v[88:91], v[216:219], v[68:71]
	v_mfma_f32_16x16x32_bf16 v[120:123], v[200:203], v[220:223], v[0:3]
	v_mfma_f32_16x16x32_bf16 v[0:3], v[92:95], v[216:219], v[72:75]
	v_mfma_f32_16x16x32_bf16 v[124:127], v[204:207], v[220:223], v[0:3]
	v_mfma_f32_16x16x32_bf16 v[0:3], v[88:91], v[236:239], v[76:79]
	v_mfma_f32_16x16x32_bf16 v[128:131], v[200:203], v[240:243], v[0:3]
	v_mfma_f32_16x16x32_bf16 v[0:3], v[92:95], v[236:239], v[80:83]
	v_mfma_f32_16x16x32_bf16 v[132:135], v[204:207], v[240:243], v[0:3]
	s_setprio 0
	s_barrier
; #define LDA(dst, b, h) for (int m = 0; m < 4; ++m) { \
;     dst[m][0] = *reinterpret_cast<const bf16x8*>((char*)SA(b, h) + aoff0 + m * 2048); \
;     dst[m][1] = *reinterpret_cast<const bf16x8*>((char*)SA(b, h) + aoff1 + m * 2048); }
; #define LDB(dst, b, h) for (int n = 0; n < 2; ++n) { \
;     dst[n][0] = *reinterpret_cast<const bf16x8*>((char*)SB(b, h) + boff0 + n * 256); \
;     dst[n][1] = *reinterpret_cast<const bf16x8*>((char*)SB(b, h) + boff1 + n * 256); }
; #define MMA(ai, bj, At, Btf) do { __builtin_amdgcn_s_setprio(1); \
;     for (int m = 0; m < 4; ++m) for (int n = 0; n < 2; ++n) for (int k = 0; k < 2; ++k) \
;       acc[ai][bj][m][n] = __builtin_amdgcn_mfma_f32_16x16x32_bf16(Btf[n][k], At[m][k], acc[ai][bj][m][n], 0, 0, 0); \
;     __builtin_amdgcn_s_setprio(0); } while (0)
; #define WAIT_V(n) asm volatile("s_waitcnt vmcnt(" #n ")" ::: "memory")
; #define WAIT_L(n) asm volatile("s_waitcnt lgkmcnt(" #n ")" ::: "memory")
; #define BAR __builtin_amdgcn_s_barrier()
; template <int EPI> ...
;     ...
;     LDB(B1, 1, 1); WAIT_V(0); BAR; WAIT_L(0); MMA(0, 1, At, B1); BAR;
;     LDA(At, 1, 1); BAR; WAIT_L(0); MMA(1, 0, At, B0); MMA(1, 1, At, B1); BAR; }
;   if (wr == 0) BAR;
	s_nop 4
	ds_read_b128 v[0:3], v174
	ds_read_b128 v[244:247], v174 offset:256
	ds_read_b128 v[248:251], v175
	ds_read_b128 v[138:141], v175 offset:256
	s_waitcnt vmcnt(0)
	s_barrier
	s_waitcnt lgkmcnt(0)
	s_setprio 1
	v_mfma_f32_16x16x32_bf16 v[12:15], v[0:3], v[16:19], v[224:227]
	v_mfma_f32_16x16x32_bf16 v[16:19], v[244:247], v[16:19], v[24:27]
	v_mfma_f32_16x16x32_bf16 v[12:15], v[248:251], v[20:23], v[12:15]
	v_mfma_f32_16x16x32_bf16 v[16:19], v[138:141], v[20:23], v[16:19]
	v_mfma_f32_16x16x32_bf16 v[20:23], v[0:3], v[84:87], v[28:31]
	v_mfma_f32_16x16x32_bf16 v[24:27], v[244:247], v[84:87], v[32:35]
	v_mfma_f32_16x16x32_bf16 v[28:31], v[0:3], v[216:219], v[36:39]
	v_mfma_f32_16x16x32_bf16 v[32:35], v[244:247], v[216:219], v[40:43]
	v_mfma_f32_16x16x32_bf16 v[36:39], v[0:3], v[236:239], v[44:47]
	v_mfma_f32_16x16x32_bf16 v[40:43], v[244:247], v[236:239], v[48:51]
	v_mfma_f32_16x16x32_bf16 v[20:23], v[248:251], v[212:215], v[20:23]
	v_mfma_f32_16x16x32_bf16 v[24:27], v[138:141], v[212:215], v[24:27]
	v_mfma_f32_16x16x32_bf16 v[28:31], v[248:251], v[220:223], v[28:31]
	v_mfma_f32_16x16x32_bf16 v[32:35], v[138:141], v[220:223], v[32:35]
	v_mfma_f32_16x16x32_bf16 v[36:39], v[248:251], v[240:243], v[36:39]
	v_mfma_f32_16x16x32_bf16 v[40:43], v[138:141], v[240:243], v[40:43]
	s_setprio 0
	s_barrier
	ds_read_b128 v[44:47], v154 offset:49152
	ds_read_b128 v[48:51], v154 offset:50176
	ds_read_b128 v[212:215], v154 offset:51200
	ds_read_b128 v[216:219], v154 offset:52224
	ds_read_b128 v[220:223], v154 offset:53248
	ds_read_b128 v[224:227], v154 offset:54272
	ds_read_b128 v[236:239], v154 offset:55296
	ds_read_b128 v[240:243], v154 offset:56320
	s_barrier
	s_waitcnt lgkmcnt(0)
	s_setprio 1
	v_mfma_f32_16x16x32_bf16 v[4:7], v[88:91], v[44:47], v[4:7]
	v_mfma_f32_16x16x32_bf16 v[64:67], v[200:203], v[48:51], v[4:7]
	v_mfma_f32_16x16x32_bf16 v[4:7], v[92:95], v[44:47], v[142:145]
	v_mfma_f32_16x16x32_bf16 v[68:71], v[204:207], v[48:51], v[4:7]
	v_mfma_f32_16x16x32_bf16 v[4:7], v[88:91], v[212:215], v[146:149]
	v_mfma_f32_16x16x32_bf16 v[72:75], v[200:203], v[216:219], v[4:7]
	v_mfma_f32_16x16x32_bf16 v[4:7], v[92:95], v[212:215], v[150:153]
	v_mfma_f32_16x16x32_bf16 v[76:79], v[204:207], v[216:219], v[4:7]
	v_mfma_f32_16x16x32_bf16 v[4:7], v[88:91], v[220:223], v[180:183]
	v_mfma_f32_16x16x32_bf16 v[80:83], v[200:203], v[224:227], v[4:7]
	v_mfma_f32_16x16x32_bf16 v[4:7], v[92:95], v[220:223], v[184:187]
	v_mfma_f32_16x16x32_bf16 v[84:87], v[204:207], v[224:227], v[4:7]
	v_mfma_f32_16x16x32_bf16 v[4:7], v[88:91], v[236:239], v[8:11]
	v_mfma_f32_16x16x32_bf16 v[88:91], v[200:203], v[240:243], v[4:7]
	v_mfma_f32_16x16x32_bf16 v[4:7], v[92:95], v[236:239], v[208:211]
	v_mfma_f32_16x16x32_bf16 v[92:95], v[204:207], v[240:243], v[4:7]
	v_mfma_f32_16x16x32_bf16 v[4:7], v[0:3], v[44:47], v[228:231]
	v_mfma_f32_16x16x32_bf16 v[60:63], v[248:251], v[48:51], v[4:7]
	v_mfma_f32_16x16x32_bf16 v[4:7], v[244:247], v[44:47], v[232:235]
	v_mfma_f32_16x16x32_bf16 v[56:59], v[138:141], v[48:51], v[4:7]
	v_mfma_f32_16x16x32_bf16 v[4:7], v[0:3], v[212:215], v[52:55]
	v_mfma_f32_16x16x32_bf16 v[52:55], v[248:251], v[216:219], v[4:7]
	v_mfma_f32_16x16x32_bf16 v[4:7], v[244:247], v[212:215], v[96:99]
	v_mfma_f32_16x16x32_bf16 v[48:51], v[138:141], v[216:219], v[4:7]
	v_mfma_f32_16x16x32_bf16 v[4:7], v[0:3], v[220:223], v[100:103]
	v_mfma_f32_16x16x32_bf16 v[44:47], v[248:251], v[224:227], v[4:7]
	v_mfma_f32_16x16x32_bf16 v[4:7], v[244:247], v[220:223], v[188:191]
	v_mfma_f32_16x16x32_bf16 v[0:3], v[0:3], v[236:239], v[192:195]
	v_mfma_f32_16x16x32_bf16 v[8:11], v[138:141], v[224:227], v[4:7]
	v_mfma_f32_16x16x32_bf16 v[4:7], v[248:251], v[240:243], v[0:3]
	v_mfma_f32_16x16x32_bf16 v[0:3], v[244:247], v[236:239], v[196:199]
	v_mfma_f32_16x16x32_bf16 v[0:3], v[138:141], v[240:243], v[0:3]
	s_setprio 0
	s_barrier
	s_and_saveexec_b64 s[54:55], s[2:3]
	s_cbranch_execz .LBB0_821
	s_barrier
	s_branch .LBB0_821

; #define STAGE(P, BASE, br, kt) do { const char* _gb = (const char*)(BASE) + ((size_t)(br) * K + (size_t)(kt) * BK) * 2; \
;     __builtin_amdgcn_global_load_lds((const unsigned*)(_gb + loff0), (unsigned*)((char*)(P) + tid * 16), 16, 0, 0); \
;     __builtin_amdgcn_global_load_lds((const unsigned*)(_gb + (size_t)K * 128 + loff0), (unsigned*)((char*)(P) + tid * 16 + 8192), 16, 0, 0); } while (0)
; #define LDA(dst, b, h) for (int m = 0; m < 4; ++m) { \
;     dst[m][0] = *reinterpret_cast<const bf16x8*>((char*)SA(b, h) + aoff0 + m * 2048); \
;     dst[m][1] = *reinterpret_cast<const bf16x8*>((char*)SA(b, h) + aoff1 + m * 2048); }
; #define WAIT_V(n) asm volatile("s_waitcnt vmcnt(" #n ")" ::: "memory")
; #define WAIT_L(n) asm volatile("s_waitcnt lgkmcnt(" #n ")" ::: "memory")
; #define BAR __builtin_amdgcn_s_barrier()
; template <int EPI> ...
;     ...
;   STAGE(SB(0, 0), Bt, bcol, 0); STAGE(SA(0, 0), A, brow, 0);
;   STAGE(SB(0, 1), Bt, bcol + HALF, 0); STAGE(SA(0, 1), A, brow + HALF, 0);
;   if (wr == 1) BAR;
;   WAIT_V(4); BAR;
;   STAGE(SB(1, 0), Bt, bcol, 1); STAGE(SA(1, 0), A, brow, 1); STAGE(SB(1, 1), Bt, bcol + HALF, 1);
;   WAIT_V(6); BAR;
;   for (int t = 0; t < nt - 2; t += 2) {
;     LDB(B0, 0, 0); SCHED; LDA(At, 0, 0); STAGE(SA(1, 1), A, brow + HALF, t + 1);
;     WAIT_L(8); BAR; WAIT_L(0); MMA(0, 0, At, B0); BAR; SCHED;
;     LDB(B1, 0, 1); STAGE(SB(0, 0), Bt, bcol, t + 2);
;     BAR; WAIT_L(0); MMA(0, 1, At, B1); BAR;
;     LDA(At, 0, 1); STAGE(SA(0, 0), A, brow, t + 2);
;     BAR; WAIT_L(0); MMA(1, 0, At, B0); BAR; SCHED;
;     STAGE(SB(0, 1), Bt, bcol + HALF, t + 2);
;     WAIT_V(6); BAR; MMA(1, 1, At, B1); BAR;
;     LDB(B0, 1, 0); SCHED; LDA(At, 1, 0); STAGE(SA(0, 1), A, brow + HALF, t + 2);
;     WAIT_L(8); BAR; WAIT_L(0); MMA(0, 0, At, B0); BAR; SCHED;
;     LDB(B1, 1, 1); STAGE(SB(1, 0), Bt, bcol, t + 3);
;     BAR; WAIT_L(0); MMA(0, 1, At, B1); BAR;
;     LDA(At, 1, 1); STAGE(SA(1, 0), A, brow, t + 3);
;     BAR; WAIT_L(0); MMA(1, 0, At, B0); BAR; SCHED;
;     STAGE(SB(1, 1), Bt, bcol + HALF, t + 3);
;     WAIT_V(6); BAR; MMA(1, 1, At, B1); BAR;
;   }
;   { LDB(B0, 0, 0); LDA(At, 0, 0); STAGE(SA(1, 1), A, brow + HALF, nt - 1);
;     BAR; WAIT_L(0); MMA(0, 0, At, B0); BAR;
;     LDB(B1, 0, 1); BAR; WAIT_L(0); MMA(0, 1, At, B1); BAR;
;     LDA(At, 0, 1); WAIT_V(4); BAR; WAIT_L(0); MMA(1, 0, At, B0); MMA(1, 1, At, B1); BAR; }
.LBB0_834:
	s_or_b64 exec, exec, s[22:23]
	v_readfirstlane_b32 s17, v141
	v_lshl_add_u64 v[6:7], v[0:1], 0, s[10:11]
	s_mov_b32 m0, s17
	s_waitcnt vmcnt(4)
	s_barrier
	global_load_lds_dwordx4 v[6:7], off
	v_add_u32_e32 v6, 0x2000, v141
	v_lshl_add_u64 v[0:1], v[0:1], 0, s[12:13]
	v_readfirstlane_b32 s17, v6
	v_add_u32_e32 v6, 0x8000, v135
	s_mov_b32 m0, s17
	v_readfirstlane_b32 s17, v6
	global_load_lds_dwordx4 v[0:1], off
	v_lshl_add_u64 v[0:1], v[2:3], 0, s[10:11]
	s_mov_b32 m0, s17
	v_readfirstlane_b32 s17, v144
	global_load_lds_dwordx4 v[0:1], off
	v_lshl_add_u64 v[0:1], v[2:3], 0, s[12:13]
	s_mov_b32 m0, s17
	v_readfirstlane_b32 s17, v145
	global_load_lds_dwordx4 v[0:1], off
	v_lshl_add_u64 v[0:1], v[4:5], 0, s[10:11]
	s_mov_b32 m0, s17
	v_readfirstlane_b32 s17, v146
	s_add_u32 s20, s27, s20
	global_load_lds_dwordx4 v[0:1], off
	v_lshl_add_u64 v[0:1], v[4:5], 0, s[12:13]
	s_mov_b32 m0, s17
	s_addc_u32 s21, s28, s21
	v_readfirstlane_b32 s17, v148
	global_load_lds_dwordx4 v[0:1], off
	v_lshl_add_u64 v[48:49], s[20:21], 0, v[128:129]
	s_mov_b32 m0, s17
	v_readfirstlane_b32 s17, v149
	s_waitcnt vmcnt(6)
	s_barrier
	ds_read_b128 v[0:3], v154
	ds_read_b128 v[4:7], v154 offset:256
	ds_read_b128 v[8:11], v155
	ds_read_b128 v[12:15], v155 offset:256
	ds_read_b128 v[16:19], v147
	ds_read_b128 v[20:23], v147 offset:1024
	ds_read_b128 v[24:27], v147 offset:2048
	ds_read_b128 v[28:31], v147 offset:3072
	ds_read_b128 v[32:35], v147 offset:4096
	ds_read_b128 v[36:39], v147 offset:5120
	ds_read_b128 v[40:43], v147 offset:6144
	ds_read_b128 v[44:47], v147 offset:7168
	global_load_lds_dwordx4 v[48:49], off
	v_lshl_add_u64 v[48:49], v[48:49], 0, s[8:9]
	s_mov_b32 m0, s17
	s_nop 0
	global_load_lds_dwordx4 v[48:49], off
	s_barrier
	s_waitcnt lgkmcnt(0)
	s_setprio 1
	v_mfma_f32_16x16x32_bf16 v[48:51], v[0:3], v[16:19], 0
	v_mfma_f32_16x16x32_bf16 v[52:55], v[4:7], v[16:19], 0
	v_mfma_f32_16x16x32_bf16 v[56:59], v[0:3], v[24:27], 0
	v_mfma_f32_16x16x32_bf16 v[60:63], v[4:7], v[24:27], 0
	v_mfma_f32_16x16x32_bf16 v[64:67], v[0:3], v[32:35], 0
	v_mfma_f32_16x16x32_bf16 v[68:71], v[4:7], v[32:35], 0
	v_mfma_f32_16x16x32_bf16 v[72:75], v[0:3], v[40:43], 0
	v_mfma_f32_16x16x32_bf16 v[76:79], v[4:7], v[40:43], 0
	v_mfma_f32_16x16x32_bf16 v[48:51], v[8:11], v[20:23], v[48:51]
	v_mfma_f32_16x16x32_bf16 v[52:55], v[12:15], v[20:23], v[52:55]
	v_mfma_f32_16x16x32_bf16 v[56:59], v[8:11], v[28:31], v[56:59]
	v_mfma_f32_16x16x32_bf16 v[60:63], v[12:15], v[28:31], v[60:63]
	v_mfma_f32_16x16x32_bf16 v[64:67], v[8:11], v[36:39], v[64:67]
	v_mfma_f32_16x16x32_bf16 v[68:71], v[12:15], v[36:39], v[68:71]
	v_mfma_f32_16x16x32_bf16 v[72:75], v[8:11], v[44:47], v[72:75]
	v_mfma_f32_16x16x32_bf16 v[76:79], v[12:15], v[44:47], v[76:79]
	s_setprio 0
	s_barrier
	ds_read_b128 v[80:83], v156
	ds_read_b128 v[84:87], v156 offset:256
	ds_read_b128 v[88:91], v157
	ds_read_b128 v[92:95], v157 offset:256
	s_barrier
	s_waitcnt lgkmcnt(0)
	s_setprio 1
	v_mfma_f32_16x16x32_bf16 v[96:99], v[80:83], v[16:19], 0
	v_mfma_f32_16x16x32_bf16 v[16:19], v[84:87], v[16:19], 0
	v_mfma_f32_16x16x32_bf16 v[96:99], v[88:91], v[20:23], v[96:99]
	v_mfma_f32_16x16x32_bf16 v[16:19], v[92:95], v[20:23], v[16:19]
	v_mfma_f32_16x16x32_bf16 v[20:23], v[80:83], v[24:27], 0
	v_mfma_f32_16x16x32_bf16 v[24:27], v[84:87], v[24:27], 0
	v_mfma_f32_16x16x32_bf16 v[20:23], v[88:91], v[28:31], v[20:23]
	v_mfma_f32_16x16x32_bf16 v[24:27], v[92:95], v[28:31], v[24:27]
	v_mfma_f32_16x16x32_bf16 v[28:31], v[80:83], v[32:35], 0
	v_mfma_f32_16x16x32_bf16 v[32:35], v[84:87], v[32:35], 0
	v_mfma_f32_16x16x32_bf16 v[28:31], v[88:91], v[36:39], v[28:31]
	v_mfma_f32_16x16x32_bf16 v[32:35], v[92:95], v[36:39], v[32:35]
	v_mfma_f32_16x16x32_bf16 v[36:39], v[80:83], v[40:43], 0
	v_mfma_f32_16x16x32_bf16 v[40:43], v[84:87], v[40:43], 0
	v_mfma_f32_16x16x32_bf16 v[36:39], v[88:91], v[44:47], v[36:39]
	v_mfma_f32_16x16x32_bf16 v[40:43], v[92:95], v[44:47], v[40:43]
	s_setprio 0
	s_barrier
	ds_read_b128 v[44:47], v147 offset:16384
	ds_read_b128 v[100:103], v147 offset:17408
	ds_read_b128 v[104:107], v147 offset:18432
	ds_read_b128 v[108:111], v147 offset:19456
	ds_read_b128 v[112:115], v147 offset:20480
	ds_read_b128 v[116:119], v147 offset:21504
	ds_read_b128 v[120:123], v147 offset:22528
	ds_read_b128 v[124:127], v147 offset:23552
	s_waitcnt vmcnt(4)
	s_barrier
	s_waitcnt lgkmcnt(0)
	s_setprio 1
	v_mfma_f32_16x16x32_bf16 v[158:161], v[0:3], v[44:47], 0
	v_mfma_f32_16x16x32_bf16 v[162:165], v[4:7], v[44:47], 0
	v_mfma_f32_16x16x32_bf16 v[166:169], v[0:3], v[104:107], 0
	v_mfma_f32_16x16x32_bf16 v[170:173], v[4:7], v[104:107], 0
	v_mfma_f32_16x16x32_bf16 v[174:177], v[0:3], v[112:115], 0
	v_mfma_f32_16x16x32_bf16 v[178:181], v[4:7], v[112:115], 0
	v_mfma_f32_16x16x32_bf16 v[0:3], v[0:3], v[120:123], 0
	v_mfma_f32_16x16x32_bf16 v[4:7], v[4:7], v[120:123], 0
	v_mfma_f32_16x16x32_bf16 v[0:3], v[8:11], v[124:127], v[0:3]
	v_mfma_f32_16x16x32_bf16 v[4:7], v[12:15], v[124:127], v[4:7]
	v_mfma_f32_16x16x32_bf16 v[158:161], v[8:11], v[100:103], v[158:161]
	v_mfma_f32_16x16x32_bf16 v[162:165], v[12:15], v[100:103], v[162:165]
	v_mfma_f32_16x16x32_bf16 v[166:169], v[8:11], v[108:111], v[166:169]
	v_mfma_f32_16x16x32_bf16 v[170:173], v[12:15], v[108:111], v[170:173]
	v_mfma_f32_16x16x32_bf16 v[174:177], v[8:11], v[116:119], v[174:177]
	v_mfma_f32_16x16x32_bf16 v[178:181], v[12:15], v[116:119], v[178:181]
	v_mfma_f32_16x16x32_bf16 v[8:11], v[80:83], v[44:47], 0
	v_mfma_f32_16x16x32_bf16 v[12:15], v[84:87], v[44:47], 0
	v_mfma_f32_16x16x32_bf16 v[44:47], v[80:83], v[104:107], 0
	v_mfma_f32_16x16x32_bf16 v[182:185], v[88:91], v[108:111], v[44:47]
	v_mfma_f32_16x16x32_bf16 v[44:47], v[84:87], v[104:107], 0
	v_mfma_f32_16x16x32_bf16 v[186:189], v[92:95], v[108:111], v[44:47]
	v_mfma_f32_16x16x32_bf16 v[44:47], v[80:83], v[112:115], 0
	v_mfma_f32_16x16x32_bf16 v[190:193], v[88:91], v[116:119], v[44:47]
	v_mfma_f32_16x16x32_bf16 v[44:47], v[84:87], v[112:115], 0
	v_mfma_f32_16x16x32_bf16 v[194:197], v[92:95], v[116:119], v[44:47]
	v_mfma_f32_16x16x32_bf16 v[44:47], v[80:83], v[120:123], 0
	v_mfma_f32_16x16x32_bf16 v[8:11], v[88:91], v[100:103], v[8:11]
	v_mfma_f32_16x16x32_bf16 v[12:15], v[92:95], v[100:103], v[12:15]
	v_mfma_f32_16x16x32_bf16 v[198:201], v[88:91], v[124:127], v[44:47]
	v_mfma_f32_16x16x32_bf16 v[44:47], v[84:87], v[120:123], 0
	v_mfma_f32_16x16x32_bf16 v[202:205], v[92:95], v[124:127], v[44:47]
	s_setprio 0
	s_barrier
; #define LDA(dst, b, h) for (int m = 0; m < 4; ++m) { \
;     dst[m][0] = *reinterpret_cast<const bf16x8*>((char*)SA(b, h) + aoff0 + m * 2048); \
;     dst[m][1] = *reinterpret_cast<const bf16x8*>((char*)SA(b, h) + aoff1 + m * 2048); }
; #define LDB(dst, b, h) for (int n = 0; n < 2; ++n) { \
;     dst[n][0] = *reinterpret_cast<const bf16x8*>((char*)SB(b, h) + boff0 + n * 256); \
;     dst[n][1] = *reinterpret_cast<const bf16x8*>((char*)SB(b, h) + boff1 + n * 256); }
; #define MMA(ai, bj, At, Btf) do { __builtin_amdgcn_s_setprio(1); \
;     for (int m = 0; m < 4; ++m) for (int n = 0; n < 2; ++n) for (int k = 0; k < 2; ++k) \
;       acc[ai][bj][m][n] = __builtin_amdgcn_mfma_f32_16x16x32_bf16(Btf[n][k], At[m][k], acc[ai][bj][m][n], 0, 0, 0); \
;     __builtin_amdgcn_s_setprio(0); } while (0)
; #define WAIT_V(n) asm volatile("s_waitcnt vmcnt(" #n ")" ::: "memory")
; #define WAIT_L(n) asm volatile("s_waitcnt lgkmcnt(" #n ")" ::: "memory")
; #define BAR __builtin_amdgcn_s_barrier()
; template <int EPI> ...
;     ...
;   { LDB(B0, 1, 0); LDA(At, 1, 0); WAIT_V(2); BAR; WAIT_L(0); MMA(0, 0, At, B0); BAR;
;     LDB(B1, 1, 1); WAIT_V(0); BAR; WAIT_L(0); MMA(0, 1, At, B1); BAR;
;     LDA(At, 1, 1); BAR; WAIT_L(0); MMA(1, 0, At, B0); MMA(1, 1, At, B1); BAR; }
;   if (wr == 0) BAR;
	ds_read_b128 v[206:209], v150
	ds_read_b128 v[210:213], v150 offset:256
	ds_read_b128 v[214:217], v151
	ds_read_b128 v[218:221], v151 offset:256
	s_nop 0
	ds_read_b128 v[44:47], v147 offset:32768
	ds_read_b128 v[88:91], v147 offset:33792
	ds_read_b128 v[92:95], v147 offset:34816
	ds_read_b128 v[222:225], v147 offset:35840
	ds_read_b128 v[226:229], v147 offset:36864
	ds_read_b128 v[230:233], v147 offset:37888
	ds_read_b128 v[234:237], v147 offset:38912
	ds_read_b128 v[238:241], v147 offset:39936
	s_waitcnt vmcnt(2)
	s_barrier
	s_waitcnt lgkmcnt(0)
	s_setprio 1
	v_mfma_f32_16x16x32_bf16 v[48:51], v[206:209], v[44:47], v[48:51]
	v_mfma_f32_16x16x32_bf16 v[120:123], v[214:217], v[88:91], v[48:51]
	v_mfma_f32_16x16x32_bf16 v[48:51], v[210:213], v[44:47], v[52:55]
	v_mfma_f32_16x16x32_bf16 v[124:127], v[218:221], v[88:91], v[48:51]
	v_mfma_f32_16x16x32_bf16 v[48:51], v[206:209], v[92:95], v[56:59]
	v_mfma_f32_16x16x32_bf16 v[112:115], v[214:217], v[222:225], v[48:51]
	v_mfma_f32_16x16x32_bf16 v[48:51], v[210:213], v[92:95], v[60:63]
	v_mfma_f32_16x16x32_bf16 v[116:119], v[218:221], v[222:225], v[48:51]
	v_mfma_f32_16x16x32_bf16 v[48:51], v[206:209], v[226:229], v[64:67]
	v_mfma_f32_16x16x32_bf16 v[104:107], v[214:217], v[230:233], v[48:51]
	v_mfma_f32_16x16x32_bf16 v[48:51], v[210:213], v[226:229], v[68:71]
	v_mfma_f32_16x16x32_bf16 v[108:111], v[218:221], v[230:233], v[48:51]
	v_mfma_f32_16x16x32_bf16 v[48:51], v[206:209], v[234:237], v[72:75]
	v_mfma_f32_16x16x32_bf16 v[80:83], v[214:217], v[238:241], v[48:51]
	v_mfma_f32_16x16x32_bf16 v[48:51], v[210:213], v[234:237], v[76:79]
	v_mfma_f32_16x16x32_bf16 v[84:87], v[218:221], v[238:241], v[48:51]
	s_setprio 0
	s_barrier
	ds_read_b128 v[242:245], v152
	ds_read_b128 v[246:249], v152 offset:256
	ds_read_b128 v[250:253], v153
	ds_read_b128 v[130:133], v153 offset:256
	s_waitcnt vmcnt(0)
	s_barrier
	s_waitcnt lgkmcnt(0)
	s_setprio 1
	v_mfma_f32_16x16x32_bf16 v[16:19], v[246:249], v[44:47], v[16:19]
	v_mfma_f32_16x16x32_bf16 v[48:51], v[242:245], v[44:47], v[96:99]
	v_mfma_f32_16x16x32_bf16 v[100:103], v[130:133], v[88:91], v[16:19]
	v_mfma_f32_16x16x32_bf16 v[16:19], v[242:245], v[92:95], v[20:23]
	v_mfma_f32_16x16x32_bf16 v[96:99], v[250:253], v[88:91], v[48:51]
	v_mfma_f32_16x16x32_bf16 v[88:91], v[250:253], v[222:225], v[16:19]
	v_mfma_f32_16x16x32_bf16 v[16:19], v[246:249], v[92:95], v[24:27]
	v_mfma_f32_16x16x32_bf16 v[92:95], v[130:133], v[222:225], v[16:19]
	v_mfma_f32_16x16x32_bf16 v[16:19], v[242:245], v[226:229], v[28:31]
	v_mfma_f32_16x16x32_bf16 v[64:67], v[250:253], v[230:233], v[16:19]
	v_mfma_f32_16x16x32_bf16 v[16:19], v[246:249], v[226:229], v[32:35]
	v_mfma_f32_16x16x32_bf16 v[68:71], v[130:133], v[230:233], v[16:19]
	v_mfma_f32_16x16x32_bf16 v[16:19], v[242:245], v[234:237], v[36:39]
	v_mfma_f32_16x16x32_bf16 v[48:51], v[250:253], v[238:241], v[16:19]
	v_mfma_f32_16x16x32_bf16 v[16:19], v[246:249], v[234:237], v[40:43]
	v_mfma_f32_16x16x32_bf16 v[52:55], v[130:133], v[238:241], v[16:19]
	s_setprio 0
	s_barrier
	s_nop 4
	ds_read_b128 v[16:19], v147 offset:49152
	ds_read_b128 v[20:23], v147 offset:50176
	ds_read_b128 v[222:225], v147 offset:51200
	ds_read_b128 v[226:229], v147 offset:52224
	ds_read_b128 v[230:233], v147 offset:53248
	ds_read_b128 v[234:237], v147 offset:54272
	ds_read_b128 v[238:241], v147 offset:55296
	ds_read_b128 v[136:139], v147 offset:56320
	s_barrier
	s_waitcnt lgkmcnt(0)
	s_setprio 1
	v_mfma_f32_16x16x32_bf16 v[24:27], v[206:209], v[16:19], v[158:161]
	v_mfma_f32_16x16x32_bf16 v[72:75], v[214:217], v[20:23], v[24:27]
	v_mfma_f32_16x16x32_bf16 v[24:27], v[210:213], v[16:19], v[162:165]
	v_mfma_f32_16x16x32_bf16 v[76:79], v[218:221], v[20:23], v[24:27]
	v_mfma_f32_16x16x32_bf16 v[24:27], v[206:209], v[222:225], v[166:169]
	v_mfma_f32_16x16x32_bf16 v[56:59], v[214:217], v[226:229], v[24:27]
	v_mfma_f32_16x16x32_bf16 v[24:27], v[210:213], v[222:225], v[170:173]
	v_mfma_f32_16x16x32_bf16 v[60:63], v[218:221], v[226:229], v[24:27]
	v_mfma_f32_16x16x32_bf16 v[24:27], v[206:209], v[230:233], v[174:177]
	v_mfma_f32_16x16x32_bf16 v[0:3], v[206:209], v[238:241], v[0:3]
	v_mfma_f32_16x16x32_bf16 v[40:43], v[214:217], v[234:237], v[24:27]
	v_mfma_f32_16x16x32_bf16 v[24:27], v[210:213], v[230:233], v[178:181]
	v_mfma_f32_16x16x32_bf16 v[32:35], v[214:217], v[136:139], v[0:3]
	v_mfma_f32_16x16x32_bf16 v[0:3], v[210:213], v[238:241], v[4:7]
	v_mfma_f32_16x16x32_bf16 v[44:47], v[218:221], v[234:237], v[24:27]
	v_mfma_f32_16x16x32_bf16 v[36:39], v[218:221], v[136:139], v[0:3]
	v_mfma_f32_16x16x32_bf16 v[0:3], v[242:245], v[16:19], v[8:11]
	v_mfma_f32_16x16x32_bf16 v[24:27], v[250:253], v[20:23], v[0:3]
	v_mfma_f32_16x16x32_bf16 v[0:3], v[246:249], v[16:19], v[12:15]
	v_mfma_f32_16x16x32_bf16 v[28:31], v[130:133], v[20:23], v[0:3]
	v_mfma_f32_16x16x32_bf16 v[0:3], v[242:245], v[222:225], v[182:185]
	v_mfma_f32_16x16x32_bf16 v[16:19], v[250:253], v[226:229], v[0:3]
	v_mfma_f32_16x16x32_bf16 v[0:3], v[246:249], v[222:225], v[186:189]
	v_mfma_f32_16x16x32_bf16 v[20:23], v[130:133], v[226:229], v[0:3]
	v_mfma_f32_16x16x32_bf16 v[0:3], v[242:245], v[230:233], v[190:193]
	v_mfma_f32_16x16x32_bf16 v[8:11], v[250:253], v[234:237], v[0:3]
	v_mfma_f32_16x16x32_bf16 v[0:3], v[246:249], v[230:233], v[194:197]
	v_mfma_f32_16x16x32_bf16 v[12:15], v[130:133], v[234:237], v[0:3]
	v_mfma_f32_16x16x32_bf16 v[0:3], v[242:245], v[238:241], v[198:201]
	v_mfma_f32_16x16x32_bf16 v[4:7], v[246:249], v[238:241], v[202:205]
	v_mfma_f32_16x16x32_bf16 v[0:3], v[250:253], v[136:139], v[0:3]
	v_mfma_f32_16x16x32_bf16 v[4:7], v[130:133], v[136:139], v[4:7]
	s_setprio 0
	s_barrier
	s_and_saveexec_b64 s[20:21], s[2:3]
	s_cbranch_execz .LBB0_829
	s_barrier
	s_branch .LBB0_829

; #define STAGE(P, BASE, br, kt) do { const char* _gb = (const char*)(BASE) + ((size_t)(br) * K + (size_t)(kt) * BK) * 2; \
;     __builtin_amdgcn_global_load_lds((const unsigned*)(_gb + loff0), (unsigned*)((char*)(P) + tid * 16), 16, 0, 0); \
;     __builtin_amdgcn_global_load_lds((const unsigned*)(_gb + (size_t)K * 128 + loff0), (unsigned*)((char*)(P) + tid * 16 + 8192), 16, 0, 0); } while (0)
; #define LDA(dst, b, h) for (int m = 0; m < 4; ++m) { \
;     dst[m][0] = *reinterpret_cast<const bf16x8*>((char*)SA(b, h) + aoff0 + m * 2048); \
;     dst[m][1] = *reinterpret_cast<const bf16x8*>((char*)SA(b, h) + aoff1 + m * 2048); }
; #define LDB(dst, b, h) for (int n = 0; n < 2; ++n) { \
;     dst[n][0] = *reinterpret_cast<const bf16x8*>((char*)SB(b, h) + boff0 + n * 256); \
;     dst[n][1] = *reinterpret_cast<const bf16x8*>((char*)SB(b, h) + boff1 + n * 256); }
; #define MMA(ai, bj, At, Btf) do { __builtin_amdgcn_s_setprio(1); \
;     for (int m = 0; m < 4; ++m) for (int n = 0; n < 2; ++n) for (int k = 0; k < 2; ++k) \
;       acc[ai][bj][m][n] = __builtin_amdgcn_mfma_f32_16x16x32_bf16(Btf[n][k], At[m][k], acc[ai][bj][m][n], 0, 0, 0); \
;     __builtin_amdgcn_s_setprio(0); } while (0)
; #define WAIT_V(n) asm volatile("s_waitcnt vmcnt(" #n ")" ::: "memory")
; #define WAIT_L(n) asm volatile("s_waitcnt lgkmcnt(" #n ")" ::: "memory")
; #define BAR __builtin_amdgcn_s_barrier()
; #define SCHED __builtin_amdgcn_sched_barrier(0)
; template <int EPI> ...
;     ...
;   STAGE(SB(0, 0), Bt, bcol, 0); STAGE(SA(0, 0), A, brow, 0);
;   STAGE(SB(0, 1), Bt, bcol + HALF, 0); STAGE(SA(0, 1), A, brow + HALF, 0);
;   if (wr == 1) BAR;
;   WAIT_V(4); BAR;
;   STAGE(SB(1, 0), Bt, bcol, 1); STAGE(SA(1, 0), A, brow, 1); STAGE(SB(1, 1), Bt, bcol + HALF, 1);
;   WAIT_V(6); BAR;
;   for (int t = 0; t < nt - 2; t += 2) {
;     LDB(B0, 0, 0); SCHED; LDA(At, 0, 0); STAGE(SA(1, 1), A, brow + HALF, t + 1);
;     WAIT_L(8); BAR; WAIT_L(0); MMA(0, 0, At, B0); BAR; SCHED;
;     LDB(B1, 0, 1); STAGE(SB(0, 0), Bt, bcol, t + 2);
;     BAR; WAIT_L(0); MMA(0, 1, At, B1); BAR;
;     LDA(At, 0, 1); STAGE(SA(0, 0), A, brow, t + 2);
;     BAR; WAIT_L(0); MMA(1, 0, At, B0); BAR; SCHED;
.LBB0_850:
	s_or_b64 exec, exec, s[28:29]
	v_readfirstlane_b32 s50, v144
	v_add_u32_e32 v10, 0x2000, v144
	v_lshl_add_u64 v[8:9], v[4:5], 0, s[8:9]
	s_mov_b32 m0, s50
	v_readfirstlane_b32 s49, v10
	v_add_u32_e32 v10, 0x8000, v135
	s_waitcnt vmcnt(4)
	s_barrier
	global_load_lds_dwordx4 v[8:9], off
	v_lshl_add_u64 v[8:9], v[4:5], 0, s[10:11]
	s_mov_b32 m0, s49
	v_readfirstlane_b32 s48, v10
	v_add_u32_e32 v10, 0xa000, v135
	global_load_lds_dwordx4 v[8:9], off
	v_lshl_add_u64 v[8:9], v[2:3], 0, s[8:9]
	s_mov_b32 m0, s48
	v_readfirstlane_b32 s47, v10
	global_load_lds_dwordx4 v[8:9], off
	v_lshl_add_u64 v[8:9], v[2:3], 0, s[10:11]
	s_mov_b32 m0, s47
	v_readfirstlane_b32 s46, v145
	global_load_lds_dwordx4 v[8:9], off
	v_lshl_add_u64 v[8:9], v[0:1], 0, s[8:9]
	s_mov_b32 m0, s46
	v_readfirstlane_b32 s29, v146
	global_load_lds_dwordx4 v[8:9], off
	v_lshl_add_u64 v[8:9], v[0:1], 0, s[10:11]
	s_mov_b32 m0, s29
	s_nop 0
	global_load_lds_dwordx4 v[8:9], off
	s_waitcnt vmcnt(6)
	s_barrier
	ds_read_b128 v[8:11], v154
	ds_read_b128 v[12:15], v154 offset:256
	ds_read_b128 v[16:19], v155
	ds_read_b128 v[20:23], v155 offset:256
	v_readfirstlane_b32 s28, v148
	v_lshl_add_u64 v[56:57], v[6:7], 0, s[8:9]
	s_mov_b32 m0, s28
	v_readfirstlane_b32 s23, v149
	ds_read_b128 v[24:27], v147
	ds_read_b128 v[28:31], v147 offset:1024
	ds_read_b128 v[32:35], v147 offset:2048
	ds_read_b128 v[36:39], v147 offset:3072
	ds_read_b128 v[40:43], v147 offset:4096
	ds_read_b128 v[44:47], v147 offset:5120
	ds_read_b128 v[48:51], v147 offset:6144
	ds_read_b128 v[52:55], v147 offset:7168
	global_load_lds_dwordx4 v[56:57], off
	v_lshl_add_u64 v[56:57], v[6:7], 0, s[10:11]
	s_mov_b32 m0, s23
	s_nop 0
	global_load_lds_dwordx4 v[56:57], off
	s_waitcnt lgkmcnt(8)
	s_barrier
	s_waitcnt lgkmcnt(0)
	s_setprio 1
	v_mfma_f32_16x16x32_bf16 v[56:59], v[8:11], v[24:27], 0
	v_mfma_f32_16x16x32_bf16 v[60:63], v[12:15], v[24:27], 0
	v_mfma_f32_16x16x32_bf16 v[64:67], v[8:11], v[32:35], 0
	v_mfma_f32_16x16x32_bf16 v[68:71], v[12:15], v[32:35], 0
	v_mfma_f32_16x16x32_bf16 v[72:75], v[8:11], v[40:43], 0
	v_mfma_f32_16x16x32_bf16 v[76:79], v[12:15], v[40:43], 0
	v_mfma_f32_16x16x32_bf16 v[80:83], v[8:11], v[48:51], 0
	v_mfma_f32_16x16x32_bf16 v[84:87], v[12:15], v[48:51], 0
	v_mfma_f32_16x16x32_bf16 v[56:59], v[16:19], v[28:31], v[56:59]
	v_mfma_f32_16x16x32_bf16 v[60:63], v[20:23], v[28:31], v[60:63]
	v_mfma_f32_16x16x32_bf16 v[64:67], v[16:19], v[36:39], v[64:67]
	v_mfma_f32_16x16x32_bf16 v[68:71], v[20:23], v[36:39], v[68:71]
	v_mfma_f32_16x16x32_bf16 v[72:75], v[16:19], v[44:47], v[72:75]
	v_mfma_f32_16x16x32_bf16 v[76:79], v[20:23], v[44:47], v[76:79]
	v_mfma_f32_16x16x32_bf16 v[80:83], v[16:19], v[52:55], v[80:83]
	v_mfma_f32_16x16x32_bf16 v[84:87], v[20:23], v[52:55], v[84:87]
	s_setprio 0
	s_barrier
	v_readfirstlane_b32 s51, v133
	v_lshl_add_u64 v[104:105], v[4:5], 0, s[12:13]
	s_mov_b32 m0, s51
	v_readfirstlane_b32 s51, v134
	ds_read_b128 v[88:91], v156
	ds_read_b128 v[92:95], v156 offset:256
	ds_read_b128 v[96:99], v157
	ds_read_b128 v[100:103], v157 offset:256
	global_load_lds_dwordx4 v[104:105], off
	v_lshl_add_u64 v[104:105], v[4:5], 0, s[16:17]
	s_mov_b32 m0, s51
	s_nop 0
	global_load_lds_dwordx4 v[104:105], off
	s_barrier
	s_waitcnt lgkmcnt(0)
	s_setprio 1
	s_waitcnt lgkmcnt(0)
	v_mfma_f32_16x16x32_bf16 v[104:107], v[88:91], v[24:27], 0
	v_mfma_f32_16x16x32_bf16 v[24:27], v[92:95], v[24:27], 0
	v_mfma_f32_16x16x32_bf16 v[104:107], v[96:99], v[28:31], v[104:107]
	v_mfma_f32_16x16x32_bf16 v[24:27], v[100:103], v[28:31], v[24:27]
	v_mfma_f32_16x16x32_bf16 v[28:31], v[88:91], v[32:35], 0
	v_mfma_f32_16x16x32_bf16 v[32:35], v[92:95], v[32:35], 0
	v_mfma_f32_16x16x32_bf16 v[28:31], v[96:99], v[36:39], v[28:31]
	v_mfma_f32_16x16x32_bf16 v[32:35], v[100:103], v[36:39], v[32:35]
	v_mfma_f32_16x16x32_bf16 v[36:39], v[88:91], v[40:43], 0
	v_mfma_f32_16x16x32_bf16 v[40:43], v[92:95], v[40:43], 0
	v_mfma_f32_16x16x32_bf16 v[36:39], v[96:99], v[44:47], v[36:39]
	v_mfma_f32_16x16x32_bf16 v[40:43], v[100:103], v[44:47], v[40:43]
	v_mfma_f32_16x16x32_bf16 v[44:47], v[88:91], v[48:51], 0
	v_mfma_f32_16x16x32_bf16 v[48:51], v[92:95], v[48:51], 0
	v_mfma_f32_16x16x32_bf16 v[44:47], v[96:99], v[52:55], v[44:47]
	v_mfma_f32_16x16x32_bf16 v[48:51], v[100:103], v[52:55], v[48:51]
	s_setprio 0
	v_readfirstlane_b32 s51, v135
	v_lshl_add_u64 v[138:139], v[2:3], 0, s[12:13]
	s_mov_b32 m0, s51
	v_readfirstlane_b32 s51, v136
	s_barrier
	ds_read_b128 v[52:55], v147 offset:16384
	ds_read_b128 v[108:111], v147 offset:17408
	ds_read_b128 v[112:115], v147 offset:18432
	ds_read_b128 v[116:119], v147 offset:19456
	ds_read_b128 v[120:123], v147 offset:20480
	ds_read_b128 v[124:127], v147 offset:21504
	ds_read_b128 v[158:161], v147 offset:22528
	ds_read_b128 v[162:165], v147 offset:23552
	global_load_lds_dwordx4 v[138:139], off
	v_lshl_add_u64 v[138:139], v[2:3], 0, s[16:17]
	s_mov_b32 m0, s51
	s_nop 0
	global_load_lds_dwordx4 v[138:139], off
	s_barrier
	s_waitcnt lgkmcnt(0)
	s_setprio 1
	v_mfma_f32_16x16x32_bf16 v[166:169], v[8:11], v[52:55], 0
	v_mfma_f32_16x16x32_bf16 v[170:173], v[12:15], v[52:55], 0
	v_mfma_f32_16x16x32_bf16 v[174:177], v[8:11], v[112:115], 0
	v_mfma_f32_16x16x32_bf16 v[178:181], v[12:15], v[112:115], 0
	v_mfma_f32_16x16x32_bf16 v[182:185], v[8:11], v[120:123], 0
	v_mfma_f32_16x16x32_bf16 v[186:189], v[12:15], v[120:123], 0
	v_mfma_f32_16x16x32_bf16 v[8:11], v[8:11], v[158:161], 0
	v_mfma_f32_16x16x32_bf16 v[12:15], v[12:15], v[158:161], 0
	v_mfma_f32_16x16x32_bf16 v[8:11], v[16:19], v[162:165], v[8:11]
	v_mfma_f32_16x16x32_bf16 v[12:15], v[20:23], v[162:165], v[12:15]
	v_mfma_f32_16x16x32_bf16 v[166:169], v[16:19], v[108:111], v[166:169]
	v_mfma_f32_16x16x32_bf16 v[170:173], v[20:23], v[108:111], v[170:173]
	v_mfma_f32_16x16x32_bf16 v[174:177], v[16:19], v[116:119], v[174:177]
	v_mfma_f32_16x16x32_bf16 v[178:181], v[20:23], v[116:119], v[178:181]
	v_mfma_f32_16x16x32_bf16 v[182:185], v[16:19], v[124:127], v[182:185]
	v_mfma_f32_16x16x32_bf16 v[186:189], v[20:23], v[124:127], v[186:189]
	s_setprio 0
	s_barrier
; #define STAGE(P, BASE, br, kt) do { const char* _gb = (const char*)(BASE) + ((size_t)(br) * K + (size_t)(kt) * BK) * 2; \
;     __builtin_amdgcn_global_load_lds((const unsigned*)(_gb + loff0), (unsigned*)((char*)(P) + tid * 16), 16, 0, 0); \
;     __builtin_amdgcn_global_load_lds((const unsigned*)(_gb + (size_t)K * 128 + loff0), (unsigned*)((char*)(P) + tid * 16 + 8192), 16, 0, 0); } while (0)
; #define LDA(dst, b, h) for (int m = 0; m < 4; ++m) { \
;     dst[m][0] = *reinterpret_cast<const bf16x8*>((char*)SA(b, h) + aoff0 + m * 2048); \
;     dst[m][1] = *reinterpret_cast<const bf16x8*>((char*)SA(b, h) + aoff1 + m * 2048); }
; #define LDB(dst, b, h) for (int n = 0; n < 2; ++n) { \
;     dst[n][0] = *reinterpret_cast<const bf16x8*>((char*)SB(b, h) + boff0 + n * 256); \
;     dst[n][1] = *reinterpret_cast<const bf16x8*>((char*)SB(b, h) + boff1 + n * 256); }
; #define MMA(ai, bj, At, Btf) do { __builtin_amdgcn_s_setprio(1); \
;     for (int m = 0; m < 4; ++m) for (int n = 0; n < 2; ++n) for (int k = 0; k < 2; ++k) \
;       acc[ai][bj][m][n] = __builtin_amdgcn_mfma_f32_16x16x32_bf16(Btf[n][k], At[m][k], acc[ai][bj][m][n], 0, 0, 0); \
;     __builtin_amdgcn_s_setprio(0); } while (0)
; #define WAIT_V(n) asm volatile("s_waitcnt vmcnt(" #n ")" ::: "memory")
; #define WAIT_L(n) asm volatile("s_waitcnt lgkmcnt(" #n ")" ::: "memory")
; #define BAR __builtin_amdgcn_s_barrier()
; #define SCHED __builtin_amdgcn_sched_barrier(0)
; template <int EPI> ...
;     ...
;     STAGE(SB(0, 1), Bt, bcol + HALF, t + 2);
;     WAIT_V(6); BAR; MMA(1, 1, At, B1); BAR;
;     LDB(B0, 1, 0); SCHED; LDA(At, 1, 0); STAGE(SA(0, 1), A, brow + HALF, t + 2);
;     WAIT_L(8); BAR; WAIT_L(0); MMA(0, 0, At, B0); BAR; SCHED;
;     LDB(B1, 1, 1); STAGE(SB(1, 0), Bt, bcol, t + 3);
;     BAR; WAIT_L(0); MMA(0, 1, At, B1); BAR;
;     LDA(At, 1, 1); STAGE(SA(1, 0), A, brow, t + 3);
	v_readfirstlane_b32 s51, v137
	v_lshl_add_u64 v[16:17], v[0:1], 0, s[12:13]
	s_mov_b32 m0, s51
	v_readfirstlane_b32 s51, v254
	global_load_lds_dwordx4 v[16:17], off
	v_lshl_add_u64 v[16:17], v[0:1], 0, s[16:17]
	s_mov_b32 m0, s51
	s_nop 0
	global_load_lds_dwordx4 v[16:17], off
	s_waitcnt vmcnt(6)
	s_barrier
	s_setprio 1
	v_mfma_f32_16x16x32_bf16 v[16:19], v[88:91], v[52:55], 0
	v_mfma_f32_16x16x32_bf16 v[20:23], v[92:95], v[52:55], 0
	v_mfma_f32_16x16x32_bf16 v[16:19], v[96:99], v[108:111], v[16:19]
	v_mfma_f32_16x16x32_bf16 v[20:23], v[100:103], v[108:111], v[20:23]
	v_mfma_f32_16x16x32_bf16 v[52:55], v[88:91], v[112:115], 0
	v_mfma_f32_16x16x32_bf16 v[108:111], v[92:95], v[112:115], 0
	v_mfma_f32_16x16x32_bf16 v[52:55], v[96:99], v[116:119], v[52:55]
	v_mfma_f32_16x16x32_bf16 v[108:111], v[100:103], v[116:119], v[108:111]
	v_mfma_f32_16x16x32_bf16 v[112:115], v[88:91], v[120:123], 0
	v_mfma_f32_16x16x32_bf16 v[116:119], v[92:95], v[120:123], 0
	v_mfma_f32_16x16x32_bf16 v[88:91], v[88:91], v[158:161], 0
	v_mfma_f32_16x16x32_bf16 v[92:95], v[92:95], v[158:161], 0
	v_mfma_f32_16x16x32_bf16 v[112:115], v[96:99], v[124:127], v[112:115]
	v_mfma_f32_16x16x32_bf16 v[116:119], v[100:103], v[124:127], v[116:119]
	v_mfma_f32_16x16x32_bf16 v[88:91], v[96:99], v[162:165], v[88:91]
	v_mfma_f32_16x16x32_bf16 v[92:95], v[100:103], v[162:165], v[92:95]
	s_setprio 0
	s_barrier
	ds_read_b128 v[96:99], v150
	ds_read_b128 v[100:103], v150 offset:256
	ds_read_b128 v[120:123], v151
	ds_read_b128 v[124:127], v151 offset:256
	v_readfirstlane_b32 s51, v142
	v_lshl_add_u64 v[138:139], v[6:7], 0, s[12:13]
	s_mov_b32 m0, s51
	v_readfirstlane_b32 s51, v143
	ds_read_b128 v[158:161], v147 offset:32768
	ds_read_b128 v[162:165], v147 offset:33792
	ds_read_b128 v[190:193], v147 offset:34816
	ds_read_b128 v[194:197], v147 offset:35840
	ds_read_b128 v[198:201], v147 offset:36864
	ds_read_b128 v[202:205], v147 offset:37888
	ds_read_b128 v[206:209], v147 offset:38912
	ds_read_b128 v[210:213], v147 offset:39936
	global_load_lds_dwordx4 v[138:139], off
	v_lshl_add_u64 v[6:7], v[6:7], 0, s[16:17]
	s_mov_b32 m0, s51
	s_nop 0
	global_load_lds_dwordx4 v[6:7], off
	s_waitcnt lgkmcnt(8)
	s_barrier
	s_waitcnt lgkmcnt(0)
	s_setprio 1
	v_mfma_f32_16x16x32_bf16 v[56:59], v[96:99], v[158:161], v[56:59]
	v_mfma_f32_16x16x32_bf16 v[60:63], v[100:103], v[158:161], v[60:63]
	v_mfma_f32_16x16x32_bf16 v[64:67], v[96:99], v[190:193], v[64:67]
	v_mfma_f32_16x16x32_bf16 v[68:71], v[100:103], v[190:193], v[68:71]
	v_mfma_f32_16x16x32_bf16 v[72:75], v[96:99], v[198:201], v[72:75]
	v_mfma_f32_16x16x32_bf16 v[76:79], v[100:103], v[198:201], v[76:79]
	v_mfma_f32_16x16x32_bf16 v[80:83], v[96:99], v[206:209], v[80:83]
	v_mfma_f32_16x16x32_bf16 v[84:87], v[100:103], v[206:209], v[84:87]
	v_mfma_f32_16x16x32_bf16 v[56:59], v[120:123], v[162:165], v[56:59]
	v_mfma_f32_16x16x32_bf16 v[60:63], v[124:127], v[162:165], v[60:63]
	v_mfma_f32_16x16x32_bf16 v[64:67], v[120:123], v[194:197], v[64:67]
	v_mfma_f32_16x16x32_bf16 v[68:71], v[124:127], v[194:197], v[68:71]
	v_mfma_f32_16x16x32_bf16 v[72:75], v[120:123], v[202:205], v[72:75]
	v_mfma_f32_16x16x32_bf16 v[76:79], v[124:127], v[202:205], v[76:79]
	v_mfma_f32_16x16x32_bf16 v[80:83], v[120:123], v[210:213], v[80:83]
	v_mfma_f32_16x16x32_bf16 v[84:87], v[124:127], v[210:213], v[84:87]
	s_setprio 0
	s_barrier
	s_mov_b32 m0, s50
	v_lshl_add_u64 v[6:7], v[4:5], 0, s[18:19]
	ds_read_b128 v[214:217], v152
	ds_read_b128 v[218:221], v152 offset:256
	ds_read_b128 v[222:225], v153
	ds_read_b128 v[226:229], v153 offset:256
	global_load_lds_dwordx4 v[6:7], off
	v_lshl_add_u64 v[4:5], v[4:5], 0, s[20:21]
	s_mov_b32 m0, s49
	s_nop 0
	global_load_lds_dwordx4 v[4:5], off
	s_barrier
	s_waitcnt lgkmcnt(0)
	s_setprio 1
	s_waitcnt lgkmcnt(0)
	v_mfma_f32_16x16x32_bf16 v[4:7], v[214:217], v[158:161], v[104:107]
	v_mfma_f32_16x16x32_bf16 v[24:27], v[218:221], v[158:161], v[24:27]
	v_mfma_f32_16x16x32_bf16 v[28:31], v[214:217], v[190:193], v[28:31]
	v_mfma_f32_16x16x32_bf16 v[32:35], v[218:221], v[190:193], v[32:35]
	v_mfma_f32_16x16x32_bf16 v[36:39], v[214:217], v[198:201], v[36:39]
	v_mfma_f32_16x16x32_bf16 v[40:43], v[218:221], v[198:201], v[40:43]
	v_mfma_f32_16x16x32_bf16 v[44:47], v[214:217], v[206:209], v[44:47]
	v_mfma_f32_16x16x32_bf16 v[48:51], v[218:221], v[206:209], v[48:51]
	v_mfma_f32_16x16x32_bf16 v[4:7], v[222:225], v[162:165], v[4:7]
	v_mfma_f32_16x16x32_bf16 v[24:27], v[226:229], v[162:165], v[24:27]
	v_mfma_f32_16x16x32_bf16 v[28:31], v[222:225], v[194:197], v[28:31]
	v_mfma_f32_16x16x32_bf16 v[32:35], v[226:229], v[194:197], v[32:35]
	v_mfma_f32_16x16x32_bf16 v[36:39], v[222:225], v[202:205], v[36:39]
	v_mfma_f32_16x16x32_bf16 v[40:43], v[226:229], v[202:205], v[40:43]
	v_mfma_f32_16x16x32_bf16 v[44:47], v[222:225], v[210:213], v[44:47]
	v_mfma_f32_16x16x32_bf16 v[48:51], v[226:229], v[210:213], v[48:51]
	s_setprio 0
	s_mov_b32 m0, s48
	v_lshl_add_u64 v[138:139], v[2:3], 0, s[18:19]
	s_barrier
	ds_read_b128 v[104:107], v147 offset:49152
	ds_read_b128 v[158:161], v147 offset:50176
	ds_read_b128 v[162:165], v147 offset:51200
	ds_read_b128 v[190:193], v147 offset:52224
	ds_read_b128 v[194:197], v147 offset:53248
	ds_read_b128 v[198:201], v147 offset:54272
	ds_read_b128 v[202:205], v147 offset:55296
	ds_read_b128 v[206:209], v147 offset:56320
	global_load_lds_dwordx4 v[138:139], off
	v_lshl_add_u64 v[2:3], v[2:3], 0, s[20:21]
	s_mov_b32 m0, s47
	s_nop 0
	global_load_lds_dwordx4 v[2:3], off
	s_barrier
; #define STAGE(P, BASE, br, kt) do { const char* _gb = (const char*)(BASE) + ((size_t)(br) * K + (size_t)(kt) * BK) * 2; \
;     __builtin_amdgcn_global_load_lds((const unsigned*)(_gb + loff0), (unsigned*)((char*)(P) + tid * 16), 16, 0, 0); \
;     __builtin_amdgcn_global_load_lds((const unsigned*)(_gb + (size_t)K * 128 + loff0), (unsigned*)((char*)(P) + tid * 16 + 8192), 16, 0, 0); } while (0)
; #define LDA(dst, b, h) for (int m = 0; m < 4; ++m) { \
;     dst[m][0] = *reinterpret_cast<const bf16x8*>((char*)SA(b, h) + aoff0 + m * 2048); \
;     dst[m][1] = *reinterpret_cast<const bf16x8*>((char*)SA(b, h) + aoff1 + m * 2048); }
; #define LDB(dst, b, h) for (int n = 0; n < 2; ++n) { \
;     dst[n][0] = *reinterpret_cast<const bf16x8*>((char*)SB(b, h) + boff0 + n * 256); \
;     dst[n][1] = *reinterpret_cast<const bf16x8*>((char*)SB(b, h) + boff1 + n * 256); }
; #define MMA(ai, bj, At, Btf) do { __builtin_amdgcn_s_setprio(1); \
;     for (int m = 0; m < 4; ++m) for (int n = 0; n < 2; ++n) for (int k = 0; k < 2; ++k) \
;       acc[ai][bj][m][n] = __builtin_amdgcn_mfma_f32_16x16x32_bf16(Btf[n][k], At[m][k], acc[ai][bj][m][n], 0, 0, 0); \
;     __builtin_amdgcn_s_setprio(0); } while (0)
; #define WAIT_V(n) asm volatile("s_waitcnt vmcnt(" #n ")" ::: "memory")
; #define WAIT_L(n) asm volatile("s_waitcnt lgkmcnt(" #n ")" ::: "memory")
; #define BAR __builtin_amdgcn_s_barrier()
; #define SCHED __builtin_amdgcn_sched_barrier(0)
; template <int EPI> ...
;     ...
;     BAR; WAIT_L(0); MMA(1, 0, At, B0); BAR; SCHED;
;     STAGE(SB(1, 1), Bt, bcol + HALF, t + 3);
;     WAIT_V(6); BAR; MMA(1, 1, At, B1); BAR;
;   }
;   { LDB(B0, 0, 0); LDA(At, 0, 0); STAGE(SA(1, 1), A, brow + HALF, nt - 1);
;     BAR; WAIT_L(0); MMA(0, 0, At, B0); BAR;
;     LDB(B1, 0, 1); BAR; WAIT_L(0); MMA(0, 1, At, B1); BAR;
	s_waitcnt lgkmcnt(0)
	s_setprio 1
	v_mfma_f32_16x16x32_bf16 v[8:11], v[96:99], v[202:205], v[8:11]
	v_mfma_f32_16x16x32_bf16 v[12:15], v[100:103], v[202:205], v[12:15]
	v_mfma_f32_16x16x32_bf16 v[166:169], v[96:99], v[104:107], v[166:169]
	v_mfma_f32_16x16x32_bf16 v[170:173], v[100:103], v[104:107], v[170:173]
	v_mfma_f32_16x16x32_bf16 v[174:177], v[96:99], v[162:165], v[174:177]
	v_mfma_f32_16x16x32_bf16 v[178:181], v[100:103], v[162:165], v[178:181]
	v_mfma_f32_16x16x32_bf16 v[182:185], v[96:99], v[194:197], v[182:185]
	v_mfma_f32_16x16x32_bf16 v[186:189], v[100:103], v[194:197], v[186:189]
	v_mfma_f32_16x16x32_bf16 v[8:11], v[120:123], v[206:209], v[8:11]
	v_mfma_f32_16x16x32_bf16 v[12:15], v[124:127], v[206:209], v[12:15]
	v_mfma_f32_16x16x32_bf16 v[166:169], v[120:123], v[158:161], v[166:169]
	v_mfma_f32_16x16x32_bf16 v[170:173], v[124:127], v[158:161], v[170:173]
	v_mfma_f32_16x16x32_bf16 v[174:177], v[120:123], v[190:193], v[174:177]
	v_mfma_f32_16x16x32_bf16 v[178:181], v[124:127], v[190:193], v[178:181]
	v_mfma_f32_16x16x32_bf16 v[182:185], v[120:123], v[198:201], v[182:185]
	v_mfma_f32_16x16x32_bf16 v[186:189], v[124:127], v[198:201], v[186:189]
	s_setprio 0
	s_barrier
	s_mov_b32 m0, s46
	v_lshl_add_u64 v[2:3], v[0:1], 0, s[18:19]
	global_load_lds_dwordx4 v[2:3], off
	v_lshl_add_u64 v[0:1], v[0:1], 0, s[20:21]
	s_mov_b32 m0, s29
	s_nop 0
	global_load_lds_dwordx4 v[0:1], off
	s_waitcnt vmcnt(6)
	s_barrier
	s_setprio 1
	v_mfma_f32_16x16x32_bf16 v[0:3], v[214:217], v[104:107], v[16:19]
	v_mfma_f32_16x16x32_bf16 v[16:19], v[218:221], v[104:107], v[20:23]
	v_mfma_f32_16x16x32_bf16 v[20:23], v[214:217], v[162:165], v[52:55]
	v_mfma_f32_16x16x32_bf16 v[52:55], v[218:221], v[162:165], v[108:111]
	v_mfma_f32_16x16x32_bf16 v[96:99], v[214:217], v[194:197], v[112:115]
	v_mfma_f32_16x16x32_bf16 v[100:103], v[218:221], v[194:197], v[116:119]
	v_mfma_f32_16x16x32_bf16 v[88:91], v[214:217], v[202:205], v[88:91]
	v_mfma_f32_16x16x32_bf16 v[92:95], v[218:221], v[202:205], v[92:95]
	v_mfma_f32_16x16x32_bf16 v[0:3], v[222:225], v[158:161], v[0:3]
	v_mfma_f32_16x16x32_bf16 v[16:19], v[226:229], v[158:161], v[16:19]
	v_mfma_f32_16x16x32_bf16 v[20:23], v[222:225], v[190:193], v[20:23]
	v_mfma_f32_16x16x32_bf16 v[52:55], v[226:229], v[190:193], v[52:55]
	v_mfma_f32_16x16x32_bf16 v[96:99], v[222:225], v[198:201], v[96:99]
	v_mfma_f32_16x16x32_bf16 v[100:103], v[226:229], v[198:201], v[100:103]
	v_mfma_f32_16x16x32_bf16 v[88:91], v[222:225], v[206:209], v[88:91]
	v_mfma_f32_16x16x32_bf16 v[92:95], v[226:229], v[206:209], v[92:95]
	s_setprio 0
	s_add_u32 s26, s37, s26
	s_addc_u32 s27, s38, s27
	s_mov_b32 m0, s28
	v_lshl_add_u64 v[138:139], s[26:27], 0, v[128:129]
	s_barrier
	ds_read_b128 v[104:107], v154
	ds_read_b128 v[108:111], v154 offset:256
	ds_read_b128 v[112:115], v155
	ds_read_b128 v[116:119], v155 offset:256
	ds_read_b128 v[120:123], v147
	ds_read_b128 v[124:127], v147 offset:1024
	ds_read_b128 v[158:161], v147 offset:2048
	ds_read_b128 v[162:165], v147 offset:3072
	ds_read_b128 v[190:193], v147 offset:4096
	ds_read_b128 v[194:197], v147 offset:5120
	ds_read_b128 v[198:201], v147 offset:6144
	ds_read_b128 v[202:205], v147 offset:7168
	global_load_lds_dwordx4 v[138:139], off
	v_lshl_add_u64 v[138:139], v[138:139], 0, s[6:7]
	s_mov_b32 m0, s23
	s_nop 0
	global_load_lds_dwordx4 v[138:139], off
	s_barrier
	s_waitcnt lgkmcnt(0)
	s_setprio 1
	v_mfma_f32_16x16x32_bf16 v[56:59], v[104:107], v[120:123], v[56:59]
	v_mfma_f32_16x16x32_bf16 v[60:63], v[108:111], v[120:123], v[60:63]
	v_mfma_f32_16x16x32_bf16 v[64:67], v[104:107], v[158:161], v[64:67]
	v_mfma_f32_16x16x32_bf16 v[68:71], v[108:111], v[158:161], v[68:71]
	v_mfma_f32_16x16x32_bf16 v[72:75], v[104:107], v[190:193], v[72:75]
	v_mfma_f32_16x16x32_bf16 v[76:79], v[108:111], v[190:193], v[76:79]
	v_mfma_f32_16x16x32_bf16 v[80:83], v[104:107], v[198:201], v[80:83]
	v_mfma_f32_16x16x32_bf16 v[84:87], v[108:111], v[198:201], v[84:87]
	v_mfma_f32_16x16x32_bf16 v[56:59], v[112:115], v[124:127], v[56:59]
	v_mfma_f32_16x16x32_bf16 v[60:63], v[116:119], v[124:127], v[60:63]
	v_mfma_f32_16x16x32_bf16 v[64:67], v[112:115], v[162:165], v[64:67]
	v_mfma_f32_16x16x32_bf16 v[68:71], v[116:119], v[162:165], v[68:71]
	v_mfma_f32_16x16x32_bf16 v[72:75], v[112:115], v[194:197], v[72:75]
	v_mfma_f32_16x16x32_bf16 v[76:79], v[116:119], v[194:197], v[76:79]
	v_mfma_f32_16x16x32_bf16 v[80:83], v[112:115], v[202:205], v[80:83]
	v_mfma_f32_16x16x32_bf16 v[84:87], v[116:119], v[202:205], v[84:87]
	s_setprio 0
	s_barrier
	ds_read_b128 v[206:209], v156
	ds_read_b128 v[210:213], v156 offset:256
	ds_read_b128 v[214:217], v157
	ds_read_b128 v[218:221], v157 offset:256
	s_barrier
	s_waitcnt lgkmcnt(0)
	s_setprio 1
	v_mfma_f32_16x16x32_bf16 v[4:7], v[206:209], v[120:123], v[4:7]
	v_mfma_f32_16x16x32_bf16 v[24:27], v[210:213], v[120:123], v[24:27]
	v_mfma_f32_16x16x32_bf16 v[28:31], v[206:209], v[158:161], v[28:31]
	v_mfma_f32_16x16x32_bf16 v[32:35], v[210:213], v[158:161], v[32:35]
	v_mfma_f32_16x16x32_bf16 v[36:39], v[206:209], v[190:193], v[36:39]
	v_mfma_f32_16x16x32_bf16 v[40:43], v[210:213], v[190:193], v[40:43]
	v_mfma_f32_16x16x32_bf16 v[44:47], v[206:209], v[198:201], v[44:47]
	v_mfma_f32_16x16x32_bf16 v[4:7], v[214:217], v[124:127], v[4:7]
	v_mfma_f32_16x16x32_bf16 v[24:27], v[218:221], v[124:127], v[24:27]
	v_mfma_f32_16x16x32_bf16 v[28:31], v[214:217], v[162:165], v[28:31]
	v_mfma_f32_16x16x32_bf16 v[32:35], v[218:221], v[162:165], v[32:35]
	v_mfma_f32_16x16x32_bf16 v[36:39], v[214:217], v[194:197], v[36:39]
	v_mfma_f32_16x16x32_bf16 v[40:43], v[218:221], v[194:197], v[40:43]
	v_mfma_f32_16x16x32_bf16 v[44:47], v[214:217], v[202:205], v[44:47]
	v_mfma_f32_16x16x32_bf16 v[48:51], v[210:213], v[198:201], v[48:51]
	v_mfma_f32_16x16x32_bf16 v[158:161], v[218:221], v[202:205], v[48:51]
	s_setprio 0
	s_barrier
; #define LDA(dst, b, h) for (int m = 0; m < 4; ++m) { \
;     dst[m][0] = *reinterpret_cast<const bf16x8*>((char*)SA(b, h) + aoff0 + m * 2048); \
;     dst[m][1] = *reinterpret_cast<const bf16x8*>((char*)SA(b, h) + aoff1 + m * 2048); }
; #define LDB(dst, b, h) for (int n = 0; n < 2; ++n) { \
;     dst[n][0] = *reinterpret_cast<const bf16x8*>((char*)SB(b, h) + boff0 + n * 256); \
;     dst[n][1] = *reinterpret_cast<const bf16x8*>((char*)SB(b, h) + boff1 + n * 256); }
; #define MMA(ai, bj, At, Btf) do { __builtin_amdgcn_s_setprio(1); \
;     for (int m = 0; m < 4; ++m) for (int n = 0; n < 2; ++n) for (int k = 0; k < 2; ++k) \
;       acc[ai][bj][m][n] = __builtin_amdgcn_mfma_f32_16x16x32_bf16(Btf[n][k], At[m][k], acc[ai][bj][m][n], 0, 0, 0); \
;     __builtin_amdgcn_s_setprio(0); } while (0)
; #define WAIT_V(n) asm volatile("s_waitcnt vmcnt(" #n ")" ::: "memory")
; #define WAIT_L(n) asm volatile("s_waitcnt lgkmcnt(" #n ")" ::: "memory")
; #define BAR __builtin_amdgcn_s_barrier()
; template <int EPI> ...
;     ...
;     LDA(At, 0, 1); WAIT_V(4); BAR; WAIT_L(0); MMA(1, 0, At, B0); MMA(1, 1, At, B1); BAR; }
;   { LDB(B0, 1, 0); LDA(At, 1, 0); WAIT_V(2); BAR; WAIT_L(0); MMA(0, 0, At, B0); BAR;
	s_nop 4
	ds_read_b128 v[48:51], v147 offset:16384
	ds_read_b128 v[120:123], v147 offset:17408
	ds_read_b128 v[124:127], v147 offset:18432
	ds_read_b128 v[162:165], v147 offset:19456
	ds_read_b128 v[190:193], v147 offset:20480
	ds_read_b128 v[194:197], v147 offset:21504
	ds_read_b128 v[198:201], v147 offset:22528
	ds_read_b128 v[202:205], v147 offset:23552
	s_waitcnt vmcnt(4)
	s_barrier
	s_waitcnt lgkmcnt(0)
	s_setprio 1
	v_mfma_f32_16x16x32_bf16 v[8:11], v[104:107], v[198:201], v[8:11]
	v_mfma_f32_16x16x32_bf16 v[12:15], v[108:111], v[198:201], v[12:15]
	v_mfma_f32_16x16x32_bf16 v[166:169], v[104:107], v[48:51], v[166:169]
	v_mfma_f32_16x16x32_bf16 v[170:173], v[108:111], v[48:51], v[170:173]
	v_mfma_f32_16x16x32_bf16 v[174:177], v[104:107], v[124:127], v[174:177]
	v_mfma_f32_16x16x32_bf16 v[178:181], v[108:111], v[124:127], v[178:181]
	v_mfma_f32_16x16x32_bf16 v[182:185], v[104:107], v[190:193], v[182:185]
	v_mfma_f32_16x16x32_bf16 v[186:189], v[108:111], v[190:193], v[186:189]
	v_mfma_f32_16x16x32_bf16 v[8:11], v[112:115], v[202:205], v[8:11]
	v_mfma_f32_16x16x32_bf16 v[12:15], v[116:119], v[202:205], v[12:15]
	v_mfma_f32_16x16x32_bf16 v[166:169], v[112:115], v[120:123], v[166:169]
	v_mfma_f32_16x16x32_bf16 v[170:173], v[116:119], v[120:123], v[170:173]
	v_mfma_f32_16x16x32_bf16 v[174:177], v[112:115], v[162:165], v[174:177]
	v_mfma_f32_16x16x32_bf16 v[178:181], v[116:119], v[162:165], v[178:181]
	v_mfma_f32_16x16x32_bf16 v[182:185], v[112:115], v[194:197], v[182:185]
	v_mfma_f32_16x16x32_bf16 v[186:189], v[116:119], v[194:197], v[186:189]
	v_mfma_f32_16x16x32_bf16 v[0:3], v[206:209], v[48:51], v[0:3]
	v_mfma_f32_16x16x32_bf16 v[16:19], v[210:213], v[48:51], v[16:19]
	v_mfma_f32_16x16x32_bf16 v[20:23], v[206:209], v[124:127], v[20:23]
	v_mfma_f32_16x16x32_bf16 v[48:51], v[210:213], v[124:127], v[52:55]
	v_mfma_f32_16x16x32_bf16 v[20:23], v[214:217], v[162:165], v[20:23]
	v_mfma_f32_16x16x32_bf16 v[162:165], v[218:221], v[162:165], v[48:51]
	v_mfma_f32_16x16x32_bf16 v[48:51], v[206:209], v[190:193], v[96:99]
	v_mfma_f32_16x16x32_bf16 v[222:225], v[214:217], v[194:197], v[48:51]
	v_mfma_f32_16x16x32_bf16 v[48:51], v[210:213], v[190:193], v[100:103]
	v_mfma_f32_16x16x32_bf16 v[190:193], v[218:221], v[194:197], v[48:51]
	v_mfma_f32_16x16x32_bf16 v[48:51], v[206:209], v[198:201], v[88:91]
	v_mfma_f32_16x16x32_bf16 v[0:3], v[214:217], v[120:123], v[0:3]
	v_mfma_f32_16x16x32_bf16 v[16:19], v[218:221], v[120:123], v[16:19]
	v_mfma_f32_16x16x32_bf16 v[194:197], v[214:217], v[202:205], v[48:51]
	v_mfma_f32_16x16x32_bf16 v[48:51], v[210:213], v[198:201], v[92:95]
	v_mfma_f32_16x16x32_bf16 v[198:201], v[218:221], v[202:205], v[48:51]
	s_setprio 0
	s_barrier
	ds_read_b128 v[202:205], v150
	ds_read_b128 v[206:209], v150 offset:256
	ds_read_b128 v[210:213], v151
	ds_read_b128 v[214:217], v151 offset:256
	s_nop 0
	ds_read_b128 v[48:51], v147 offset:32768
	ds_read_b128 v[52:55], v147 offset:33792
	ds_read_b128 v[92:95], v147 offset:34816
	ds_read_b128 v[218:221], v147 offset:35840
	ds_read_b128 v[226:229], v147 offset:36864
	ds_read_b128 v[230:233], v147 offset:37888
	ds_read_b128 v[234:237], v147 offset:38912
	ds_read_b128 v[238:241], v147 offset:39936
	s_waitcnt vmcnt(2)
	s_barrier
	s_waitcnt lgkmcnt(0)
	s_setprio 1
	v_mfma_f32_16x16x32_bf16 v[56:59], v[202:205], v[48:51], v[56:59]
	v_mfma_f32_16x16x32_bf16 v[120:123], v[210:213], v[52:55], v[56:59]
	v_mfma_f32_16x16x32_bf16 v[56:59], v[206:209], v[48:51], v[60:63]
	v_mfma_f32_16x16x32_bf16 v[124:127], v[214:217], v[52:55], v[56:59]
	v_mfma_f32_16x16x32_bf16 v[56:59], v[202:205], v[92:95], v[64:67]
	v_mfma_f32_16x16x32_bf16 v[112:115], v[210:213], v[218:221], v[56:59]
	v_mfma_f32_16x16x32_bf16 v[56:59], v[206:209], v[92:95], v[68:71]
	v_mfma_f32_16x16x32_bf16 v[116:119], v[214:217], v[218:221], v[56:59]
	v_mfma_f32_16x16x32_bf16 v[56:59], v[202:205], v[226:229], v[72:75]
	v_mfma_f32_16x16x32_bf16 v[104:107], v[210:213], v[230:233], v[56:59]
	v_mfma_f32_16x16x32_bf16 v[56:59], v[206:209], v[226:229], v[76:79]
	v_mfma_f32_16x16x32_bf16 v[108:111], v[214:217], v[230:233], v[56:59]
	v_mfma_f32_16x16x32_bf16 v[56:59], v[202:205], v[234:237], v[80:83]
	v_mfma_f32_16x16x32_bf16 v[80:83], v[210:213], v[238:241], v[56:59]
	v_mfma_f32_16x16x32_bf16 v[56:59], v[206:209], v[234:237], v[84:87]
	v_mfma_f32_16x16x32_bf16 v[84:87], v[214:217], v[238:241], v[56:59]
	s_setprio 0
	s_barrier
; #define LDA(dst, b, h) for (int m = 0; m < 4; ++m) { \
;     dst[m][0] = *reinterpret_cast<const bf16x8*>((char*)SA(b, h) + aoff0 + m * 2048); \
;     dst[m][1] = *reinterpret_cast<const bf16x8*>((char*)SA(b, h) + aoff1 + m * 2048); }
; #define LDB(dst, b, h) for (int n = 0; n < 2; ++n) { \
;     dst[n][0] = *reinterpret_cast<const bf16x8*>((char*)SB(b, h) + boff0 + n * 256); \
;     dst[n][1] = *reinterpret_cast<const bf16x8*>((char*)SB(b, h) + boff1 + n * 256); }
; #define MMA(ai, bj, At, Btf) do { __builtin_amdgcn_s_setprio(1); \
;     for (int m = 0; m < 4; ++m) for (int n = 0; n < 2; ++n) for (int k = 0; k < 2; ++k) \
;       acc[ai][bj][m][n] = __builtin_amdgcn_mfma_f32_16x16x32_bf16(Btf[n][k], At[m][k], acc[ai][bj][m][n], 0, 0, 0); \
;     __builtin_amdgcn_s_setprio(0); } while (0)
; #define WAIT_V(n) asm volatile("s_waitcnt vmcnt(" #n ")" ::: "memory")
; #define WAIT_L(n) asm volatile("s_waitcnt lgkmcnt(" #n ")" ::: "memory")
; #define BAR __builtin_amdgcn_s_barrier()
; template <int EPI> ...
;     ...
;     LDB(B1, 1, 1); WAIT_V(0); BAR; WAIT_L(0); MMA(0, 1, At, B1); BAR;
;     LDA(At, 1, 1); BAR; WAIT_L(0); MMA(1, 0, At, B0); MMA(1, 1, At, B1); BAR; }
;   if (wr == 0) BAR;
	ds_read_b128 v[242:245], v152
	ds_read_b128 v[246:249], v152 offset:256
	ds_read_b128 v[250:253], v153
	ds_read_b128 v[138:141], v153 offset:256
	s_waitcnt vmcnt(0)
	s_barrier
	s_waitcnt lgkmcnt(0)
	s_setprio 1
	v_mfma_f32_16x16x32_bf16 v[4:7], v[242:245], v[48:51], v[4:7]
	v_mfma_f32_16x16x32_bf16 v[96:99], v[250:253], v[52:55], v[4:7]
	v_mfma_f32_16x16x32_bf16 v[4:7], v[246:249], v[48:51], v[24:27]
	v_mfma_f32_16x16x32_bf16 v[100:103], v[138:141], v[52:55], v[4:7]
	v_mfma_f32_16x16x32_bf16 v[4:7], v[242:245], v[92:95], v[28:31]
	v_mfma_f32_16x16x32_bf16 v[88:91], v[250:253], v[218:221], v[4:7]
	v_mfma_f32_16x16x32_bf16 v[4:7], v[246:249], v[92:95], v[32:35]
	v_mfma_f32_16x16x32_bf16 v[92:95], v[138:141], v[218:221], v[4:7]
	v_mfma_f32_16x16x32_bf16 v[4:7], v[242:245], v[226:229], v[36:39]
	v_mfma_f32_16x16x32_bf16 v[64:67], v[250:253], v[230:233], v[4:7]
	v_mfma_f32_16x16x32_bf16 v[4:7], v[246:249], v[226:229], v[40:43]
	v_mfma_f32_16x16x32_bf16 v[68:71], v[138:141], v[230:233], v[4:7]
	v_mfma_f32_16x16x32_bf16 v[4:7], v[242:245], v[234:237], v[44:47]
	v_mfma_f32_16x16x32_bf16 v[48:51], v[250:253], v[238:241], v[4:7]
	v_mfma_f32_16x16x32_bf16 v[4:7], v[246:249], v[234:237], v[158:161]
	v_mfma_f32_16x16x32_bf16 v[52:55], v[138:141], v[238:241], v[4:7]
	s_setprio 0
	s_barrier
	s_nop 4
	ds_read_b128 v[4:7], v147 offset:49152
	ds_read_b128 v[28:31], v147 offset:50176
	ds_read_b128 v[158:161], v147 offset:51200
	ds_read_b128 v[218:221], v147 offset:52224
	ds_read_b128 v[226:229], v147 offset:53248
	ds_read_b128 v[230:233], v147 offset:54272
	ds_read_b128 v[234:237], v147 offset:55296
	ds_read_b128 v[238:241], v147 offset:56320
	s_barrier
	s_waitcnt lgkmcnt(0)
	s_setprio 1
	v_mfma_f32_16x16x32_bf16 v[24:27], v[202:205], v[4:7], v[166:169]
	v_mfma_f32_16x16x32_bf16 v[72:75], v[210:213], v[28:31], v[24:27]
	v_mfma_f32_16x16x32_bf16 v[24:27], v[206:209], v[4:7], v[170:173]
	v_mfma_f32_16x16x32_bf16 v[76:79], v[214:217], v[28:31], v[24:27]
	v_mfma_f32_16x16x32_bf16 v[24:27], v[202:205], v[158:161], v[174:177]
	v_mfma_f32_16x16x32_bf16 v[56:59], v[210:213], v[218:221], v[24:27]
	v_mfma_f32_16x16x32_bf16 v[24:27], v[206:209], v[158:161], v[178:181]
	v_mfma_f32_16x16x32_bf16 v[60:63], v[214:217], v[218:221], v[24:27]
	v_mfma_f32_16x16x32_bf16 v[24:27], v[202:205], v[226:229], v[182:185]
	v_mfma_f32_16x16x32_bf16 v[8:11], v[202:205], v[234:237], v[8:11]
	v_mfma_f32_16x16x32_bf16 v[40:43], v[210:213], v[230:233], v[24:27]
	v_mfma_f32_16x16x32_bf16 v[24:27], v[206:209], v[226:229], v[186:189]
	v_mfma_f32_16x16x32_bf16 v[32:35], v[210:213], v[238:241], v[8:11]
	v_mfma_f32_16x16x32_bf16 v[8:11], v[206:209], v[234:237], v[12:15]
	v_mfma_f32_16x16x32_bf16 v[44:47], v[214:217], v[230:233], v[24:27]
	v_mfma_f32_16x16x32_bf16 v[36:39], v[214:217], v[238:241], v[8:11]
	v_mfma_f32_16x16x32_bf16 v[0:3], v[242:245], v[4:7], v[0:3]
	v_mfma_f32_16x16x32_bf16 v[24:27], v[250:253], v[28:31], v[0:3]
	v_mfma_f32_16x16x32_bf16 v[0:3], v[246:249], v[4:7], v[16:19]
	v_mfma_f32_16x16x32_bf16 v[28:31], v[138:141], v[28:31], v[0:3]
	v_mfma_f32_16x16x32_bf16 v[0:3], v[242:245], v[158:161], v[20:23]
	v_mfma_f32_16x16x32_bf16 v[16:19], v[250:253], v[218:221], v[0:3]
	v_mfma_f32_16x16x32_bf16 v[0:3], v[246:249], v[158:161], v[162:165]
	v_mfma_f32_16x16x32_bf16 v[20:23], v[138:141], v[218:221], v[0:3]
	v_mfma_f32_16x16x32_bf16 v[0:3], v[242:245], v[226:229], v[222:225]
	v_mfma_f32_16x16x32_bf16 v[8:11], v[250:253], v[230:233], v[0:3]
	v_mfma_f32_16x16x32_bf16 v[0:3], v[246:249], v[226:229], v[190:193]
	v_mfma_f32_16x16x32_bf16 v[12:15], v[138:141], v[230:233], v[0:3]
	v_mfma_f32_16x16x32_bf16 v[0:3], v[242:245], v[234:237], v[194:197]
	v_mfma_f32_16x16x32_bf16 v[4:7], v[246:249], v[234:237], v[198:201]
	v_mfma_f32_16x16x32_bf16 v[0:3], v[250:253], v[238:241], v[0:3]
	v_mfma_f32_16x16x32_bf16 v[4:7], v[138:141], v[238:241], v[4:7]
	s_setprio 0
	s_barrier
	s_and_saveexec_b64 s[26:27], s[2:3]
	s_cbranch_execz .LBB0_845
	s_barrier
	s_branch .LBB0_845

; #define STAGE(P, BASE, br, kt) do { const char* _gb = (const char*)(BASE) + ((size_t)(br) * K + (size_t)(kt) * BK) * 2; \
;     __builtin_amdgcn_global_load_lds((const unsigned*)(_gb + loff0), (unsigned*)((char*)(P) + tid * 16), 16, 0, 0); \
;     __builtin_amdgcn_global_load_lds((const unsigned*)(_gb + (size_t)K * 128 + loff0), (unsigned*)((char*)(P) + tid * 16 + 8192), 16, 0, 0); } while (0)
; #define LDA(dst, b, h) for (int m = 0; m < 4; ++m) { \
;     dst[m][0] = *reinterpret_cast<const bf16x8*>((char*)SA(b, h) + aoff0 + m * 2048); \
;     dst[m][1] = *reinterpret_cast<const bf16x8*>((char*)SA(b, h) + aoff1 + m * 2048); }
; #define LDB(dst, b, h) for (int n = 0; n < 2; ++n) { \
;     dst[n][0] = *reinterpret_cast<const bf16x8*>((char*)SB(b, h) + boff0 + n * 256); \
;     dst[n][1] = *reinterpret_cast<const bf16x8*>((char*)SB(b, h) + boff1 + n * 256); }
; #define MMA(ai, bj, At, Btf) do { __builtin_amdgcn_s_setprio(1); \
;     for (int m = 0; m < 4; ++m) for (int n = 0; n < 2; ++n) for (int k = 0; k < 2; ++k) \
;       acc[ai][bj][m][n] = __builtin_amdgcn_mfma_f32_16x16x32_bf16(Btf[n][k], At[m][k], acc[ai][bj][m][n], 0, 0, 0); \
;     __builtin_amdgcn_s_setprio(0); } while (0)
; #define WAIT_V(n) asm volatile("s_waitcnt vmcnt(" #n ")" ::: "memory")
; #define WAIT_L(n) asm volatile("s_waitcnt lgkmcnt(" #n ")" ::: "memory")
; #define BAR __builtin_amdgcn_s_barrier()
; #define SCHED __builtin_amdgcn_sched_barrier(0)
; template <int EPI> ...
;     ...
;   STAGE(SB(1, 0), Bt, bcol, 1); STAGE(SA(1, 0), A, brow, 1); STAGE(SB(1, 1), Bt, bcol + HALF, 1);
;   WAIT_V(6); BAR;
;   for (int t = 0; t < nt - 2; t += 2) {
;     LDB(B0, 0, 0); SCHED; LDA(At, 0, 0); STAGE(SA(1, 1), A, brow + HALF, t + 1);
;     WAIT_L(8); BAR; WAIT_L(0); MMA(0, 0, At, B0); BAR; SCHED;
;     LDB(B1, 0, 1); STAGE(SB(0, 0), Bt, bcol, t + 2);
;     BAR; WAIT_L(0); MMA(0, 1, At, B1); BAR;
;     LDA(At, 0, 1); STAGE(SA(0, 0), A, brow, t + 2);
;     BAR; WAIT_L(0); MMA(1, 0, At, B0); BAR; SCHED;
.LBB0_972:
	s_or_b64 exec, exec, s[52:53]
	v_readfirstlane_b32 s52, v164
	v_add_u32_e32 v10, 0x2000, v164
	v_lshl_add_u64 v[8:9], v[6:7], 0, s[8:9]
	s_mov_b32 m0, s52
	v_readfirstlane_b32 s49, v10
	s_waitcnt vmcnt(4)
	s_barrier
	global_load_lds_dwordx4 v[8:9], off
	v_lshl_add_u64 v[8:9], v[6:7], 0, s[10:11]
	s_mov_b32 m0, s49
	v_readfirstlane_b32 s72, v254
	global_load_lds_dwordx4 v[8:9], off
	v_lshl_add_u64 v[8:9], v[4:5], 0, s[8:9]
	s_mov_b32 m0, s72
	v_readfirstlane_b32 s71, v165
	global_load_lds_dwordx4 v[8:9], off
	v_lshl_add_u64 v[8:9], v[4:5], 0, s[10:11]
	s_mov_b32 m0, s71
	v_readfirstlane_b32 s70, v168
	global_load_lds_dwordx4 v[8:9], off
	v_lshl_add_u64 v[8:9], v[2:3], 0, s[8:9]
	s_mov_b32 m0, s70
	v_readfirstlane_b32 s69, v169
	global_load_lds_dwordx4 v[8:9], off
	v_lshl_add_u64 v[8:9], v[2:3], 0, s[10:11]
	s_mov_b32 m0, s69
	s_nop 0
	global_load_lds_dwordx4 v[8:9], off
	s_waitcnt vmcnt(6)
	s_barrier
	ds_read_b128 v[8:11], v176
	ds_read_b128 v[12:15], v176 offset:256
	ds_read_b128 v[16:19], v177
	s_waitcnt vmcnt(0)
	ds_read_b128 v[20:23], v177 offset:256
	v_readfirstlane_b32 s66, v170
	v_lshl_add_u64 v[56:57], v[0:1], 0, s[8:9]
	s_mov_b32 m0, s66
	v_readfirstlane_b32 s53, v171
	ds_read_b128 v[24:27], v154
	ds_read_b128 v[28:31], v154 offset:1024
	ds_read_b128 v[32:35], v154 offset:2048
	ds_read_b128 v[36:39], v154 offset:3072
	ds_read_b128 v[40:43], v154 offset:4096
	ds_read_b128 v[44:47], v154 offset:5120
	ds_read_b128 v[48:51], v154 offset:6144
	ds_read_b128 v[52:55], v154 offset:7168
	global_load_lds_dwordx4 v[56:57], off
	v_lshl_add_u64 v[56:57], v[0:1], 0, s[10:11]
	s_mov_b32 m0, s53
	s_nop 0
	global_load_lds_dwordx4 v[56:57], off
	s_waitcnt lgkmcnt(8)
	s_barrier
	s_waitcnt lgkmcnt(0)
	s_setprio 1
	v_mfma_f32_16x16x32_bf16 v[56:59], v[8:11], v[24:27], 0
	v_mfma_f32_16x16x32_bf16 v[60:63], v[12:15], v[24:27], 0
	v_mfma_f32_16x16x32_bf16 v[64:67], v[8:11], v[32:35], 0
	v_mfma_f32_16x16x32_bf16 v[68:71], v[12:15], v[32:35], 0
	v_mfma_f32_16x16x32_bf16 v[72:75], v[8:11], v[40:43], 0
	v_mfma_f32_16x16x32_bf16 v[76:79], v[12:15], v[40:43], 0
	v_mfma_f32_16x16x32_bf16 v[80:83], v[8:11], v[48:51], 0
	v_mfma_f32_16x16x32_bf16 v[84:87], v[12:15], v[48:51], 0
	v_mfma_f32_16x16x32_bf16 v[56:59], v[16:19], v[28:31], v[56:59]
	v_mfma_f32_16x16x32_bf16 v[60:63], v[20:23], v[28:31], v[60:63]
	v_mfma_f32_16x16x32_bf16 v[64:67], v[16:19], v[36:39], v[64:67]
	v_mfma_f32_16x16x32_bf16 v[68:71], v[20:23], v[36:39], v[68:71]
	v_mfma_f32_16x16x32_bf16 v[72:75], v[16:19], v[44:47], v[72:75]
	v_mfma_f32_16x16x32_bf16 v[76:79], v[20:23], v[44:47], v[76:79]
	v_mfma_f32_16x16x32_bf16 v[80:83], v[16:19], v[52:55], v[80:83]
	v_mfma_f32_16x16x32_bf16 v[84:87], v[20:23], v[52:55], v[84:87]
	s_setprio 0
	s_barrier
	v_readfirstlane_b32 s65, v156
	v_lshl_add_u64 v[104:105], v[6:7], 0, s[12:13]
	s_mov_b32 m0, s65
	v_readfirstlane_b32 s60, v157
	ds_read_b128 v[88:91], v178
	ds_read_b128 v[92:95], v178 offset:256
	ds_read_b128 v[96:99], v179
	ds_read_b128 v[100:103], v179 offset:256
	global_load_lds_dwordx4 v[104:105], off
	v_lshl_add_u64 v[104:105], v[6:7], 0, s[16:17]
	s_mov_b32 m0, s60
	s_nop 0
	global_load_lds_dwordx4 v[104:105], off
	s_barrier
	s_waitcnt lgkmcnt(0)
	s_setprio 1
	s_waitcnt lgkmcnt(0)
	v_mfma_f32_16x16x32_bf16 v[104:107], v[88:91], v[24:27], 0
	v_mfma_f32_16x16x32_bf16 v[24:27], v[92:95], v[24:27], 0
	v_mfma_f32_16x16x32_bf16 v[104:107], v[96:99], v[28:31], v[104:107]
	v_mfma_f32_16x16x32_bf16 v[24:27], v[100:103], v[28:31], v[24:27]
	v_mfma_f32_16x16x32_bf16 v[28:31], v[88:91], v[32:35], 0
	v_mfma_f32_16x16x32_bf16 v[32:35], v[92:95], v[32:35], 0
	v_mfma_f32_16x16x32_bf16 v[28:31], v[96:99], v[36:39], v[28:31]
	v_mfma_f32_16x16x32_bf16 v[32:35], v[100:103], v[36:39], v[32:35]
	v_mfma_f32_16x16x32_bf16 v[36:39], v[88:91], v[40:43], 0
	v_mfma_f32_16x16x32_bf16 v[40:43], v[92:95], v[40:43], 0
	v_mfma_f32_16x16x32_bf16 v[36:39], v[96:99], v[44:47], v[36:39]
	v_mfma_f32_16x16x32_bf16 v[40:43], v[100:103], v[44:47], v[40:43]
	v_mfma_f32_16x16x32_bf16 v[44:47], v[88:91], v[48:51], 0
	v_mfma_f32_16x16x32_bf16 v[48:51], v[92:95], v[48:51], 0
	v_mfma_f32_16x16x32_bf16 v[44:47], v[96:99], v[52:55], v[44:47]
	v_mfma_f32_16x16x32_bf16 v[48:51], v[100:103], v[52:55], v[48:51]
	s_setprio 0
	v_readfirstlane_b32 s67, v158
	v_lshl_add_u64 v[138:139], v[4:5], 0, s[12:13]
	s_mov_b32 m0, s67
	v_readfirstlane_b32 s61, v159
	s_barrier
	ds_read_b128 v[52:55], v154 offset:16384
	ds_read_b128 v[108:111], v154 offset:17408
	ds_read_b128 v[112:115], v154 offset:18432
	ds_read_b128 v[116:119], v154 offset:19456
	ds_read_b128 v[120:123], v154 offset:20480
	ds_read_b128 v[124:127], v154 offset:21504
	ds_read_b128 v[128:131], v154 offset:22528
	ds_read_b128 v[132:135], v154 offset:23552
	global_load_lds_dwordx4 v[138:139], off
	v_lshl_add_u64 v[138:139], v[4:5], 0, s[16:17]
	s_mov_b32 m0, s61
	s_nop 0
	global_load_lds_dwordx4 v[138:139], off
	s_barrier
	s_waitcnt lgkmcnt(0)
	s_setprio 1
	v_mfma_f32_16x16x32_bf16 v[142:145], v[8:11], v[52:55], 0
	v_mfma_f32_16x16x32_bf16 v[146:149], v[12:15], v[52:55], 0
	v_mfma_f32_16x16x32_bf16 v[150:153], v[8:11], v[112:115], 0
	v_mfma_f32_16x16x32_bf16 v[180:183], v[12:15], v[112:115], 0
	v_mfma_f32_16x16x32_bf16 v[184:187], v[8:11], v[120:123], 0
	v_mfma_f32_16x16x32_bf16 v[188:191], v[12:15], v[120:123], 0
	v_mfma_f32_16x16x32_bf16 v[8:11], v[8:11], v[128:131], 0
	v_mfma_f32_16x16x32_bf16 v[12:15], v[12:15], v[128:131], 0
	v_mfma_f32_16x16x32_bf16 v[8:11], v[16:19], v[132:135], v[8:11]
	v_mfma_f32_16x16x32_bf16 v[12:15], v[20:23], v[132:135], v[12:15]
	v_mfma_f32_16x16x32_bf16 v[142:145], v[16:19], v[108:111], v[142:145]
	v_mfma_f32_16x16x32_bf16 v[146:149], v[20:23], v[108:111], v[146:149]
	v_mfma_f32_16x16x32_bf16 v[150:153], v[16:19], v[116:119], v[150:153]
	v_mfma_f32_16x16x32_bf16 v[180:183], v[20:23], v[116:119], v[180:183]
	v_mfma_f32_16x16x32_bf16 v[184:187], v[16:19], v[124:127], v[184:187]
	v_mfma_f32_16x16x32_bf16 v[188:191], v[20:23], v[124:127], v[188:191]
	s_setprio 0
	s_barrier
; #define STAGE(P, BASE, br, kt) do { const char* _gb = (const char*)(BASE) + ((size_t)(br) * K + (size_t)(kt) * BK) * 2; \
;     __builtin_amdgcn_global_load_lds((const unsigned*)(_gb + loff0), (unsigned*)((char*)(P) + tid * 16), 16, 0, 0); \
;     __builtin_amdgcn_global_load_lds((const unsigned*)(_gb + (size_t)K * 128 + loff0), (unsigned*)((char*)(P) + tid * 16 + 8192), 16, 0, 0); } while (0)
; #define LDA(dst, b, h) for (int m = 0; m < 4; ++m) { \
;     dst[m][0] = *reinterpret_cast<const bf16x8*>((char*)SA(b, h) + aoff0 + m * 2048); \
;     dst[m][1] = *reinterpret_cast<const bf16x8*>((char*)SA(b, h) + aoff1 + m * 2048); }
; #define LDB(dst, b, h) for (int n = 0; n < 2; ++n) { \
;     dst[n][0] = *reinterpret_cast<const bf16x8*>((char*)SB(b, h) + boff0 + n * 256); \
;     dst[n][1] = *reinterpret_cast<const bf16x8*>((char*)SB(b, h) + boff1 + n * 256); }
; #define MMA(ai, bj, At, Btf) do { __builtin_amdgcn_s_setprio(1); \
;     for (int m = 0; m < 4; ++m) for (int n = 0; n < 2; ++n) for (int k = 0; k < 2; ++k) \
;       acc[ai][bj][m][n] = __builtin_amdgcn_mfma_f32_16x16x32_bf16(Btf[n][k], At[m][k], acc[ai][bj][m][n], 0, 0, 0); \
;     __builtin_amdgcn_s_setprio(0); } while (0)
; #define WAIT_V(n) asm volatile("s_waitcnt vmcnt(" #n ")" ::: "memory")
; #define WAIT_L(n) asm volatile("s_waitcnt lgkmcnt(" #n ")" ::: "memory")
; #define BAR __builtin_amdgcn_s_barrier()
; #define SCHED __builtin_amdgcn_sched_barrier(0)
; template <int EPI> ...
;     ...
;     STAGE(SB(0, 1), Bt, bcol + HALF, t + 2);
;     WAIT_V(6); BAR; MMA(1, 1, At, B1); BAR;
;     LDB(B0, 1, 0); SCHED; LDA(At, 1, 0); STAGE(SA(0, 1), A, brow + HALF, t + 2);
;     WAIT_L(8); BAR; WAIT_L(0); MMA(0, 0, At, B0); BAR; SCHED;
;     LDB(B1, 1, 1); STAGE(SB(1, 0), Bt, bcol, t + 3);
;     BAR; WAIT_L(0); MMA(0, 1, At, B1); BAR;
;     LDA(At, 1, 1); STAGE(SA(1, 0), A, brow, t + 3);
	v_readfirstlane_b32 s64, v160
	v_lshl_add_u64 v[16:17], v[2:3], 0, s[12:13]
	s_mov_b32 m0, s64
	v_readfirstlane_b32 s62, v161
	global_load_lds_dwordx4 v[16:17], off
	v_lshl_add_u64 v[16:17], v[2:3], 0, s[16:17]
	s_mov_b32 m0, s62
	s_nop 0
	global_load_lds_dwordx4 v[16:17], off
	s_waitcnt vmcnt(6)
	s_barrier
	s_setprio 1
	v_mfma_f32_16x16x32_bf16 v[16:19], v[88:91], v[52:55], 0
	v_mfma_f32_16x16x32_bf16 v[20:23], v[92:95], v[52:55], 0
	v_mfma_f32_16x16x32_bf16 v[16:19], v[96:99], v[108:111], v[16:19]
	v_mfma_f32_16x16x32_bf16 v[20:23], v[100:103], v[108:111], v[20:23]
	v_mfma_f32_16x16x32_bf16 v[52:55], v[88:91], v[112:115], 0
	v_mfma_f32_16x16x32_bf16 v[108:111], v[92:95], v[112:115], 0
	v_mfma_f32_16x16x32_bf16 v[52:55], v[96:99], v[116:119], v[52:55]
	v_mfma_f32_16x16x32_bf16 v[108:111], v[100:103], v[116:119], v[108:111]
	v_mfma_f32_16x16x32_bf16 v[112:115], v[88:91], v[120:123], 0
	v_mfma_f32_16x16x32_bf16 v[116:119], v[92:95], v[120:123], 0
	v_mfma_f32_16x16x32_bf16 v[88:91], v[88:91], v[128:131], 0
	v_mfma_f32_16x16x32_bf16 v[92:95], v[92:95], v[128:131], 0
	v_mfma_f32_16x16x32_bf16 v[112:115], v[96:99], v[124:127], v[112:115]
	v_mfma_f32_16x16x32_bf16 v[116:119], v[100:103], v[124:127], v[116:119]
	v_mfma_f32_16x16x32_bf16 v[88:91], v[96:99], v[132:135], v[88:91]
	v_mfma_f32_16x16x32_bf16 v[92:95], v[100:103], v[132:135], v[92:95]
	s_setprio 0
	s_barrier
	ds_read_b128 v[96:99], v172
	ds_read_b128 v[100:103], v172 offset:256
	ds_read_b128 v[120:123], v173
	ds_read_b128 v[124:127], v173 offset:256
	v_readfirstlane_b32 s68, v162
	v_lshl_add_u64 v[138:139], v[0:1], 0, s[12:13]
	s_mov_b32 m0, s68
	v_readfirstlane_b32 s63, v163
	ds_read_b128 v[128:131], v154 offset:32768
	ds_read_b128 v[132:135], v154 offset:33792
	ds_read_b128 v[192:195], v154 offset:34816
	ds_read_b128 v[196:199], v154 offset:35840
	ds_read_b128 v[200:203], v154 offset:36864
	ds_read_b128 v[204:207], v154 offset:37888
	ds_read_b128 v[208:211], v154 offset:38912
	ds_read_b128 v[212:215], v154 offset:39936
	global_load_lds_dwordx4 v[138:139], off
	v_lshl_add_u64 v[138:139], v[0:1], 0, s[16:17]
	s_mov_b32 m0, s63
	s_nop 0
	global_load_lds_dwordx4 v[138:139], off
	s_waitcnt lgkmcnt(8)
	s_barrier
	s_waitcnt lgkmcnt(0)
	s_setprio 1
	v_mfma_f32_16x16x32_bf16 v[56:59], v[96:99], v[128:131], v[56:59]
	v_mfma_f32_16x16x32_bf16 v[60:63], v[100:103], v[128:131], v[60:63]
	v_mfma_f32_16x16x32_bf16 v[64:67], v[96:99], v[192:195], v[64:67]
	v_mfma_f32_16x16x32_bf16 v[68:71], v[100:103], v[192:195], v[68:71]
	v_mfma_f32_16x16x32_bf16 v[72:75], v[96:99], v[200:203], v[72:75]
	v_mfma_f32_16x16x32_bf16 v[76:79], v[100:103], v[200:203], v[76:79]
	v_mfma_f32_16x16x32_bf16 v[80:83], v[96:99], v[208:211], v[80:83]
	v_mfma_f32_16x16x32_bf16 v[84:87], v[100:103], v[208:211], v[84:87]
	v_mfma_f32_16x16x32_bf16 v[56:59], v[120:123], v[132:135], v[56:59]
	v_mfma_f32_16x16x32_bf16 v[60:63], v[124:127], v[132:135], v[60:63]
	v_mfma_f32_16x16x32_bf16 v[64:67], v[120:123], v[196:199], v[64:67]
	v_mfma_f32_16x16x32_bf16 v[68:71], v[124:127], v[196:199], v[68:71]
	v_mfma_f32_16x16x32_bf16 v[72:75], v[120:123], v[204:207], v[72:75]
	v_mfma_f32_16x16x32_bf16 v[76:79], v[124:127], v[204:207], v[76:79]
	v_mfma_f32_16x16x32_bf16 v[80:83], v[120:123], v[212:215], v[80:83]
	v_mfma_f32_16x16x32_bf16 v[84:87], v[124:127], v[212:215], v[84:87]
	s_setprio 0
	s_barrier
	s_mov_b32 m0, s52
	v_lshl_add_u64 v[138:139], v[6:7], 0, s[18:19]
	ds_read_b128 v[216:219], v174
	ds_read_b128 v[220:223], v174 offset:256
	ds_read_b128 v[224:227], v175
	ds_read_b128 v[228:231], v175 offset:256
	global_load_lds_dwordx4 v[138:139], off
	v_lshl_add_u64 v[138:139], v[6:7], 0, s[20:21]
	s_mov_b32 m0, s49
	s_nop 0
	global_load_lds_dwordx4 v[138:139], off
	s_barrier
	s_waitcnt lgkmcnt(0)
	s_setprio 1
	s_waitcnt lgkmcnt(0)
	v_mfma_f32_16x16x32_bf16 v[104:107], v[216:219], v[128:131], v[104:107]
	v_mfma_f32_16x16x32_bf16 v[24:27], v[220:223], v[128:131], v[24:27]
	v_mfma_f32_16x16x32_bf16 v[28:31], v[216:219], v[192:195], v[28:31]
	v_mfma_f32_16x16x32_bf16 v[32:35], v[220:223], v[192:195], v[32:35]
	v_mfma_f32_16x16x32_bf16 v[36:39], v[216:219], v[200:203], v[36:39]
	v_mfma_f32_16x16x32_bf16 v[40:43], v[220:223], v[200:203], v[40:43]
	v_mfma_f32_16x16x32_bf16 v[44:47], v[216:219], v[208:211], v[44:47]
	v_mfma_f32_16x16x32_bf16 v[48:51], v[220:223], v[208:211], v[48:51]
	v_mfma_f32_16x16x32_bf16 v[104:107], v[224:227], v[132:135], v[104:107]
	v_mfma_f32_16x16x32_bf16 v[24:27], v[228:231], v[132:135], v[24:27]
	v_mfma_f32_16x16x32_bf16 v[28:31], v[224:227], v[196:199], v[28:31]
	v_mfma_f32_16x16x32_bf16 v[32:35], v[228:231], v[196:199], v[32:35]
	v_mfma_f32_16x16x32_bf16 v[36:39], v[224:227], v[204:207], v[36:39]
	v_mfma_f32_16x16x32_bf16 v[40:43], v[228:231], v[204:207], v[40:43]
	v_mfma_f32_16x16x32_bf16 v[44:47], v[224:227], v[212:215], v[44:47]
	v_mfma_f32_16x16x32_bf16 v[48:51], v[228:231], v[212:215], v[48:51]
	s_setprio 0
	s_mov_b32 m0, s72
	v_lshl_add_u64 v[138:139], v[4:5], 0, s[18:19]
	s_barrier
	ds_read_b128 v[128:131], v154 offset:49152
	ds_read_b128 v[132:135], v154 offset:50176
	ds_read_b128 v[192:195], v154 offset:51200
	ds_read_b128 v[196:199], v154 offset:52224
	ds_read_b128 v[200:203], v154 offset:53248
	ds_read_b128 v[204:207], v154 offset:54272
	ds_read_b128 v[208:211], v154 offset:55296
	ds_read_b128 v[212:215], v154 offset:56320
	global_load_lds_dwordx4 v[138:139], off
	v_lshl_add_u64 v[138:139], v[4:5], 0, s[20:21]
	s_mov_b32 m0, s71
	s_nop 0
	global_load_lds_dwordx4 v[138:139], off
	s_barrier
; #define STAGE(P, BASE, br, kt) do { const char* _gb = (const char*)(BASE) + ((size_t)(br) * K + (size_t)(kt) * BK) * 2; \
;     __builtin_amdgcn_global_load_lds((const unsigned*)(_gb + loff0), (unsigned*)((char*)(P) + tid * 16), 16, 0, 0); \
;     __builtin_amdgcn_global_load_lds((const unsigned*)(_gb + (size_t)K * 128 + loff0), (unsigned*)((char*)(P) + tid * 16 + 8192), 16, 0, 0); } while (0)
; #define LDA(dst, b, h) for (int m = 0; m < 4; ++m) { \
;     dst[m][0] = *reinterpret_cast<const bf16x8*>((char*)SA(b, h) + aoff0 + m * 2048); \
;     dst[m][1] = *reinterpret_cast<const bf16x8*>((char*)SA(b, h) + aoff1 + m * 2048); }
; #define LDB(dst, b, h) for (int n = 0; n < 2; ++n) { \
;     dst[n][0] = *reinterpret_cast<const bf16x8*>((char*)SB(b, h) + boff0 + n * 256); \
;     dst[n][1] = *reinterpret_cast<const bf16x8*>((char*)SB(b, h) + boff1 + n * 256); }
; #define MMA(ai, bj, At, Btf) do { __builtin_amdgcn_s_setprio(1); \
;     for (int m = 0; m < 4; ++m) for (int n = 0; n < 2; ++n) for (int k = 0; k < 2; ++k) \
;       acc[ai][bj][m][n] = __builtin_amdgcn_mfma_f32_16x16x32_bf16(Btf[n][k], At[m][k], acc[ai][bj][m][n], 0, 0, 0); \
;     __builtin_amdgcn_s_setprio(0); } while (0)
; #define WAIT_V(n) asm volatile("s_waitcnt vmcnt(" #n ")" ::: "memory")
; #define WAIT_L(n) asm volatile("s_waitcnt lgkmcnt(" #n ")" ::: "memory")
; #define BAR __builtin_amdgcn_s_barrier()
; #define SCHED __builtin_amdgcn_sched_barrier(0)
; template <int EPI> ...
;     ...
;     LDB(B0, 0, 0); SCHED; LDA(At, 0, 0); STAGE(SA(1, 1), A, brow + HALF, t + 1);
;     WAIT_L(8); BAR; WAIT_L(0); MMA(0, 0, At, B0); BAR; SCHED;
;     LDB(B1, 0, 1); STAGE(SB(0, 0), Bt, bcol, t + 2);
;     BAR; WAIT_L(0); MMA(0, 1, At, B1); BAR;
;     ...
;     BAR; WAIT_L(0); MMA(1, 0, At, B0); BAR; SCHED;
;     STAGE(SB(1, 1), Bt, bcol + HALF, t + 3);
;     WAIT_V(6); BAR; MMA(1, 1, At, B1); BAR;
	s_waitcnt lgkmcnt(0)
	s_setprio 1
	v_mfma_f32_16x16x32_bf16 v[8:11], v[96:99], v[208:211], v[8:11]
	v_mfma_f32_16x16x32_bf16 v[12:15], v[100:103], v[208:211], v[12:15]
	v_mfma_f32_16x16x32_bf16 v[142:145], v[96:99], v[128:131], v[142:145]
	v_mfma_f32_16x16x32_bf16 v[146:149], v[100:103], v[128:131], v[146:149]
	v_mfma_f32_16x16x32_bf16 v[150:153], v[96:99], v[192:195], v[150:153]
	v_mfma_f32_16x16x32_bf16 v[180:183], v[100:103], v[192:195], v[180:183]
	v_mfma_f32_16x16x32_bf16 v[184:187], v[96:99], v[200:203], v[184:187]
	v_mfma_f32_16x16x32_bf16 v[188:191], v[100:103], v[200:203], v[188:191]
	v_mfma_f32_16x16x32_bf16 v[8:11], v[120:123], v[212:215], v[8:11]
	v_mfma_f32_16x16x32_bf16 v[12:15], v[124:127], v[212:215], v[12:15]
	v_mfma_f32_16x16x32_bf16 v[142:145], v[120:123], v[132:135], v[142:145]
	v_mfma_f32_16x16x32_bf16 v[146:149], v[124:127], v[132:135], v[146:149]
	v_mfma_f32_16x16x32_bf16 v[150:153], v[120:123], v[196:199], v[150:153]
	v_mfma_f32_16x16x32_bf16 v[180:183], v[124:127], v[196:199], v[180:183]
	v_mfma_f32_16x16x32_bf16 v[184:187], v[120:123], v[204:207], v[184:187]
	v_mfma_f32_16x16x32_bf16 v[188:191], v[124:127], v[204:207], v[188:191]
	s_setprio 0
	s_barrier
	s_mov_b32 m0, s70
	v_lshl_add_u64 v[96:97], v[2:3], 0, s[18:19]
	global_load_lds_dwordx4 v[96:97], off
	v_lshl_add_u64 v[96:97], v[2:3], 0, s[20:21]
	s_mov_b32 m0, s69
	s_nop 0
	global_load_lds_dwordx4 v[96:97], off
	s_waitcnt vmcnt(6)
	s_barrier
	s_setprio 1
	v_mfma_f32_16x16x32_bf16 v[16:19], v[216:219], v[128:131], v[16:19]
	v_mfma_f32_16x16x32_bf16 v[20:23], v[220:223], v[128:131], v[20:23]
	v_mfma_f32_16x16x32_bf16 v[52:55], v[216:219], v[192:195], v[52:55]
	v_mfma_f32_16x16x32_bf16 v[96:99], v[220:223], v[192:195], v[108:111]
	v_mfma_f32_16x16x32_bf16 v[108:111], v[220:223], v[200:203], v[116:119]
	v_mfma_f32_16x16x32_bf16 v[88:91], v[216:219], v[208:211], v[88:91]
	v_mfma_f32_16x16x32_bf16 v[92:95], v[220:223], v[208:211], v[92:95]
	v_mfma_f32_16x16x32_bf16 v[16:19], v[224:227], v[132:135], v[16:19]
	v_mfma_f32_16x16x32_bf16 v[20:23], v[228:231], v[132:135], v[20:23]
	v_mfma_f32_16x16x32_bf16 v[52:55], v[224:227], v[196:199], v[52:55]
	v_mfma_f32_16x16x32_bf16 v[100:103], v[216:219], v[200:203], v[112:115]
	v_mfma_f32_16x16x32_bf16 v[108:111], v[228:231], v[204:207], v[108:111]
	v_mfma_f32_16x16x32_bf16 v[88:91], v[224:227], v[212:215], v[88:91]
	v_mfma_f32_16x16x32_bf16 v[92:95], v[228:231], v[212:215], v[92:95]
	v_mfma_f32_16x16x32_bf16 v[96:99], v[228:231], v[196:199], v[96:99]
	v_mfma_f32_16x16x32_bf16 v[100:103], v[224:227], v[204:207], v[100:103]
	s_setprio 0
	s_barrier
	ds_read_b128 v[112:115], v176
	ds_read_b128 v[116:119], v176 offset:256
	ds_read_b128 v[120:123], v177
	ds_read_b128 v[124:127], v177 offset:256
	s_mov_b32 m0, s66
	v_lshl_add_u64 v[138:139], v[0:1], 0, s[18:19]
	ds_read_b128 v[128:131], v154
	ds_read_b128 v[132:135], v154 offset:1024
	ds_read_b128 v[192:195], v154 offset:2048
	ds_read_b128 v[196:199], v154 offset:3072
	ds_read_b128 v[200:203], v154 offset:4096
	ds_read_b128 v[204:207], v154 offset:5120
	ds_read_b128 v[208:211], v154 offset:6144
	ds_read_b128 v[212:215], v154 offset:7168
	global_load_lds_dwordx4 v[138:139], off
	v_lshl_add_u64 v[138:139], v[0:1], 0, s[20:21]
	s_mov_b32 m0, s53
	s_nop 0
	global_load_lds_dwordx4 v[138:139], off
	s_waitcnt lgkmcnt(8)
	s_barrier
	s_waitcnt lgkmcnt(0)
	s_setprio 1
	v_mfma_f32_16x16x32_bf16 v[56:59], v[112:115], v[128:131], v[56:59]
	v_mfma_f32_16x16x32_bf16 v[60:63], v[116:119], v[128:131], v[60:63]
	v_mfma_f32_16x16x32_bf16 v[64:67], v[112:115], v[192:195], v[64:67]
	v_mfma_f32_16x16x32_bf16 v[68:71], v[116:119], v[192:195], v[68:71]
	v_mfma_f32_16x16x32_bf16 v[72:75], v[112:115], v[200:203], v[72:75]
	v_mfma_f32_16x16x32_bf16 v[76:79], v[116:119], v[200:203], v[76:79]
	v_mfma_f32_16x16x32_bf16 v[80:83], v[112:115], v[208:211], v[80:83]
	v_mfma_f32_16x16x32_bf16 v[84:87], v[116:119], v[208:211], v[84:87]
	v_mfma_f32_16x16x32_bf16 v[56:59], v[120:123], v[132:135], v[56:59]
	v_mfma_f32_16x16x32_bf16 v[60:63], v[124:127], v[132:135], v[60:63]
	v_mfma_f32_16x16x32_bf16 v[64:67], v[120:123], v[196:199], v[64:67]
	v_mfma_f32_16x16x32_bf16 v[68:71], v[124:127], v[196:199], v[68:71]
	v_mfma_f32_16x16x32_bf16 v[72:75], v[120:123], v[204:207], v[72:75]
	v_mfma_f32_16x16x32_bf16 v[76:79], v[124:127], v[204:207], v[76:79]
	v_mfma_f32_16x16x32_bf16 v[80:83], v[120:123], v[212:215], v[80:83]
	v_mfma_f32_16x16x32_bf16 v[84:87], v[124:127], v[212:215], v[84:87]
	s_setprio 0
	s_barrier
	s_mov_b32 m0, s65
	v_lshl_add_u64 v[138:139], v[6:7], 0, s[22:23]
	ds_read_b128 v[216:219], v178
	ds_read_b128 v[220:223], v178 offset:256
	ds_read_b128 v[224:227], v179
	ds_read_b128 v[228:231], v179 offset:256
	global_load_lds_dwordx4 v[138:139], off
	v_lshl_add_u64 v[138:139], v[6:7], 0, s[24:25]
	s_mov_b32 m0, s60
	s_nop 0
	global_load_lds_dwordx4 v[138:139], off
	s_barrier
	s_waitcnt lgkmcnt(0)
	s_setprio 1
	s_waitcnt lgkmcnt(0)
	v_mfma_f32_16x16x32_bf16 v[104:107], v[216:219], v[128:131], v[104:107]
	v_mfma_f32_16x16x32_bf16 v[24:27], v[220:223], v[128:131], v[24:27]
	v_mfma_f32_16x16x32_bf16 v[28:31], v[216:219], v[192:195], v[28:31]
	v_mfma_f32_16x16x32_bf16 v[32:35], v[220:223], v[192:195], v[32:35]
	v_mfma_f32_16x16x32_bf16 v[36:39], v[216:219], v[200:203], v[36:39]
	v_mfma_f32_16x16x32_bf16 v[40:43], v[220:223], v[200:203], v[40:43]
	v_mfma_f32_16x16x32_bf16 v[44:47], v[216:219], v[208:211], v[44:47]
	v_mfma_f32_16x16x32_bf16 v[48:51], v[220:223], v[208:211], v[48:51]
	v_mfma_f32_16x16x32_bf16 v[104:107], v[224:227], v[132:135], v[104:107]
	v_mfma_f32_16x16x32_bf16 v[24:27], v[228:231], v[132:135], v[24:27]
	v_mfma_f32_16x16x32_bf16 v[28:31], v[224:227], v[196:199], v[28:31]
	v_mfma_f32_16x16x32_bf16 v[32:35], v[228:231], v[196:199], v[32:35]
	v_mfma_f32_16x16x32_bf16 v[36:39], v[224:227], v[204:207], v[36:39]
	v_mfma_f32_16x16x32_bf16 v[40:43], v[228:231], v[204:207], v[40:43]
	v_mfma_f32_16x16x32_bf16 v[44:47], v[224:227], v[212:215], v[44:47]
	v_mfma_f32_16x16x32_bf16 v[48:51], v[228:231], v[212:215], v[48:51]
	s_setprio 0
	s_mov_b32 m0, s67
	v_lshl_add_u64 v[138:139], v[4:5], 0, s[22:23]
	s_barrier
; #define STAGE(P, BASE, br, kt) do { const char* _gb = (const char*)(BASE) + ((size_t)(br) * K + (size_t)(kt) * BK) * 2; \
;     __builtin_amdgcn_global_load_lds((const unsigned*)(_gb + loff0), (unsigned*)((char*)(P) + tid * 16), 16, 0, 0); \
;     __builtin_amdgcn_global_load_lds((const unsigned*)(_gb + (size_t)K * 128 + loff0), (unsigned*)((char*)(P) + tid * 16 + 8192), 16, 0, 0); } while (0)
; #define LDA(dst, b, h) for (int m = 0; m < 4; ++m) { \
;     dst[m][0] = *reinterpret_cast<const bf16x8*>((char*)SA(b, h) + aoff0 + m * 2048); \
;     dst[m][1] = *reinterpret_cast<const bf16x8*>((char*)SA(b, h) + aoff1 + m * 2048); }
; #define LDB(dst, b, h) for (int n = 0; n < 2; ++n) { \
;     dst[n][0] = *reinterpret_cast<const bf16x8*>((char*)SB(b, h) + boff0 + n * 256); \
;     dst[n][1] = *reinterpret_cast<const bf16x8*>((char*)SB(b, h) + boff1 + n * 256); }
; #define MMA(ai, bj, At, Btf) do { __builtin_amdgcn_s_setprio(1); \
;     for (int m = 0; m < 4; ++m) for (int n = 0; n < 2; ++n) for (int k = 0; k < 2; ++k) \
;       acc[ai][bj][m][n] = __builtin_amdgcn_mfma_f32_16x16x32_bf16(Btf[n][k], At[m][k], acc[ai][bj][m][n], 0, 0, 0); \
;     __builtin_amdgcn_s_setprio(0); } while (0)
; #define WAIT_V(n) asm volatile("s_waitcnt vmcnt(" #n ")" ::: "memory")
; #define WAIT_L(n) asm volatile("s_waitcnt lgkmcnt(" #n ")" ::: "memory")
; #define BAR __builtin_amdgcn_s_barrier()
; #define SCHED __builtin_amdgcn_sched_barrier(0)
; template <int EPI> ...
;     ...
;     LDA(At, 0, 1); STAGE(SA(0, 0), A, brow, t + 2);
;     BAR; WAIT_L(0); MMA(1, 0, At, B0); BAR; SCHED;
;     STAGE(SB(0, 1), Bt, bcol + HALF, t + 2);
;     WAIT_V(6); BAR; MMA(1, 1, At, B1); BAR;
;     LDB(B0, 1, 0); SCHED; LDA(At, 1, 0); STAGE(SA(0, 1), A, brow + HALF, t + 2);
;     WAIT_L(8); BAR; WAIT_L(0); MMA(0, 0, At, B0); BAR; SCHED;
;     LDB(B1, 1, 1); STAGE(SB(1, 0), Bt, bcol, t + 3);
	ds_read_b128 v[128:131], v154 offset:16384
	ds_read_b128 v[132:135], v154 offset:17408
	ds_read_b128 v[192:195], v154 offset:18432
	ds_read_b128 v[196:199], v154 offset:19456
	ds_read_b128 v[200:203], v154 offset:20480
	ds_read_b128 v[204:207], v154 offset:21504
	ds_read_b128 v[208:211], v154 offset:22528
	ds_read_b128 v[212:215], v154 offset:23552
	global_load_lds_dwordx4 v[138:139], off
	v_lshl_add_u64 v[138:139], v[4:5], 0, s[24:25]
	s_mov_b32 m0, s61
	s_nop 0
	global_load_lds_dwordx4 v[138:139], off
	s_barrier
	s_waitcnt lgkmcnt(0)
	s_setprio 1
	v_mfma_f32_16x16x32_bf16 v[8:11], v[112:115], v[208:211], v[8:11]
	v_mfma_f32_16x16x32_bf16 v[12:15], v[116:119], v[208:211], v[12:15]
	v_mfma_f32_16x16x32_bf16 v[142:145], v[112:115], v[128:131], v[142:145]
	v_mfma_f32_16x16x32_bf16 v[146:149], v[116:119], v[128:131], v[146:149]
	v_mfma_f32_16x16x32_bf16 v[150:153], v[112:115], v[192:195], v[150:153]
	v_mfma_f32_16x16x32_bf16 v[180:183], v[116:119], v[192:195], v[180:183]
	v_mfma_f32_16x16x32_bf16 v[184:187], v[112:115], v[200:203], v[184:187]
	v_mfma_f32_16x16x32_bf16 v[188:191], v[116:119], v[200:203], v[188:191]
	v_mfma_f32_16x16x32_bf16 v[8:11], v[120:123], v[212:215], v[8:11]
	v_mfma_f32_16x16x32_bf16 v[12:15], v[124:127], v[212:215], v[12:15]
	v_mfma_f32_16x16x32_bf16 v[142:145], v[120:123], v[132:135], v[142:145]
	v_mfma_f32_16x16x32_bf16 v[146:149], v[124:127], v[132:135], v[146:149]
	v_mfma_f32_16x16x32_bf16 v[150:153], v[120:123], v[196:199], v[150:153]
	v_mfma_f32_16x16x32_bf16 v[180:183], v[124:127], v[196:199], v[180:183]
	v_mfma_f32_16x16x32_bf16 v[184:187], v[120:123], v[204:207], v[184:187]
	v_mfma_f32_16x16x32_bf16 v[188:191], v[124:127], v[204:207], v[188:191]
	s_setprio 0
	s_barrier
	s_mov_b32 m0, s64
	v_lshl_add_u64 v[112:113], v[2:3], 0, s[22:23]
	global_load_lds_dwordx4 v[112:113], off
	v_lshl_add_u64 v[112:113], v[2:3], 0, s[24:25]
	s_mov_b32 m0, s62
	s_nop 0
	global_load_lds_dwordx4 v[112:113], off
	s_waitcnt vmcnt(6)
	s_barrier
	s_setprio 1
	v_mfma_f32_16x16x32_bf16 v[16:19], v[216:219], v[128:131], v[16:19]
	v_mfma_f32_16x16x32_bf16 v[20:23], v[220:223], v[128:131], v[20:23]
	v_mfma_f32_16x16x32_bf16 v[52:55], v[216:219], v[192:195], v[52:55]
	v_mfma_f32_16x16x32_bf16 v[108:111], v[220:223], v[200:203], v[108:111]
	v_mfma_f32_16x16x32_bf16 v[88:91], v[216:219], v[208:211], v[88:91]
	v_mfma_f32_16x16x32_bf16 v[92:95], v[220:223], v[208:211], v[92:95]
	v_mfma_f32_16x16x32_bf16 v[16:19], v[224:227], v[132:135], v[16:19]
	v_mfma_f32_16x16x32_bf16 v[20:23], v[228:231], v[132:135], v[20:23]
	v_mfma_f32_16x16x32_bf16 v[52:55], v[224:227], v[196:199], v[52:55]
	v_mfma_f32_16x16x32_bf16 v[96:99], v[220:223], v[192:195], v[96:99]
	v_mfma_f32_16x16x32_bf16 v[100:103], v[216:219], v[200:203], v[100:103]
	v_mfma_f32_16x16x32_bf16 v[108:111], v[228:231], v[204:207], v[108:111]
	v_mfma_f32_16x16x32_bf16 v[88:91], v[224:227], v[212:215], v[88:91]
	v_mfma_f32_16x16x32_bf16 v[92:95], v[228:231], v[212:215], v[92:95]
	v_mfma_f32_16x16x32_bf16 v[96:99], v[228:231], v[196:199], v[96:99]
	v_mfma_f32_16x16x32_bf16 v[100:103], v[224:227], v[204:207], v[100:103]
	s_setprio 0
	s_barrier
	ds_read_b128 v[112:115], v172
	ds_read_b128 v[116:119], v172 offset:256
	ds_read_b128 v[120:123], v173
	ds_read_b128 v[124:127], v173 offset:256
	s_mov_b32 m0, s68
	v_lshl_add_u64 v[138:139], v[0:1], 0, s[22:23]
	ds_read_b128 v[128:131], v154 offset:32768
	ds_read_b128 v[132:135], v154 offset:33792
	ds_read_b128 v[192:195], v154 offset:34816
	ds_read_b128 v[196:199], v154 offset:35840
	ds_read_b128 v[200:203], v154 offset:36864
	ds_read_b128 v[204:207], v154 offset:37888
	ds_read_b128 v[208:211], v154 offset:38912
	ds_read_b128 v[212:215], v154 offset:39936
	global_load_lds_dwordx4 v[138:139], off
	v_lshl_add_u64 v[138:139], v[0:1], 0, s[24:25]
	s_mov_b32 m0, s63
	s_nop 0
	global_load_lds_dwordx4 v[138:139], off
	s_waitcnt lgkmcnt(8)
	s_barrier
	s_waitcnt lgkmcnt(0)
	s_setprio 1
	v_mfma_f32_16x16x32_bf16 v[56:59], v[112:115], v[128:131], v[56:59]
	v_mfma_f32_16x16x32_bf16 v[60:63], v[116:119], v[128:131], v[60:63]
	v_mfma_f32_16x16x32_bf16 v[64:67], v[112:115], v[192:195], v[64:67]
	v_mfma_f32_16x16x32_bf16 v[68:71], v[116:119], v[192:195], v[68:71]
	v_mfma_f32_16x16x32_bf16 v[72:75], v[112:115], v[200:203], v[72:75]
	v_mfma_f32_16x16x32_bf16 v[76:79], v[116:119], v[200:203], v[76:79]
	v_mfma_f32_16x16x32_bf16 v[80:83], v[112:115], v[208:211], v[80:83]
	v_mfma_f32_16x16x32_bf16 v[84:87], v[116:119], v[208:211], v[84:87]
	v_mfma_f32_16x16x32_bf16 v[56:59], v[120:123], v[132:135], v[56:59]
	v_mfma_f32_16x16x32_bf16 v[60:63], v[124:127], v[132:135], v[60:63]
	v_mfma_f32_16x16x32_bf16 v[64:67], v[120:123], v[196:199], v[64:67]
	v_mfma_f32_16x16x32_bf16 v[68:71], v[124:127], v[196:199], v[68:71]
	v_mfma_f32_16x16x32_bf16 v[72:75], v[120:123], v[204:207], v[72:75]
	v_mfma_f32_16x16x32_bf16 v[76:79], v[124:127], v[204:207], v[76:79]
	v_mfma_f32_16x16x32_bf16 v[80:83], v[120:123], v[212:215], v[80:83]
	v_mfma_f32_16x16x32_bf16 v[84:87], v[124:127], v[212:215], v[84:87]
	s_setprio 0
	s_barrier
	s_mov_b32 m0, s52
	v_lshl_add_u64 v[138:139], v[6:7], 0, s[26:27]
	ds_read_b128 v[216:219], v174
	ds_read_b128 v[220:223], v174 offset:256
	ds_read_b128 v[224:227], v175
	ds_read_b128 v[228:231], v175 offset:256
	global_load_lds_dwordx4 v[138:139], off
	v_lshl_add_u64 v[138:139], v[6:7], 0, s[28:29]
	s_mov_b32 m0, s49
	s_nop 0
	global_load_lds_dwordx4 v[138:139], off
	s_barrier
; #define STAGE(P, BASE, br, kt) do { const char* _gb = (const char*)(BASE) + ((size_t)(br) * K + (size_t)(kt) * BK) * 2; \
;     __builtin_amdgcn_global_load_lds((const unsigned*)(_gb + loff0), (unsigned*)((char*)(P) + tid * 16), 16, 0, 0); \
;     __builtin_amdgcn_global_load_lds((const unsigned*)(_gb + (size_t)K * 128 + loff0), (unsigned*)((char*)(P) + tid * 16 + 8192), 16, 0, 0); } while (0)
; #define LDA(dst, b, h) for (int m = 0; m < 4; ++m) { \
;     dst[m][0] = *reinterpret_cast<const bf16x8*>((char*)SA(b, h) + aoff0 + m * 2048); \
;     dst[m][1] = *reinterpret_cast<const bf16x8*>((char*)SA(b, h) + aoff1 + m * 2048); }
; #define LDB(dst, b, h) for (int n = 0; n < 2; ++n) { \
;     dst[n][0] = *reinterpret_cast<const bf16x8*>((char*)SB(b, h) + boff0 + n * 256); \
;     dst[n][1] = *reinterpret_cast<const bf16x8*>((char*)SB(b, h) + boff1 + n * 256); }
; #define MMA(ai, bj, At, Btf) do { __builtin_amdgcn_s_setprio(1); \
;     for (int m = 0; m < 4; ++m) for (int n = 0; n < 2; ++n) for (int k = 0; k < 2; ++k) \
;       acc[ai][bj][m][n] = __builtin_amdgcn_mfma_f32_16x16x32_bf16(Btf[n][k], At[m][k], acc[ai][bj][m][n], 0, 0, 0); \
;     __builtin_amdgcn_s_setprio(0); } while (0)
; #define WAIT_V(n) asm volatile("s_waitcnt vmcnt(" #n ")" ::: "memory")
; #define WAIT_L(n) asm volatile("s_waitcnt lgkmcnt(" #n ")" ::: "memory")
; #define BAR __builtin_amdgcn_s_barrier()
; #define SCHED __builtin_amdgcn_sched_barrier(0)
; template <int EPI> ...
;     ...
;     LDB(B0, 0, 0); SCHED; LDA(At, 0, 0); STAGE(SA(1, 1), A, brow + HALF, t + 1);
;     WAIT_L(8); BAR; WAIT_L(0); MMA(0, 0, At, B0); BAR; SCHED;
;     ...
;     BAR; WAIT_L(0); MMA(0, 1, At, B1); BAR;
;     LDA(At, 1, 1); STAGE(SA(1, 0), A, brow, t + 3);
;     BAR; WAIT_L(0); MMA(1, 0, At, B0); BAR; SCHED;
;     STAGE(SB(1, 1), Bt, bcol + HALF, t + 3);
;     WAIT_V(6); BAR; MMA(1, 1, At, B1); BAR;
	s_waitcnt lgkmcnt(0)
	s_setprio 1
	s_waitcnt lgkmcnt(0)
	v_mfma_f32_16x16x32_bf16 v[104:107], v[216:219], v[128:131], v[104:107]
	v_mfma_f32_16x16x32_bf16 v[24:27], v[220:223], v[128:131], v[24:27]
	v_mfma_f32_16x16x32_bf16 v[28:31], v[216:219], v[192:195], v[28:31]
	v_mfma_f32_16x16x32_bf16 v[32:35], v[220:223], v[192:195], v[32:35]
	v_mfma_f32_16x16x32_bf16 v[36:39], v[216:219], v[200:203], v[36:39]
	v_mfma_f32_16x16x32_bf16 v[40:43], v[220:223], v[200:203], v[40:43]
	v_mfma_f32_16x16x32_bf16 v[44:47], v[216:219], v[208:211], v[44:47]
	v_mfma_f32_16x16x32_bf16 v[48:51], v[220:223], v[208:211], v[48:51]
	v_mfma_f32_16x16x32_bf16 v[104:107], v[224:227], v[132:135], v[104:107]
	v_mfma_f32_16x16x32_bf16 v[24:27], v[228:231], v[132:135], v[24:27]
	v_mfma_f32_16x16x32_bf16 v[28:31], v[224:227], v[196:199], v[28:31]
	v_mfma_f32_16x16x32_bf16 v[32:35], v[228:231], v[196:199], v[32:35]
	v_mfma_f32_16x16x32_bf16 v[36:39], v[224:227], v[204:207], v[36:39]
	v_mfma_f32_16x16x32_bf16 v[40:43], v[228:231], v[204:207], v[40:43]
	v_mfma_f32_16x16x32_bf16 v[44:47], v[224:227], v[212:215], v[44:47]
	v_mfma_f32_16x16x32_bf16 v[48:51], v[228:231], v[212:215], v[48:51]
	s_setprio 0
	v_readfirstlane_b32 s63, v254
	v_lshl_add_u64 v[138:139], v[4:5], 0, s[26:27]
	s_mov_b32 m0, s63
	v_readfirstlane_b32 s53, v165
	s_barrier
	ds_read_b128 v[128:131], v154 offset:49152
	ds_read_b128 v[132:135], v154 offset:50176
	ds_read_b128 v[192:195], v154 offset:51200
	ds_read_b128 v[196:199], v154 offset:52224
	ds_read_b128 v[200:203], v154 offset:53248
	ds_read_b128 v[204:207], v154 offset:54272
	ds_read_b128 v[208:211], v154 offset:55296
	ds_read_b128 v[212:215], v154 offset:56320
	global_load_lds_dwordx4 v[138:139], off
	v_lshl_add_u64 v[138:139], v[4:5], 0, s[28:29]
	s_mov_b32 m0, s53
	s_nop 0
	global_load_lds_dwordx4 v[138:139], off
	s_barrier
	s_waitcnt lgkmcnt(0)
	s_setprio 1
	v_mfma_f32_16x16x32_bf16 v[8:11], v[112:115], v[208:211], v[8:11]
	v_mfma_f32_16x16x32_bf16 v[12:15], v[116:119], v[208:211], v[12:15]
	v_mfma_f32_16x16x32_bf16 v[142:145], v[112:115], v[128:131], v[142:145]
	v_mfma_f32_16x16x32_bf16 v[146:149], v[116:119], v[128:131], v[146:149]
	v_mfma_f32_16x16x32_bf16 v[150:153], v[112:115], v[192:195], v[150:153]
	v_mfma_f32_16x16x32_bf16 v[180:183], v[116:119], v[192:195], v[180:183]
	v_mfma_f32_16x16x32_bf16 v[184:187], v[112:115], v[200:203], v[184:187]
	v_mfma_f32_16x16x32_bf16 v[188:191], v[116:119], v[200:203], v[188:191]
	v_mfma_f32_16x16x32_bf16 v[8:11], v[120:123], v[212:215], v[8:11]
	v_mfma_f32_16x16x32_bf16 v[12:15], v[124:127], v[212:215], v[12:15]
	v_mfma_f32_16x16x32_bf16 v[142:145], v[120:123], v[132:135], v[142:145]
	v_mfma_f32_16x16x32_bf16 v[146:149], v[124:127], v[132:135], v[146:149]
	v_mfma_f32_16x16x32_bf16 v[150:153], v[120:123], v[196:199], v[150:153]
	v_mfma_f32_16x16x32_bf16 v[180:183], v[124:127], v[196:199], v[180:183]
	v_mfma_f32_16x16x32_bf16 v[184:187], v[120:123], v[204:207], v[184:187]
	v_mfma_f32_16x16x32_bf16 v[188:191], v[124:127], v[204:207], v[188:191]
	s_setprio 0
	s_barrier
	v_readfirstlane_b32 s61, v168
	v_lshl_add_u64 v[112:113], v[2:3], 0, s[26:27]
	s_mov_b32 m0, s61
	v_readfirstlane_b32 s60, v169
	global_load_lds_dwordx4 v[112:113], off
	v_lshl_add_u64 v[112:113], v[2:3], 0, s[28:29]
	s_mov_b32 m0, s60
	s_nop 0
	global_load_lds_dwordx4 v[112:113], off
	s_waitcnt vmcnt(6)
	s_barrier
	s_setprio 1
	v_mfma_f32_16x16x32_bf16 v[16:19], v[216:219], v[128:131], v[16:19]
	v_mfma_f32_16x16x32_bf16 v[20:23], v[220:223], v[128:131], v[20:23]
	v_mfma_f32_16x16x32_bf16 v[52:55], v[216:219], v[192:195], v[52:55]
	v_mfma_f32_16x16x32_bf16 v[108:111], v[220:223], v[200:203], v[108:111]
	v_mfma_f32_16x16x32_bf16 v[88:91], v[216:219], v[208:211], v[88:91]
	v_mfma_f32_16x16x32_bf16 v[92:95], v[220:223], v[208:211], v[92:95]
	v_mfma_f32_16x16x32_bf16 v[16:19], v[224:227], v[132:135], v[16:19]
	v_mfma_f32_16x16x32_bf16 v[20:23], v[228:231], v[132:135], v[20:23]
	v_mfma_f32_16x16x32_bf16 v[52:55], v[224:227], v[196:199], v[52:55]
	v_mfma_f32_16x16x32_bf16 v[96:99], v[220:223], v[192:195], v[96:99]
	v_mfma_f32_16x16x32_bf16 v[100:103], v[216:219], v[200:203], v[100:103]
	v_mfma_f32_16x16x32_bf16 v[108:111], v[228:231], v[204:207], v[108:111]
	v_mfma_f32_16x16x32_bf16 v[88:91], v[224:227], v[212:215], v[88:91]
	v_mfma_f32_16x16x32_bf16 v[92:95], v[228:231], v[212:215], v[92:95]
	v_mfma_f32_16x16x32_bf16 v[96:99], v[228:231], v[196:199], v[96:99]
	v_mfma_f32_16x16x32_bf16 v[100:103], v[224:227], v[204:207], v[100:103]
	s_setprio 0
	s_barrier
	ds_read_b128 v[112:115], v176
	ds_read_b128 v[116:119], v176 offset:256
	ds_read_b128 v[120:123], v177
	ds_read_b128 v[124:127], v177 offset:256
	v_readfirstlane_b32 s64, v170
	v_lshl_add_u64 v[138:139], v[0:1], 0, s[26:27]
	s_mov_b32 m0, s64
	v_readfirstlane_b32 s62, v171
	ds_read_b128 v[128:131], v154
	ds_read_b128 v[132:135], v154 offset:1024
	ds_read_b128 v[192:195], v154 offset:2048
	ds_read_b128 v[196:199], v154 offset:3072
	ds_read_b128 v[200:203], v154 offset:4096
	ds_read_b128 v[204:207], v154 offset:5120
	ds_read_b128 v[208:211], v154 offset:6144
	ds_read_b128 v[212:215], v154 offset:7168
	global_load_lds_dwordx4 v[138:139], off
	v_lshl_add_u64 v[138:139], v[0:1], 0, s[28:29]
	s_mov_b32 m0, s62
	s_nop 0
	global_load_lds_dwordx4 v[138:139], off
	s_waitcnt lgkmcnt(8)
	s_barrier
; #define STAGE(P, BASE, br, kt) do { const char* _gb = (const char*)(BASE) + ((size_t)(br) * K + (size_t)(kt) * BK) * 2; \
;     __builtin_amdgcn_global_load_lds((const unsigned*)(_gb + loff0), (unsigned*)((char*)(P) + tid * 16), 16, 0, 0); \
;     __builtin_amdgcn_global_load_lds((const unsigned*)(_gb + (size_t)K * 128 + loff0), (unsigned*)((char*)(P) + tid * 16 + 8192), 16, 0, 0); } while (0)
; #define LDA(dst, b, h) for (int m = 0; m < 4; ++m) { \
;     dst[m][0] = *reinterpret_cast<const bf16x8*>((char*)SA(b, h) + aoff0 + m * 2048); \
;     dst[m][1] = *reinterpret_cast<const bf16x8*>((char*)SA(b, h) + aoff1 + m * 2048); }
; #define LDB(dst, b, h) for (int n = 0; n < 2; ++n) { \
;     dst[n][0] = *reinterpret_cast<const bf16x8*>((char*)SB(b, h) + boff0 + n * 256); \
;     dst[n][1] = *reinterpret_cast<const bf16x8*>((char*)SB(b, h) + boff1 + n * 256); }
; #define MMA(ai, bj, At, Btf) do { __builtin_amdgcn_s_setprio(1); \
;     for (int m = 0; m < 4; ++m) for (int n = 0; n < 2; ++n) for (int k = 0; k < 2; ++k) \
;       acc[ai][bj][m][n] = __builtin_amdgcn_mfma_f32_16x16x32_bf16(Btf[n][k], At[m][k], acc[ai][bj][m][n], 0, 0, 0); \
;     __builtin_amdgcn_s_setprio(0); } while (0)
; #define WAIT_V(n) asm volatile("s_waitcnt vmcnt(" #n ")" ::: "memory")
; #define WAIT_L(n) asm volatile("s_waitcnt lgkmcnt(" #n ")" ::: "memory")
; #define BAR __builtin_amdgcn_s_barrier()
; #define SCHED __builtin_amdgcn_sched_barrier(0)
; template <int EPI> ...
;     ...
;     WAIT_L(8); BAR; WAIT_L(0); MMA(0, 0, At, B0); BAR; SCHED;
;     LDB(B1, 0, 1); STAGE(SB(0, 0), Bt, bcol, t + 2);
;     BAR; WAIT_L(0); MMA(0, 1, At, B1); BAR;
;     LDA(At, 0, 1); STAGE(SA(0, 0), A, brow, t + 2);
;     BAR; WAIT_L(0); MMA(1, 0, At, B0); BAR; SCHED;
;     STAGE(SB(0, 1), Bt, bcol + HALF, t + 2);
;     WAIT_V(6); BAR; MMA(1, 1, At, B1); BAR;
	s_waitcnt lgkmcnt(0)
	s_setprio 1
	v_mfma_f32_16x16x32_bf16 v[56:59], v[112:115], v[128:131], v[56:59]
	v_mfma_f32_16x16x32_bf16 v[60:63], v[116:119], v[128:131], v[60:63]
	v_mfma_f32_16x16x32_bf16 v[64:67], v[112:115], v[192:195], v[64:67]
	v_mfma_f32_16x16x32_bf16 v[68:71], v[116:119], v[192:195], v[68:71]
	v_mfma_f32_16x16x32_bf16 v[72:75], v[112:115], v[200:203], v[72:75]
	v_mfma_f32_16x16x32_bf16 v[76:79], v[116:119], v[200:203], v[76:79]
	v_mfma_f32_16x16x32_bf16 v[80:83], v[112:115], v[208:211], v[80:83]
	v_mfma_f32_16x16x32_bf16 v[84:87], v[116:119], v[208:211], v[84:87]
	v_mfma_f32_16x16x32_bf16 v[56:59], v[120:123], v[132:135], v[56:59]
	v_mfma_f32_16x16x32_bf16 v[60:63], v[124:127], v[132:135], v[60:63]
	v_mfma_f32_16x16x32_bf16 v[64:67], v[120:123], v[196:199], v[64:67]
	v_mfma_f32_16x16x32_bf16 v[68:71], v[124:127], v[196:199], v[68:71]
	v_mfma_f32_16x16x32_bf16 v[72:75], v[120:123], v[204:207], v[72:75]
	v_mfma_f32_16x16x32_bf16 v[76:79], v[124:127], v[204:207], v[76:79]
	v_mfma_f32_16x16x32_bf16 v[80:83], v[120:123], v[212:215], v[80:83]
	v_mfma_f32_16x16x32_bf16 v[84:87], v[124:127], v[212:215], v[84:87]
	s_setprio 0
	s_barrier
	v_readfirstlane_b32 s65, v156
	v_lshl_add_u64 v[138:139], v[6:7], 0, s[30:31]
	s_mov_b32 m0, s65
	v_readfirstlane_b32 s65, v157
	ds_read_b128 v[216:219], v178
	ds_read_b128 v[220:223], v178 offset:256
	ds_read_b128 v[224:227], v179
	ds_read_b128 v[228:231], v179 offset:256
	global_load_lds_dwordx4 v[138:139], off
	v_lshl_add_u64 v[138:139], v[6:7], 0, s[36:37]
	s_mov_b32 m0, s65
	s_nop 0
	global_load_lds_dwordx4 v[138:139], off
	s_barrier
	s_waitcnt lgkmcnt(0)
	s_setprio 1
	s_waitcnt lgkmcnt(0)
	v_mfma_f32_16x16x32_bf16 v[104:107], v[216:219], v[128:131], v[104:107]
	v_mfma_f32_16x16x32_bf16 v[24:27], v[220:223], v[128:131], v[24:27]
	v_mfma_f32_16x16x32_bf16 v[28:31], v[216:219], v[192:195], v[28:31]
	v_mfma_f32_16x16x32_bf16 v[32:35], v[220:223], v[192:195], v[32:35]
	v_mfma_f32_16x16x32_bf16 v[36:39], v[216:219], v[200:203], v[36:39]
	v_mfma_f32_16x16x32_bf16 v[40:43], v[220:223], v[200:203], v[40:43]
	v_mfma_f32_16x16x32_bf16 v[44:47], v[216:219], v[208:211], v[44:47]
	v_mfma_f32_16x16x32_bf16 v[48:51], v[220:223], v[208:211], v[48:51]
	v_mfma_f32_16x16x32_bf16 v[104:107], v[224:227], v[132:135], v[104:107]
	v_mfma_f32_16x16x32_bf16 v[24:27], v[228:231], v[132:135], v[24:27]
	v_mfma_f32_16x16x32_bf16 v[28:31], v[224:227], v[196:199], v[28:31]
	v_mfma_f32_16x16x32_bf16 v[32:35], v[228:231], v[196:199], v[32:35]
	v_mfma_f32_16x16x32_bf16 v[36:39], v[224:227], v[204:207], v[36:39]
	v_mfma_f32_16x16x32_bf16 v[40:43], v[228:231], v[204:207], v[40:43]
	v_mfma_f32_16x16x32_bf16 v[44:47], v[224:227], v[212:215], v[44:47]
	v_mfma_f32_16x16x32_bf16 v[48:51], v[228:231], v[212:215], v[48:51]
	s_setprio 0
	v_readfirstlane_b32 s65, v158
	v_lshl_add_u64 v[138:139], v[4:5], 0, s[30:31]
	s_mov_b32 m0, s65
	v_readfirstlane_b32 s65, v159
	s_barrier
	ds_read_b128 v[128:131], v154 offset:16384
	ds_read_b128 v[132:135], v154 offset:17408
	ds_read_b128 v[192:195], v154 offset:18432
	ds_read_b128 v[196:199], v154 offset:19456
	ds_read_b128 v[200:203], v154 offset:20480
	ds_read_b128 v[204:207], v154 offset:21504
	ds_read_b128 v[208:211], v154 offset:22528
	ds_read_b128 v[212:215], v154 offset:23552
	global_load_lds_dwordx4 v[138:139], off
	v_lshl_add_u64 v[138:139], v[4:5], 0, s[36:37]
	s_mov_b32 m0, s65
	s_nop 0
	global_load_lds_dwordx4 v[138:139], off
	s_barrier
	s_waitcnt lgkmcnt(0)
	s_setprio 1
	v_mfma_f32_16x16x32_bf16 v[8:11], v[112:115], v[208:211], v[8:11]
	v_mfma_f32_16x16x32_bf16 v[12:15], v[116:119], v[208:211], v[12:15]
	v_mfma_f32_16x16x32_bf16 v[142:145], v[112:115], v[128:131], v[142:145]
	v_mfma_f32_16x16x32_bf16 v[146:149], v[116:119], v[128:131], v[146:149]
	v_mfma_f32_16x16x32_bf16 v[150:153], v[112:115], v[192:195], v[150:153]
	v_mfma_f32_16x16x32_bf16 v[180:183], v[116:119], v[192:195], v[180:183]
	v_mfma_f32_16x16x32_bf16 v[184:187], v[112:115], v[200:203], v[184:187]
	v_mfma_f32_16x16x32_bf16 v[188:191], v[116:119], v[200:203], v[188:191]
	v_mfma_f32_16x16x32_bf16 v[8:11], v[120:123], v[212:215], v[8:11]
	v_mfma_f32_16x16x32_bf16 v[12:15], v[124:127], v[212:215], v[12:15]
	v_mfma_f32_16x16x32_bf16 v[142:145], v[120:123], v[132:135], v[142:145]
	v_mfma_f32_16x16x32_bf16 v[146:149], v[124:127], v[132:135], v[146:149]
	v_mfma_f32_16x16x32_bf16 v[150:153], v[120:123], v[196:199], v[150:153]
	v_mfma_f32_16x16x32_bf16 v[180:183], v[124:127], v[196:199], v[180:183]
	v_mfma_f32_16x16x32_bf16 v[184:187], v[120:123], v[204:207], v[184:187]
	v_mfma_f32_16x16x32_bf16 v[188:191], v[124:127], v[204:207], v[188:191]
	s_setprio 0
	s_barrier
	v_readfirstlane_b32 s65, v160
	v_lshl_add_u64 v[112:113], v[2:3], 0, s[30:31]
	s_mov_b32 m0, s65
	v_readfirstlane_b32 s65, v161
	global_load_lds_dwordx4 v[112:113], off
	v_lshl_add_u64 v[112:113], v[2:3], 0, s[36:37]
	s_mov_b32 m0, s65
	s_nop 0
	global_load_lds_dwordx4 v[112:113], off
	s_waitcnt vmcnt(6)
	s_barrier
	s_setprio 1
	v_mfma_f32_16x16x32_bf16 v[16:19], v[216:219], v[128:131], v[16:19]
	v_mfma_f32_16x16x32_bf16 v[20:23], v[220:223], v[128:131], v[20:23]
	v_mfma_f32_16x16x32_bf16 v[52:55], v[216:219], v[192:195], v[52:55]
	v_mfma_f32_16x16x32_bf16 v[108:111], v[220:223], v[200:203], v[108:111]
	v_mfma_f32_16x16x32_bf16 v[88:91], v[216:219], v[208:211], v[88:91]
	v_mfma_f32_16x16x32_bf16 v[92:95], v[220:223], v[208:211], v[92:95]
	v_mfma_f32_16x16x32_bf16 v[16:19], v[224:227], v[132:135], v[16:19]
	v_mfma_f32_16x16x32_bf16 v[20:23], v[228:231], v[132:135], v[20:23]
	v_mfma_f32_16x16x32_bf16 v[52:55], v[224:227], v[196:199], v[52:55]
	v_mfma_f32_16x16x32_bf16 v[96:99], v[220:223], v[192:195], v[96:99]
	v_mfma_f32_16x16x32_bf16 v[100:103], v[216:219], v[200:203], v[100:103]
	v_mfma_f32_16x16x32_bf16 v[108:111], v[228:231], v[204:207], v[108:111]
	v_mfma_f32_16x16x32_bf16 v[88:91], v[224:227], v[212:215], v[88:91]
	v_mfma_f32_16x16x32_bf16 v[92:95], v[228:231], v[212:215], v[92:95]
	v_mfma_f32_16x16x32_bf16 v[96:99], v[228:231], v[196:199], v[96:99]
	v_mfma_f32_16x16x32_bf16 v[100:103], v[224:227], v[204:207], v[100:103]
	s_setprio 0
	s_barrier
; #define STAGE(P, BASE, br, kt) do { const char* _gb = (const char*)(BASE) + ((size_t)(br) * K + (size_t)(kt) * BK) * 2; \
;     __builtin_amdgcn_global_load_lds((const unsigned*)(_gb + loff0), (unsigned*)((char*)(P) + tid * 16), 16, 0, 0); \
;     __builtin_amdgcn_global_load_lds((const unsigned*)(_gb + (size_t)K * 128 + loff0), (unsigned*)((char*)(P) + tid * 16 + 8192), 16, 0, 0); } while (0)
; #define LDA(dst, b, h) for (int m = 0; m < 4; ++m) { \
;     dst[m][0] = *reinterpret_cast<const bf16x8*>((char*)SA(b, h) + aoff0 + m * 2048); \
;     dst[m][1] = *reinterpret_cast<const bf16x8*>((char*)SA(b, h) + aoff1 + m * 2048); }
; #define LDB(dst, b, h) for (int n = 0; n < 2; ++n) { \
;     dst[n][0] = *reinterpret_cast<const bf16x8*>((char*)SB(b, h) + boff0 + n * 256); \
;     dst[n][1] = *reinterpret_cast<const bf16x8*>((char*)SB(b, h) + boff1 + n * 256); }
; #define MMA(ai, bj, At, Btf) do { __builtin_amdgcn_s_setprio(1); \
;     for (int m = 0; m < 4; ++m) for (int n = 0; n < 2; ++n) for (int k = 0; k < 2; ++k) \
;       acc[ai][bj][m][n] = __builtin_amdgcn_mfma_f32_16x16x32_bf16(Btf[n][k], At[m][k], acc[ai][bj][m][n], 0, 0, 0); \
;     __builtin_amdgcn_s_setprio(0); } while (0)
; #define WAIT_V(n) asm volatile("s_waitcnt vmcnt(" #n ")" ::: "memory")
; #define WAIT_L(n) asm volatile("s_waitcnt lgkmcnt(" #n ")" ::: "memory")
; #define BAR __builtin_amdgcn_s_barrier()
; #define SCHED __builtin_amdgcn_sched_barrier(0)
; template <int EPI> ...
;     ...
;     LDB(B0, 1, 0); SCHED; LDA(At, 1, 0); STAGE(SA(0, 1), A, brow + HALF, t + 2);
;     WAIT_L(8); BAR; WAIT_L(0); MMA(0, 0, At, B0); BAR; SCHED;
;     LDB(B1, 1, 1); STAGE(SB(1, 0), Bt, bcol, t + 3);
;     BAR; WAIT_L(0); MMA(0, 1, At, B1); BAR;
;     LDA(At, 1, 1); STAGE(SA(1, 0), A, brow, t + 3);
;     BAR; WAIT_L(0); MMA(1, 0, At, B0); BAR; SCHED;
;     STAGE(SB(1, 1), Bt, bcol + HALF, t + 3);
;     WAIT_V(6); BAR; MMA(1, 1, At, B1); BAR;
	ds_read_b128 v[112:115], v172
	ds_read_b128 v[116:119], v172 offset:256
	ds_read_b128 v[120:123], v173
	ds_read_b128 v[124:127], v173 offset:256
	v_readfirstlane_b32 s65, v162
	v_lshl_add_u64 v[138:139], v[0:1], 0, s[30:31]
	s_mov_b32 m0, s65
	v_readfirstlane_b32 s65, v163
	ds_read_b128 v[128:131], v154 offset:32768
	ds_read_b128 v[132:135], v154 offset:33792
	ds_read_b128 v[192:195], v154 offset:34816
	ds_read_b128 v[196:199], v154 offset:35840
	ds_read_b128 v[200:203], v154 offset:36864
	ds_read_b128 v[204:207], v154 offset:37888
	ds_read_b128 v[208:211], v154 offset:38912
	ds_read_b128 v[212:215], v154 offset:39936
	global_load_lds_dwordx4 v[138:139], off
	v_lshl_add_u64 v[138:139], v[0:1], 0, s[36:37]
	s_mov_b32 m0, s65
	s_nop 0
	global_load_lds_dwordx4 v[138:139], off
	s_waitcnt lgkmcnt(8)
	s_barrier
	s_waitcnt lgkmcnt(0)
	s_setprio 1
	v_mfma_f32_16x16x32_bf16 v[56:59], v[112:115], v[128:131], v[56:59]
	v_mfma_f32_16x16x32_bf16 v[60:63], v[116:119], v[128:131], v[60:63]
	v_mfma_f32_16x16x32_bf16 v[64:67], v[112:115], v[192:195], v[64:67]
	v_mfma_f32_16x16x32_bf16 v[68:71], v[116:119], v[192:195], v[68:71]
	v_mfma_f32_16x16x32_bf16 v[72:75], v[112:115], v[200:203], v[72:75]
	v_mfma_f32_16x16x32_bf16 v[76:79], v[116:119], v[200:203], v[76:79]
	v_mfma_f32_16x16x32_bf16 v[80:83], v[112:115], v[208:211], v[80:83]
	v_mfma_f32_16x16x32_bf16 v[84:87], v[116:119], v[208:211], v[84:87]
	v_mfma_f32_16x16x32_bf16 v[56:59], v[120:123], v[132:135], v[56:59]
	v_mfma_f32_16x16x32_bf16 v[60:63], v[124:127], v[132:135], v[60:63]
	v_mfma_f32_16x16x32_bf16 v[64:67], v[120:123], v[196:199], v[64:67]
	v_mfma_f32_16x16x32_bf16 v[68:71], v[124:127], v[196:199], v[68:71]
	v_mfma_f32_16x16x32_bf16 v[72:75], v[120:123], v[204:207], v[72:75]
	v_mfma_f32_16x16x32_bf16 v[76:79], v[124:127], v[204:207], v[76:79]
	v_mfma_f32_16x16x32_bf16 v[80:83], v[120:123], v[212:215], v[80:83]
	v_mfma_f32_16x16x32_bf16 v[84:87], v[124:127], v[212:215], v[84:87]
	s_setprio 0
	s_barrier
	s_mov_b32 m0, s52
	v_lshl_add_u64 v[138:139], v[6:7], 0, s[38:39]
	ds_read_b128 v[216:219], v174
	ds_read_b128 v[220:223], v174 offset:256
	ds_read_b128 v[224:227], v175
	ds_read_b128 v[228:231], v175 offset:256
	global_load_lds_dwordx4 v[138:139], off
	v_lshl_add_u64 v[6:7], v[6:7], 0, s[46:47]
	s_mov_b32 m0, s49
	s_nop 0
	global_load_lds_dwordx4 v[6:7], off
	s_barrier
	s_waitcnt lgkmcnt(0)
	s_setprio 1
	s_waitcnt lgkmcnt(0)
	v_mfma_f32_16x16x32_bf16 v[104:107], v[216:219], v[128:131], v[104:107]
	v_mfma_f32_16x16x32_bf16 v[24:27], v[220:223], v[128:131], v[24:27]
	v_mfma_f32_16x16x32_bf16 v[28:31], v[216:219], v[192:195], v[28:31]
	v_mfma_f32_16x16x32_bf16 v[32:35], v[220:223], v[192:195], v[32:35]
	v_mfma_f32_16x16x32_bf16 v[36:39], v[216:219], v[200:203], v[36:39]
	v_mfma_f32_16x16x32_bf16 v[40:43], v[220:223], v[200:203], v[40:43]
	v_mfma_f32_16x16x32_bf16 v[44:47], v[216:219], v[208:211], v[44:47]
	v_mfma_f32_16x16x32_bf16 v[48:51], v[220:223], v[208:211], v[48:51]
	v_mfma_f32_16x16x32_bf16 v[104:107], v[224:227], v[132:135], v[104:107]
	v_mfma_f32_16x16x32_bf16 v[24:27], v[228:231], v[132:135], v[24:27]
	v_mfma_f32_16x16x32_bf16 v[28:31], v[224:227], v[196:199], v[28:31]
	v_mfma_f32_16x16x32_bf16 v[32:35], v[228:231], v[196:199], v[32:35]
	v_mfma_f32_16x16x32_bf16 v[36:39], v[224:227], v[204:207], v[36:39]
	v_mfma_f32_16x16x32_bf16 v[40:43], v[228:231], v[204:207], v[40:43]
	v_mfma_f32_16x16x32_bf16 v[44:47], v[224:227], v[212:215], v[44:47]
	v_mfma_f32_16x16x32_bf16 v[48:51], v[228:231], v[212:215], v[48:51]
	s_setprio 0
	s_mov_b32 m0, s63
	v_lshl_add_u64 v[6:7], v[4:5], 0, s[38:39]
	s_barrier
	ds_read_b128 v[128:131], v154 offset:49152
	ds_read_b128 v[132:135], v154 offset:50176
	ds_read_b128 v[192:195], v154 offset:51200
	ds_read_b128 v[196:199], v154 offset:52224
	ds_read_b128 v[200:203], v154 offset:53248
	ds_read_b128 v[204:207], v154 offset:54272
	ds_read_b128 v[208:211], v154 offset:55296
	ds_read_b128 v[212:215], v154 offset:56320
	global_load_lds_dwordx4 v[6:7], off
	v_lshl_add_u64 v[4:5], v[4:5], 0, s[46:47]
	s_mov_b32 m0, s53
	s_nop 0
	global_load_lds_dwordx4 v[4:5], off
	s_barrier
	s_waitcnt lgkmcnt(0)
	s_setprio 1
	v_mfma_f32_16x16x32_bf16 v[4:7], v[112:115], v[128:131], v[142:145]
	v_mfma_f32_16x16x32_bf16 v[8:11], v[112:115], v[208:211], v[8:11]
	v_mfma_f32_16x16x32_bf16 v[12:15], v[116:119], v[208:211], v[12:15]
	v_mfma_f32_16x16x32_bf16 v[4:7], v[120:123], v[132:135], v[4:7]
	v_mfma_f32_16x16x32_bf16 v[142:145], v[116:119], v[128:131], v[146:149]
	v_mfma_f32_16x16x32_bf16 v[146:149], v[112:115], v[192:195], v[150:153]
	v_mfma_f32_16x16x32_bf16 v[150:153], v[116:119], v[192:195], v[180:183]
	v_mfma_f32_16x16x32_bf16 v[180:183], v[112:115], v[200:203], v[184:187]
	v_mfma_f32_16x16x32_bf16 v[184:187], v[116:119], v[200:203], v[188:191]
	v_mfma_f32_16x16x32_bf16 v[8:11], v[120:123], v[212:215], v[8:11]
	v_mfma_f32_16x16x32_bf16 v[12:15], v[124:127], v[212:215], v[12:15]
	v_mfma_f32_16x16x32_bf16 v[142:145], v[124:127], v[132:135], v[142:145]
	v_mfma_f32_16x16x32_bf16 v[146:149], v[120:123], v[196:199], v[146:149]
	v_mfma_f32_16x16x32_bf16 v[150:153], v[124:127], v[196:199], v[150:153]
	v_mfma_f32_16x16x32_bf16 v[180:183], v[120:123], v[204:207], v[180:183]
	v_mfma_f32_16x16x32_bf16 v[184:187], v[124:127], v[204:207], v[184:187]
	s_setprio 0
	s_barrier
	s_mov_b32 m0, s61
	v_lshl_add_u64 v[112:113], v[2:3], 0, s[38:39]
	global_load_lds_dwordx4 v[112:113], off
	v_lshl_add_u64 v[2:3], v[2:3], 0, s[46:47]
	s_mov_b32 m0, s60
	s_nop 0
	global_load_lds_dwordx4 v[2:3], off
	s_waitcnt vmcnt(6)
	s_barrier
; #define STAGE(P, BASE, br, kt) do { const char* _gb = (const char*)(BASE) + ((size_t)(br) * K + (size_t)(kt) * BK) * 2; \
;     __builtin_amdgcn_global_load_lds((const unsigned*)(_gb + loff0), (unsigned*)((char*)(P) + tid * 16), 16, 0, 0); \
;     __builtin_amdgcn_global_load_lds((const unsigned*)(_gb + (size_t)K * 128 + loff0), (unsigned*)((char*)(P) + tid * 16 + 8192), 16, 0, 0); } while (0)
; #define LDA(dst, b, h) for (int m = 0; m < 4; ++m) { \
;     dst[m][0] = *reinterpret_cast<const bf16x8*>((char*)SA(b, h) + aoff0 + m * 2048); \
;     dst[m][1] = *reinterpret_cast<const bf16x8*>((char*)SA(b, h) + aoff1 + m * 2048); }
; #define LDB(dst, b, h) for (int n = 0; n < 2; ++n) { \
;     dst[n][0] = *reinterpret_cast<const bf16x8*>((char*)SB(b, h) + boff0 + n * 256); \
;     dst[n][1] = *reinterpret_cast<const bf16x8*>((char*)SB(b, h) + boff1 + n * 256); }
; #define MMA(ai, bj, At, Btf) do { __builtin_amdgcn_s_setprio(1); \
;     for (int m = 0; m < 4; ++m) for (int n = 0; n < 2; ++n) for (int k = 0; k < 2; ++k) \
;       acc[ai][bj][m][n] = __builtin_amdgcn_mfma_f32_16x16x32_bf16(Btf[n][k], At[m][k], acc[ai][bj][m][n], 0, 0, 0); \
;     __builtin_amdgcn_s_setprio(0); } while (0)
; #define WAIT_V(n) asm volatile("s_waitcnt vmcnt(" #n ")" ::: "memory")
; #define WAIT_L(n) asm volatile("s_waitcnt lgkmcnt(" #n ")" ::: "memory")
; #define BAR __builtin_amdgcn_s_barrier()
; template <int EPI> ...
;     ...
;     WAIT_V(6); BAR; MMA(1, 1, At, B1); BAR;
;   }
;   { LDB(B0, 0, 0); LDA(At, 0, 0); STAGE(SA(1, 1), A, brow + HALF, nt - 1);
;     BAR; WAIT_L(0); MMA(0, 0, At, B0); BAR;
;     LDB(B1, 0, 1); BAR; WAIT_L(0); MMA(0, 1, At, B1); BAR;
;     LDA(At, 0, 1); WAIT_V(4); BAR; WAIT_L(0); MMA(1, 0, At, B0); MMA(1, 1, At, B1); BAR; }
	s_setprio 1
	v_mfma_f32_16x16x32_bf16 v[16:19], v[216:219], v[128:131], v[16:19]
	v_mfma_f32_16x16x32_bf16 v[20:23], v[220:223], v[128:131], v[20:23]
	v_mfma_f32_16x16x32_bf16 v[52:55], v[216:219], v[192:195], v[52:55]
	v_mfma_f32_16x16x32_bf16 v[108:111], v[220:223], v[200:203], v[108:111]
	v_mfma_f32_16x16x32_bf16 v[88:91], v[216:219], v[208:211], v[88:91]
	v_mfma_f32_16x16x32_bf16 v[92:95], v[220:223], v[208:211], v[92:95]
	v_mfma_f32_16x16x32_bf16 v[16:19], v[224:227], v[132:135], v[16:19]
	v_mfma_f32_16x16x32_bf16 v[20:23], v[228:231], v[132:135], v[20:23]
	v_mfma_f32_16x16x32_bf16 v[52:55], v[224:227], v[196:199], v[52:55]
	v_mfma_f32_16x16x32_bf16 v[96:99], v[220:223], v[192:195], v[96:99]
	v_mfma_f32_16x16x32_bf16 v[100:103], v[216:219], v[200:203], v[100:103]
	v_mfma_f32_16x16x32_bf16 v[108:111], v[228:231], v[204:207], v[108:111]
	v_mfma_f32_16x16x32_bf16 v[88:91], v[224:227], v[212:215], v[88:91]
	v_mfma_f32_16x16x32_bf16 v[92:95], v[228:231], v[212:215], v[92:95]
	v_mfma_f32_16x16x32_bf16 v[96:99], v[228:231], v[196:199], v[96:99]
	v_mfma_f32_16x16x32_bf16 v[100:103], v[224:227], v[204:207], v[100:103]
	s_setprio 0
	s_mov_b32 m0, s64
	v_lshl_add_u64 v[2:3], v[0:1], 0, s[38:39]
	s_barrier
	ds_read_b128 v[112:115], v176
	ds_read_b128 v[116:119], v176 offset:256
	ds_read_b128 v[120:123], v177
	ds_read_b128 v[124:127], v177 offset:256
	ds_read_b128 v[128:131], v154
	ds_read_b128 v[132:135], v154 offset:1024
	ds_read_b128 v[188:191], v154 offset:2048
	ds_read_b128 v[192:195], v154 offset:3072
	ds_read_b128 v[196:199], v154 offset:4096
	ds_read_b128 v[200:203], v154 offset:5120
	ds_read_b128 v[204:207], v154 offset:6144
	ds_read_b128 v[208:211], v154 offset:7168
	global_load_lds_dwordx4 v[2:3], off
	v_lshl_add_u64 v[0:1], v[0:1], 0, s[46:47]
	s_mov_b32 m0, s62
	s_nop 0
	global_load_lds_dwordx4 v[0:1], off
	s_barrier
	s_waitcnt lgkmcnt(0)
	s_setprio 1
	v_mfma_f32_16x16x32_bf16 v[0:3], v[112:115], v[128:131], v[56:59]
	v_mfma_f32_16x16x32_bf16 v[56:59], v[116:119], v[128:131], v[60:63]
	v_mfma_f32_16x16x32_bf16 v[60:63], v[112:115], v[188:191], v[64:67]
	v_mfma_f32_16x16x32_bf16 v[64:67], v[116:119], v[188:191], v[68:71]
	v_mfma_f32_16x16x32_bf16 v[68:71], v[112:115], v[196:199], v[72:75]
	v_mfma_f32_16x16x32_bf16 v[72:75], v[116:119], v[196:199], v[76:79]
	v_mfma_f32_16x16x32_bf16 v[76:79], v[112:115], v[204:207], v[80:83]
	v_mfma_f32_16x16x32_bf16 v[80:83], v[116:119], v[204:207], v[84:87]
	v_mfma_f32_16x16x32_bf16 v[0:3], v[120:123], v[132:135], v[0:3]
	v_mfma_f32_16x16x32_bf16 v[56:59], v[124:127], v[132:135], v[56:59]
	v_mfma_f32_16x16x32_bf16 v[60:63], v[120:123], v[192:195], v[60:63]
	v_mfma_f32_16x16x32_bf16 v[64:67], v[124:127], v[192:195], v[64:67]
	v_mfma_f32_16x16x32_bf16 v[68:71], v[120:123], v[200:203], v[68:71]
	v_mfma_f32_16x16x32_bf16 v[72:75], v[124:127], v[200:203], v[72:75]
	v_mfma_f32_16x16x32_bf16 v[76:79], v[120:123], v[208:211], v[76:79]
	v_mfma_f32_16x16x32_bf16 v[80:83], v[124:127], v[208:211], v[80:83]
	s_setprio 0
	s_barrier
	ds_read_b128 v[84:87], v178
	ds_read_b128 v[212:215], v178 offset:256
	ds_read_b128 v[216:219], v179
	ds_read_b128 v[220:223], v179 offset:256
	s_barrier
	s_waitcnt lgkmcnt(0)
	s_setprio 1
	v_mfma_f32_16x16x32_bf16 v[24:27], v[212:215], v[128:131], v[24:27]
	v_mfma_f32_16x16x32_bf16 v[28:31], v[84:87], v[188:191], v[28:31]
	v_mfma_f32_16x16x32_bf16 v[32:35], v[212:215], v[188:191], v[32:35]
	v_mfma_f32_16x16x32_bf16 v[36:39], v[84:87], v[196:199], v[36:39]
	v_mfma_f32_16x16x32_bf16 v[40:43], v[212:215], v[196:199], v[40:43]
	v_mfma_f32_16x16x32_bf16 v[44:47], v[84:87], v[204:207], v[44:47]
	v_mfma_f32_16x16x32_bf16 v[48:51], v[212:215], v[204:207], v[48:51]
	v_mfma_f32_16x16x32_bf16 v[104:107], v[84:87], v[128:131], v[104:107]
	v_mfma_f32_16x16x32_bf16 v[24:27], v[220:223], v[132:135], v[24:27]
	v_mfma_f32_16x16x32_bf16 v[28:31], v[216:219], v[192:195], v[28:31]
	v_mfma_f32_16x16x32_bf16 v[32:35], v[220:223], v[192:195], v[32:35]
	v_mfma_f32_16x16x32_bf16 v[36:39], v[216:219], v[200:203], v[36:39]
	v_mfma_f32_16x16x32_bf16 v[40:43], v[220:223], v[200:203], v[40:43]
	v_mfma_f32_16x16x32_bf16 v[44:47], v[216:219], v[208:211], v[44:47]
	v_mfma_f32_16x16x32_bf16 v[48:51], v[220:223], v[208:211], v[48:51]
	v_mfma_f32_16x16x32_bf16 v[224:227], v[216:219], v[132:135], v[104:107]
	s_setprio 0
	s_barrier
	s_nop 0
	ds_read_b128 v[104:107], v154 offset:16384
	ds_read_b128 v[128:131], v154 offset:17408
	ds_read_b128 v[132:135], v154 offset:18432
	ds_read_b128 v[188:191], v154 offset:19456
	ds_read_b128 v[192:195], v154 offset:20480
	ds_read_b128 v[196:199], v154 offset:21504
	ds_read_b128 v[200:203], v154 offset:22528
	ds_read_b128 v[204:207], v154 offset:23552
	s_waitcnt vmcnt(4)
	s_barrier
; #define LDA(dst, b, h) for (int m = 0; m < 4; ++m) { \
;     dst[m][0] = *reinterpret_cast<const bf16x8*>((char*)SA(b, h) + aoff0 + m * 2048); \
;     dst[m][1] = *reinterpret_cast<const bf16x8*>((char*)SA(b, h) + aoff1 + m * 2048); }
; #define LDB(dst, b, h) for (int n = 0; n < 2; ++n) { \
;     dst[n][0] = *reinterpret_cast<const bf16x8*>((char*)SB(b, h) + boff0 + n * 256); \
;     dst[n][1] = *reinterpret_cast<const bf16x8*>((char*)SB(b, h) + boff1 + n * 256); }
; #define MMA(ai, bj, At, Btf) do { __builtin_amdgcn_s_setprio(1); \
;     for (int m = 0; m < 4; ++m) for (int n = 0; n < 2; ++n) for (int k = 0; k < 2; ++k) \
;       acc[ai][bj][m][n] = __builtin_amdgcn_mfma_f32_16x16x32_bf16(Btf[n][k], At[m][k], acc[ai][bj][m][n], 0, 0, 0); \
;     __builtin_amdgcn_s_setprio(0); } while (0)
; #define WAIT_V(n) asm volatile("s_waitcnt vmcnt(" #n ")" ::: "memory")
; #define WAIT_L(n) asm volatile("s_waitcnt lgkmcnt(" #n ")" ::: "memory")
; #define BAR __builtin_amdgcn_s_barrier()
; template <int EPI> ...
;     ...
;     LDA(At, 0, 1); WAIT_V(4); BAR; WAIT_L(0); MMA(1, 0, At, B0); MMA(1, 1, At, B1); BAR; }
;   { LDB(B0, 1, 0); LDA(At, 1, 0); WAIT_V(2); BAR; WAIT_L(0); MMA(0, 0, At, B0); BAR;
	s_waitcnt lgkmcnt(0)
	s_setprio 1
	v_mfma_f32_16x16x32_bf16 v[4:7], v[112:115], v[104:107], v[4:7]
	v_mfma_f32_16x16x32_bf16 v[8:11], v[112:115], v[200:203], v[8:11]
	v_mfma_f32_16x16x32_bf16 v[4:7], v[120:123], v[128:131], v[4:7]
	v_mfma_f32_16x16x32_bf16 v[142:145], v[116:119], v[104:107], v[142:145]
	v_mfma_f32_16x16x32_bf16 v[146:149], v[112:115], v[132:135], v[146:149]
	v_mfma_f32_16x16x32_bf16 v[150:153], v[116:119], v[132:135], v[150:153]
	v_mfma_f32_16x16x32_bf16 v[180:183], v[112:115], v[192:195], v[180:183]
	v_mfma_f32_16x16x32_bf16 v[184:187], v[116:119], v[192:195], v[184:187]
	v_mfma_f32_16x16x32_bf16 v[8:11], v[120:123], v[204:207], v[8:11]
	v_mfma_f32_16x16x32_bf16 v[12:15], v[116:119], v[200:203], v[12:15]
	v_mfma_f32_16x16x32_bf16 v[142:145], v[124:127], v[128:131], v[142:145]
	v_mfma_f32_16x16x32_bf16 v[146:149], v[120:123], v[188:191], v[146:149]
	v_mfma_f32_16x16x32_bf16 v[150:153], v[124:127], v[188:191], v[150:153]
	v_mfma_f32_16x16x32_bf16 v[180:183], v[120:123], v[196:199], v[180:183]
	v_mfma_f32_16x16x32_bf16 v[184:187], v[124:127], v[196:199], v[184:187]
	v_mfma_f32_16x16x32_bf16 v[208:211], v[124:127], v[204:207], v[12:15]
	v_mfma_f32_16x16x32_bf16 v[12:15], v[84:87], v[104:107], v[16:19]
	v_mfma_f32_16x16x32_bf16 v[228:231], v[216:219], v[128:131], v[12:15]
	v_mfma_f32_16x16x32_bf16 v[12:15], v[212:215], v[104:107], v[20:23]
	v_mfma_f32_16x16x32_bf16 v[232:235], v[220:223], v[128:131], v[12:15]
	v_mfma_f32_16x16x32_bf16 v[12:15], v[84:87], v[132:135], v[52:55]
	v_mfma_f32_16x16x32_bf16 v[52:55], v[216:219], v[188:191], v[12:15]
	v_mfma_f32_16x16x32_bf16 v[12:15], v[212:215], v[132:135], v[96:99]
	v_mfma_f32_16x16x32_bf16 v[96:99], v[220:223], v[188:191], v[12:15]
	v_mfma_f32_16x16x32_bf16 v[12:15], v[84:87], v[192:195], v[100:103]
	v_mfma_f32_16x16x32_bf16 v[100:103], v[216:219], v[196:199], v[12:15]
	v_mfma_f32_16x16x32_bf16 v[12:15], v[212:215], v[192:195], v[108:111]
	v_mfma_f32_16x16x32_bf16 v[188:191], v[220:223], v[196:199], v[12:15]
	v_mfma_f32_16x16x32_bf16 v[12:15], v[84:87], v[200:203], v[88:91]
	v_mfma_f32_16x16x32_bf16 v[192:195], v[216:219], v[204:207], v[12:15]
	v_mfma_f32_16x16x32_bf16 v[12:15], v[212:215], v[200:203], v[92:95]
	v_mfma_f32_16x16x32_bf16 v[196:199], v[220:223], v[204:207], v[12:15]
	s_setprio 0
	s_barrier
	ds_read_b128 v[88:91], v172
	ds_read_b128 v[92:95], v172 offset:256
	ds_read_b128 v[200:203], v173
	ds_read_b128 v[204:207], v173 offset:256
	ds_read_b128 v[16:19], v154 offset:32768
	ds_read_b128 v[20:23], v154 offset:33792
	ds_read_b128 v[84:87], v154 offset:34816
	ds_read_b128 v[212:215], v154 offset:35840
	ds_read_b128 v[216:219], v154 offset:36864
	ds_read_b128 v[220:223], v154 offset:37888
	ds_read_b128 v[236:239], v154 offset:38912
	ds_read_b128 v[240:243], v154 offset:39936
	s_waitcnt vmcnt(2)
	s_barrier
	s_waitcnt lgkmcnt(0)
	s_setprio 1
	v_mfma_f32_16x16x32_bf16 v[0:3], v[88:91], v[16:19], v[0:3]
	v_mfma_f32_16x16x32_bf16 v[104:107], v[200:203], v[20:23], v[0:3]
	v_mfma_f32_16x16x32_bf16 v[0:3], v[92:95], v[16:19], v[56:59]
	v_mfma_f32_16x16x32_bf16 v[108:111], v[204:207], v[20:23], v[0:3]
	v_mfma_f32_16x16x32_bf16 v[0:3], v[88:91], v[84:87], v[60:63]
	v_mfma_f32_16x16x32_bf16 v[112:115], v[200:203], v[212:215], v[0:3]
	v_mfma_f32_16x16x32_bf16 v[0:3], v[92:95], v[84:87], v[64:67]
	v_mfma_f32_16x16x32_bf16 v[116:119], v[204:207], v[212:215], v[0:3]
	v_mfma_f32_16x16x32_bf16 v[0:3], v[88:91], v[216:219], v[68:71]
	v_mfma_f32_16x16x32_bf16 v[120:123], v[200:203], v[220:223], v[0:3]
	v_mfma_f32_16x16x32_bf16 v[0:3], v[92:95], v[216:219], v[72:75]
	v_mfma_f32_16x16x32_bf16 v[124:127], v[204:207], v[220:223], v[0:3]
	v_mfma_f32_16x16x32_bf16 v[0:3], v[88:91], v[236:239], v[76:79]
	v_mfma_f32_16x16x32_bf16 v[128:131], v[200:203], v[240:243], v[0:3]
	v_mfma_f32_16x16x32_bf16 v[0:3], v[92:95], v[236:239], v[80:83]
	v_mfma_f32_16x16x32_bf16 v[132:135], v[204:207], v[240:243], v[0:3]
	s_setprio 0
	s_barrier
; #define LDA(dst, b, h) for (int m = 0; m < 4; ++m) { \
;     dst[m][0] = *reinterpret_cast<const bf16x8*>((char*)SA(b, h) + aoff0 + m * 2048); \
;     dst[m][1] = *reinterpret_cast<const bf16x8*>((char*)SA(b, h) + aoff1 + m * 2048); }
; #define LDB(dst, b, h) for (int n = 0; n < 2; ++n) { \
;     dst[n][0] = *reinterpret_cast<const bf16x8*>((char*)SB(b, h) + boff0 + n * 256); \
;     dst[n][1] = *reinterpret_cast<const bf16x8*>((char*)SB(b, h) + boff1 + n * 256); }
; #define MMA(ai, bj, At, Btf) do { __builtin_amdgcn_s_setprio(1); \
;     for (int m = 0; m < 4; ++m) for (int n = 0; n < 2; ++n) for (int k = 0; k < 2; ++k) \
;       acc[ai][bj][m][n] = __builtin_amdgcn_mfma_f32_16x16x32_bf16(Btf[n][k], At[m][k], acc[ai][bj][m][n], 0, 0, 0); \
;     __builtin_amdgcn_s_setprio(0); } while (0)
; #define WAIT_V(n) asm volatile("s_waitcnt vmcnt(" #n ")" ::: "memory")
; #define WAIT_L(n) asm volatile("s_waitcnt lgkmcnt(" #n ")" ::: "memory")
; #define BAR __builtin_amdgcn_s_barrier()
; template <int EPI> ...
;     ...
;     LDB(B1, 1, 1); WAIT_V(0); BAR; WAIT_L(0); MMA(0, 1, At, B1); BAR;
;     LDA(At, 1, 1); BAR; WAIT_L(0); MMA(1, 0, At, B0); MMA(1, 1, At, B1); BAR; }
;   if (wr == 0) BAR;
	s_nop 4
	ds_read_b128 v[0:3], v174
	ds_read_b128 v[244:247], v174 offset:256
	ds_read_b128 v[248:251], v175
	ds_read_b128 v[138:141], v175 offset:256
	s_waitcnt vmcnt(0)
	s_barrier
	s_waitcnt lgkmcnt(0)
	s_setprio 1
	v_mfma_f32_16x16x32_bf16 v[12:15], v[0:3], v[16:19], v[224:227]
	v_mfma_f32_16x16x32_bf16 v[16:19], v[244:247], v[16:19], v[24:27]
	v_mfma_f32_16x16x32_bf16 v[12:15], v[248:251], v[20:23], v[12:15]
	v_mfma_f32_16x16x32_bf16 v[16:19], v[138:141], v[20:23], v[16:19]
	v_mfma_f32_16x16x32_bf16 v[20:23], v[0:3], v[84:87], v[28:31]
	v_mfma_f32_16x16x32_bf16 v[24:27], v[244:247], v[84:87], v[32:35]
	v_mfma_f32_16x16x32_bf16 v[28:31], v[0:3], v[216:219], v[36:39]
	v_mfma_f32_16x16x32_bf16 v[32:35], v[244:247], v[216:219], v[40:43]
	v_mfma_f32_16x16x32_bf16 v[36:39], v[0:3], v[236:239], v[44:47]
	v_mfma_f32_16x16x32_bf16 v[40:43], v[244:247], v[236:239], v[48:51]
	v_mfma_f32_16x16x32_bf16 v[20:23], v[248:251], v[212:215], v[20:23]
	v_mfma_f32_16x16x32_bf16 v[24:27], v[138:141], v[212:215], v[24:27]
	v_mfma_f32_16x16x32_bf16 v[28:31], v[248:251], v[220:223], v[28:31]
	v_mfma_f32_16x16x32_bf16 v[32:35], v[138:141], v[220:223], v[32:35]
	v_mfma_f32_16x16x32_bf16 v[36:39], v[248:251], v[240:243], v[36:39]
	v_mfma_f32_16x16x32_bf16 v[40:43], v[138:141], v[240:243], v[40:43]
	s_setprio 0
	s_barrier
	ds_read_b128 v[44:47], v154 offset:49152
	ds_read_b128 v[48:51], v154 offset:50176
	ds_read_b128 v[212:215], v154 offset:51200
	ds_read_b128 v[216:219], v154 offset:52224
	ds_read_b128 v[220:223], v154 offset:53248
	ds_read_b128 v[224:227], v154 offset:54272
	ds_read_b128 v[236:239], v154 offset:55296
	ds_read_b128 v[240:243], v154 offset:56320
	s_barrier
	s_waitcnt lgkmcnt(0)
	s_setprio 1
	v_mfma_f32_16x16x32_bf16 v[4:7], v[88:91], v[44:47], v[4:7]
	v_mfma_f32_16x16x32_bf16 v[64:67], v[200:203], v[48:51], v[4:7]
	v_mfma_f32_16x16x32_bf16 v[4:7], v[92:95], v[44:47], v[142:145]
	v_mfma_f32_16x16x32_bf16 v[68:71], v[204:207], v[48:51], v[4:7]
	v_mfma_f32_16x16x32_bf16 v[4:7], v[88:91], v[212:215], v[146:149]
	v_mfma_f32_16x16x32_bf16 v[72:75], v[200:203], v[216:219], v[4:7]
	v_mfma_f32_16x16x32_bf16 v[4:7], v[92:95], v[212:215], v[150:153]
	v_mfma_f32_16x16x32_bf16 v[76:79], v[204:207], v[216:219], v[4:7]
	v_mfma_f32_16x16x32_bf16 v[4:7], v[88:91], v[220:223], v[180:183]
	v_mfma_f32_16x16x32_bf16 v[80:83], v[200:203], v[224:227], v[4:7]
	v_mfma_f32_16x16x32_bf16 v[4:7], v[92:95], v[220:223], v[184:187]
	v_mfma_f32_16x16x32_bf16 v[84:87], v[204:207], v[224:227], v[4:7]
	v_mfma_f32_16x16x32_bf16 v[4:7], v[88:91], v[236:239], v[8:11]
	v_mfma_f32_16x16x32_bf16 v[88:91], v[200:203], v[240:243], v[4:7]
	v_mfma_f32_16x16x32_bf16 v[4:7], v[92:95], v[236:239], v[208:211]
	v_mfma_f32_16x16x32_bf16 v[92:95], v[204:207], v[240:243], v[4:7]
	v_mfma_f32_16x16x32_bf16 v[4:7], v[0:3], v[44:47], v[228:231]
	v_mfma_f32_16x16x32_bf16 v[60:63], v[248:251], v[48:51], v[4:7]
	v_mfma_f32_16x16x32_bf16 v[4:7], v[244:247], v[44:47], v[232:235]
	v_mfma_f32_16x16x32_bf16 v[56:59], v[138:141], v[48:51], v[4:7]
	v_mfma_f32_16x16x32_bf16 v[4:7], v[0:3], v[212:215], v[52:55]
	v_mfma_f32_16x16x32_bf16 v[52:55], v[248:251], v[216:219], v[4:7]
	v_mfma_f32_16x16x32_bf16 v[4:7], v[244:247], v[212:215], v[96:99]
	v_mfma_f32_16x16x32_bf16 v[48:51], v[138:141], v[216:219], v[4:7]
	v_mfma_f32_16x16x32_bf16 v[4:7], v[0:3], v[220:223], v[100:103]
	v_mfma_f32_16x16x32_bf16 v[44:47], v[248:251], v[224:227], v[4:7]
	v_mfma_f32_16x16x32_bf16 v[4:7], v[244:247], v[220:223], v[188:191]
	v_mfma_f32_16x16x32_bf16 v[0:3], v[0:3], v[236:239], v[192:195]
	v_mfma_f32_16x16x32_bf16 v[8:11], v[138:141], v[224:227], v[4:7]
	v_mfma_f32_16x16x32_bf16 v[4:7], v[248:251], v[240:243], v[0:3]
	v_mfma_f32_16x16x32_bf16 v[0:3], v[244:247], v[236:239], v[196:199]
	v_mfma_f32_16x16x32_bf16 v[0:3], v[138:141], v[240:243], v[0:3]
	s_setprio 0
	s_barrier
	s_and_saveexec_b64 s[52:53], s[2:3]
	s_cbranch_execz .LBB0_967
	s_barrier
	s_branch .LBB0_967

; #define STAGE(P, BASE, br, kt) do { const char* _gb = (const char*)(BASE) + ((size_t)(br) * K + (size_t)(kt) * BK) * 2; \
;     __builtin_amdgcn_global_load_lds((const unsigned*)(_gb + loff0), (unsigned*)((char*)(P) + tid * 16), 16, 0, 0); \
;     __builtin_amdgcn_global_load_lds((const unsigned*)(_gb + (size_t)K * 128 + loff0), (unsigned*)((char*)(P) + tid * 16 + 8192), 16, 0, 0); } while (0)
; #define LDA(dst, b, h) for (int m = 0; m < 4; ++m) { \
;     dst[m][0] = *reinterpret_cast<const bf16x8*>((char*)SA(b, h) + aoff0 + m * 2048); \
;     dst[m][1] = *reinterpret_cast<const bf16x8*>((char*)SA(b, h) + aoff1 + m * 2048); }
; #define LDB(dst, b, h) for (int n = 0; n < 2; ++n) { \
;     dst[n][0] = *reinterpret_cast<const bf16x8*>((char*)SB(b, h) + boff0 + n * 256); \
;     dst[n][1] = *reinterpret_cast<const bf16x8*>((char*)SB(b, h) + boff1 + n * 256); }
; #define MMA(ai, bj, At, Btf) do { __builtin_amdgcn_s_setprio(1); \
;     for (int m = 0; m < 4; ++m) for (int n = 0; n < 2; ++n) for (int k = 0; k < 2; ++k) \
;       acc[ai][bj][m][n] = __builtin_amdgcn_mfma_f32_16x16x32_bf16(Btf[n][k], At[m][k], acc[ai][bj][m][n], 0, 0, 0); \
;     __builtin_amdgcn_s_setprio(0); } while (0)
; #define WAIT_L(n) asm volatile("s_waitcnt lgkmcnt(" #n ")" ::: "memory")
; #define BAR __builtin_amdgcn_s_barrier()
; #define SCHED __builtin_amdgcn_sched_barrier(0)
; template <int EPI> ...
;     ...
;     LDB(B0, 0, 0); SCHED; LDA(At, 0, 0); STAGE(SA(1, 1), A, brow + HALF, t + 1);
;     WAIT_L(8); BAR; WAIT_L(0); MMA(0, 0, At, B0); BAR; SCHED;
;     LDB(B1, 0, 1); STAGE(SB(0, 0), Bt, bcol, t + 2);
;     BAR; WAIT_L(0); MMA(0, 1, At, B1); BAR;
;     LDA(At, 0, 1); STAGE(SA(0, 0), A, brow, t + 2);
;     BAR; WAIT_L(0); MMA(1, 0, At, B0); BAR; SCHED;
.LBB0_1018:
	ds_read_b128 v[160:163], v152
	ds_read_b128 v[164:167], v152 offset:256
	ds_read_b128 v[168:171], v153
	ds_read_b128 v[172:175], v153 offset:256
	v_lshl_add_u64 v[224:225], s[66:67], 0, v[132:133]
	v_readfirstlane_b32 s68, v150
	v_lshl_add_u64 v[208:209], v[224:225], 0, s[16:17]
	s_mov_b32 m0, s68
	v_readfirstlane_b32 s68, v151
	ds_read_b128 v[176:179], v149
	ds_read_b128 v[180:183], v149 offset:1024
	ds_read_b128 v[184:187], v149 offset:2048
	ds_read_b128 v[188:191], v149 offset:3072
	ds_read_b128 v[192:195], v149 offset:4096
	ds_read_b128 v[196:199], v149 offset:5120
	ds_read_b128 v[200:203], v149 offset:6144
	ds_read_b128 v[204:207], v149 offset:7168
	global_load_lds_dwordx4 v[208:209], off
	v_lshl_add_u64 v[208:209], v[224:225], 0, s[18:19]
	s_mov_b32 m0, s68
	s_nop 0
	global_load_lds_dwordx4 v[208:209], off
	s_waitcnt lgkmcnt(8)
	v_readfirstlane_b32 s68, v148
	v_lshl_add_u64 v[246:247], v[226:227], 0, s[56:57]
	s_mov_b32 m0, s68
	s_nop 0
	global_load_lds_dwordx4 v[246:247], off
	ds_read_b128 v[208:211], v154
	ds_read_b128 v[212:215], v154 offset:256
	ds_read_b128 v[216:219], v155
	ds_read_b128 v[220:223], v155 offset:256
	s_barrier
	s_waitcnt lgkmcnt(0)
	s_setprio 1
	v_mfma_f32_16x16x32_bf16 v[124:127], v[160:163], v[176:179], v[124:127]
	v_mfma_f32_16x16x32_bf16 v[120:123], v[164:167], v[176:179], v[120:123]
	v_mfma_f32_16x16x32_bf16 v[116:119], v[160:163], v[184:187], v[116:119]
	v_mfma_f32_16x16x32_bf16 v[112:115], v[164:167], v[184:187], v[112:115]
	v_mfma_f32_16x16x32_bf16 v[108:111], v[160:163], v[192:195], v[108:111]
	v_mfma_f32_16x16x32_bf16 v[104:107], v[164:167], v[192:195], v[104:107]
	v_mfma_f32_16x16x32_bf16 v[100:103], v[160:163], v[200:203], v[100:103]
	v_mfma_f32_16x16x32_bf16 v[96:99], v[164:167], v[200:203], v[96:99]
	v_mfma_f32_16x16x32_bf16 v[124:127], v[168:171], v[180:183], v[124:127]
	v_mfma_f32_16x16x32_bf16 v[120:123], v[172:175], v[180:183], v[120:123]
	v_mfma_f32_16x16x32_bf16 v[116:119], v[168:171], v[188:191], v[116:119]
	v_mfma_f32_16x16x32_bf16 v[112:115], v[172:175], v[188:191], v[112:115]
	v_mfma_f32_16x16x32_bf16 v[108:111], v[168:171], v[196:199], v[108:111]
	v_mfma_f32_16x16x32_bf16 v[104:107], v[172:175], v[196:199], v[104:107]
	v_mfma_f32_16x16x32_bf16 v[100:103], v[168:171], v[204:207], v[100:103]
	v_mfma_f32_16x16x32_bf16 v[96:99], v[172:175], v[204:207], v[96:99]
	v_mfma_f32_16x16x32_bf16 v[92:95], v[208:211], v[176:179], v[92:95]
	v_mfma_f32_16x16x32_bf16 v[88:91], v[212:215], v[176:179], v[88:91]
	v_mfma_f32_16x16x32_bf16 v[84:87], v[208:211], v[184:187], v[84:87]
	v_mfma_f32_16x16x32_bf16 v[80:83], v[212:215], v[184:187], v[80:83]
	v_mfma_f32_16x16x32_bf16 v[76:79], v[208:211], v[192:195], v[76:79]
	v_mfma_f32_16x16x32_bf16 v[72:75], v[212:215], v[192:195], v[72:75]
	v_mfma_f32_16x16x32_bf16 v[68:71], v[208:211], v[200:203], v[68:71]
	v_mfma_f32_16x16x32_bf16 v[64:67], v[212:215], v[200:203], v[64:67]
	v_mfma_f32_16x16x32_bf16 v[92:95], v[216:219], v[180:183], v[92:95]
	v_mfma_f32_16x16x32_bf16 v[88:91], v[220:223], v[180:183], v[88:91]
	v_mfma_f32_16x16x32_bf16 v[84:87], v[216:219], v[188:191], v[84:87]
	v_mfma_f32_16x16x32_bf16 v[80:83], v[220:223], v[188:191], v[80:83]
	v_mfma_f32_16x16x32_bf16 v[76:79], v[216:219], v[196:199], v[76:79]
	v_mfma_f32_16x16x32_bf16 v[72:75], v[220:223], v[196:199], v[72:75]
	v_mfma_f32_16x16x32_bf16 v[68:71], v[216:219], v[204:207], v[68:71]
	v_mfma_f32_16x16x32_bf16 v[64:67], v[220:223], v[204:207], v[64:67]
	s_setprio 0
	s_barrier
	v_lshl_add_u64 v[226:227], s[64:65], 0, v[132:133]
	v_readfirstlane_b32 s68, v135
	v_lshl_add_u64 v[228:229], v[226:227], 0, s[20:21]
	s_mov_b32 m0, s68
	v_readfirstlane_b32 s68, v136
	global_load_lds_dwordx4 v[228:229], off
	v_lshl_add_u64 v[228:229], v[226:227], 0, s[22:23]
	s_mov_b32 m0, s68
	s_nop 0
	global_load_lds_dwordx4 v[228:229], off
	v_readfirstlane_b32 s68, v137
	v_lshl_add_u64 v[228:229], v[224:225], 0, s[24:25]
	s_mov_b32 m0, s68
	v_readfirstlane_b32 s68, v138
	ds_read_b128 v[176:179], v149 offset:16384
	ds_read_b128 v[180:183], v149 offset:17408
	ds_read_b128 v[184:187], v149 offset:18432
	ds_read_b128 v[188:191], v149 offset:19456
	ds_read_b128 v[192:195], v149 offset:20480
	ds_read_b128 v[196:199], v149 offset:21504
	ds_read_b128 v[200:203], v149 offset:22528
	ds_read_b128 v[204:207], v149 offset:23552
	global_load_lds_dwordx4 v[228:229], off
	v_lshl_add_u64 v[228:229], v[224:225], 0, s[26:27]
	s_mov_b32 m0, s68
	s_nop 0
	global_load_lds_dwordx4 v[228:229], off
	v_readfirstlane_b32 s68, v139
	v_lshl_add_u64 v[246:247], v[226:227], 0, s[28:29]
	s_mov_b32 m0, s68
	v_readfirstlane_b32 s68, v140
	global_load_lds_dwordx4 v[246:247], off
	s_waitcnt vmcnt(5)
	s_barrier
; #define STAGE(P, BASE, br, kt) do { const char* _gb = (const char*)(BASE) + ((size_t)(br) * K + (size_t)(kt) * BK) * 2; \
;     __builtin_amdgcn_global_load_lds((const unsigned*)(_gb + loff0), (unsigned*)((char*)(P) + tid * 16), 16, 0, 0); \
;     __builtin_amdgcn_global_load_lds((const unsigned*)(_gb + (size_t)K * 128 + loff0), (unsigned*)((char*)(P) + tid * 16 + 8192), 16, 0, 0); } while (0)
; #define LDA(dst, b, h) for (int m = 0; m < 4; ++m) { \
;     dst[m][0] = *reinterpret_cast<const bf16x8*>((char*)SA(b, h) + aoff0 + m * 2048); \
;     dst[m][1] = *reinterpret_cast<const bf16x8*>((char*)SA(b, h) + aoff1 + m * 2048); }
; #define LDB(dst, b, h) for (int n = 0; n < 2; ++n) { \
;     dst[n][0] = *reinterpret_cast<const bf16x8*>((char*)SB(b, h) + boff0 + n * 256); \
;     dst[n][1] = *reinterpret_cast<const bf16x8*>((char*)SB(b, h) + boff1 + n * 256); }
; #define MMA(ai, bj, At, Btf) do { __builtin_amdgcn_s_setprio(1); \
;     for (int m = 0; m < 4; ++m) for (int n = 0; n < 2; ++n) for (int k = 0; k < 2; ++k) \
;       acc[ai][bj][m][n] = __builtin_amdgcn_mfma_f32_16x16x32_bf16(Btf[n][k], At[m][k], acc[ai][bj][m][n], 0, 0, 0); \
;     __builtin_amdgcn_s_setprio(0); } while (0)
; #define WAIT_V(n) asm volatile("s_waitcnt vmcnt(" #n ")" ::: "memory")
; #define WAIT_L(n) asm volatile("s_waitcnt lgkmcnt(" #n ")" ::: "memory")
; #define BAR __builtin_amdgcn_s_barrier()
; #define SCHED __builtin_amdgcn_sched_barrier(0)
; template <int EPI> ...
;     ...
;     BAR; WAIT_L(0); MMA(1, 0, At, B0); BAR; SCHED;
;     STAGE(SB(0, 1), Bt, bcol + HALF, t + 2);
;     WAIT_V(6); BAR; MMA(1, 1, At, B1); BAR;
;     LDB(B0, 1, 0); SCHED; LDA(At, 1, 0); STAGE(SA(0, 1), A, brow + HALF, t + 2);
;     WAIT_L(8); BAR; WAIT_L(0); MMA(0, 0, At, B0); BAR; SCHED;
;     LDB(B1, 1, 1); STAGE(SB(1, 0), Bt, bcol, t + 3);
;     BAR; WAIT_L(0); MMA(0, 1, At, B1); BAR;
	s_waitcnt lgkmcnt(0)
	s_setprio 1
	v_mfma_f32_16x16x32_bf16 v[60:63], v[160:163], v[176:179], v[60:63]
	v_mfma_f32_16x16x32_bf16 v[56:59], v[164:167], v[176:179], v[56:59]
	v_mfma_f32_16x16x32_bf16 v[52:55], v[160:163], v[184:187], v[52:55]
	v_mfma_f32_16x16x32_bf16 v[48:51], v[164:167], v[184:187], v[48:51]
	v_mfma_f32_16x16x32_bf16 v[44:47], v[160:163], v[192:195], v[44:47]
	v_mfma_f32_16x16x32_bf16 v[40:43], v[164:167], v[192:195], v[40:43]
	v_mfma_f32_16x16x32_bf16 v[36:39], v[160:163], v[200:203], v[36:39]
	v_mfma_f32_16x16x32_bf16 v[32:35], v[164:167], v[200:203], v[32:35]
	v_mfma_f32_16x16x32_bf16 v[60:63], v[168:171], v[180:183], v[60:63]
	v_mfma_f32_16x16x32_bf16 v[56:59], v[172:175], v[180:183], v[56:59]
	v_mfma_f32_16x16x32_bf16 v[52:55], v[168:171], v[188:191], v[52:55]
	v_mfma_f32_16x16x32_bf16 v[48:51], v[172:175], v[188:191], v[48:51]
	v_mfma_f32_16x16x32_bf16 v[44:47], v[168:171], v[196:199], v[44:47]
	v_mfma_f32_16x16x32_bf16 v[40:43], v[172:175], v[196:199], v[40:43]
	v_mfma_f32_16x16x32_bf16 v[36:39], v[168:171], v[204:207], v[36:39]
	v_mfma_f32_16x16x32_bf16 v[32:35], v[172:175], v[204:207], v[32:35]
	v_mfma_f32_16x16x32_bf16 v[28:31], v[208:211], v[176:179], v[28:31]
	v_mfma_f32_16x16x32_bf16 v[24:27], v[212:215], v[176:179], v[24:27]
	v_mfma_f32_16x16x32_bf16 v[20:23], v[208:211], v[184:187], v[20:23]
	v_mfma_f32_16x16x32_bf16 v[16:19], v[212:215], v[184:187], v[16:19]
	v_mfma_f32_16x16x32_bf16 v[12:15], v[208:211], v[192:195], v[12:15]
	v_mfma_f32_16x16x32_bf16 v[8:11], v[212:215], v[192:195], v[8:11]
	v_mfma_f32_16x16x32_bf16 v[4:7], v[208:211], v[200:203], v[4:7]
	v_mfma_f32_16x16x32_bf16 v[0:3], v[212:215], v[200:203], v[0:3]
	v_mfma_f32_16x16x32_bf16 v[28:31], v[216:219], v[180:183], v[28:31]
	v_mfma_f32_16x16x32_bf16 v[24:27], v[220:223], v[180:183], v[24:27]
	v_mfma_f32_16x16x32_bf16 v[20:23], v[216:219], v[188:191], v[20:23]
	v_mfma_f32_16x16x32_bf16 v[16:19], v[220:223], v[188:191], v[16:19]
	v_mfma_f32_16x16x32_bf16 v[12:15], v[216:219], v[196:199], v[12:15]
	v_mfma_f32_16x16x32_bf16 v[8:11], v[220:223], v[196:199], v[8:11]
	v_mfma_f32_16x16x32_bf16 v[4:7], v[216:219], v[204:207], v[4:7]
	v_mfma_f32_16x16x32_bf16 v[0:3], v[220:223], v[204:207], v[0:3]
	s_setprio 0
	s_barrier
	ds_read_b128 v[160:163], v156
	ds_read_b128 v[164:167], v156 offset:256
	ds_read_b128 v[168:171], v157
	ds_read_b128 v[172:175], v157 offset:256
	v_readfirstlane_b32 s68, v141
	v_lshl_add_u64 v[208:209], v[224:225], 0, s[36:37]
	s_mov_b32 m0, s68
	v_readfirstlane_b32 s68, v142
	ds_read_b128 v[176:179], v149 offset:32768
	ds_read_b128 v[180:183], v149 offset:33792
	ds_read_b128 v[184:187], v149 offset:34816
	ds_read_b128 v[188:191], v149 offset:35840
	ds_read_b128 v[192:195], v149 offset:36864
	ds_read_b128 v[196:199], v149 offset:37888
	ds_read_b128 v[200:203], v149 offset:38912
	ds_read_b128 v[204:207], v149 offset:39936
	global_load_lds_dwordx4 v[208:209], off
	v_lshl_add_u64 v[208:209], v[224:225], 0, s[38:39]
	s_mov_b32 m0, s68
	s_nop 0
	global_load_lds_dwordx4 v[208:209], off
	s_waitcnt lgkmcnt(8)
	v_readfirstlane_b32 s68, v140
	v_lshl_add_u64 v[246:247], v[226:227], 0, s[30:31]
	s_mov_b32 m0, s68
	s_nop 0
	global_load_lds_dwordx4 v[246:247], off
	ds_read_b128 v[208:211], v158
	ds_read_b128 v[212:215], v158 offset:256
	ds_read_b128 v[216:219], v159
	ds_read_b128 v[220:223], v159 offset:256
	s_barrier
	s_waitcnt lgkmcnt(0)
	s_setprio 1
	v_mfma_f32_16x16x32_bf16 v[124:127], v[160:163], v[176:179], v[124:127]
	v_mfma_f32_16x16x32_bf16 v[120:123], v[164:167], v[176:179], v[120:123]
	v_mfma_f32_16x16x32_bf16 v[116:119], v[160:163], v[184:187], v[116:119]
	v_mfma_f32_16x16x32_bf16 v[112:115], v[164:167], v[184:187], v[112:115]
	v_mfma_f32_16x16x32_bf16 v[108:111], v[160:163], v[192:195], v[108:111]
	v_mfma_f32_16x16x32_bf16 v[104:107], v[164:167], v[192:195], v[104:107]
	v_mfma_f32_16x16x32_bf16 v[100:103], v[160:163], v[200:203], v[100:103]
	v_mfma_f32_16x16x32_bf16 v[96:99], v[164:167], v[200:203], v[96:99]
	v_mfma_f32_16x16x32_bf16 v[124:127], v[168:171], v[180:183], v[124:127]
	v_mfma_f32_16x16x32_bf16 v[120:123], v[172:175], v[180:183], v[120:123]
	v_mfma_f32_16x16x32_bf16 v[116:119], v[168:171], v[188:191], v[116:119]
	v_mfma_f32_16x16x32_bf16 v[112:115], v[172:175], v[188:191], v[112:115]
	v_mfma_f32_16x16x32_bf16 v[108:111], v[168:171], v[196:199], v[108:111]
	v_mfma_f32_16x16x32_bf16 v[104:107], v[172:175], v[196:199], v[104:107]
	v_mfma_f32_16x16x32_bf16 v[100:103], v[168:171], v[204:207], v[100:103]
	v_mfma_f32_16x16x32_bf16 v[96:99], v[172:175], v[204:207], v[96:99]
	v_mfma_f32_16x16x32_bf16 v[92:95], v[208:211], v[176:179], v[92:95]
	v_mfma_f32_16x16x32_bf16 v[88:91], v[212:215], v[176:179], v[88:91]
	v_mfma_f32_16x16x32_bf16 v[84:87], v[208:211], v[184:187], v[84:87]
	v_mfma_f32_16x16x32_bf16 v[80:83], v[212:215], v[184:187], v[80:83]
	v_mfma_f32_16x16x32_bf16 v[76:79], v[208:211], v[192:195], v[76:79]
	v_mfma_f32_16x16x32_bf16 v[72:75], v[212:215], v[192:195], v[72:75]
	v_mfma_f32_16x16x32_bf16 v[68:71], v[208:211], v[200:203], v[68:71]
	v_mfma_f32_16x16x32_bf16 v[64:67], v[212:215], v[200:203], v[64:67]
	v_mfma_f32_16x16x32_bf16 v[92:95], v[216:219], v[180:183], v[92:95]
	v_mfma_f32_16x16x32_bf16 v[88:91], v[220:223], v[180:183], v[88:91]
	v_mfma_f32_16x16x32_bf16 v[84:87], v[216:219], v[188:191], v[84:87]
	v_mfma_f32_16x16x32_bf16 v[80:83], v[220:223], v[188:191], v[80:83]
	v_mfma_f32_16x16x32_bf16 v[76:79], v[216:219], v[196:199], v[76:79]
	v_mfma_f32_16x16x32_bf16 v[72:75], v[220:223], v[196:199], v[72:75]
	v_mfma_f32_16x16x32_bf16 v[68:71], v[216:219], v[204:207], v[68:71]
	v_mfma_f32_16x16x32_bf16 v[64:67], v[220:223], v[204:207], v[64:67]
	s_setprio 0
	s_barrier
; #define STAGE(P, BASE, br, kt) do { const char* _gb = (const char*)(BASE) + ((size_t)(br) * K + (size_t)(kt) * BK) * 2; \
;     __builtin_amdgcn_global_load_lds((const unsigned*)(_gb + loff0), (unsigned*)((char*)(P) + tid * 16), 16, 0, 0); \
;     __builtin_amdgcn_global_load_lds((const unsigned*)(_gb + (size_t)K * 128 + loff0), (unsigned*)((char*)(P) + tid * 16 + 8192), 16, 0, 0); } while (0)
; #define LDA(dst, b, h) for (int m = 0; m < 4; ++m) { \
;     dst[m][0] = *reinterpret_cast<const bf16x8*>((char*)SA(b, h) + aoff0 + m * 2048); \
;     dst[m][1] = *reinterpret_cast<const bf16x8*>((char*)SA(b, h) + aoff1 + m * 2048); }
; #define LDB(dst, b, h) for (int n = 0; n < 2; ++n) { \
;     dst[n][0] = *reinterpret_cast<const bf16x8*>((char*)SB(b, h) + boff0 + n * 256); \
;     dst[n][1] = *reinterpret_cast<const bf16x8*>((char*)SB(b, h) + boff1 + n * 256); }
; #define MMA(ai, bj, At, Btf) do { __builtin_amdgcn_s_setprio(1); \
;     for (int m = 0; m < 4; ++m) for (int n = 0; n < 2; ++n) for (int k = 0; k < 2; ++k) \
;       acc[ai][bj][m][n] = __builtin_amdgcn_mfma_f32_16x16x32_bf16(Btf[n][k], At[m][k], acc[ai][bj][m][n], 0, 0, 0); \
;     __builtin_amdgcn_s_setprio(0); } while (0)
; #define WAIT_V(n) asm volatile("s_waitcnt vmcnt(" #n ")" ::: "memory")
; #define WAIT_L(n) asm volatile("s_waitcnt lgkmcnt(" #n ")" ::: "memory")
; #define BAR __builtin_amdgcn_s_barrier()
; #define SCHED __builtin_amdgcn_sched_barrier(0)
; template <int EPI> ...
;     ...
;     LDA(At, 1, 1); STAGE(SA(1, 0), A, brow, t + 3);
;     BAR; WAIT_L(0); MMA(1, 0, At, B0); BAR; SCHED;
;     STAGE(SB(1, 1), Bt, bcol + HALF, t + 3);
;     WAIT_V(6); BAR; MMA(1, 1, At, B1); BAR;
;   }
;   { LDB(B0, 0, 0); LDA(At, 0, 0); STAGE(SA(1, 1), A, brow + HALF, nt - 1);
;     BAR; WAIT_L(0); MMA(0, 0, At, B0); BAR;
;     LDB(B1, 0, 1); BAR; WAIT_L(0); MMA(0, 1, At, B1); BAR;
	v_readfirstlane_b32 s68, v143
	v_lshl_add_u64 v[228:229], v[226:227], 0, s[46:47]
	s_mov_b32 m0, s68
	v_readfirstlane_b32 s68, v144
	global_load_lds_dwordx4 v[228:229], off
	v_lshl_add_u64 v[228:229], v[226:227], 0, s[48:49]
	s_mov_b32 m0, s68
	s_nop 0
	global_load_lds_dwordx4 v[228:229], off
	v_readfirstlane_b32 s68, v145
	v_lshl_add_u64 v[228:229], v[224:225], 0, s[50:51]
	s_mov_b32 m0, s68
	v_readfirstlane_b32 s68, v146
	ds_read_b128 v[176:179], v149 offset:49152
	ds_read_b128 v[180:183], v149 offset:50176
	ds_read_b128 v[184:187], v149 offset:51200
	ds_read_b128 v[188:191], v149 offset:52224
	ds_read_b128 v[192:195], v149 offset:53248
	ds_read_b128 v[196:199], v149 offset:54272
	ds_read_b128 v[200:203], v149 offset:55296
	ds_read_b128 v[204:207], v149 offset:56320
	global_load_lds_dwordx4 v[228:229], off
	v_lshl_add_u64 v[224:225], v[224:225], 0, s[52:53]
	s_mov_b32 m0, s68
	s_nop 0
	global_load_lds_dwordx4 v[224:225], off
	v_readfirstlane_b32 s68, v147
	v_lshl_add_u64 v[246:247], v[226:227], 0, s[54:55]
	s_mov_b32 m0, s68
	v_readfirstlane_b32 s68, v148
	global_load_lds_dwordx4 v[246:247], off
	s_waitcnt vmcnt(5)
	s_barrier
	s_waitcnt lgkmcnt(0)
	s_setprio 1
	s_waitcnt lgkmcnt(0)
	v_mfma_f32_16x16x32_bf16 v[60:63], v[160:163], v[176:179], v[60:63]
	v_mfma_f32_16x16x32_bf16 v[56:59], v[164:167], v[176:179], v[56:59]
	v_mfma_f32_16x16x32_bf16 v[52:55], v[160:163], v[184:187], v[52:55]
	v_mfma_f32_16x16x32_bf16 v[48:51], v[164:167], v[184:187], v[48:51]
	v_mfma_f32_16x16x32_bf16 v[44:47], v[160:163], v[192:195], v[44:47]
	v_mfma_f32_16x16x32_bf16 v[40:43], v[164:167], v[192:195], v[40:43]
	v_mfma_f32_16x16x32_bf16 v[36:39], v[160:163], v[200:203], v[36:39]
	v_mfma_f32_16x16x32_bf16 v[32:35], v[164:167], v[200:203], v[32:35]
	v_mfma_f32_16x16x32_bf16 v[60:63], v[168:171], v[180:183], v[60:63]
	v_mfma_f32_16x16x32_bf16 v[56:59], v[172:175], v[180:183], v[56:59]
	v_mfma_f32_16x16x32_bf16 v[52:55], v[168:171], v[188:191], v[52:55]
	v_mfma_f32_16x16x32_bf16 v[48:51], v[172:175], v[188:191], v[48:51]
	v_mfma_f32_16x16x32_bf16 v[44:47], v[168:171], v[196:199], v[44:47]
	v_mfma_f32_16x16x32_bf16 v[40:43], v[172:175], v[196:199], v[40:43]
	v_mfma_f32_16x16x32_bf16 v[36:39], v[168:171], v[204:207], v[36:39]
	v_mfma_f32_16x16x32_bf16 v[32:35], v[172:175], v[204:207], v[32:35]
	s_setprio 0
	s_setprio 1
	v_mfma_f32_16x16x32_bf16 v[28:31], v[208:211], v[176:179], v[28:31]
	v_mfma_f32_16x16x32_bf16 v[24:27], v[212:215], v[176:179], v[24:27]
	v_mfma_f32_16x16x32_bf16 v[20:23], v[208:211], v[184:187], v[20:23]
	v_mfma_f32_16x16x32_bf16 v[16:19], v[212:215], v[184:187], v[16:19]
	v_mfma_f32_16x16x32_bf16 v[12:15], v[208:211], v[192:195], v[12:15]
	v_mfma_f32_16x16x32_bf16 v[8:11], v[212:215], v[192:195], v[8:11]
	v_mfma_f32_16x16x32_bf16 v[4:7], v[208:211], v[200:203], v[4:7]
	v_mfma_f32_16x16x32_bf16 v[0:3], v[212:215], v[200:203], v[0:3]
	v_mfma_f32_16x16x32_bf16 v[28:31], v[216:219], v[180:183], v[28:31]
	v_mfma_f32_16x16x32_bf16 v[24:27], v[220:223], v[180:183], v[24:27]
	v_mfma_f32_16x16x32_bf16 v[20:23], v[216:219], v[188:191], v[20:23]
	v_mfma_f32_16x16x32_bf16 v[16:19], v[220:223], v[188:191], v[16:19]
	v_mfma_f32_16x16x32_bf16 v[12:15], v[216:219], v[196:199], v[12:15]
	v_mfma_f32_16x16x32_bf16 v[8:11], v[220:223], v[196:199], v[8:11]
	v_mfma_f32_16x16x32_bf16 v[4:7], v[216:219], v[204:207], v[4:7]
	v_mfma_f32_16x16x32_bf16 v[0:3], v[220:223], v[204:207], v[0:3]
	s_setprio 0
	s_add_i32 s59, s59, 2
	s_add_u32 s64, s64, 0x100
	s_addc_u32 s65, s65, 0
	s_add_u32 s66, s66, 0x100
	s_addc_u32 s67, s67, 0
	s_cmp_lt_u32 s59, 28
	s_barrier
	s_cbranch_scc1 .LBB0_1018
	v_readfirstlane_b32 s68, v148
	v_lshl_add_u64 v[246:247], v[226:227], 0, s[56:57]
	s_mov_b32 m0, s68
	s_nop 0
	global_load_lds_dwordx4 v[246:247], off
	s_add_u32 s62, s72, s62
	s_addc_u32 s63, s73, s63
	v_readfirstlane_b32 s59, v150
	v_lshl_add_u64 v[208:209], s[62:63], 0, v[128:129]
	s_mov_b32 m0, s59
	v_readfirstlane_b32 s59, v151
	ds_read_b128 v[160:163], v152
	ds_read_b128 v[164:167], v152 offset:256
	ds_read_b128 v[168:171], v153
	ds_read_b128 v[172:175], v153 offset:256
	ds_read_b128 v[176:179], v149
	ds_read_b128 v[180:183], v149 offset:1024
	ds_read_b128 v[184:187], v149 offset:2048
	ds_read_b128 v[188:191], v149 offset:3072
	ds_read_b128 v[192:195], v149 offset:4096
	ds_read_b128 v[196:199], v149 offset:5120
	ds_read_b128 v[200:203], v149 offset:6144
	ds_read_b128 v[204:207], v149 offset:7168
	global_load_lds_dwordx4 v[208:209], off
	v_lshl_add_u64 v[208:209], v[208:209], 0, s[8:9]
	s_mov_b32 m0, s59
	s_nop 0
	global_load_lds_dwordx4 v[208:209], off
	s_barrier
	s_waitcnt lgkmcnt(0)
	s_setprio 1
	v_mfma_f32_16x16x32_bf16 v[124:127], v[160:163], v[176:179], v[124:127]
	v_mfma_f32_16x16x32_bf16 v[116:119], v[160:163], v[184:187], v[116:119]
	v_mfma_f32_16x16x32_bf16 v[108:111], v[160:163], v[192:195], v[108:111]
	v_mfma_f32_16x16x32_bf16 v[100:103], v[160:163], v[200:203], v[100:103]
	v_mfma_f32_16x16x32_bf16 v[96:99], v[164:167], v[200:203], v[96:99]
	v_mfma_f32_16x16x32_bf16 v[124:127], v[168:171], v[180:183], v[124:127]
	v_mfma_f32_16x16x32_bf16 v[120:123], v[164:167], v[176:179], v[120:123]
	v_mfma_f32_16x16x32_bf16 v[116:119], v[168:171], v[188:191], v[116:119]
	v_mfma_f32_16x16x32_bf16 v[112:115], v[164:167], v[184:187], v[112:115]
	v_mfma_f32_16x16x32_bf16 v[108:111], v[168:171], v[196:199], v[108:111]
	v_mfma_f32_16x16x32_bf16 v[104:107], v[164:167], v[192:195], v[104:107]
	v_mfma_f32_16x16x32_bf16 v[100:103], v[168:171], v[204:207], v[100:103]
	v_mfma_f32_16x16x32_bf16 v[96:99], v[172:175], v[204:207], v[96:99]
	v_mfma_f32_16x16x32_bf16 v[208:211], v[172:175], v[180:183], v[120:123]
	v_mfma_f32_16x16x32_bf16 v[212:215], v[172:175], v[188:191], v[112:115]
	v_mfma_f32_16x16x32_bf16 v[216:219], v[172:175], v[196:199], v[104:107]
	s_setprio 0
	s_barrier
; #define LDA(dst, b, h) for (int m = 0; m < 4; ++m) { \
;     dst[m][0] = *reinterpret_cast<const bf16x8*>((char*)SA(b, h) + aoff0 + m * 2048); \
;     dst[m][1] = *reinterpret_cast<const bf16x8*>((char*)SA(b, h) + aoff1 + m * 2048); }
; #define LDB(dst, b, h) for (int n = 0; n < 2; ++n) { \
;     dst[n][0] = *reinterpret_cast<const bf16x8*>((char*)SB(b, h) + boff0 + n * 256); \
;     dst[n][1] = *reinterpret_cast<const bf16x8*>((char*)SB(b, h) + boff1 + n * 256); }
; #define MMA(ai, bj, At, Btf) do { __builtin_amdgcn_s_setprio(1); \
;     for (int m = 0; m < 4; ++m) for (int n = 0; n < 2; ++n) for (int k = 0; k < 2; ++k) \
;       acc[ai][bj][m][n] = __builtin_amdgcn_mfma_f32_16x16x32_bf16(Btf[n][k], At[m][k], acc[ai][bj][m][n], 0, 0, 0); \
;     __builtin_amdgcn_s_setprio(0); } while (0)
; #define WAIT_V(n) asm volatile("s_waitcnt vmcnt(" #n ")" ::: "memory")
; #define WAIT_L(n) asm volatile("s_waitcnt lgkmcnt(" #n ")" ::: "memory")
; #define BAR __builtin_amdgcn_s_barrier()
; template <int EPI> ...
;     ...
;     LDB(B1, 0, 1); BAR; WAIT_L(0); MMA(0, 1, At, B1); BAR;
;     LDA(At, 0, 1); WAIT_V(4); BAR; WAIT_L(0); MMA(1, 0, At, B0); MMA(1, 1, At, B1); BAR; }
;   { LDB(B0, 1, 0); LDA(At, 1, 0); WAIT_V(2); BAR; WAIT_L(0); MMA(0, 0, At, B0); BAR;
	s_nop 0
	ds_read_b128 v[104:107], v154
	ds_read_b128 v[112:115], v154 offset:256
	ds_read_b128 v[120:123], v155
	ds_read_b128 v[220:223], v155 offset:256
	s_barrier
	s_waitcnt lgkmcnt(0)
	s_setprio 1
	v_mfma_f32_16x16x32_bf16 v[84:87], v[104:107], v[184:187], v[84:87]
	v_mfma_f32_16x16x32_bf16 v[76:79], v[104:107], v[192:195], v[76:79]
	v_mfma_f32_16x16x32_bf16 v[72:75], v[112:115], v[192:195], v[72:75]
	v_mfma_f32_16x16x32_bf16 v[92:95], v[104:107], v[176:179], v[92:95]
	v_mfma_f32_16x16x32_bf16 v[88:91], v[112:115], v[176:179], v[88:91]
	v_mfma_f32_16x16x32_bf16 v[84:87], v[120:123], v[188:191], v[84:87]
	v_mfma_f32_16x16x32_bf16 v[80:83], v[112:115], v[184:187], v[80:83]
	v_mfma_f32_16x16x32_bf16 v[76:79], v[120:123], v[196:199], v[76:79]
	v_mfma_f32_16x16x32_bf16 v[72:75], v[220:223], v[196:199], v[72:75]
	v_mfma_f32_16x16x32_bf16 v[68:71], v[104:107], v[200:203], v[68:71]
	v_mfma_f32_16x16x32_bf16 v[64:67], v[112:115], v[200:203], v[64:67]
	v_mfma_f32_16x16x32_bf16 v[224:227], v[120:123], v[180:183], v[92:95]
	v_mfma_f32_16x16x32_bf16 v[176:179], v[220:223], v[180:183], v[88:91]
	v_mfma_f32_16x16x32_bf16 v[180:183], v[220:223], v[188:191], v[80:83]
	v_mfma_f32_16x16x32_bf16 v[184:187], v[120:123], v[204:207], v[68:71]
	v_mfma_f32_16x16x32_bf16 v[188:191], v[220:223], v[204:207], v[64:67]
	s_setprio 0
	s_barrier
	s_nop 0
	ds_read_b128 v[64:67], v149 offset:16384
	ds_read_b128 v[68:71], v149 offset:17408
	ds_read_b128 v[80:83], v149 offset:18432
	ds_read_b128 v[88:91], v149 offset:19456
	ds_read_b128 v[92:95], v149 offset:20480
	ds_read_b128 v[192:195], v149 offset:21504
	ds_read_b128 v[196:199], v149 offset:22528
	ds_read_b128 v[200:203], v149 offset:23552
	s_waitcnt vmcnt(4)
	s_barrier
	s_waitcnt lgkmcnt(0)
	s_setprio 1
	v_mfma_f32_16x16x32_bf16 v[52:55], v[160:163], v[80:83], v[52:55]
	v_mfma_f32_16x16x32_bf16 v[44:47], v[160:163], v[92:95], v[44:47]
	v_mfma_f32_16x16x32_bf16 v[36:39], v[160:163], v[196:199], v[36:39]
	v_mfma_f32_16x16x32_bf16 v[60:63], v[160:163], v[64:67], v[60:63]
	v_mfma_f32_16x16x32_bf16 v[56:59], v[164:167], v[64:67], v[56:59]
	v_mfma_f32_16x16x32_bf16 v[52:55], v[168:171], v[88:91], v[52:55]
	v_mfma_f32_16x16x32_bf16 v[48:51], v[164:167], v[80:83], v[48:51]
	v_mfma_f32_16x16x32_bf16 v[44:47], v[168:171], v[192:195], v[44:47]
	v_mfma_f32_16x16x32_bf16 v[40:43], v[164:167], v[92:95], v[40:43]
	v_mfma_f32_16x16x32_bf16 v[36:39], v[168:171], v[200:203], v[36:39]
	v_mfma_f32_16x16x32_bf16 v[32:35], v[164:167], v[196:199], v[32:35]
	v_mfma_f32_16x16x32_bf16 v[204:207], v[168:171], v[68:71], v[60:63]
	v_mfma_f32_16x16x32_bf16 v[228:231], v[172:175], v[68:71], v[56:59]
	v_mfma_f32_16x16x32_bf16 v[232:235], v[172:175], v[88:91], v[48:51]
	v_mfma_f32_16x16x32_bf16 v[236:239], v[172:175], v[192:195], v[40:43]
	v_mfma_f32_16x16x32_bf16 v[160:163], v[172:175], v[200:203], v[32:35]
	v_mfma_f32_16x16x32_bf16 v[28:31], v[104:107], v[64:67], v[28:31]
	v_mfma_f32_16x16x32_bf16 v[20:23], v[104:107], v[80:83], v[20:23]
	v_mfma_f32_16x16x32_bf16 v[12:15], v[104:107], v[92:95], v[12:15]
	v_mfma_f32_16x16x32_bf16 v[4:7], v[104:107], v[196:199], v[4:7]
	v_mfma_f32_16x16x32_bf16 v[28:31], v[120:123], v[68:71], v[28:31]
	v_mfma_f32_16x16x32_bf16 v[24:27], v[112:115], v[64:67], v[24:27]
	v_mfma_f32_16x16x32_bf16 v[20:23], v[120:123], v[88:91], v[20:23]
	v_mfma_f32_16x16x32_bf16 v[16:19], v[112:115], v[80:83], v[16:19]
	v_mfma_f32_16x16x32_bf16 v[12:15], v[120:123], v[192:195], v[12:15]
	v_mfma_f32_16x16x32_bf16 v[8:11], v[112:115], v[92:95], v[8:11]
	v_mfma_f32_16x16x32_bf16 v[4:7], v[120:123], v[200:203], v[4:7]
	v_mfma_f32_16x16x32_bf16 v[0:3], v[112:115], v[196:199], v[0:3]
	v_mfma_f32_16x16x32_bf16 v[164:167], v[220:223], v[68:71], v[24:27]
	v_mfma_f32_16x16x32_bf16 v[168:171], v[220:223], v[88:91], v[16:19]
	v_mfma_f32_16x16x32_bf16 v[172:175], v[220:223], v[192:195], v[8:11]
	v_mfma_f32_16x16x32_bf16 v[192:195], v[220:223], v[200:203], v[0:3]
	s_setprio 0
	s_barrier
	s_nop 1
	ds_read_b128 v[0:3], v156
	ds_read_b128 v[8:11], v156 offset:256
	ds_read_b128 v[16:19], v157
	ds_read_b128 v[24:27], v157 offset:256
	ds_read_b128 v[32:35], v149 offset:32768
	ds_read_b128 v[40:43], v149 offset:33792
	ds_read_b128 v[48:51], v149 offset:34816
	ds_read_b128 v[56:59], v149 offset:35840
	ds_read_b128 v[60:63], v149 offset:36864
	ds_read_b128 v[68:71], v149 offset:37888
	ds_read_b128 v[196:199], v149 offset:38912
	ds_read_b128 v[200:203], v149 offset:39936
	s_waitcnt vmcnt(2)
	s_barrier
; #define LDA(dst, b, h) for (int m = 0; m < 4; ++m) { \
;     dst[m][0] = *reinterpret_cast<const bf16x8*>((char*)SA(b, h) + aoff0 + m * 2048); \
;     dst[m][1] = *reinterpret_cast<const bf16x8*>((char*)SA(b, h) + aoff1 + m * 2048); }
; #define LDB(dst, b, h) for (int n = 0; n < 2; ++n) { \
;     dst[n][0] = *reinterpret_cast<const bf16x8*>((char*)SB(b, h) + boff0 + n * 256); \
;     dst[n][1] = *reinterpret_cast<const bf16x8*>((char*)SB(b, h) + boff1 + n * 256); }
; #define MMA(ai, bj, At, Btf) do { __builtin_amdgcn_s_setprio(1); \
;     for (int m = 0; m < 4; ++m) for (int n = 0; n < 2; ++n) for (int k = 0; k < 2; ++k) \
;       acc[ai][bj][m][n] = __builtin_amdgcn_mfma_f32_16x16x32_bf16(Btf[n][k], At[m][k], acc[ai][bj][m][n], 0, 0, 0); \
;     __builtin_amdgcn_s_setprio(0); } while (0)
; #define WAIT_V(n) asm volatile("s_waitcnt vmcnt(" #n ")" ::: "memory")
; #define WAIT_L(n) asm volatile("s_waitcnt lgkmcnt(" #n ")" ::: "memory")
; #define BAR __builtin_amdgcn_s_barrier()
; template <int EPI> ...
;     ...
;   { LDB(B0, 1, 0); LDA(At, 1, 0); WAIT_V(2); BAR; WAIT_L(0); MMA(0, 0, At, B0); BAR;
;     LDB(B1, 1, 1); WAIT_V(0); BAR; WAIT_L(0); MMA(0, 1, At, B1); BAR;
;     LDA(At, 1, 1); BAR; WAIT_L(0); MMA(1, 0, At, B0); MMA(1, 1, At, B1); BAR; }
;   if (wr == 0) BAR;
	s_waitcnt lgkmcnt(0)
	s_setprio 1
	v_mfma_f32_16x16x32_bf16 v[64:67], v[0:3], v[32:35], v[124:127]
	v_mfma_f32_16x16x32_bf16 v[120:123], v[16:19], v[40:43], v[64:67]
	v_mfma_f32_16x16x32_bf16 v[64:67], v[8:11], v[32:35], v[208:211]
	v_mfma_f32_16x16x32_bf16 v[124:127], v[24:27], v[40:43], v[64:67]
	v_mfma_f32_16x16x32_bf16 v[64:67], v[0:3], v[48:51], v[116:119]
	v_mfma_f32_16x16x32_bf16 v[112:115], v[16:19], v[56:59], v[64:67]
	v_mfma_f32_16x16x32_bf16 v[64:67], v[8:11], v[48:51], v[212:215]
	v_mfma_f32_16x16x32_bf16 v[116:119], v[24:27], v[56:59], v[64:67]
	v_mfma_f32_16x16x32_bf16 v[64:67], v[0:3], v[60:63], v[108:111]
	v_mfma_f32_16x16x32_bf16 v[104:107], v[16:19], v[68:71], v[64:67]
	v_mfma_f32_16x16x32_bf16 v[64:67], v[8:11], v[60:63], v[216:219]
	v_mfma_f32_16x16x32_bf16 v[108:111], v[24:27], v[68:71], v[64:67]
	v_mfma_f32_16x16x32_bf16 v[64:67], v[0:3], v[196:199], v[100:103]
	v_mfma_f32_16x16x32_bf16 v[88:91], v[16:19], v[200:203], v[64:67]
	v_mfma_f32_16x16x32_bf16 v[64:67], v[8:11], v[196:199], v[96:99]
	v_mfma_f32_16x16x32_bf16 v[92:95], v[24:27], v[200:203], v[64:67]
	s_setprio 0
	s_barrier
	ds_read_b128 v[208:211], v158
	ds_read_b128 v[212:215], v158 offset:256
	ds_read_b128 v[216:219], v159
	ds_read_b128 v[220:223], v159 offset:256
	s_waitcnt vmcnt(0)
	s_barrier
	s_waitcnt lgkmcnt(0)
	s_setprio 1
	v_mfma_f32_16x16x32_bf16 v[64:67], v[208:211], v[32:35], v[224:227]
	v_mfma_f32_16x16x32_bf16 v[32:35], v[212:215], v[32:35], v[176:179]
	v_mfma_f32_16x16x32_bf16 v[100:103], v[220:223], v[40:43], v[32:35]
	v_mfma_f32_16x16x32_bf16 v[32:35], v[208:211], v[48:51], v[84:87]
	v_mfma_f32_16x16x32_bf16 v[80:83], v[216:219], v[56:59], v[32:35]
	v_mfma_f32_16x16x32_bf16 v[32:35], v[212:215], v[48:51], v[180:183]
	v_mfma_f32_16x16x32_bf16 v[84:87], v[220:223], v[56:59], v[32:35]
	v_mfma_f32_16x16x32_bf16 v[32:35], v[208:211], v[60:63], v[76:79]
	v_mfma_f32_16x16x32_bf16 v[96:99], v[216:219], v[40:43], v[64:67]
	v_mfma_f32_16x16x32_bf16 v[64:67], v[216:219], v[68:71], v[32:35]
	v_mfma_f32_16x16x32_bf16 v[32:35], v[212:215], v[60:63], v[72:75]
	v_mfma_f32_16x16x32_bf16 v[68:71], v[220:223], v[68:71], v[32:35]
	v_mfma_f32_16x16x32_bf16 v[32:35], v[208:211], v[196:199], v[184:187]
	v_mfma_f32_16x16x32_bf16 v[56:59], v[216:219], v[200:203], v[32:35]
	v_mfma_f32_16x16x32_bf16 v[32:35], v[212:215], v[196:199], v[188:191]
	v_mfma_f32_16x16x32_bf16 v[60:63], v[220:223], v[200:203], v[32:35]
	s_setprio 0
	s_barrier
	ds_read_b128 v[176:179], v149 offset:49152
	ds_read_b128 v[180:183], v149 offset:50176
	ds_read_b128 v[184:187], v149 offset:51200
	ds_read_b128 v[188:191], v149 offset:52224
	ds_read_b128 v[196:199], v149 offset:53248
	ds_read_b128 v[200:203], v149 offset:54272
	ds_read_b128 v[224:227], v149 offset:55296
	ds_read_b128 v[240:243], v149 offset:56320
	s_barrier
	s_waitcnt lgkmcnt(0)
	s_setprio 1
	v_mfma_f32_16x16x32_bf16 v[32:35], v[0:3], v[176:179], v[204:207]
	v_mfma_f32_16x16x32_bf16 v[72:75], v[16:19], v[180:183], v[32:35]
	v_mfma_f32_16x16x32_bf16 v[32:35], v[8:11], v[176:179], v[228:231]
	v_mfma_f32_16x16x32_bf16 v[76:79], v[24:27], v[180:183], v[32:35]
	v_mfma_f32_16x16x32_bf16 v[32:35], v[0:3], v[184:187], v[52:55]
	v_mfma_f32_16x16x32_bf16 v[48:51], v[16:19], v[188:191], v[32:35]
	v_mfma_f32_16x16x32_bf16 v[32:35], v[8:11], v[184:187], v[232:235]
	v_mfma_f32_16x16x32_bf16 v[52:55], v[24:27], v[188:191], v[32:35]
	v_mfma_f32_16x16x32_bf16 v[32:35], v[0:3], v[196:199], v[44:47]
	v_mfma_f32_16x16x32_bf16 v[40:43], v[16:19], v[200:203], v[32:35]
	v_mfma_f32_16x16x32_bf16 v[32:35], v[8:11], v[196:199], v[236:239]
	v_mfma_f32_16x16x32_bf16 v[0:3], v[0:3], v[224:227], v[36:39]
	v_mfma_f32_16x16x32_bf16 v[44:47], v[24:27], v[200:203], v[32:35]
	v_mfma_f32_16x16x32_bf16 v[32:35], v[16:19], v[240:243], v[0:3]
	v_mfma_f32_16x16x32_bf16 v[0:3], v[8:11], v[224:227], v[160:163]
	v_mfma_f32_16x16x32_bf16 v[36:39], v[24:27], v[240:243], v[0:3]
	v_mfma_f32_16x16x32_bf16 v[0:3], v[208:211], v[176:179], v[28:31]
	v_mfma_f32_16x16x32_bf16 v[24:27], v[216:219], v[180:183], v[0:3]
	v_mfma_f32_16x16x32_bf16 v[0:3], v[212:215], v[176:179], v[164:167]
	v_mfma_f32_16x16x32_bf16 v[28:31], v[220:223], v[180:183], v[0:3]
	v_mfma_f32_16x16x32_bf16 v[0:3], v[208:211], v[184:187], v[20:23]
	v_mfma_f32_16x16x32_bf16 v[16:19], v[216:219], v[188:191], v[0:3]
	v_mfma_f32_16x16x32_bf16 v[0:3], v[212:215], v[184:187], v[168:171]
	v_mfma_f32_16x16x32_bf16 v[20:23], v[220:223], v[188:191], v[0:3]
	v_mfma_f32_16x16x32_bf16 v[0:3], v[208:211], v[196:199], v[12:15]
	v_mfma_f32_16x16x32_bf16 v[8:11], v[216:219], v[200:203], v[0:3]
	v_mfma_f32_16x16x32_bf16 v[0:3], v[212:215], v[196:199], v[172:175]
	v_mfma_f32_16x16x32_bf16 v[12:15], v[220:223], v[200:203], v[0:3]
	v_mfma_f32_16x16x32_bf16 v[0:3], v[208:211], v[224:227], v[4:7]
	v_mfma_f32_16x16x32_bf16 v[4:7], v[212:215], v[224:227], v[192:195]
	v_mfma_f32_16x16x32_bf16 v[0:3], v[216:219], v[240:243], v[0:3]
	v_mfma_f32_16x16x32_bf16 v[4:7], v[220:223], v[240:243], v[4:7]
	s_setprio 0
	s_barrier
	s_and_saveexec_b64 s[62:63], s[2:3]
	s_cbranch_execz .LBB0_1012
	s_barrier
	s_branch .LBB0_1012

; #define STAGE(P, BASE, br, kt) do { const char* _gb = (const char*)(BASE) + ((size_t)(br) * K + (size_t)(kt) * BK) * 2; \
;     __builtin_amdgcn_global_load_lds((const unsigned*)(_gb + loff0), (unsigned*)((char*)(P) + tid * 16), 16, 0, 0); \
;     __builtin_amdgcn_global_load_lds((const unsigned*)(_gb + (size_t)K * 128 + loff0), (unsigned*)((char*)(P) + tid * 16 + 8192), 16, 0, 0); } while (0)
; #define LDA(dst, b, h) for (int m = 0; m < 4; ++m) { \
;     dst[m][0] = *reinterpret_cast<const bf16x8*>((char*)SA(b, h) + aoff0 + m * 2048); \
;     dst[m][1] = *reinterpret_cast<const bf16x8*>((char*)SA(b, h) + aoff1 + m * 2048); }
; #define LDB(dst, b, h) for (int n = 0; n < 2; ++n) { \
;     dst[n][0] = *reinterpret_cast<const bf16x8*>((char*)SB(b, h) + boff0 + n * 256); \
;     dst[n][1] = *reinterpret_cast<const bf16x8*>((char*)SB(b, h) + boff1 + n * 256); }
; #define MMA(ai, bj, At, Btf) do { __builtin_amdgcn_s_setprio(1); \
;     for (int m = 0; m < 4; ++m) for (int n = 0; n < 2; ++n) for (int k = 0; k < 2; ++k) \
;       acc[ai][bj][m][n] = __builtin_amdgcn_mfma_f32_16x16x32_bf16(Btf[n][k], At[m][k], acc[ai][bj][m][n], 0, 0, 0); \
;     __builtin_amdgcn_s_setprio(0); } while (0)
; #define WAIT_L(n) asm volatile("s_waitcnt lgkmcnt(" #n ")" ::: "memory")
; #define BAR __builtin_amdgcn_s_barrier()
; #define SCHED __builtin_amdgcn_sched_barrier(0)
; template <int EPI> ...
;     ...
;     LDB(B0, 0, 0); SCHED; LDA(At, 0, 0); STAGE(SA(1, 1), A, brow + HALF, t + 1);
;     WAIT_L(8); BAR; WAIT_L(0); MMA(0, 0, At, B0); BAR; SCHED;
;     LDB(B1, 0, 1); STAGE(SB(0, 0), Bt, bcol, t + 2);
;     BAR; WAIT_L(0); MMA(0, 1, At, B1); BAR;
;     LDA(At, 0, 1); STAGE(SA(0, 0), A, brow, t + 2);
;     BAR; WAIT_L(0); MMA(1, 0, At, B0); BAR; SCHED;
.LBB0_1105:
	ds_read_b128 v[162:165], v153
	ds_read_b128 v[166:169], v153 offset:256
	ds_read_b128 v[170:173], v154
	ds_read_b128 v[174:177], v154 offset:256
	v_lshl_add_u64 v[226:227], s[66:67], 0, v[130:131]
	v_readfirstlane_b32 s70, v151
	v_lshl_add_u64 v[210:211], v[226:227], 0, s[18:19]
	s_mov_b32 m0, s70
	v_readfirstlane_b32 s70, v152
	ds_read_b128 v[178:181], v150
	ds_read_b128 v[182:185], v150 offset:1024
	ds_read_b128 v[186:189], v150 offset:2048
	ds_read_b128 v[190:193], v150 offset:3072
	ds_read_b128 v[194:197], v150 offset:4096
	ds_read_b128 v[198:201], v150 offset:5120
	ds_read_b128 v[202:205], v150 offset:6144
	ds_read_b128 v[206:209], v150 offset:7168
	global_load_lds_dwordx4 v[210:211], off
	v_lshl_add_u64 v[210:211], v[226:227], 0, s[20:21]
	s_mov_b32 m0, s70
	s_nop 0
	global_load_lds_dwordx4 v[210:211], off
	s_waitcnt lgkmcnt(8)
	v_readfirstlane_b32 s70, v149
	v_lshl_add_u64 v[246:247], v[228:229], 0, s[58:59]
	s_mov_b32 m0, s70
	s_nop 0
	global_load_lds_dwordx4 v[246:247], off
	ds_read_b128 v[210:213], v155
	ds_read_b128 v[214:217], v155 offset:256
	ds_read_b128 v[218:221], v156
	ds_read_b128 v[222:225], v156 offset:256
	s_barrier
	s_waitcnt lgkmcnt(0)
	s_setprio 1
	v_mfma_f32_16x16x32_bf16 v[124:127], v[162:165], v[178:181], v[124:127]
	v_mfma_f32_16x16x32_bf16 v[120:123], v[166:169], v[178:181], v[120:123]
	v_mfma_f32_16x16x32_bf16 v[116:119], v[162:165], v[186:189], v[116:119]
	v_mfma_f32_16x16x32_bf16 v[112:115], v[166:169], v[186:189], v[112:115]
	v_mfma_f32_16x16x32_bf16 v[108:111], v[162:165], v[194:197], v[108:111]
	v_mfma_f32_16x16x32_bf16 v[104:107], v[166:169], v[194:197], v[104:107]
	v_mfma_f32_16x16x32_bf16 v[100:103], v[162:165], v[202:205], v[100:103]
	v_mfma_f32_16x16x32_bf16 v[96:99], v[166:169], v[202:205], v[96:99]
	v_mfma_f32_16x16x32_bf16 v[124:127], v[170:173], v[182:185], v[124:127]
	v_mfma_f32_16x16x32_bf16 v[120:123], v[174:177], v[182:185], v[120:123]
	v_mfma_f32_16x16x32_bf16 v[116:119], v[170:173], v[190:193], v[116:119]
	v_mfma_f32_16x16x32_bf16 v[112:115], v[174:177], v[190:193], v[112:115]
	v_mfma_f32_16x16x32_bf16 v[108:111], v[170:173], v[198:201], v[108:111]
	v_mfma_f32_16x16x32_bf16 v[104:107], v[174:177], v[198:201], v[104:107]
	v_mfma_f32_16x16x32_bf16 v[100:103], v[170:173], v[206:209], v[100:103]
	v_mfma_f32_16x16x32_bf16 v[96:99], v[174:177], v[206:209], v[96:99]
	v_mfma_f32_16x16x32_bf16 v[92:95], v[210:213], v[178:181], v[92:95]
	v_mfma_f32_16x16x32_bf16 v[88:91], v[214:217], v[178:181], v[88:91]
	v_mfma_f32_16x16x32_bf16 v[84:87], v[210:213], v[186:189], v[84:87]
	v_mfma_f32_16x16x32_bf16 v[80:83], v[214:217], v[186:189], v[80:83]
	v_mfma_f32_16x16x32_bf16 v[76:79], v[210:213], v[194:197], v[76:79]
	v_mfma_f32_16x16x32_bf16 v[72:75], v[214:217], v[194:197], v[72:75]
	v_mfma_f32_16x16x32_bf16 v[68:71], v[210:213], v[202:205], v[68:71]
	v_mfma_f32_16x16x32_bf16 v[64:67], v[214:217], v[202:205], v[64:67]
	v_mfma_f32_16x16x32_bf16 v[92:95], v[218:221], v[182:185], v[92:95]
	v_mfma_f32_16x16x32_bf16 v[88:91], v[222:225], v[182:185], v[88:91]
	v_mfma_f32_16x16x32_bf16 v[84:87], v[218:221], v[190:193], v[84:87]
	v_mfma_f32_16x16x32_bf16 v[80:83], v[222:225], v[190:193], v[80:83]
	v_mfma_f32_16x16x32_bf16 v[76:79], v[218:221], v[198:201], v[76:79]
	v_mfma_f32_16x16x32_bf16 v[72:75], v[222:225], v[198:201], v[72:75]
	v_mfma_f32_16x16x32_bf16 v[68:71], v[218:221], v[206:209], v[68:71]
	v_mfma_f32_16x16x32_bf16 v[64:67], v[222:225], v[206:209], v[64:67]
	s_setprio 0
	s_barrier
	v_lshl_add_u64 v[228:229], s[68:69], 0, v[130:131]
	v_readfirstlane_b32 s70, v136
	v_lshl_add_u64 v[230:231], v[228:229], 0, s[22:23]
	s_mov_b32 m0, s70
	v_readfirstlane_b32 s70, v137
	global_load_lds_dwordx4 v[230:231], off
	v_lshl_add_u64 v[230:231], v[228:229], 0, s[24:25]
	s_mov_b32 m0, s70
	s_nop 0
	global_load_lds_dwordx4 v[230:231], off
	v_readfirstlane_b32 s70, v138
	v_lshl_add_u64 v[230:231], v[226:227], 0, s[26:27]
	s_mov_b32 m0, s70
	v_readfirstlane_b32 s70, v139
	ds_read_b128 v[178:181], v150 offset:16384
	ds_read_b128 v[182:185], v150 offset:17408
	ds_read_b128 v[186:189], v150 offset:18432
	ds_read_b128 v[190:193], v150 offset:19456
	ds_read_b128 v[194:197], v150 offset:20480
	ds_read_b128 v[198:201], v150 offset:21504
	ds_read_b128 v[202:205], v150 offset:22528
	ds_read_b128 v[206:209], v150 offset:23552
	global_load_lds_dwordx4 v[230:231], off
	v_lshl_add_u64 v[230:231], v[226:227], 0, s[28:29]
	s_mov_b32 m0, s70
	s_nop 0
	global_load_lds_dwordx4 v[230:231], off
	v_readfirstlane_b32 s70, v140
	v_lshl_add_u64 v[246:247], v[228:229], 0, s[30:31]
	s_mov_b32 m0, s70
	v_readfirstlane_b32 s70, v141
	global_load_lds_dwordx4 v[246:247], off
	s_waitcnt vmcnt(5)
	s_barrier
; #define STAGE(P, BASE, br, kt) do { const char* _gb = (const char*)(BASE) + ((size_t)(br) * K + (size_t)(kt) * BK) * 2; \
;     __builtin_amdgcn_global_load_lds((const unsigned*)(_gb + loff0), (unsigned*)((char*)(P) + tid * 16), 16, 0, 0); \
;     __builtin_amdgcn_global_load_lds((const unsigned*)(_gb + (size_t)K * 128 + loff0), (unsigned*)((char*)(P) + tid * 16 + 8192), 16, 0, 0); } while (0)
; #define LDA(dst, b, h) for (int m = 0; m < 4; ++m) { \
;     dst[m][0] = *reinterpret_cast<const bf16x8*>((char*)SA(b, h) + aoff0 + m * 2048); \
;     dst[m][1] = *reinterpret_cast<const bf16x8*>((char*)SA(b, h) + aoff1 + m * 2048); }
; #define LDB(dst, b, h) for (int n = 0; n < 2; ++n) { \
;     dst[n][0] = *reinterpret_cast<const bf16x8*>((char*)SB(b, h) + boff0 + n * 256); \
;     dst[n][1] = *reinterpret_cast<const bf16x8*>((char*)SB(b, h) + boff1 + n * 256); }
; #define MMA(ai, bj, At, Btf) do { __builtin_amdgcn_s_setprio(1); \
;     for (int m = 0; m < 4; ++m) for (int n = 0; n < 2; ++n) for (int k = 0; k < 2; ++k) \
;       acc[ai][bj][m][n] = __builtin_amdgcn_mfma_f32_16x16x32_bf16(Btf[n][k], At[m][k], acc[ai][bj][m][n], 0, 0, 0); \
;     __builtin_amdgcn_s_setprio(0); } while (0)
; #define WAIT_V(n) asm volatile("s_waitcnt vmcnt(" #n ")" ::: "memory")
; #define WAIT_L(n) asm volatile("s_waitcnt lgkmcnt(" #n ")" ::: "memory")
; #define BAR __builtin_amdgcn_s_barrier()
; #define SCHED __builtin_amdgcn_sched_barrier(0)
; template <int EPI> ...
;     ...
;     LDA(At, 0, 1); STAGE(SA(0, 0), A, brow, t + 2);
;     BAR; WAIT_L(0); MMA(1, 0, At, B0); BAR; SCHED;
;     STAGE(SB(0, 1), Bt, bcol + HALF, t + 2);
;     WAIT_V(6); BAR; MMA(1, 1, At, B1); BAR;
;     LDB(B0, 1, 0); SCHED; LDA(At, 1, 0); STAGE(SA(0, 1), A, brow + HALF, t + 2);
;     WAIT_L(8); BAR; WAIT_L(0); MMA(0, 0, At, B0); BAR; SCHED;
;     LDB(B1, 1, 1); STAGE(SB(1, 0), Bt, bcol, t + 3);
;     BAR; WAIT_L(0); MMA(0, 1, At, B1); BAR;
	s_waitcnt lgkmcnt(0)
	s_setprio 1
	v_mfma_f32_16x16x32_bf16 v[60:63], v[162:165], v[178:181], v[60:63]
	v_mfma_f32_16x16x32_bf16 v[56:59], v[166:169], v[178:181], v[56:59]
	v_mfma_f32_16x16x32_bf16 v[52:55], v[162:165], v[186:189], v[52:55]
	v_mfma_f32_16x16x32_bf16 v[48:51], v[166:169], v[186:189], v[48:51]
	v_mfma_f32_16x16x32_bf16 v[44:47], v[162:165], v[194:197], v[44:47]
	v_mfma_f32_16x16x32_bf16 v[40:43], v[166:169], v[194:197], v[40:43]
	v_mfma_f32_16x16x32_bf16 v[36:39], v[162:165], v[202:205], v[36:39]
	v_mfma_f32_16x16x32_bf16 v[32:35], v[166:169], v[202:205], v[32:35]
	v_mfma_f32_16x16x32_bf16 v[60:63], v[170:173], v[182:185], v[60:63]
	v_mfma_f32_16x16x32_bf16 v[56:59], v[174:177], v[182:185], v[56:59]
	v_mfma_f32_16x16x32_bf16 v[52:55], v[170:173], v[190:193], v[52:55]
	v_mfma_f32_16x16x32_bf16 v[48:51], v[174:177], v[190:193], v[48:51]
	v_mfma_f32_16x16x32_bf16 v[44:47], v[170:173], v[198:201], v[44:47]
	v_mfma_f32_16x16x32_bf16 v[40:43], v[174:177], v[198:201], v[40:43]
	v_mfma_f32_16x16x32_bf16 v[36:39], v[170:173], v[206:209], v[36:39]
	v_mfma_f32_16x16x32_bf16 v[32:35], v[174:177], v[206:209], v[32:35]
	v_mfma_f32_16x16x32_bf16 v[28:31], v[210:213], v[178:181], v[28:31]
	v_mfma_f32_16x16x32_bf16 v[24:27], v[214:217], v[178:181], v[24:27]
	v_mfma_f32_16x16x32_bf16 v[20:23], v[210:213], v[186:189], v[20:23]
	v_mfma_f32_16x16x32_bf16 v[16:19], v[214:217], v[186:189], v[16:19]
	v_mfma_f32_16x16x32_bf16 v[12:15], v[210:213], v[194:197], v[12:15]
	v_mfma_f32_16x16x32_bf16 v[8:11], v[214:217], v[194:197], v[8:11]
	v_mfma_f32_16x16x32_bf16 v[4:7], v[210:213], v[202:205], v[4:7]
	v_mfma_f32_16x16x32_bf16 v[0:3], v[214:217], v[202:205], v[0:3]
	v_mfma_f32_16x16x32_bf16 v[28:31], v[218:221], v[182:185], v[28:31]
	v_mfma_f32_16x16x32_bf16 v[24:27], v[222:225], v[182:185], v[24:27]
	v_mfma_f32_16x16x32_bf16 v[20:23], v[218:221], v[190:193], v[20:23]
	v_mfma_f32_16x16x32_bf16 v[16:19], v[222:225], v[190:193], v[16:19]
	v_mfma_f32_16x16x32_bf16 v[12:15], v[218:221], v[198:201], v[12:15]
	v_mfma_f32_16x16x32_bf16 v[8:11], v[222:225], v[198:201], v[8:11]
	v_mfma_f32_16x16x32_bf16 v[4:7], v[218:221], v[206:209], v[4:7]
	v_mfma_f32_16x16x32_bf16 v[0:3], v[222:225], v[206:209], v[0:3]
	s_setprio 0
	s_barrier
	ds_read_b128 v[162:165], v157
	ds_read_b128 v[166:169], v157 offset:256
	ds_read_b128 v[170:173], v158
	ds_read_b128 v[174:177], v158 offset:256
	v_readfirstlane_b32 s70, v142
	v_lshl_add_u64 v[210:211], v[226:227], 0, s[38:39]
	s_mov_b32 m0, s70
	v_readfirstlane_b32 s70, v143
	ds_read_b128 v[178:181], v150 offset:32768
	ds_read_b128 v[182:185], v150 offset:33792
	ds_read_b128 v[186:189], v150 offset:34816
	ds_read_b128 v[190:193], v150 offset:35840
	ds_read_b128 v[194:197], v150 offset:36864
	ds_read_b128 v[198:201], v150 offset:37888
	ds_read_b128 v[202:205], v150 offset:38912
	ds_read_b128 v[206:209], v150 offset:39936
	global_load_lds_dwordx4 v[210:211], off
	v_lshl_add_u64 v[210:211], v[226:227], 0, s[46:47]
	s_mov_b32 m0, s70
	s_nop 0
	global_load_lds_dwordx4 v[210:211], off
	s_waitcnt lgkmcnt(8)
	v_readfirstlane_b32 s70, v141
	v_lshl_add_u64 v[246:247], v[228:229], 0, s[36:37]
	s_mov_b32 m0, s70
	s_nop 0
	global_load_lds_dwordx4 v[246:247], off
	ds_read_b128 v[210:213], v159
	ds_read_b128 v[214:217], v159 offset:256
	ds_read_b128 v[218:221], v160
	ds_read_b128 v[222:225], v160 offset:256
	s_barrier
	s_waitcnt lgkmcnt(0)
	s_setprio 1
	v_mfma_f32_16x16x32_bf16 v[124:127], v[162:165], v[178:181], v[124:127]
	v_mfma_f32_16x16x32_bf16 v[120:123], v[166:169], v[178:181], v[120:123]
	v_mfma_f32_16x16x32_bf16 v[116:119], v[162:165], v[186:189], v[116:119]
	v_mfma_f32_16x16x32_bf16 v[112:115], v[166:169], v[186:189], v[112:115]
	v_mfma_f32_16x16x32_bf16 v[108:111], v[162:165], v[194:197], v[108:111]
	v_mfma_f32_16x16x32_bf16 v[104:107], v[166:169], v[194:197], v[104:107]
	v_mfma_f32_16x16x32_bf16 v[100:103], v[162:165], v[202:205], v[100:103]
	v_mfma_f32_16x16x32_bf16 v[96:99], v[166:169], v[202:205], v[96:99]
	v_mfma_f32_16x16x32_bf16 v[124:127], v[170:173], v[182:185], v[124:127]
	v_mfma_f32_16x16x32_bf16 v[120:123], v[174:177], v[182:185], v[120:123]
	v_mfma_f32_16x16x32_bf16 v[116:119], v[170:173], v[190:193], v[116:119]
	v_mfma_f32_16x16x32_bf16 v[112:115], v[174:177], v[190:193], v[112:115]
	v_mfma_f32_16x16x32_bf16 v[108:111], v[170:173], v[198:201], v[108:111]
	v_mfma_f32_16x16x32_bf16 v[104:107], v[174:177], v[198:201], v[104:107]
	v_mfma_f32_16x16x32_bf16 v[100:103], v[170:173], v[206:209], v[100:103]
	v_mfma_f32_16x16x32_bf16 v[96:99], v[174:177], v[206:209], v[96:99]
	v_mfma_f32_16x16x32_bf16 v[92:95], v[210:213], v[178:181], v[92:95]
	v_mfma_f32_16x16x32_bf16 v[88:91], v[214:217], v[178:181], v[88:91]
	v_mfma_f32_16x16x32_bf16 v[84:87], v[210:213], v[186:189], v[84:87]
	v_mfma_f32_16x16x32_bf16 v[80:83], v[214:217], v[186:189], v[80:83]
	v_mfma_f32_16x16x32_bf16 v[76:79], v[210:213], v[194:197], v[76:79]
	v_mfma_f32_16x16x32_bf16 v[72:75], v[214:217], v[194:197], v[72:75]
	v_mfma_f32_16x16x32_bf16 v[68:71], v[210:213], v[202:205], v[68:71]
	v_mfma_f32_16x16x32_bf16 v[64:67], v[214:217], v[202:205], v[64:67]
	v_mfma_f32_16x16x32_bf16 v[92:95], v[218:221], v[182:185], v[92:95]
	v_mfma_f32_16x16x32_bf16 v[88:91], v[222:225], v[182:185], v[88:91]
	v_mfma_f32_16x16x32_bf16 v[84:87], v[218:221], v[190:193], v[84:87]
	v_mfma_f32_16x16x32_bf16 v[80:83], v[222:225], v[190:193], v[80:83]
	v_mfma_f32_16x16x32_bf16 v[76:79], v[218:221], v[198:201], v[76:79]
	v_mfma_f32_16x16x32_bf16 v[72:75], v[222:225], v[198:201], v[72:75]
	v_mfma_f32_16x16x32_bf16 v[68:71], v[218:221], v[206:209], v[68:71]
	v_mfma_f32_16x16x32_bf16 v[64:67], v[222:225], v[206:209], v[64:67]
	s_setprio 0
	s_barrier
; #define STAGE(P, BASE, br, kt) do { const char* _gb = (const char*)(BASE) + ((size_t)(br) * K + (size_t)(kt) * BK) * 2; \
;     __builtin_amdgcn_global_load_lds((const unsigned*)(_gb + loff0), (unsigned*)((char*)(P) + tid * 16), 16, 0, 0); \
;     __builtin_amdgcn_global_load_lds((const unsigned*)(_gb + (size_t)K * 128 + loff0), (unsigned*)((char*)(P) + tid * 16 + 8192), 16, 0, 0); } while (0)
; #define LDA(dst, b, h) for (int m = 0; m < 4; ++m) { \
;     dst[m][0] = *reinterpret_cast<const bf16x8*>((char*)SA(b, h) + aoff0 + m * 2048); \
;     dst[m][1] = *reinterpret_cast<const bf16x8*>((char*)SA(b, h) + aoff1 + m * 2048); }
; #define LDB(dst, b, h) for (int n = 0; n < 2; ++n) { \
;     dst[n][0] = *reinterpret_cast<const bf16x8*>((char*)SB(b, h) + boff0 + n * 256); \
;     dst[n][1] = *reinterpret_cast<const bf16x8*>((char*)SB(b, h) + boff1 + n * 256); }
; #define MMA(ai, bj, At, Btf) do { __builtin_amdgcn_s_setprio(1); \
;     for (int m = 0; m < 4; ++m) for (int n = 0; n < 2; ++n) for (int k = 0; k < 2; ++k) \
;       acc[ai][bj][m][n] = __builtin_amdgcn_mfma_f32_16x16x32_bf16(Btf[n][k], At[m][k], acc[ai][bj][m][n], 0, 0, 0); \
;     __builtin_amdgcn_s_setprio(0); } while (0)
; #define WAIT_V(n) asm volatile("s_waitcnt vmcnt(" #n ")" ::: "memory")
; #define WAIT_L(n) asm volatile("s_waitcnt lgkmcnt(" #n ")" ::: "memory")
; #define BAR __builtin_amdgcn_s_barrier()
; #define SCHED __builtin_amdgcn_sched_barrier(0)
; template <int EPI> ...
;     ...
;     LDA(At, 1, 1); STAGE(SA(1, 0), A, brow, t + 3);
;     BAR; WAIT_L(0); MMA(1, 0, At, B0); BAR; SCHED;
;     STAGE(SB(1, 1), Bt, bcol + HALF, t + 3);
;     WAIT_V(6); BAR; MMA(1, 1, At, B1); BAR;
;   }
;   { LDB(B0, 0, 0); LDA(At, 0, 0); STAGE(SA(1, 1), A, brow + HALF, nt - 1);
;     BAR; WAIT_L(0); MMA(0, 0, At, B0); BAR;
	v_readfirstlane_b32 s70, v144
	v_lshl_add_u64 v[230:231], v[228:229], 0, s[48:49]
	s_mov_b32 m0, s70
	v_readfirstlane_b32 s70, v145
	global_load_lds_dwordx4 v[230:231], off
	v_lshl_add_u64 v[230:231], v[228:229], 0, s[50:51]
	s_mov_b32 m0, s70
	s_nop 0
	global_load_lds_dwordx4 v[230:231], off
	v_readfirstlane_b32 s70, v146
	v_lshl_add_u64 v[230:231], v[226:227], 0, s[52:53]
	s_mov_b32 m0, s70
	v_readfirstlane_b32 s70, v147
	ds_read_b128 v[178:181], v150 offset:49152
	ds_read_b128 v[182:185], v150 offset:50176
	ds_read_b128 v[186:189], v150 offset:51200
	ds_read_b128 v[190:193], v150 offset:52224
	ds_read_b128 v[194:197], v150 offset:53248
	ds_read_b128 v[198:201], v150 offset:54272
	ds_read_b128 v[202:205], v150 offset:55296
	ds_read_b128 v[206:209], v150 offset:56320
	global_load_lds_dwordx4 v[230:231], off
	v_lshl_add_u64 v[226:227], v[226:227], 0, s[54:55]
	s_mov_b32 m0, s70
	s_nop 0
	global_load_lds_dwordx4 v[226:227], off
	v_readfirstlane_b32 s70, v148
	v_lshl_add_u64 v[246:247], v[228:229], 0, s[56:57]
	s_mov_b32 m0, s70
	v_readfirstlane_b32 s70, v149
	global_load_lds_dwordx4 v[246:247], off
	s_waitcnt vmcnt(5)
	s_barrier
	s_waitcnt lgkmcnt(0)
	s_setprio 1
	s_waitcnt lgkmcnt(0)
	v_mfma_f32_16x16x32_bf16 v[60:63], v[162:165], v[178:181], v[60:63]
	v_mfma_f32_16x16x32_bf16 v[56:59], v[166:169], v[178:181], v[56:59]
	v_mfma_f32_16x16x32_bf16 v[52:55], v[162:165], v[186:189], v[52:55]
	v_mfma_f32_16x16x32_bf16 v[48:51], v[166:169], v[186:189], v[48:51]
	v_mfma_f32_16x16x32_bf16 v[44:47], v[162:165], v[194:197], v[44:47]
	v_mfma_f32_16x16x32_bf16 v[40:43], v[166:169], v[194:197], v[40:43]
	v_mfma_f32_16x16x32_bf16 v[36:39], v[162:165], v[202:205], v[36:39]
	v_mfma_f32_16x16x32_bf16 v[32:35], v[166:169], v[202:205], v[32:35]
	v_mfma_f32_16x16x32_bf16 v[60:63], v[170:173], v[182:185], v[60:63]
	v_mfma_f32_16x16x32_bf16 v[56:59], v[174:177], v[182:185], v[56:59]
	v_mfma_f32_16x16x32_bf16 v[52:55], v[170:173], v[190:193], v[52:55]
	v_mfma_f32_16x16x32_bf16 v[48:51], v[174:177], v[190:193], v[48:51]
	v_mfma_f32_16x16x32_bf16 v[44:47], v[170:173], v[198:201], v[44:47]
	v_mfma_f32_16x16x32_bf16 v[40:43], v[174:177], v[198:201], v[40:43]
	v_mfma_f32_16x16x32_bf16 v[36:39], v[170:173], v[206:209], v[36:39]
	v_mfma_f32_16x16x32_bf16 v[32:35], v[174:177], v[206:209], v[32:35]
	s_setprio 0
	s_setprio 1
	v_mfma_f32_16x16x32_bf16 v[28:31], v[210:213], v[178:181], v[28:31]
	v_mfma_f32_16x16x32_bf16 v[24:27], v[214:217], v[178:181], v[24:27]
	v_mfma_f32_16x16x32_bf16 v[20:23], v[210:213], v[186:189], v[20:23]
	v_mfma_f32_16x16x32_bf16 v[16:19], v[214:217], v[186:189], v[16:19]
	v_mfma_f32_16x16x32_bf16 v[12:15], v[210:213], v[194:197], v[12:15]
	v_mfma_f32_16x16x32_bf16 v[8:11], v[214:217], v[194:197], v[8:11]
	v_mfma_f32_16x16x32_bf16 v[4:7], v[210:213], v[202:205], v[4:7]
	v_mfma_f32_16x16x32_bf16 v[0:3], v[214:217], v[202:205], v[0:3]
	v_mfma_f32_16x16x32_bf16 v[28:31], v[218:221], v[182:185], v[28:31]
	v_mfma_f32_16x16x32_bf16 v[24:27], v[222:225], v[182:185], v[24:27]
	v_mfma_f32_16x16x32_bf16 v[20:23], v[218:221], v[190:193], v[20:23]
	v_mfma_f32_16x16x32_bf16 v[16:19], v[222:225], v[190:193], v[16:19]
	v_mfma_f32_16x16x32_bf16 v[12:15], v[218:221], v[198:201], v[12:15]
	v_mfma_f32_16x16x32_bf16 v[8:11], v[222:225], v[198:201], v[8:11]
	v_mfma_f32_16x16x32_bf16 v[4:7], v[218:221], v[206:209], v[4:7]
	v_mfma_f32_16x16x32_bf16 v[0:3], v[222:225], v[206:209], v[0:3]
	s_setprio 0
	s_add_i32 s65, s65, 2
	s_add_u32 s66, s66, 0x100
	s_addc_u32 s67, s67, 0
	s_add_u32 s68, s68, 0x100
	s_addc_u32 s69, s69, 0
	s_cmp_lt_u32 s65, 28
	s_barrier
	s_cbranch_scc1 .LBB0_1105
	v_readfirstlane_b32 s70, v149
	v_lshl_add_u64 v[246:247], v[228:229], 0, s[58:59]
	s_mov_b32 m0, s70
	s_nop 0
	global_load_lds_dwordx4 v[246:247], off
	v_readfirstlane_b32 s65, v151
	v_lshl_add_u64 v[210:211], v[132:133], 0, s[60:61]
	s_mov_b32 m0, s65
	v_readfirstlane_b32 s65, v152
	ds_read_b128 v[162:165], v153
	ds_read_b128 v[166:169], v153 offset:256
	ds_read_b128 v[170:173], v154
	ds_read_b128 v[174:177], v154 offset:256
	ds_read_b128 v[178:181], v150
	ds_read_b128 v[182:185], v150 offset:1024
	ds_read_b128 v[186:189], v150 offset:2048
	ds_read_b128 v[190:193], v150 offset:3072
	ds_read_b128 v[194:197], v150 offset:4096
	ds_read_b128 v[198:201], v150 offset:5120
	ds_read_b128 v[202:205], v150 offset:6144
	ds_read_b128 v[206:209], v150 offset:7168
	global_load_lds_dwordx4 v[210:211], off
	v_lshl_add_u64 v[132:133], v[132:133], 0, s[62:63]
	s_mov_b32 m0, s65
	s_nop 0
	global_load_lds_dwordx4 v[132:133], off
	s_barrier
	s_waitcnt lgkmcnt(0)
	s_setprio 1
	v_mfma_f32_16x16x32_bf16 v[124:127], v[162:165], v[178:181], v[124:127]
	v_mfma_f32_16x16x32_bf16 v[116:119], v[162:165], v[186:189], v[116:119]
	v_mfma_f32_16x16x32_bf16 v[108:111], v[162:165], v[194:197], v[108:111]
	v_mfma_f32_16x16x32_bf16 v[100:103], v[162:165], v[202:205], v[100:103]
	v_mfma_f32_16x16x32_bf16 v[124:127], v[170:173], v[182:185], v[124:127]
	v_mfma_f32_16x16x32_bf16 v[120:123], v[166:169], v[178:181], v[120:123]
	v_mfma_f32_16x16x32_bf16 v[116:119], v[170:173], v[190:193], v[116:119]
	v_mfma_f32_16x16x32_bf16 v[112:115], v[166:169], v[186:189], v[112:115]
	v_mfma_f32_16x16x32_bf16 v[108:111], v[170:173], v[198:201], v[108:111]
	v_mfma_f32_16x16x32_bf16 v[104:107], v[166:169], v[194:197], v[104:107]
	v_mfma_f32_16x16x32_bf16 v[100:103], v[170:173], v[206:209], v[100:103]
	v_mfma_f32_16x16x32_bf16 v[96:99], v[166:169], v[202:205], v[96:99]
	v_mfma_f32_16x16x32_bf16 v[210:213], v[174:177], v[182:185], v[120:123]
	v_mfma_f32_16x16x32_bf16 v[214:217], v[174:177], v[190:193], v[112:115]
	v_mfma_f32_16x16x32_bf16 v[218:221], v[174:177], v[198:201], v[104:107]
	v_mfma_f32_16x16x32_bf16 v[222:225], v[174:177], v[206:209], v[96:99]
	s_setprio 0
	s_barrier
; #define LDA(dst, b, h) for (int m = 0; m < 4; ++m) { \
;     dst[m][0] = *reinterpret_cast<const bf16x8*>((char*)SA(b, h) + aoff0 + m * 2048); \
;     dst[m][1] = *reinterpret_cast<const bf16x8*>((char*)SA(b, h) + aoff1 + m * 2048); }
; #define LDB(dst, b, h) for (int n = 0; n < 2; ++n) { \
;     dst[n][0] = *reinterpret_cast<const bf16x8*>((char*)SB(b, h) + boff0 + n * 256); \
;     dst[n][1] = *reinterpret_cast<const bf16x8*>((char*)SB(b, h) + boff1 + n * 256); }
; #define MMA(ai, bj, At, Btf) do { __builtin_amdgcn_s_setprio(1); \
;     for (int m = 0; m < 4; ++m) for (int n = 0; n < 2; ++n) for (int k = 0; k < 2; ++k) \
;       acc[ai][bj][m][n] = __builtin_amdgcn_mfma_f32_16x16x32_bf16(Btf[n][k], At[m][k], acc[ai][bj][m][n], 0, 0, 0); \
;     __builtin_amdgcn_s_setprio(0); } while (0)
; #define WAIT_V(n) asm volatile("s_waitcnt vmcnt(" #n ")" ::: "memory")
; #define WAIT_L(n) asm volatile("s_waitcnt lgkmcnt(" #n ")" ::: "memory")
; #define BAR __builtin_amdgcn_s_barrier()
; template <int EPI> ...
;     ...
;     LDB(B1, 0, 1); BAR; WAIT_L(0); MMA(0, 1, At, B1); BAR;
;     LDA(At, 0, 1); WAIT_V(4); BAR; WAIT_L(0); MMA(1, 0, At, B0); MMA(1, 1, At, B1); BAR; }
;   { LDB(B0, 1, 0); LDA(At, 1, 0); WAIT_V(2); BAR; WAIT_L(0); MMA(0, 0, At, B0); BAR;
	s_nop 1
	ds_read_b128 v[96:99], v155
	ds_read_b128 v[104:107], v155 offset:256
	ds_read_b128 v[112:115], v156
	ds_read_b128 v[120:123], v156 offset:256
	s_barrier
	s_waitcnt lgkmcnt(0)
	s_setprio 1
	v_mfma_f32_16x16x32_bf16 v[92:95], v[96:99], v[178:181], v[92:95]
	v_mfma_f32_16x16x32_bf16 v[84:87], v[96:99], v[186:189], v[84:87]
	v_mfma_f32_16x16x32_bf16 v[76:79], v[96:99], v[194:197], v[76:79]
	v_mfma_f32_16x16x32_bf16 v[68:71], v[96:99], v[202:205], v[68:71]
	v_mfma_f32_16x16x32_bf16 v[92:95], v[112:115], v[182:185], v[92:95]
	v_mfma_f32_16x16x32_bf16 v[88:91], v[104:107], v[178:181], v[88:91]
	v_mfma_f32_16x16x32_bf16 v[84:87], v[112:115], v[190:193], v[84:87]
	v_mfma_f32_16x16x32_bf16 v[80:83], v[104:107], v[186:189], v[80:83]
	v_mfma_f32_16x16x32_bf16 v[76:79], v[112:115], v[198:201], v[76:79]
	v_mfma_f32_16x16x32_bf16 v[72:75], v[104:107], v[194:197], v[72:75]
	v_mfma_f32_16x16x32_bf16 v[68:71], v[112:115], v[206:209], v[68:71]
	v_mfma_f32_16x16x32_bf16 v[64:67], v[104:107], v[202:205], v[64:67]
	v_mfma_f32_16x16x32_bf16 v[178:181], v[120:123], v[182:185], v[88:91]
	v_mfma_f32_16x16x32_bf16 v[182:185], v[120:123], v[190:193], v[80:83]
	v_mfma_f32_16x16x32_bf16 v[186:189], v[120:123], v[198:201], v[72:75]
	v_mfma_f32_16x16x32_bf16 v[190:193], v[120:123], v[206:209], v[64:67]
	s_setprio 0
	s_barrier
	s_nop 1
	ds_read_b128 v[64:67], v150 offset:16384
	ds_read_b128 v[72:75], v150 offset:17408
	ds_read_b128 v[80:83], v150 offset:18432
	ds_read_b128 v[88:91], v150 offset:19456
	ds_read_b128 v[194:197], v150 offset:20480
	ds_read_b128 v[198:201], v150 offset:21504
	ds_read_b128 v[202:205], v150 offset:22528
	ds_read_b128 v[206:209], v150 offset:23552
	s_waitcnt vmcnt(4)
	s_barrier
	s_waitcnt lgkmcnt(0)
	s_setprio 1
	v_mfma_f32_16x16x32_bf16 v[60:63], v[162:165], v[64:67], v[60:63]
	v_mfma_f32_16x16x32_bf16 v[56:59], v[166:169], v[64:67], v[56:59]
	v_mfma_f32_16x16x32_bf16 v[52:55], v[162:165], v[80:83], v[52:55]
	v_mfma_f32_16x16x32_bf16 v[40:43], v[166:169], v[194:197], v[40:43]
	v_mfma_f32_16x16x32_bf16 v[36:39], v[162:165], v[202:205], v[36:39]
	v_mfma_f32_16x16x32_bf16 v[60:63], v[170:173], v[72:75], v[60:63]
	v_mfma_f32_16x16x32_bf16 v[56:59], v[174:177], v[72:75], v[56:59]
	v_mfma_f32_16x16x32_bf16 v[52:55], v[170:173], v[88:91], v[52:55]
	v_mfma_f32_16x16x32_bf16 v[48:51], v[166:169], v[80:83], v[48:51]
	v_mfma_f32_16x16x32_bf16 v[44:47], v[162:165], v[194:197], v[44:47]
	v_mfma_f32_16x16x32_bf16 v[40:43], v[174:177], v[198:201], v[40:43]
	v_mfma_f32_16x16x32_bf16 v[36:39], v[170:173], v[206:209], v[36:39]
	v_mfma_f32_16x16x32_bf16 v[32:35], v[166:169], v[202:205], v[32:35]
	v_mfma_f32_16x16x32_bf16 v[226:229], v[174:177], v[88:91], v[48:51]
	v_mfma_f32_16x16x32_bf16 v[230:233], v[170:173], v[198:201], v[44:47]
	v_mfma_f32_16x16x32_bf16 v[162:165], v[174:177], v[206:209], v[32:35]
	v_mfma_f32_16x16x32_bf16 v[24:27], v[104:107], v[64:67], v[24:27]
	v_mfma_f32_16x16x32_bf16 v[20:23], v[96:99], v[80:83], v[20:23]
	v_mfma_f32_16x16x32_bf16 v[8:11], v[104:107], v[194:197], v[8:11]
	v_mfma_f32_16x16x32_bf16 v[4:7], v[96:99], v[202:205], v[4:7]
	v_mfma_f32_16x16x32_bf16 v[28:31], v[96:99], v[64:67], v[28:31]
	v_mfma_f32_16x16x32_bf16 v[24:27], v[120:123], v[72:75], v[24:27]
	v_mfma_f32_16x16x32_bf16 v[20:23], v[112:115], v[88:91], v[20:23]
	v_mfma_f32_16x16x32_bf16 v[16:19], v[104:107], v[80:83], v[16:19]
	v_mfma_f32_16x16x32_bf16 v[12:15], v[96:99], v[194:197], v[12:15]
	v_mfma_f32_16x16x32_bf16 v[8:11], v[120:123], v[198:201], v[8:11]
	v_mfma_f32_16x16x32_bf16 v[4:7], v[112:115], v[206:209], v[4:7]
	v_mfma_f32_16x16x32_bf16 v[0:3], v[104:107], v[202:205], v[0:3]
	v_mfma_f32_16x16x32_bf16 v[166:169], v[112:115], v[72:75], v[28:31]
	v_mfma_f32_16x16x32_bf16 v[170:173], v[120:123], v[88:91], v[16:19]
	v_mfma_f32_16x16x32_bf16 v[174:177], v[112:115], v[198:201], v[12:15]
	v_mfma_f32_16x16x32_bf16 v[194:197], v[120:123], v[206:209], v[0:3]
	s_setprio 0
	s_barrier
	s_nop 1
	ds_read_b128 v[0:3], v157
	ds_read_b128 v[198:201], v157 offset:256
	ds_read_b128 v[12:15], v158
	ds_read_b128 v[202:205], v158 offset:256
	ds_read_b128 v[16:19], v150 offset:32768
	ds_read_b128 v[28:31], v150 offset:33792
	ds_read_b128 v[32:35], v150 offset:34816
	ds_read_b128 v[44:47], v150 offset:35840
	ds_read_b128 v[48:51], v150 offset:36864
	ds_read_b128 v[206:209], v150 offset:37888
	ds_read_b128 v[234:237], v150 offset:38912
	ds_read_b128 v[238:241], v150 offset:39936
	s_waitcnt vmcnt(2)
	s_barrier
; #define LDA(dst, b, h) for (int m = 0; m < 4; ++m) { \
;     dst[m][0] = *reinterpret_cast<const bf16x8*>((char*)SA(b, h) + aoff0 + m * 2048); \
;     dst[m][1] = *reinterpret_cast<const bf16x8*>((char*)SA(b, h) + aoff1 + m * 2048); }
; #define LDB(dst, b, h) for (int n = 0; n < 2; ++n) { \
;     dst[n][0] = *reinterpret_cast<const bf16x8*>((char*)SB(b, h) + boff0 + n * 256); \
;     dst[n][1] = *reinterpret_cast<const bf16x8*>((char*)SB(b, h) + boff1 + n * 256); }
; #define MMA(ai, bj, At, Btf) do { __builtin_amdgcn_s_setprio(1); \
;     for (int m = 0; m < 4; ++m) for (int n = 0; n < 2; ++n) for (int k = 0; k < 2; ++k) \
;       acc[ai][bj][m][n] = __builtin_amdgcn_mfma_f32_16x16x32_bf16(Btf[n][k], At[m][k], acc[ai][bj][m][n], 0, 0, 0); \
;     __builtin_amdgcn_s_setprio(0); } while (0)
; #define WAIT_V(n) asm volatile("s_waitcnt vmcnt(" #n ")" ::: "memory")
; #define WAIT_L(n) asm volatile("s_waitcnt lgkmcnt(" #n ")" ::: "memory")
; #define BAR __builtin_amdgcn_s_barrier()
; template <int EPI> ...
;     ...
;   { LDB(B0, 1, 0); LDA(At, 1, 0); WAIT_V(2); BAR; WAIT_L(0); MMA(0, 0, At, B0); BAR;
;     LDB(B1, 1, 1); WAIT_V(0); BAR; WAIT_L(0); MMA(0, 1, At, B1); BAR;
;     LDA(At, 1, 1); BAR; WAIT_L(0); MMA(1, 0, At, B0); MMA(1, 1, At, B1); BAR; }
;   if (wr == 0) BAR;
	s_waitcnt lgkmcnt(0)
	s_setprio 1
	v_mfma_f32_16x16x32_bf16 v[64:67], v[0:3], v[16:19], v[124:127]
	v_mfma_f32_16x16x32_bf16 v[120:123], v[12:15], v[28:31], v[64:67]
	v_mfma_f32_16x16x32_bf16 v[64:67], v[198:201], v[16:19], v[210:213]
	v_mfma_f32_16x16x32_bf16 v[112:115], v[202:205], v[28:31], v[64:67]
	v_mfma_f32_16x16x32_bf16 v[64:67], v[0:3], v[32:35], v[116:119]
	v_mfma_f32_16x16x32_bf16 v[104:107], v[12:15], v[44:47], v[64:67]
	v_mfma_f32_16x16x32_bf16 v[64:67], v[198:201], v[32:35], v[214:217]
	v_mfma_f32_16x16x32_bf16 v[96:99], v[202:205], v[44:47], v[64:67]
	v_mfma_f32_16x16x32_bf16 v[64:67], v[0:3], v[48:51], v[108:111]
	v_mfma_f32_16x16x32_bf16 v[88:91], v[12:15], v[206:209], v[64:67]
	v_mfma_f32_16x16x32_bf16 v[64:67], v[198:201], v[48:51], v[218:221]
	v_mfma_f32_16x16x32_bf16 v[80:83], v[202:205], v[206:209], v[64:67]
	v_mfma_f32_16x16x32_bf16 v[64:67], v[0:3], v[234:237], v[100:103]
	v_mfma_f32_16x16x32_bf16 v[72:75], v[12:15], v[238:241], v[64:67]
	v_mfma_f32_16x16x32_bf16 v[64:67], v[198:201], v[234:237], v[222:225]
	v_mfma_f32_16x16x32_bf16 v[64:67], v[202:205], v[238:241], v[64:67]
	s_setprio 0
	s_barrier
	ds_read_b128 v[210:213], v159
	ds_read_b128 v[214:217], v159 offset:256
	ds_read_b128 v[218:221], v160
	ds_read_b128 v[222:225], v160 offset:256
	s_waitcnt vmcnt(0)
	s_barrier
	s_waitcnt lgkmcnt(0)
	s_setprio 1
	v_mfma_f32_16x16x32_bf16 v[92:95], v[210:213], v[16:19], v[92:95]
	v_mfma_f32_16x16x32_bf16 v[16:19], v[214:217], v[16:19], v[178:181]
	v_mfma_f32_16x16x32_bf16 v[116:119], v[222:225], v[28:31], v[16:19]
	v_mfma_f32_16x16x32_bf16 v[16:19], v[210:213], v[32:35], v[84:87]
	v_mfma_f32_16x16x32_bf16 v[108:111], v[218:221], v[44:47], v[16:19]
	v_mfma_f32_16x16x32_bf16 v[16:19], v[214:217], v[32:35], v[182:185]
	v_mfma_f32_16x16x32_bf16 v[100:103], v[222:225], v[44:47], v[16:19]
	v_mfma_f32_16x16x32_bf16 v[16:19], v[210:213], v[48:51], v[76:79]
	v_mfma_f32_16x16x32_bf16 v[124:127], v[218:221], v[28:31], v[92:95]
	v_mfma_f32_16x16x32_bf16 v[92:95], v[218:221], v[206:209], v[16:19]
	v_mfma_f32_16x16x32_bf16 v[16:19], v[214:217], v[48:51], v[186:189]
	v_mfma_f32_16x16x32_bf16 v[84:87], v[222:225], v[206:209], v[16:19]
	v_mfma_f32_16x16x32_bf16 v[16:19], v[210:213], v[234:237], v[68:71]
	v_mfma_f32_16x16x32_bf16 v[76:79], v[218:221], v[238:241], v[16:19]
	v_mfma_f32_16x16x32_bf16 v[16:19], v[214:217], v[234:237], v[190:193]
	v_mfma_f32_16x16x32_bf16 v[68:71], v[222:225], v[238:241], v[16:19]
	s_setprio 0
	s_barrier
	ds_read_b128 v[178:181], v150 offset:49152
	ds_read_b128 v[182:185], v150 offset:50176
	ds_read_b128 v[186:189], v150 offset:51200
	ds_read_b128 v[190:193], v150 offset:52224
	ds_read_b128 v[206:209], v150 offset:53248
	ds_read_b128 v[234:237], v150 offset:54272
	ds_read_b128 v[238:241], v150 offset:55296
	ds_read_b128 v[242:245], v150 offset:56320
	s_barrier
	s_waitcnt lgkmcnt(0)
	s_setprio 1
	v_mfma_f32_16x16x32_bf16 v[16:19], v[0:3], v[178:181], v[60:63]
	v_mfma_f32_16x16x32_bf16 v[60:63], v[12:15], v[182:185], v[16:19]
	v_mfma_f32_16x16x32_bf16 v[16:19], v[198:201], v[178:181], v[56:59]
	v_mfma_f32_16x16x32_bf16 v[48:51], v[202:205], v[182:185], v[16:19]
	v_mfma_f32_16x16x32_bf16 v[16:19], v[0:3], v[186:189], v[52:55]
	v_mfma_f32_16x16x32_bf16 v[44:47], v[12:15], v[190:193], v[16:19]
	v_mfma_f32_16x16x32_bf16 v[16:19], v[198:201], v[186:189], v[226:229]
	v_mfma_f32_16x16x32_bf16 v[32:35], v[202:205], v[190:193], v[16:19]
	v_mfma_f32_16x16x32_bf16 v[16:19], v[0:3], v[206:209], v[230:233]
	v_mfma_f32_16x16x32_bf16 v[0:3], v[0:3], v[238:241], v[36:39]
	v_mfma_f32_16x16x32_bf16 v[28:31], v[12:15], v[234:237], v[16:19]
	v_mfma_f32_16x16x32_bf16 v[16:19], v[198:201], v[206:209], v[40:43]
	v_mfma_f32_16x16x32_bf16 v[12:15], v[12:15], v[242:245], v[0:3]
	v_mfma_f32_16x16x32_bf16 v[0:3], v[198:201], v[238:241], v[162:165]
	v_mfma_f32_16x16x32_bf16 v[16:19], v[202:205], v[234:237], v[16:19]
	v_mfma_f32_16x16x32_bf16 v[0:3], v[202:205], v[242:245], v[0:3]
	v_mfma_f32_16x16x32_bf16 v[20:23], v[210:213], v[186:189], v[20:23]
	v_mfma_f32_16x16x32_bf16 v[36:39], v[210:213], v[178:181], v[166:169]
	v_mfma_f32_16x16x32_bf16 v[40:43], v[218:221], v[190:193], v[20:23]
	v_mfma_f32_16x16x32_bf16 v[20:23], v[214:217], v[186:189], v[170:173]
	v_mfma_f32_16x16x32_bf16 v[56:59], v[218:221], v[182:185], v[36:39]
	v_mfma_f32_16x16x32_bf16 v[24:27], v[214:217], v[178:181], v[24:27]
	v_mfma_f32_16x16x32_bf16 v[36:39], v[222:225], v[190:193], v[20:23]
	v_mfma_f32_16x16x32_bf16 v[20:23], v[210:213], v[206:209], v[174:177]
	v_mfma_f32_16x16x32_bf16 v[8:11], v[214:217], v[206:209], v[8:11]
	v_mfma_f32_16x16x32_bf16 v[4:7], v[210:213], v[238:241], v[4:7]
	v_mfma_f32_16x16x32_bf16 v[52:55], v[222:225], v[182:185], v[24:27]
	v_mfma_f32_16x16x32_bf16 v[24:27], v[218:221], v[234:237], v[20:23]
	v_mfma_f32_16x16x32_bf16 v[20:23], v[222:225], v[234:237], v[8:11]
	v_mfma_f32_16x16x32_bf16 v[8:11], v[218:221], v[242:245], v[4:7]
	v_mfma_f32_16x16x32_bf16 v[4:7], v[214:217], v[238:241], v[194:197]
	v_mfma_f32_16x16x32_bf16 v[4:7], v[222:225], v[242:245], v[4:7]
	s_setprio 0
	s_barrier
	s_and_saveexec_b64 s[66:67], s[2:3]
	s_cbranch_execz .LBB0_1099
	s_barrier
	s_branch .LBB0_1099

; #define STAGE(P, BASE, br, kt) do { const char* _gb = (const char*)(BASE) + ((size_t)(br) * K + (size_t)(kt) * BK) * 2; \
;     __builtin_amdgcn_global_load_lds((const unsigned*)(_gb + loff0), (unsigned*)((char*)(P) + tid * 16), 16, 0, 0); \
;     __builtin_amdgcn_global_load_lds((const unsigned*)(_gb + (size_t)K * 128 + loff0), (unsigned*)((char*)(P) + tid * 16 + 8192), 16, 0, 0); } while (0)
; #define LDA(dst, b, h) for (int m = 0; m < 4; ++m) { \
;     dst[m][0] = *reinterpret_cast<const bf16x8*>((char*)SA(b, h) + aoff0 + m * 2048); \
;     dst[m][1] = *reinterpret_cast<const bf16x8*>((char*)SA(b, h) + aoff1 + m * 2048); }
; #define LDB(dst, b, h) for (int n = 0; n < 2; ++n) { \
;     dst[n][0] = *reinterpret_cast<const bf16x8*>((char*)SB(b, h) + boff0 + n * 256); \
;     dst[n][1] = *reinterpret_cast<const bf16x8*>((char*)SB(b, h) + boff1 + n * 256); }
; #define MMA(ai, bj, At, Btf) do { __builtin_amdgcn_s_setprio(1); \
;     for (int m = 0; m < 4; ++m) for (int n = 0; n < 2; ++n) for (int k = 0; k < 2; ++k) \
;       acc[ai][bj][m][n] = __builtin_amdgcn_mfma_f32_16x16x32_bf16(Btf[n][k], At[m][k], acc[ai][bj][m][n], 0, 0, 0); \
;     __builtin_amdgcn_s_setprio(0); } while (0)
; #define WAIT_L(n) asm volatile("s_waitcnt lgkmcnt(" #n ")" ::: "memory")
; #define BAR __builtin_amdgcn_s_barrier()
; #define SCHED __builtin_amdgcn_sched_barrier(0)
; template <int EPI> ...
;     ...
;     LDB(B0, 0, 0); SCHED; LDA(At, 0, 0); STAGE(SA(1, 1), A, brow + HALF, t + 1);
;     WAIT_L(8); BAR; WAIT_L(0); MMA(0, 0, At, B0); BAR; SCHED;
;     LDB(B1, 0, 1); STAGE(SB(0, 0), Bt, bcol, t + 2);
;     BAR; WAIT_L(0); MMA(0, 1, At, B1); BAR;
;     LDA(At, 0, 1); STAGE(SA(0, 0), A, brow, t + 2);
;     BAR; WAIT_L(0); MMA(1, 0, At, B0); BAR; SCHED;
.LBB0_1152:
	ds_read_b128 v[160:163], v152
	ds_read_b128 v[164:167], v152 offset:256
	ds_read_b128 v[168:171], v153
	ds_read_b128 v[172:175], v153 offset:256
	v_lshl_add_u64 v[224:225], s[62:63], 0, v[132:133]
	v_readfirstlane_b32 s75, v150
	v_lshl_add_u64 v[208:209], v[224:225], 0, s[16:17]
	s_mov_b32 m0, s75
	v_readfirstlane_b32 s75, v151
	ds_read_b128 v[176:179], v149
	ds_read_b128 v[180:183], v149 offset:1024
	ds_read_b128 v[184:187], v149 offset:2048
	ds_read_b128 v[188:191], v149 offset:3072
	ds_read_b128 v[192:195], v149 offset:4096
	ds_read_b128 v[196:199], v149 offset:5120
	ds_read_b128 v[200:203], v149 offset:6144
	ds_read_b128 v[204:207], v149 offset:7168
	global_load_lds_dwordx4 v[208:209], off
	v_lshl_add_u64 v[208:209], v[224:225], 0, s[18:19]
	s_mov_b32 m0, s75
	s_nop 0
	global_load_lds_dwordx4 v[208:209], off
	s_waitcnt lgkmcnt(8)
	v_readfirstlane_b32 s75, v148
	v_lshl_add_u64 v[246:247], v[228:229], 0, s[56:57]
	s_mov_b32 m0, s75
	s_nop 0
	global_load_lds_dwordx4 v[246:247], off
	ds_read_b128 v[208:211], v154
	ds_read_b128 v[212:215], v154 offset:256
	ds_read_b128 v[216:219], v155
	ds_read_b128 v[220:223], v155 offset:256
	s_barrier
	s_waitcnt lgkmcnt(0)
	s_setprio 1
	v_mfma_f32_16x16x32_bf16 v[124:127], v[160:163], v[176:179], v[124:127]
	v_mfma_f32_16x16x32_bf16 v[120:123], v[164:167], v[176:179], v[120:123]
	v_mfma_f32_16x16x32_bf16 v[116:119], v[160:163], v[184:187], v[116:119]
	v_mfma_f32_16x16x32_bf16 v[112:115], v[164:167], v[184:187], v[112:115]
	v_mfma_f32_16x16x32_bf16 v[108:111], v[160:163], v[192:195], v[108:111]
	v_mfma_f32_16x16x32_bf16 v[104:107], v[164:167], v[192:195], v[104:107]
	v_mfma_f32_16x16x32_bf16 v[100:103], v[160:163], v[200:203], v[100:103]
	v_mfma_f32_16x16x32_bf16 v[96:99], v[164:167], v[200:203], v[96:99]
	v_mfma_f32_16x16x32_bf16 v[124:127], v[168:171], v[180:183], v[124:127]
	v_mfma_f32_16x16x32_bf16 v[120:123], v[172:175], v[180:183], v[120:123]
	v_mfma_f32_16x16x32_bf16 v[116:119], v[168:171], v[188:191], v[116:119]
	v_mfma_f32_16x16x32_bf16 v[112:115], v[172:175], v[188:191], v[112:115]
	v_mfma_f32_16x16x32_bf16 v[108:111], v[168:171], v[196:199], v[108:111]
	v_mfma_f32_16x16x32_bf16 v[104:107], v[172:175], v[196:199], v[104:107]
	v_mfma_f32_16x16x32_bf16 v[100:103], v[168:171], v[204:207], v[100:103]
	v_mfma_f32_16x16x32_bf16 v[96:99], v[172:175], v[204:207], v[96:99]
	v_mfma_f32_16x16x32_bf16 v[92:95], v[208:211], v[176:179], v[92:95]
	v_mfma_f32_16x16x32_bf16 v[88:91], v[212:215], v[176:179], v[88:91]
	v_mfma_f32_16x16x32_bf16 v[84:87], v[208:211], v[184:187], v[84:87]
	v_mfma_f32_16x16x32_bf16 v[80:83], v[212:215], v[184:187], v[80:83]
	v_mfma_f32_16x16x32_bf16 v[76:79], v[208:211], v[192:195], v[76:79]
	v_mfma_f32_16x16x32_bf16 v[72:75], v[212:215], v[192:195], v[72:75]
	v_mfma_f32_16x16x32_bf16 v[68:71], v[208:211], v[200:203], v[68:71]
	v_mfma_f32_16x16x32_bf16 v[64:67], v[212:215], v[200:203], v[64:67]
	v_mfma_f32_16x16x32_bf16 v[92:95], v[216:219], v[180:183], v[92:95]
	v_mfma_f32_16x16x32_bf16 v[88:91], v[220:223], v[180:183], v[88:91]
	v_mfma_f32_16x16x32_bf16 v[84:87], v[216:219], v[188:191], v[84:87]
	v_mfma_f32_16x16x32_bf16 v[80:83], v[220:223], v[188:191], v[80:83]
	v_mfma_f32_16x16x32_bf16 v[76:79], v[216:219], v[196:199], v[76:79]
	v_mfma_f32_16x16x32_bf16 v[72:75], v[220:223], v[196:199], v[72:75]
	v_mfma_f32_16x16x32_bf16 v[68:71], v[216:219], v[204:207], v[68:71]
	v_mfma_f32_16x16x32_bf16 v[64:67], v[220:223], v[204:207], v[64:67]
	s_setprio 0
	s_barrier
	v_lshl_add_u64 v[226:227], s[64:65], 0, v[132:133]
	v_readfirstlane_b32 s75, v135
	v_lshl_add_u64 v[228:229], v[226:227], 0, s[20:21]
	s_mov_b32 m0, s75
	v_readfirstlane_b32 s75, v136
	global_load_lds_dwordx4 v[228:229], off
	v_lshl_add_u64 v[228:229], v[226:227], 0, s[22:23]
	s_mov_b32 m0, s75
	s_nop 0
	global_load_lds_dwordx4 v[228:229], off
	v_readfirstlane_b32 s75, v137
	v_lshl_add_u64 v[228:229], v[224:225], 0, s[24:25]
	s_mov_b32 m0, s75
	v_readfirstlane_b32 s75, v138
	ds_read_b128 v[176:179], v149 offset:16384
	ds_read_b128 v[180:183], v149 offset:17408
	ds_read_b128 v[184:187], v149 offset:18432
	ds_read_b128 v[188:191], v149 offset:19456
	ds_read_b128 v[192:195], v149 offset:20480
	ds_read_b128 v[196:199], v149 offset:21504
	ds_read_b128 v[200:203], v149 offset:22528
	ds_read_b128 v[204:207], v149 offset:23552
	global_load_lds_dwordx4 v[228:229], off
	v_lshl_add_u64 v[228:229], v[224:225], 0, s[26:27]
	s_mov_b32 m0, s75
	s_nop 0
	global_load_lds_dwordx4 v[228:229], off
	v_lshl_add_u64 v[228:229], s[60:61], 0, v[132:133]
	v_readfirstlane_b32 s75, v139
	v_lshl_add_u64 v[246:247], v[228:229], 0, s[28:29]
	s_mov_b32 m0, s75
	v_readfirstlane_b32 s75, v140
	global_load_lds_dwordx4 v[246:247], off
	s_waitcnt vmcnt(5)
	s_barrier
; #define STAGE(P, BASE, br, kt) do { const char* _gb = (const char*)(BASE) + ((size_t)(br) * K + (size_t)(kt) * BK) * 2; \
;     __builtin_amdgcn_global_load_lds((const unsigned*)(_gb + loff0), (unsigned*)((char*)(P) + tid * 16), 16, 0, 0); \
;     __builtin_amdgcn_global_load_lds((const unsigned*)(_gb + (size_t)K * 128 + loff0), (unsigned*)((char*)(P) + tid * 16 + 8192), 16, 0, 0); } while (0)
; #define LDA(dst, b, h) for (int m = 0; m < 4; ++m) { \
;     dst[m][0] = *reinterpret_cast<const bf16x8*>((char*)SA(b, h) + aoff0 + m * 2048); \
;     dst[m][1] = *reinterpret_cast<const bf16x8*>((char*)SA(b, h) + aoff1 + m * 2048); }
; #define LDB(dst, b, h) for (int n = 0; n < 2; ++n) { \
;     dst[n][0] = *reinterpret_cast<const bf16x8*>((char*)SB(b, h) + boff0 + n * 256); \
;     dst[n][1] = *reinterpret_cast<const bf16x8*>((char*)SB(b, h) + boff1 + n * 256); }
; #define MMA(ai, bj, At, Btf) do { __builtin_amdgcn_s_setprio(1); \
;     for (int m = 0; m < 4; ++m) for (int n = 0; n < 2; ++n) for (int k = 0; k < 2; ++k) \
;       acc[ai][bj][m][n] = __builtin_amdgcn_mfma_f32_16x16x32_bf16(Btf[n][k], At[m][k], acc[ai][bj][m][n], 0, 0, 0); \
;     __builtin_amdgcn_s_setprio(0); } while (0)
; #define WAIT_V(n) asm volatile("s_waitcnt vmcnt(" #n ")" ::: "memory")
; #define WAIT_L(n) asm volatile("s_waitcnt lgkmcnt(" #n ")" ::: "memory")
; #define BAR __builtin_amdgcn_s_barrier()
; #define SCHED __builtin_amdgcn_sched_barrier(0)
; template <int EPI> ...
;     ...
;     BAR; WAIT_L(0); MMA(1, 0, At, B0); BAR; SCHED;
;     STAGE(SB(0, 1), Bt, bcol + HALF, t + 2);
;     WAIT_V(6); BAR; MMA(1, 1, At, B1); BAR;
;     LDB(B0, 1, 0); SCHED; LDA(At, 1, 0); STAGE(SA(0, 1), A, brow + HALF, t + 2);
;     WAIT_L(8); BAR; WAIT_L(0); MMA(0, 0, At, B0); BAR; SCHED;
;     LDB(B1, 1, 1); STAGE(SB(1, 0), Bt, bcol, t + 3);
;     BAR; WAIT_L(0); MMA(0, 1, At, B1); BAR;
	s_waitcnt lgkmcnt(0)
	s_setprio 1
	v_mfma_f32_16x16x32_bf16 v[60:63], v[160:163], v[176:179], v[60:63]
	v_mfma_f32_16x16x32_bf16 v[56:59], v[164:167], v[176:179], v[56:59]
	v_mfma_f32_16x16x32_bf16 v[52:55], v[160:163], v[184:187], v[52:55]
	v_mfma_f32_16x16x32_bf16 v[48:51], v[164:167], v[184:187], v[48:51]
	v_mfma_f32_16x16x32_bf16 v[44:47], v[160:163], v[192:195], v[44:47]
	v_mfma_f32_16x16x32_bf16 v[40:43], v[164:167], v[192:195], v[40:43]
	v_mfma_f32_16x16x32_bf16 v[36:39], v[160:163], v[200:203], v[36:39]
	v_mfma_f32_16x16x32_bf16 v[32:35], v[164:167], v[200:203], v[32:35]
	v_mfma_f32_16x16x32_bf16 v[60:63], v[168:171], v[180:183], v[60:63]
	v_mfma_f32_16x16x32_bf16 v[56:59], v[172:175], v[180:183], v[56:59]
	v_mfma_f32_16x16x32_bf16 v[52:55], v[168:171], v[188:191], v[52:55]
	v_mfma_f32_16x16x32_bf16 v[48:51], v[172:175], v[188:191], v[48:51]
	v_mfma_f32_16x16x32_bf16 v[44:47], v[168:171], v[196:199], v[44:47]
	v_mfma_f32_16x16x32_bf16 v[40:43], v[172:175], v[196:199], v[40:43]
	v_mfma_f32_16x16x32_bf16 v[36:39], v[168:171], v[204:207], v[36:39]
	v_mfma_f32_16x16x32_bf16 v[32:35], v[172:175], v[204:207], v[32:35]
	v_mfma_f32_16x16x32_bf16 v[28:31], v[208:211], v[176:179], v[28:31]
	v_mfma_f32_16x16x32_bf16 v[24:27], v[212:215], v[176:179], v[24:27]
	v_mfma_f32_16x16x32_bf16 v[20:23], v[208:211], v[184:187], v[20:23]
	v_mfma_f32_16x16x32_bf16 v[16:19], v[212:215], v[184:187], v[16:19]
	v_mfma_f32_16x16x32_bf16 v[12:15], v[208:211], v[192:195], v[12:15]
	v_mfma_f32_16x16x32_bf16 v[8:11], v[212:215], v[192:195], v[8:11]
	v_mfma_f32_16x16x32_bf16 v[4:7], v[208:211], v[200:203], v[4:7]
	v_mfma_f32_16x16x32_bf16 v[0:3], v[212:215], v[200:203], v[0:3]
	v_mfma_f32_16x16x32_bf16 v[28:31], v[216:219], v[180:183], v[28:31]
	v_mfma_f32_16x16x32_bf16 v[24:27], v[220:223], v[180:183], v[24:27]
	v_mfma_f32_16x16x32_bf16 v[20:23], v[216:219], v[188:191], v[20:23]
	v_mfma_f32_16x16x32_bf16 v[16:19], v[220:223], v[188:191], v[16:19]
	v_mfma_f32_16x16x32_bf16 v[12:15], v[216:219], v[196:199], v[12:15]
	v_mfma_f32_16x16x32_bf16 v[8:11], v[220:223], v[196:199], v[8:11]
	v_mfma_f32_16x16x32_bf16 v[4:7], v[216:219], v[204:207], v[4:7]
	v_mfma_f32_16x16x32_bf16 v[0:3], v[220:223], v[204:207], v[0:3]
	s_setprio 0
	s_barrier
	ds_read_b128 v[160:163], v156
	ds_read_b128 v[164:167], v156 offset:256
	ds_read_b128 v[168:171], v157
	ds_read_b128 v[172:175], v157 offset:256
	v_readfirstlane_b32 s75, v141
	v_lshl_add_u64 v[208:209], v[224:225], 0, s[36:37]
	s_mov_b32 m0, s75
	v_readfirstlane_b32 s75, v142
	ds_read_b128 v[176:179], v149 offset:32768
	ds_read_b128 v[180:183], v149 offset:33792
	ds_read_b128 v[184:187], v149 offset:34816
	ds_read_b128 v[188:191], v149 offset:35840
	ds_read_b128 v[192:195], v149 offset:36864
	ds_read_b128 v[196:199], v149 offset:37888
	ds_read_b128 v[200:203], v149 offset:38912
	ds_read_b128 v[204:207], v149 offset:39936
	global_load_lds_dwordx4 v[208:209], off
	v_lshl_add_u64 v[208:209], v[224:225], 0, s[38:39]
	s_mov_b32 m0, s75
	s_nop 0
	global_load_lds_dwordx4 v[208:209], off
	s_waitcnt lgkmcnt(8)
	v_readfirstlane_b32 s75, v140
	v_lshl_add_u64 v[246:247], v[228:229], 0, s[30:31]
	s_mov_b32 m0, s75
	s_nop 0
	global_load_lds_dwordx4 v[246:247], off
	ds_read_b128 v[208:211], v158
	ds_read_b128 v[212:215], v158 offset:256
	ds_read_b128 v[216:219], v159
	ds_read_b128 v[220:223], v159 offset:256
	s_barrier
	s_waitcnt lgkmcnt(0)
	s_setprio 1
	v_mfma_f32_16x16x32_bf16 v[124:127], v[160:163], v[176:179], v[124:127]
	v_mfma_f32_16x16x32_bf16 v[120:123], v[164:167], v[176:179], v[120:123]
	v_mfma_f32_16x16x32_bf16 v[116:119], v[160:163], v[184:187], v[116:119]
	v_mfma_f32_16x16x32_bf16 v[112:115], v[164:167], v[184:187], v[112:115]
	v_mfma_f32_16x16x32_bf16 v[108:111], v[160:163], v[192:195], v[108:111]
	v_mfma_f32_16x16x32_bf16 v[104:107], v[164:167], v[192:195], v[104:107]
	v_mfma_f32_16x16x32_bf16 v[100:103], v[160:163], v[200:203], v[100:103]
	v_mfma_f32_16x16x32_bf16 v[96:99], v[164:167], v[200:203], v[96:99]
	v_mfma_f32_16x16x32_bf16 v[124:127], v[168:171], v[180:183], v[124:127]
	v_mfma_f32_16x16x32_bf16 v[120:123], v[172:175], v[180:183], v[120:123]
	v_mfma_f32_16x16x32_bf16 v[116:119], v[168:171], v[188:191], v[116:119]
	v_mfma_f32_16x16x32_bf16 v[112:115], v[172:175], v[188:191], v[112:115]
	v_mfma_f32_16x16x32_bf16 v[108:111], v[168:171], v[196:199], v[108:111]
	v_mfma_f32_16x16x32_bf16 v[104:107], v[172:175], v[196:199], v[104:107]
	v_mfma_f32_16x16x32_bf16 v[100:103], v[168:171], v[204:207], v[100:103]
	v_mfma_f32_16x16x32_bf16 v[96:99], v[172:175], v[204:207], v[96:99]
	v_mfma_f32_16x16x32_bf16 v[92:95], v[208:211], v[176:179], v[92:95]
	v_mfma_f32_16x16x32_bf16 v[88:91], v[212:215], v[176:179], v[88:91]
	v_mfma_f32_16x16x32_bf16 v[84:87], v[208:211], v[184:187], v[84:87]
	v_mfma_f32_16x16x32_bf16 v[80:83], v[212:215], v[184:187], v[80:83]
	v_mfma_f32_16x16x32_bf16 v[76:79], v[208:211], v[192:195], v[76:79]
	v_mfma_f32_16x16x32_bf16 v[72:75], v[212:215], v[192:195], v[72:75]
	v_mfma_f32_16x16x32_bf16 v[68:71], v[208:211], v[200:203], v[68:71]
	v_mfma_f32_16x16x32_bf16 v[64:67], v[212:215], v[200:203], v[64:67]
	v_mfma_f32_16x16x32_bf16 v[92:95], v[216:219], v[180:183], v[92:95]
	v_mfma_f32_16x16x32_bf16 v[88:91], v[220:223], v[180:183], v[88:91]
	v_mfma_f32_16x16x32_bf16 v[84:87], v[216:219], v[188:191], v[84:87]
	v_mfma_f32_16x16x32_bf16 v[80:83], v[220:223], v[188:191], v[80:83]
	v_mfma_f32_16x16x32_bf16 v[76:79], v[216:219], v[196:199], v[76:79]
	v_mfma_f32_16x16x32_bf16 v[72:75], v[220:223], v[196:199], v[72:75]
	v_mfma_f32_16x16x32_bf16 v[68:71], v[216:219], v[204:207], v[68:71]
	v_mfma_f32_16x16x32_bf16 v[64:67], v[220:223], v[204:207], v[64:67]
	s_setprio 0
	s_barrier
; #define STAGE(P, BASE, br, kt) do { const char* _gb = (const char*)(BASE) + ((size_t)(br) * K + (size_t)(kt) * BK) * 2; \
;     __builtin_amdgcn_global_load_lds((const unsigned*)(_gb + loff0), (unsigned*)((char*)(P) + tid * 16), 16, 0, 0); \
;     __builtin_amdgcn_global_load_lds((const unsigned*)(_gb + (size_t)K * 128 + loff0), (unsigned*)((char*)(P) + tid * 16 + 8192), 16, 0, 0); } while (0)
; #define LDA(dst, b, h) for (int m = 0; m < 4; ++m) { \
;     dst[m][0] = *reinterpret_cast<const bf16x8*>((char*)SA(b, h) + aoff0 + m * 2048); \
;     dst[m][1] = *reinterpret_cast<const bf16x8*>((char*)SA(b, h) + aoff1 + m * 2048); }
; #define LDB(dst, b, h) for (int n = 0; n < 2; ++n) { \
;     dst[n][0] = *reinterpret_cast<const bf16x8*>((char*)SB(b, h) + boff0 + n * 256); \
;     dst[n][1] = *reinterpret_cast<const bf16x8*>((char*)SB(b, h) + boff1 + n * 256); }
; #define MMA(ai, bj, At, Btf) do { __builtin_amdgcn_s_setprio(1); \
;     for (int m = 0; m < 4; ++m) for (int n = 0; n < 2; ++n) for (int k = 0; k < 2; ++k) \
;       acc[ai][bj][m][n] = __builtin_amdgcn_mfma_f32_16x16x32_bf16(Btf[n][k], At[m][k], acc[ai][bj][m][n], 0, 0, 0); \
;     __builtin_amdgcn_s_setprio(0); } while (0)
; #define WAIT_V(n) asm volatile("s_waitcnt vmcnt(" #n ")" ::: "memory")
; #define WAIT_L(n) asm volatile("s_waitcnt lgkmcnt(" #n ")" ::: "memory")
; #define BAR __builtin_amdgcn_s_barrier()
; #define SCHED __builtin_amdgcn_sched_barrier(0)
; template <int EPI> ...
;     ...
;     LDA(At, 1, 1); STAGE(SA(1, 0), A, brow, t + 3);
;     BAR; WAIT_L(0); MMA(1, 0, At, B0); BAR; SCHED;
;     STAGE(SB(1, 1), Bt, bcol + HALF, t + 3);
;     WAIT_V(6); BAR; MMA(1, 1, At, B1); BAR;
;   }
;   { LDB(B0, 0, 0); LDA(At, 0, 0); STAGE(SA(1, 1), A, brow + HALF, nt - 1);
;     BAR; WAIT_L(0); MMA(0, 0, At, B0); BAR;
	v_readfirstlane_b32 s75, v143
	v_lshl_add_u64 v[230:231], v[226:227], 0, s[46:47]
	s_mov_b32 m0, s75
	v_readfirstlane_b32 s75, v144
	global_load_lds_dwordx4 v[230:231], off
	v_lshl_add_u64 v[226:227], v[226:227], 0, s[48:49]
	s_mov_b32 m0, s75
	s_nop 0
	global_load_lds_dwordx4 v[226:227], off
	v_readfirstlane_b32 s75, v145
	v_lshl_add_u64 v[226:227], v[224:225], 0, s[50:51]
	s_mov_b32 m0, s75
	v_readfirstlane_b32 s75, v146
	ds_read_b128 v[176:179], v149 offset:49152
	ds_read_b128 v[180:183], v149 offset:50176
	ds_read_b128 v[184:187], v149 offset:51200
	ds_read_b128 v[188:191], v149 offset:52224
	ds_read_b128 v[192:195], v149 offset:53248
	ds_read_b128 v[196:199], v149 offset:54272
	ds_read_b128 v[200:203], v149 offset:55296
	ds_read_b128 v[204:207], v149 offset:56320
	global_load_lds_dwordx4 v[226:227], off
	v_lshl_add_u64 v[224:225], v[224:225], 0, s[52:53]
	s_mov_b32 m0, s75
	s_nop 0
	global_load_lds_dwordx4 v[224:225], off
	v_readfirstlane_b32 s75, v147
	v_lshl_add_u64 v[246:247], v[228:229], 0, s[54:55]
	s_mov_b32 m0, s75
	v_readfirstlane_b32 s75, v148
	global_load_lds_dwordx4 v[246:247], off
	s_waitcnt vmcnt(5)
	s_barrier
	s_waitcnt lgkmcnt(0)
	s_setprio 1
	s_waitcnt lgkmcnt(0)
	v_mfma_f32_16x16x32_bf16 v[60:63], v[160:163], v[176:179], v[60:63]
	v_mfma_f32_16x16x32_bf16 v[56:59], v[164:167], v[176:179], v[56:59]
	v_mfma_f32_16x16x32_bf16 v[52:55], v[160:163], v[184:187], v[52:55]
	v_mfma_f32_16x16x32_bf16 v[48:51], v[164:167], v[184:187], v[48:51]
	v_mfma_f32_16x16x32_bf16 v[44:47], v[160:163], v[192:195], v[44:47]
	v_mfma_f32_16x16x32_bf16 v[40:43], v[164:167], v[192:195], v[40:43]
	v_mfma_f32_16x16x32_bf16 v[36:39], v[160:163], v[200:203], v[36:39]
	v_mfma_f32_16x16x32_bf16 v[32:35], v[164:167], v[200:203], v[32:35]
	v_mfma_f32_16x16x32_bf16 v[60:63], v[168:171], v[180:183], v[60:63]
	v_mfma_f32_16x16x32_bf16 v[56:59], v[172:175], v[180:183], v[56:59]
	v_mfma_f32_16x16x32_bf16 v[52:55], v[168:171], v[188:191], v[52:55]
	v_mfma_f32_16x16x32_bf16 v[48:51], v[172:175], v[188:191], v[48:51]
	v_mfma_f32_16x16x32_bf16 v[44:47], v[168:171], v[196:199], v[44:47]
	v_mfma_f32_16x16x32_bf16 v[40:43], v[172:175], v[196:199], v[40:43]
	v_mfma_f32_16x16x32_bf16 v[36:39], v[168:171], v[204:207], v[36:39]
	v_mfma_f32_16x16x32_bf16 v[32:35], v[172:175], v[204:207], v[32:35]
	s_setprio 0
	s_setprio 1
	v_mfma_f32_16x16x32_bf16 v[28:31], v[208:211], v[176:179], v[28:31]
	v_mfma_f32_16x16x32_bf16 v[24:27], v[212:215], v[176:179], v[24:27]
	v_mfma_f32_16x16x32_bf16 v[20:23], v[208:211], v[184:187], v[20:23]
	v_mfma_f32_16x16x32_bf16 v[16:19], v[212:215], v[184:187], v[16:19]
	v_mfma_f32_16x16x32_bf16 v[12:15], v[208:211], v[192:195], v[12:15]
	v_mfma_f32_16x16x32_bf16 v[8:11], v[212:215], v[192:195], v[8:11]
	v_mfma_f32_16x16x32_bf16 v[4:7], v[208:211], v[200:203], v[4:7]
	v_mfma_f32_16x16x32_bf16 v[0:3], v[212:215], v[200:203], v[0:3]
	v_mfma_f32_16x16x32_bf16 v[28:31], v[216:219], v[180:183], v[28:31]
	v_mfma_f32_16x16x32_bf16 v[24:27], v[220:223], v[180:183], v[24:27]
	v_mfma_f32_16x16x32_bf16 v[20:23], v[216:219], v[188:191], v[20:23]
	v_mfma_f32_16x16x32_bf16 v[16:19], v[220:223], v[188:191], v[16:19]
	v_mfma_f32_16x16x32_bf16 v[12:15], v[216:219], v[196:199], v[12:15]
	v_mfma_f32_16x16x32_bf16 v[8:11], v[220:223], v[196:199], v[8:11]
	v_mfma_f32_16x16x32_bf16 v[4:7], v[216:219], v[204:207], v[4:7]
	v_mfma_f32_16x16x32_bf16 v[0:3], v[220:223], v[204:207], v[0:3]
	s_setprio 0
	s_add_i32 s74, s74, 2
	s_add_u32 s60, s60, 0x100
	s_addc_u32 s61, s61, 0
	s_add_u32 s62, s62, 0x100
	s_addc_u32 s63, s63, 0
	s_add_u32 s64, s64, 0x100
	s_addc_u32 s65, s65, 0
	s_cmpk_lt_u32 s74, 0x54
	s_barrier
	s_cbranch_scc1 .LBB0_1152
	v_readfirstlane_b32 s75, v148
	v_lshl_add_u64 v[246:247], v[228:229], 0, s[56:57]
	s_mov_b32 m0, s75
	s_nop 0
	global_load_lds_dwordx4 v[246:247], off
	s_add_u32 s60, s68, s73
	s_addc_u32 s61, s69, s72
	v_lshl_add_u64 v[208:209], s[60:61], 0, v[128:129]
	v_readfirstlane_b32 s60, v150
	s_mov_b32 m0, s60
	v_readfirstlane_b32 s60, v151
	ds_read_b128 v[160:163], v152
	ds_read_b128 v[164:167], v152 offset:256
	ds_read_b128 v[168:171], v153
	ds_read_b128 v[172:175], v153 offset:256
	ds_read_b128 v[176:179], v149
	ds_read_b128 v[180:183], v149 offset:1024
	ds_read_b128 v[184:187], v149 offset:2048
	ds_read_b128 v[188:191], v149 offset:3072
	ds_read_b128 v[192:195], v149 offset:4096
	ds_read_b128 v[196:199], v149 offset:5120
	ds_read_b128 v[200:203], v149 offset:6144
	ds_read_b128 v[204:207], v149 offset:7168
	global_load_lds_dwordx4 v[208:209], off
	v_lshl_add_u64 v[208:209], v[208:209], 0, s[8:9]
	s_mov_b32 m0, s60
	s_nop 0
	global_load_lds_dwordx4 v[208:209], off
	s_barrier
	s_waitcnt lgkmcnt(0)
	s_setprio 1
	v_mfma_f32_16x16x32_bf16 v[124:127], v[160:163], v[176:179], v[124:127]
	v_mfma_f32_16x16x32_bf16 v[116:119], v[160:163], v[184:187], v[116:119]
	v_mfma_f32_16x16x32_bf16 v[108:111], v[160:163], v[192:195], v[108:111]
	v_mfma_f32_16x16x32_bf16 v[100:103], v[160:163], v[200:203], v[100:103]
	v_mfma_f32_16x16x32_bf16 v[96:99], v[164:167], v[200:203], v[96:99]
	v_mfma_f32_16x16x32_bf16 v[124:127], v[168:171], v[180:183], v[124:127]
	v_mfma_f32_16x16x32_bf16 v[120:123], v[164:167], v[176:179], v[120:123]
	v_mfma_f32_16x16x32_bf16 v[116:119], v[168:171], v[188:191], v[116:119]
	v_mfma_f32_16x16x32_bf16 v[112:115], v[164:167], v[184:187], v[112:115]
	v_mfma_f32_16x16x32_bf16 v[108:111], v[168:171], v[196:199], v[108:111]
	v_mfma_f32_16x16x32_bf16 v[104:107], v[164:167], v[192:195], v[104:107]
	v_mfma_f32_16x16x32_bf16 v[100:103], v[168:171], v[204:207], v[100:103]
	v_mfma_f32_16x16x32_bf16 v[96:99], v[172:175], v[204:207], v[96:99]
	v_mfma_f32_16x16x32_bf16 v[208:211], v[172:175], v[180:183], v[120:123]
	v_mfma_f32_16x16x32_bf16 v[212:215], v[172:175], v[188:191], v[112:115]
	v_mfma_f32_16x16x32_bf16 v[216:219], v[172:175], v[196:199], v[104:107]
	s_setprio 0
	s_barrier
; #define LDA(dst, b, h) for (int m = 0; m < 4; ++m) { \
;     dst[m][0] = *reinterpret_cast<const bf16x8*>((char*)SA(b, h) + aoff0 + m * 2048); \
;     dst[m][1] = *reinterpret_cast<const bf16x8*>((char*)SA(b, h) + aoff1 + m * 2048); }
; #define LDB(dst, b, h) for (int n = 0; n < 2; ++n) { \
;     dst[n][0] = *reinterpret_cast<const bf16x8*>((char*)SB(b, h) + boff0 + n * 256); \
;     dst[n][1] = *reinterpret_cast<const bf16x8*>((char*)SB(b, h) + boff1 + n * 256); }
; #define MMA(ai, bj, At, Btf) do { __builtin_amdgcn_s_setprio(1); \
;     for (int m = 0; m < 4; ++m) for (int n = 0; n < 2; ++n) for (int k = 0; k < 2; ++k) \
;       acc[ai][bj][m][n] = __builtin_amdgcn_mfma_f32_16x16x32_bf16(Btf[n][k], At[m][k], acc[ai][bj][m][n], 0, 0, 0); \
;     __builtin_amdgcn_s_setprio(0); } while (0)
; #define WAIT_V(n) asm volatile("s_waitcnt vmcnt(" #n ")" ::: "memory")
; #define WAIT_L(n) asm volatile("s_waitcnt lgkmcnt(" #n ")" ::: "memory")
; #define BAR __builtin_amdgcn_s_barrier()
; template <int EPI> ...
;     ...
;     LDB(B1, 0, 1); BAR; WAIT_L(0); MMA(0, 1, At, B1); BAR;
;     LDA(At, 0, 1); WAIT_V(4); BAR; WAIT_L(0); MMA(1, 0, At, B0); MMA(1, 1, At, B1); BAR; }
;   { LDB(B0, 1, 0); LDA(At, 1, 0); WAIT_V(2); BAR; WAIT_L(0); MMA(0, 0, At, B0); BAR;
	s_nop 0
	ds_read_b128 v[104:107], v154
	ds_read_b128 v[112:115], v154 offset:256
	ds_read_b128 v[120:123], v155
	ds_read_b128 v[220:223], v155 offset:256
	s_barrier
	s_waitcnt lgkmcnt(0)
	s_setprio 1
	v_mfma_f32_16x16x32_bf16 v[84:87], v[104:107], v[184:187], v[84:87]
	v_mfma_f32_16x16x32_bf16 v[76:79], v[104:107], v[192:195], v[76:79]
	v_mfma_f32_16x16x32_bf16 v[72:75], v[112:115], v[192:195], v[72:75]
	v_mfma_f32_16x16x32_bf16 v[92:95], v[104:107], v[176:179], v[92:95]
	v_mfma_f32_16x16x32_bf16 v[88:91], v[112:115], v[176:179], v[88:91]
	v_mfma_f32_16x16x32_bf16 v[84:87], v[120:123], v[188:191], v[84:87]
	v_mfma_f32_16x16x32_bf16 v[80:83], v[112:115], v[184:187], v[80:83]
	v_mfma_f32_16x16x32_bf16 v[76:79], v[120:123], v[196:199], v[76:79]
	v_mfma_f32_16x16x32_bf16 v[72:75], v[220:223], v[196:199], v[72:75]
	v_mfma_f32_16x16x32_bf16 v[68:71], v[104:107], v[200:203], v[68:71]
	v_mfma_f32_16x16x32_bf16 v[64:67], v[112:115], v[200:203], v[64:67]
	v_mfma_f32_16x16x32_bf16 v[224:227], v[120:123], v[180:183], v[92:95]
	v_mfma_f32_16x16x32_bf16 v[176:179], v[220:223], v[180:183], v[88:91]
	v_mfma_f32_16x16x32_bf16 v[180:183], v[220:223], v[188:191], v[80:83]
	v_mfma_f32_16x16x32_bf16 v[184:187], v[120:123], v[204:207], v[68:71]
	v_mfma_f32_16x16x32_bf16 v[188:191], v[220:223], v[204:207], v[64:67]
	s_setprio 0
	s_barrier
	s_nop 0
	ds_read_b128 v[64:67], v149 offset:16384
	ds_read_b128 v[68:71], v149 offset:17408
	ds_read_b128 v[80:83], v149 offset:18432
	ds_read_b128 v[88:91], v149 offset:19456
	ds_read_b128 v[92:95], v149 offset:20480
	ds_read_b128 v[192:195], v149 offset:21504
	ds_read_b128 v[196:199], v149 offset:22528
	ds_read_b128 v[200:203], v149 offset:23552
	s_waitcnt vmcnt(4)
	s_barrier
	s_waitcnt lgkmcnt(0)
	s_setprio 1
	v_mfma_f32_16x16x32_bf16 v[52:55], v[160:163], v[80:83], v[52:55]
	v_mfma_f32_16x16x32_bf16 v[44:47], v[160:163], v[92:95], v[44:47]
	v_mfma_f32_16x16x32_bf16 v[36:39], v[160:163], v[196:199], v[36:39]
	v_mfma_f32_16x16x32_bf16 v[60:63], v[160:163], v[64:67], v[60:63]
	v_mfma_f32_16x16x32_bf16 v[56:59], v[164:167], v[64:67], v[56:59]
	v_mfma_f32_16x16x32_bf16 v[52:55], v[168:171], v[88:91], v[52:55]
	v_mfma_f32_16x16x32_bf16 v[48:51], v[164:167], v[80:83], v[48:51]
	v_mfma_f32_16x16x32_bf16 v[44:47], v[168:171], v[192:195], v[44:47]
	v_mfma_f32_16x16x32_bf16 v[40:43], v[164:167], v[92:95], v[40:43]
	v_mfma_f32_16x16x32_bf16 v[36:39], v[168:171], v[200:203], v[36:39]
	v_mfma_f32_16x16x32_bf16 v[32:35], v[164:167], v[196:199], v[32:35]
	v_mfma_f32_16x16x32_bf16 v[204:207], v[168:171], v[68:71], v[60:63]
	v_mfma_f32_16x16x32_bf16 v[228:231], v[172:175], v[68:71], v[56:59]
	v_mfma_f32_16x16x32_bf16 v[232:235], v[172:175], v[88:91], v[48:51]
	v_mfma_f32_16x16x32_bf16 v[236:239], v[172:175], v[192:195], v[40:43]
	v_mfma_f32_16x16x32_bf16 v[160:163], v[172:175], v[200:203], v[32:35]
	v_mfma_f32_16x16x32_bf16 v[28:31], v[104:107], v[64:67], v[28:31]
	v_mfma_f32_16x16x32_bf16 v[20:23], v[104:107], v[80:83], v[20:23]
	v_mfma_f32_16x16x32_bf16 v[12:15], v[104:107], v[92:95], v[12:15]
	v_mfma_f32_16x16x32_bf16 v[4:7], v[104:107], v[196:199], v[4:7]
	v_mfma_f32_16x16x32_bf16 v[28:31], v[120:123], v[68:71], v[28:31]
	v_mfma_f32_16x16x32_bf16 v[24:27], v[112:115], v[64:67], v[24:27]
	v_mfma_f32_16x16x32_bf16 v[20:23], v[120:123], v[88:91], v[20:23]
	v_mfma_f32_16x16x32_bf16 v[16:19], v[112:115], v[80:83], v[16:19]
	v_mfma_f32_16x16x32_bf16 v[12:15], v[120:123], v[192:195], v[12:15]
	v_mfma_f32_16x16x32_bf16 v[8:11], v[112:115], v[92:95], v[8:11]
	v_mfma_f32_16x16x32_bf16 v[4:7], v[120:123], v[200:203], v[4:7]
	v_mfma_f32_16x16x32_bf16 v[0:3], v[112:115], v[196:199], v[0:3]
	v_mfma_f32_16x16x32_bf16 v[164:167], v[220:223], v[68:71], v[24:27]
	v_mfma_f32_16x16x32_bf16 v[168:171], v[220:223], v[88:91], v[16:19]
	v_mfma_f32_16x16x32_bf16 v[172:175], v[220:223], v[192:195], v[8:11]
	v_mfma_f32_16x16x32_bf16 v[192:195], v[220:223], v[200:203], v[0:3]
	s_setprio 0
	s_barrier
	s_nop 1
	ds_read_b128 v[0:3], v156
	ds_read_b128 v[8:11], v156 offset:256
	ds_read_b128 v[16:19], v157
	ds_read_b128 v[24:27], v157 offset:256
	ds_read_b128 v[32:35], v149 offset:32768
	ds_read_b128 v[40:43], v149 offset:33792
	ds_read_b128 v[48:51], v149 offset:34816
	ds_read_b128 v[56:59], v149 offset:35840
	ds_read_b128 v[60:63], v149 offset:36864
	ds_read_b128 v[68:71], v149 offset:37888
	ds_read_b128 v[196:199], v149 offset:38912
	ds_read_b128 v[200:203], v149 offset:39936
	s_waitcnt vmcnt(2)
	s_barrier
; #define LDA(dst, b, h) for (int m = 0; m < 4; ++m) { \
;     dst[m][0] = *reinterpret_cast<const bf16x8*>((char*)SA(b, h) + aoff0 + m * 2048); \
;     dst[m][1] = *reinterpret_cast<const bf16x8*>((char*)SA(b, h) + aoff1 + m * 2048); }
; #define LDB(dst, b, h) for (int n = 0; n < 2; ++n) { \
;     dst[n][0] = *reinterpret_cast<const bf16x8*>((char*)SB(b, h) + boff0 + n * 256); \
;     dst[n][1] = *reinterpret_cast<const bf16x8*>((char*)SB(b, h) + boff1 + n * 256); }
; #define MMA(ai, bj, At, Btf) do { __builtin_amdgcn_s_setprio(1); \
;     for (int m = 0; m < 4; ++m) for (int n = 0; n < 2; ++n) for (int k = 0; k < 2; ++k) \
;       acc[ai][bj][m][n] = __builtin_amdgcn_mfma_f32_16x16x32_bf16(Btf[n][k], At[m][k], acc[ai][bj][m][n], 0, 0, 0); \
;     __builtin_amdgcn_s_setprio(0); } while (0)
; #define WAIT_V(n) asm volatile("s_waitcnt vmcnt(" #n ")" ::: "memory")
; #define WAIT_L(n) asm volatile("s_waitcnt lgkmcnt(" #n ")" ::: "memory")
; #define BAR __builtin_amdgcn_s_barrier()
; template <int EPI> ...
;     ...
;   { LDB(B0, 1, 0); LDA(At, 1, 0); WAIT_V(2); BAR; WAIT_L(0); MMA(0, 0, At, B0); BAR;
;     LDB(B1, 1, 1); WAIT_V(0); BAR; WAIT_L(0); MMA(0, 1, At, B1); BAR;
;     LDA(At, 1, 1); BAR; WAIT_L(0); MMA(1, 0, At, B0); MMA(1, 1, At, B1); BAR; }
;   if (wr == 0) BAR;
	s_waitcnt lgkmcnt(0)
	s_setprio 1
	v_mfma_f32_16x16x32_bf16 v[64:67], v[0:3], v[32:35], v[124:127]
	v_mfma_f32_16x16x32_bf16 v[120:123], v[16:19], v[40:43], v[64:67]
	v_mfma_f32_16x16x32_bf16 v[64:67], v[8:11], v[32:35], v[208:211]
	v_mfma_f32_16x16x32_bf16 v[124:127], v[24:27], v[40:43], v[64:67]
	v_mfma_f32_16x16x32_bf16 v[64:67], v[0:3], v[48:51], v[116:119]
	v_mfma_f32_16x16x32_bf16 v[112:115], v[16:19], v[56:59], v[64:67]
	v_mfma_f32_16x16x32_bf16 v[64:67], v[8:11], v[48:51], v[212:215]
	v_mfma_f32_16x16x32_bf16 v[116:119], v[24:27], v[56:59], v[64:67]
	v_mfma_f32_16x16x32_bf16 v[64:67], v[0:3], v[60:63], v[108:111]
	v_mfma_f32_16x16x32_bf16 v[104:107], v[16:19], v[68:71], v[64:67]
	v_mfma_f32_16x16x32_bf16 v[64:67], v[8:11], v[60:63], v[216:219]
	v_mfma_f32_16x16x32_bf16 v[108:111], v[24:27], v[68:71], v[64:67]
	v_mfma_f32_16x16x32_bf16 v[64:67], v[0:3], v[196:199], v[100:103]
	v_mfma_f32_16x16x32_bf16 v[88:91], v[16:19], v[200:203], v[64:67]
	v_mfma_f32_16x16x32_bf16 v[64:67], v[8:11], v[196:199], v[96:99]
	v_mfma_f32_16x16x32_bf16 v[92:95], v[24:27], v[200:203], v[64:67]
	s_setprio 0
	s_barrier
	ds_read_b128 v[208:211], v158
	ds_read_b128 v[212:215], v158 offset:256
	ds_read_b128 v[216:219], v159
	ds_read_b128 v[220:223], v159 offset:256
	s_waitcnt vmcnt(0)
	s_barrier
	s_waitcnt lgkmcnt(0)
	s_setprio 1
	v_mfma_f32_16x16x32_bf16 v[64:67], v[208:211], v[32:35], v[224:227]
	v_mfma_f32_16x16x32_bf16 v[32:35], v[212:215], v[32:35], v[176:179]
	v_mfma_f32_16x16x32_bf16 v[100:103], v[220:223], v[40:43], v[32:35]
	v_mfma_f32_16x16x32_bf16 v[32:35], v[208:211], v[48:51], v[84:87]
	v_mfma_f32_16x16x32_bf16 v[80:83], v[216:219], v[56:59], v[32:35]
	v_mfma_f32_16x16x32_bf16 v[32:35], v[212:215], v[48:51], v[180:183]
	v_mfma_f32_16x16x32_bf16 v[84:87], v[220:223], v[56:59], v[32:35]
	v_mfma_f32_16x16x32_bf16 v[32:35], v[208:211], v[60:63], v[76:79]
	v_mfma_f32_16x16x32_bf16 v[96:99], v[216:219], v[40:43], v[64:67]
	v_mfma_f32_16x16x32_bf16 v[64:67], v[216:219], v[68:71], v[32:35]
	v_mfma_f32_16x16x32_bf16 v[32:35], v[212:215], v[60:63], v[72:75]
	v_mfma_f32_16x16x32_bf16 v[68:71], v[220:223], v[68:71], v[32:35]
	v_mfma_f32_16x16x32_bf16 v[32:35], v[208:211], v[196:199], v[184:187]
	v_mfma_f32_16x16x32_bf16 v[56:59], v[216:219], v[200:203], v[32:35]
	v_mfma_f32_16x16x32_bf16 v[32:35], v[212:215], v[196:199], v[188:191]
	v_mfma_f32_16x16x32_bf16 v[60:63], v[220:223], v[200:203], v[32:35]
	s_setprio 0
	s_barrier
	ds_read_b128 v[176:179], v149 offset:49152
	ds_read_b128 v[180:183], v149 offset:50176
	ds_read_b128 v[184:187], v149 offset:51200
	ds_read_b128 v[188:191], v149 offset:52224
	ds_read_b128 v[196:199], v149 offset:53248
	ds_read_b128 v[200:203], v149 offset:54272
	ds_read_b128 v[224:227], v149 offset:55296
	ds_read_b128 v[240:243], v149 offset:56320
	s_barrier
	s_waitcnt lgkmcnt(0)
	s_setprio 1
	v_mfma_f32_16x16x32_bf16 v[32:35], v[0:3], v[176:179], v[204:207]
	v_mfma_f32_16x16x32_bf16 v[72:75], v[16:19], v[180:183], v[32:35]
	v_mfma_f32_16x16x32_bf16 v[32:35], v[8:11], v[176:179], v[228:231]
	v_mfma_f32_16x16x32_bf16 v[76:79], v[24:27], v[180:183], v[32:35]
	v_mfma_f32_16x16x32_bf16 v[32:35], v[0:3], v[184:187], v[52:55]
	v_mfma_f32_16x16x32_bf16 v[48:51], v[16:19], v[188:191], v[32:35]
	v_mfma_f32_16x16x32_bf16 v[32:35], v[8:11], v[184:187], v[232:235]
	v_mfma_f32_16x16x32_bf16 v[52:55], v[24:27], v[188:191], v[32:35]
	v_mfma_f32_16x16x32_bf16 v[32:35], v[0:3], v[196:199], v[44:47]
	v_mfma_f32_16x16x32_bf16 v[40:43], v[16:19], v[200:203], v[32:35]
	v_mfma_f32_16x16x32_bf16 v[32:35], v[8:11], v[196:199], v[236:239]
	v_mfma_f32_16x16x32_bf16 v[0:3], v[0:3], v[224:227], v[36:39]
	v_mfma_f32_16x16x32_bf16 v[44:47], v[24:27], v[200:203], v[32:35]
	v_mfma_f32_16x16x32_bf16 v[32:35], v[16:19], v[240:243], v[0:3]
	v_mfma_f32_16x16x32_bf16 v[0:3], v[8:11], v[224:227], v[160:163]
	v_mfma_f32_16x16x32_bf16 v[36:39], v[24:27], v[240:243], v[0:3]
	v_mfma_f32_16x16x32_bf16 v[0:3], v[208:211], v[176:179], v[28:31]
	v_mfma_f32_16x16x32_bf16 v[24:27], v[216:219], v[180:183], v[0:3]
	v_mfma_f32_16x16x32_bf16 v[0:3], v[212:215], v[176:179], v[164:167]
	v_mfma_f32_16x16x32_bf16 v[28:31], v[220:223], v[180:183], v[0:3]
	v_mfma_f32_16x16x32_bf16 v[0:3], v[208:211], v[184:187], v[20:23]
	v_mfma_f32_16x16x32_bf16 v[16:19], v[216:219], v[188:191], v[0:3]
	v_mfma_f32_16x16x32_bf16 v[0:3], v[212:215], v[184:187], v[168:171]
	v_mfma_f32_16x16x32_bf16 v[20:23], v[220:223], v[188:191], v[0:3]
	v_mfma_f32_16x16x32_bf16 v[0:3], v[208:211], v[196:199], v[12:15]
	v_mfma_f32_16x16x32_bf16 v[8:11], v[216:219], v[200:203], v[0:3]
	v_mfma_f32_16x16x32_bf16 v[0:3], v[212:215], v[196:199], v[172:175]
	v_mfma_f32_16x16x32_bf16 v[12:15], v[220:223], v[200:203], v[0:3]
	v_mfma_f32_16x16x32_bf16 v[0:3], v[208:211], v[224:227], v[4:7]
	v_mfma_f32_16x16x32_bf16 v[4:7], v[212:215], v[224:227], v[192:195]
	v_mfma_f32_16x16x32_bf16 v[0:3], v[216:219], v[240:243], v[0:3]
	v_mfma_f32_16x16x32_bf16 v[4:7], v[220:223], v[240:243], v[4:7]
	s_setprio 0
	s_barrier
	s_and_saveexec_b64 s[60:61], s[2:3]
	s_cbranch_execz .LBB0_1146
	s_barrier
	s_branch .LBB0_1146
